# hand-off: closing barrier 4 MFMAs early, finishing wave at prio 2 for its last 4, partner at prio 1 from the start
# speedup vs baseline: 1.0089x; 1.0089x over previous
.LBB0_183:
	s_ashr_i32 s13, s12, 31
	s_lshl_b64 s[24:25], s[12:13], 19
	s_add_u32 s24, s80, s24
	s_addc_u32 s25, s81, s25
	s_and_b64 s[30:31], s[4:5], exec
	s_cselect_b32 s13, s25, s45
	s_cselect_b32 s66, s24, s44
	s_ashr_i32 s11, s10, 31
	s_lshl_b64 s[30:31], s[10:11], 19
	s_add_u32 s30, s52, s30
	s_addc_u32 s31, s53, s31
	s_and_b64 s[48:49], s[4:5], exec
	s_cselect_b32 s11, s31, s47
	s_cselect_b32 s67, s30, s46
	s_add_u32 s44, s44, 0x40080
	s_addc_u32 s45, s45, 0
	s_add_u32 s68, s46, 0x100
	s_addc_u32 s69, s47, 0
	s_mov_b32 s70, -2
	ds_read_b128 v[140:143], v147
	ds_read_b128 v[150:153], v147 offset:1024
	ds_read_b128 v[154:157], v147 offset:2048
	ds_read_b128 v[158:161], v147 offset:3072
	ds_read_b128 v[162:165], v148
	ds_read_b128 v[166:169], v148 offset:1024
	ds_read_b128 v[170:173], v148 offset:2048
	ds_read_b128 v[174:177], v148 offset:3072
	s_add_u32 s18, s44, 0xfffc0080
	s_addc_u32 s19, s45, -1
	s_cmp_eq_u32 s70, 12
	s_cselect_b32 s49, s13, s19
	s_cselect_b32 s48, s66, s18
	s_cselect_b32 s47, s11, s69
	s_cselect_b32 s46, s67, s68
	v_lshl_add_u64 v[178:179], s[44:45], 0, v[132:133]
	s_add_i32 m0, s37, 0xc000
	ds_read_b128 v[184:187], v149
	ds_read_b128 v[188:191], v149 offset:1024
	ds_read_b128 v[192:195], v149 offset:2048
	ds_read_b128 v[196:199], v149 offset:3072
	ds_read_b128 v[200:203], v149 offset:4096
	ds_read_b128 v[204:207], v149 offset:5120
	ds_read_b128 v[208:211], v149 offset:6144
	ds_read_b128 v[212:215], v149 offset:7168
	global_load_lds_dwordx4 v[178:179], off
	v_lshl_add_u64 v[178:179], s[44:45], 0, v[134:135]
	s_add_i32 m0, s37, 0xe000
	s_nop 0
	global_load_lds_dwordx4 v[178:179], off
	s_waitcnt vmcnt(8)
	s_waitcnt lgkmcnt(0)
	s_barrier
	s_setprio 1
	s_waitcnt lgkmcnt(0)
	v_mfma_f32_16x16x32_bf16 v[124:127], v[140:143], v[184:187], 0
	v_mfma_f32_16x16x32_bf16 v[124:127], v[150:153], v[188:191], v[124:127]
	v_mfma_f32_16x16x32_bf16 v[120:123], v[154:157], v[184:187], 0
	v_mfma_f32_16x16x32_bf16 v[120:123], v[158:161], v[188:191], v[120:123]
	v_mfma_f32_16x16x32_bf16 v[108:111], v[140:143], v[192:195], 0
	v_mfma_f32_16x16x32_bf16 v[108:111], v[150:153], v[196:199], v[108:111]
	v_mfma_f32_16x16x32_bf16 v[104:107], v[154:157], v[192:195], 0
	v_mfma_f32_16x16x32_bf16 v[104:107], v[158:161], v[196:199], v[104:107]
	v_mfma_f32_16x16x32_bf16 v[92:95], v[140:143], v[200:203], 0
	v_mfma_f32_16x16x32_bf16 v[92:95], v[150:153], v[204:207], v[92:95]
	v_mfma_f32_16x16x32_bf16 v[88:91], v[154:157], v[200:203], 0
	v_mfma_f32_16x16x32_bf16 v[88:91], v[158:161], v[204:207], v[88:91]
	v_mfma_f32_16x16x32_bf16 v[76:79], v[140:143], v[208:211], 0
	v_mfma_f32_16x16x32_bf16 v[76:79], v[150:153], v[212:215], v[76:79]
	v_mfma_f32_16x16x32_bf16 v[72:75], v[154:157], v[208:211], 0
	v_mfma_f32_16x16x32_bf16 v[72:75], v[158:161], v[212:215], v[72:75]
	v_mfma_f32_16x16x32_bf16 v[116:119], v[162:165], v[184:187], 0
	v_mfma_f32_16x16x32_bf16 v[116:119], v[166:169], v[188:191], v[116:119]
	v_mfma_f32_16x16x32_bf16 v[112:115], v[170:173], v[184:187], 0
	v_mfma_f32_16x16x32_bf16 v[112:115], v[174:177], v[188:191], v[112:115]
	v_mfma_f32_16x16x32_bf16 v[100:103], v[162:165], v[192:195], 0
	v_mfma_f32_16x16x32_bf16 v[100:103], v[166:169], v[196:199], v[100:103]
	v_mfma_f32_16x16x32_bf16 v[96:99], v[170:173], v[192:195], 0
	v_mfma_f32_16x16x32_bf16 v[96:99], v[174:177], v[196:199], v[96:99]
	v_mfma_f32_16x16x32_bf16 v[84:87], v[162:165], v[200:203], 0
	v_mfma_f32_16x16x32_bf16 v[84:87], v[166:169], v[204:207], v[84:87]
	v_mfma_f32_16x16x32_bf16 v[80:83], v[170:173], v[200:203], 0
	v_mfma_f32_16x16x32_bf16 v[80:83], v[174:177], v[204:207], v[80:83]
	s_setprio 2
	s_barrier
	v_mfma_f32_16x16x32_bf16 v[68:71], v[162:165], v[208:211], 0
	v_mfma_f32_16x16x32_bf16 v[68:71], v[166:169], v[212:215], v[68:71]
	v_mfma_f32_16x16x32_bf16 v[64:67], v[170:173], v[208:211], 0
	v_mfma_f32_16x16x32_bf16 v[64:67], v[174:177], v[212:215], v[64:67]
	s_setprio 0
	s_add_i32 s18, s62, s54
	v_lshl_add_u64 v[178:179], s[46:47], 0, v[130:131]
	s_mov_b32 m0, s18
	ds_read_b128 v[184:187], v149 offset:16384
	ds_read_b128 v[188:191], v149 offset:17408
	ds_read_b128 v[192:195], v149 offset:18432
	ds_read_b128 v[196:199], v149 offset:19456
	ds_read_b128 v[200:203], v149 offset:20480
	ds_read_b128 v[204:207], v149 offset:21504
	ds_read_b128 v[208:211], v149 offset:22528
	ds_read_b128 v[212:215], v149 offset:23552
	global_load_lds_dwordx4 v[178:179], off
	s_add_i32 m0, s18, 0x2000
	s_add_u32 s72, s46, 0x40000
	v_lshl_add_u64 v[216:217], s[46:47], 0, v[128:129]
	s_addc_u32 s73, s47, 0
	s_add_i32 s18, s63, s54
	global_load_lds_dwordx4 v[216:217], off
	v_lshl_add_u64 v[218:219], s[72:73], 0, v[130:131]
	s_mov_b32 m0, s18
	v_lshl_add_u64 v[220:221], s[48:49], 0, v[128:129]
	global_load_lds_dwordx4 v[218:219], off
	v_lshl_add_u64 v[218:219], s[72:73], 0, v[128:129]
	s_add_i32 m0, s18, 0x2000
	s_nop 0
	global_load_lds_dwordx4 v[218:219], off
	v_lshl_add_u64 v[218:219], s[48:49], 0, v[130:131]
	s_mov_b32 m0, s37
	s_nop 0
	global_load_lds_dwordx4 v[218:219], off
	s_mov_b32 m0, s56
	s_nop 0
	global_load_lds_dwordx4 v[220:221], off
	s_waitcnt vmcnt(8)
	s_waitcnt lgkmcnt(0)
	s_barrier
	s_setprio 1
	s_waitcnt lgkmcnt(0)
	v_mfma_f32_16x16x32_bf16 v[60:63], v[140:143], v[184:187], 0
	v_mfma_f32_16x16x32_bf16 v[60:63], v[150:153], v[188:191], v[60:63]
	v_mfma_f32_16x16x32_bf16 v[56:59], v[154:157], v[184:187], 0
	v_mfma_f32_16x16x32_bf16 v[56:59], v[158:161], v[188:191], v[56:59]
	v_mfma_f32_16x16x32_bf16 v[44:47], v[140:143], v[192:195], 0
	v_mfma_f32_16x16x32_bf16 v[44:47], v[150:153], v[196:199], v[44:47]
	v_mfma_f32_16x16x32_bf16 v[40:43], v[154:157], v[192:195], 0
	v_mfma_f32_16x16x32_bf16 v[40:43], v[158:161], v[196:199], v[40:43]
	v_mfma_f32_16x16x32_bf16 v[28:31], v[140:143], v[200:203], 0
	v_mfma_f32_16x16x32_bf16 v[28:31], v[150:153], v[204:207], v[28:31]
	v_mfma_f32_16x16x32_bf16 v[24:27], v[154:157], v[200:203], 0
	v_mfma_f32_16x16x32_bf16 v[24:27], v[158:161], v[204:207], v[24:27]
	v_mfma_f32_16x16x32_bf16 v[12:15], v[140:143], v[208:211], 0
	v_mfma_f32_16x16x32_bf16 v[12:15], v[150:153], v[212:215], v[12:15]
	v_mfma_f32_16x16x32_bf16 v[8:11], v[154:157], v[208:211], 0
	v_mfma_f32_16x16x32_bf16 v[8:11], v[158:161], v[212:215], v[8:11]
	v_mfma_f32_16x16x32_bf16 v[52:55], v[162:165], v[184:187], 0
	v_mfma_f32_16x16x32_bf16 v[52:55], v[166:169], v[188:191], v[52:55]
	v_mfma_f32_16x16x32_bf16 v[48:51], v[170:173], v[184:187], 0
	v_mfma_f32_16x16x32_bf16 v[48:51], v[174:177], v[188:191], v[48:51]
	v_mfma_f32_16x16x32_bf16 v[36:39], v[162:165], v[192:195], 0
	v_mfma_f32_16x16x32_bf16 v[36:39], v[166:169], v[196:199], v[36:39]
	v_mfma_f32_16x16x32_bf16 v[32:35], v[170:173], v[192:195], 0
	v_mfma_f32_16x16x32_bf16 v[32:35], v[174:177], v[196:199], v[32:35]
	v_mfma_f32_16x16x32_bf16 v[20:23], v[162:165], v[200:203], 0
	v_mfma_f32_16x16x32_bf16 v[20:23], v[166:169], v[204:207], v[20:23]
	v_mfma_f32_16x16x32_bf16 v[16:19], v[170:173], v[200:203], 0
	v_mfma_f32_16x16x32_bf16 v[16:19], v[174:177], v[204:207], v[16:19]
	s_setprio 2
	s_barrier
	v_mfma_f32_16x16x32_bf16 v[4:7], v[162:165], v[208:211], 0
	v_mfma_f32_16x16x32_bf16 v[4:7], v[166:169], v[212:215], v[4:7]
	v_mfma_f32_16x16x32_bf16 v[0:3], v[170:173], v[208:211], 0
	v_mfma_f32_16x16x32_bf16 v[0:3], v[174:177], v[212:215], v[0:3]
	s_setprio 0
	s_branch .Lmid_gemm0
.LBB0_184:
	ds_read_b128 v[140:143], v147
	ds_read_b128 v[150:153], v147 offset:1024
	ds_read_b128 v[154:157], v147 offset:2048
	ds_read_b128 v[158:161], v147 offset:3072
	ds_read_b128 v[162:165], v148
	ds_read_b128 v[166:169], v148 offset:1024
	ds_read_b128 v[170:173], v148 offset:2048
	ds_read_b128 v[174:177], v148 offset:3072
	s_add_u32 s18, s44, 0xfffc0080
	s_addc_u32 s19, s45, -1
	s_cmp_eq_u32 s70, 12
	s_cselect_b32 s49, s13, s19
	s_cselect_b32 s48, s66, s18
	s_cselect_b32 s47, s11, s69
	s_cselect_b32 s46, s67, s68
	v_lshl_add_u64 v[178:179], s[44:45], 0, v[132:133]
	s_add_i32 m0, s37, 0xc000
	ds_read_b128 v[184:187], v149
	ds_read_b128 v[188:191], v149 offset:1024
	ds_read_b128 v[192:195], v149 offset:2048
	ds_read_b128 v[196:199], v149 offset:3072
	ds_read_b128 v[200:203], v149 offset:4096
	ds_read_b128 v[204:207], v149 offset:5120
	ds_read_b128 v[208:211], v149 offset:6144
	ds_read_b128 v[212:215], v149 offset:7168
	global_load_lds_dwordx4 v[178:179], off
	v_lshl_add_u64 v[178:179], s[44:45], 0, v[134:135]
	s_add_i32 m0, s37, 0xe000
	s_nop 0
	global_load_lds_dwordx4 v[178:179], off
	s_waitcnt vmcnt(8)
	s_waitcnt lgkmcnt(0)
	s_barrier
	s_setprio 1
	s_waitcnt lgkmcnt(0)
	v_mfma_f32_16x16x32_bf16 v[124:127], v[140:143], v[184:187], v[124:127]
	v_mfma_f32_16x16x32_bf16 v[124:127], v[150:153], v[188:191], v[124:127]
	v_mfma_f32_16x16x32_bf16 v[120:123], v[154:157], v[184:187], v[120:123]
	v_mfma_f32_16x16x32_bf16 v[120:123], v[158:161], v[188:191], v[120:123]
	v_mfma_f32_16x16x32_bf16 v[108:111], v[140:143], v[192:195], v[108:111]
	v_mfma_f32_16x16x32_bf16 v[108:111], v[150:153], v[196:199], v[108:111]
	v_mfma_f32_16x16x32_bf16 v[104:107], v[154:157], v[192:195], v[104:107]
	v_mfma_f32_16x16x32_bf16 v[104:107], v[158:161], v[196:199], v[104:107]
	v_mfma_f32_16x16x32_bf16 v[92:95], v[140:143], v[200:203], v[92:95]
	v_mfma_f32_16x16x32_bf16 v[92:95], v[150:153], v[204:207], v[92:95]
	v_mfma_f32_16x16x32_bf16 v[88:91], v[154:157], v[200:203], v[88:91]
	v_mfma_f32_16x16x32_bf16 v[88:91], v[158:161], v[204:207], v[88:91]
	v_mfma_f32_16x16x32_bf16 v[76:79], v[140:143], v[208:211], v[76:79]
	v_mfma_f32_16x16x32_bf16 v[76:79], v[150:153], v[212:215], v[76:79]
	v_mfma_f32_16x16x32_bf16 v[72:75], v[154:157], v[208:211], v[72:75]
	v_mfma_f32_16x16x32_bf16 v[72:75], v[158:161], v[212:215], v[72:75]
	v_mfma_f32_16x16x32_bf16 v[116:119], v[162:165], v[184:187], v[116:119]
	v_mfma_f32_16x16x32_bf16 v[116:119], v[166:169], v[188:191], v[116:119]
	v_mfma_f32_16x16x32_bf16 v[112:115], v[170:173], v[184:187], v[112:115]
	v_mfma_f32_16x16x32_bf16 v[112:115], v[174:177], v[188:191], v[112:115]
	v_mfma_f32_16x16x32_bf16 v[100:103], v[162:165], v[192:195], v[100:103]
	v_mfma_f32_16x16x32_bf16 v[100:103], v[166:169], v[196:199], v[100:103]
	v_mfma_f32_16x16x32_bf16 v[96:99], v[170:173], v[192:195], v[96:99]
	v_mfma_f32_16x16x32_bf16 v[96:99], v[174:177], v[196:199], v[96:99]
	v_mfma_f32_16x16x32_bf16 v[84:87], v[162:165], v[200:203], v[84:87]
	v_mfma_f32_16x16x32_bf16 v[84:87], v[166:169], v[204:207], v[84:87]
	v_mfma_f32_16x16x32_bf16 v[80:83], v[170:173], v[200:203], v[80:83]
	v_mfma_f32_16x16x32_bf16 v[80:83], v[174:177], v[204:207], v[80:83]
	s_setprio 2
	s_barrier
	v_mfma_f32_16x16x32_bf16 v[68:71], v[162:165], v[208:211], v[68:71]
	v_mfma_f32_16x16x32_bf16 v[68:71], v[166:169], v[212:215], v[68:71]
	v_mfma_f32_16x16x32_bf16 v[64:67], v[170:173], v[208:211], v[64:67]
	v_mfma_f32_16x16x32_bf16 v[64:67], v[174:177], v[212:215], v[64:67]
	s_setprio 0
	s_add_i32 s18, s62, s54
	v_lshl_add_u64 v[178:179], s[46:47], 0, v[130:131]
	s_mov_b32 m0, s18
	ds_read_b128 v[184:187], v149 offset:16384
	ds_read_b128 v[188:191], v149 offset:17408
	ds_read_b128 v[192:195], v149 offset:18432
	ds_read_b128 v[196:199], v149 offset:19456
	ds_read_b128 v[200:203], v149 offset:20480
	ds_read_b128 v[204:207], v149 offset:21504
	ds_read_b128 v[208:211], v149 offset:22528
	ds_read_b128 v[212:215], v149 offset:23552
	global_load_lds_dwordx4 v[178:179], off
	s_add_i32 m0, s18, 0x2000
	s_add_u32 s72, s46, 0x40000
	v_lshl_add_u64 v[216:217], s[46:47], 0, v[128:129]
	s_addc_u32 s73, s47, 0
	s_add_i32 s18, s63, s54
	global_load_lds_dwordx4 v[216:217], off
	v_lshl_add_u64 v[218:219], s[72:73], 0, v[130:131]
	s_mov_b32 m0, s18
	v_lshl_add_u64 v[220:221], s[48:49], 0, v[128:129]
	global_load_lds_dwordx4 v[218:219], off
	v_lshl_add_u64 v[218:219], s[72:73], 0, v[128:129]
	s_add_i32 m0, s18, 0x2000
	s_nop 0
	global_load_lds_dwordx4 v[218:219], off
	v_lshl_add_u64 v[218:219], s[48:49], 0, v[130:131]
	s_mov_b32 m0, s37
	s_nop 0
	global_load_lds_dwordx4 v[218:219], off
	s_mov_b32 m0, s56
	s_nop 0
	global_load_lds_dwordx4 v[220:221], off
	s_waitcnt vmcnt(8)
	s_waitcnt lgkmcnt(0)
	s_barrier
	s_setprio 1
	s_waitcnt lgkmcnt(0)
	v_mfma_f32_16x16x32_bf16 v[60:63], v[140:143], v[184:187], v[60:63]
	v_mfma_f32_16x16x32_bf16 v[60:63], v[150:153], v[188:191], v[60:63]
	v_mfma_f32_16x16x32_bf16 v[56:59], v[154:157], v[184:187], v[56:59]
	v_mfma_f32_16x16x32_bf16 v[56:59], v[158:161], v[188:191], v[56:59]
	v_mfma_f32_16x16x32_bf16 v[44:47], v[140:143], v[192:195], v[44:47]
	v_mfma_f32_16x16x32_bf16 v[44:47], v[150:153], v[196:199], v[44:47]
	v_mfma_f32_16x16x32_bf16 v[40:43], v[154:157], v[192:195], v[40:43]
	v_mfma_f32_16x16x32_bf16 v[40:43], v[158:161], v[196:199], v[40:43]
	v_mfma_f32_16x16x32_bf16 v[28:31], v[140:143], v[200:203], v[28:31]
	v_mfma_f32_16x16x32_bf16 v[28:31], v[150:153], v[204:207], v[28:31]
	v_mfma_f32_16x16x32_bf16 v[24:27], v[154:157], v[200:203], v[24:27]
	v_mfma_f32_16x16x32_bf16 v[24:27], v[158:161], v[204:207], v[24:27]
	v_mfma_f32_16x16x32_bf16 v[12:15], v[140:143], v[208:211], v[12:15]
	v_mfma_f32_16x16x32_bf16 v[12:15], v[150:153], v[212:215], v[12:15]
	v_mfma_f32_16x16x32_bf16 v[8:11], v[154:157], v[208:211], v[8:11]
	v_mfma_f32_16x16x32_bf16 v[8:11], v[158:161], v[212:215], v[8:11]
	v_mfma_f32_16x16x32_bf16 v[52:55], v[162:165], v[184:187], v[52:55]
	v_mfma_f32_16x16x32_bf16 v[52:55], v[166:169], v[188:191], v[52:55]
	v_mfma_f32_16x16x32_bf16 v[48:51], v[170:173], v[184:187], v[48:51]
	v_mfma_f32_16x16x32_bf16 v[48:51], v[174:177], v[188:191], v[48:51]
	v_mfma_f32_16x16x32_bf16 v[36:39], v[162:165], v[192:195], v[36:39]
	v_mfma_f32_16x16x32_bf16 v[36:39], v[166:169], v[196:199], v[36:39]
	v_mfma_f32_16x16x32_bf16 v[32:35], v[170:173], v[192:195], v[32:35]
	v_mfma_f32_16x16x32_bf16 v[32:35], v[174:177], v[196:199], v[32:35]
	v_mfma_f32_16x16x32_bf16 v[20:23], v[162:165], v[200:203], v[20:23]
	v_mfma_f32_16x16x32_bf16 v[20:23], v[166:169], v[204:207], v[20:23]
	v_mfma_f32_16x16x32_bf16 v[16:19], v[170:173], v[200:203], v[16:19]
	v_mfma_f32_16x16x32_bf16 v[16:19], v[174:177], v[204:207], v[16:19]
	s_setprio 2
	s_barrier
	v_mfma_f32_16x16x32_bf16 v[4:7], v[162:165], v[208:211], v[4:7]
	v_mfma_f32_16x16x32_bf16 v[4:7], v[166:169], v[212:215], v[4:7]
	v_mfma_f32_16x16x32_bf16 v[0:3], v[170:173], v[208:211], v[0:3]
	v_mfma_f32_16x16x32_bf16 v[0:3], v[174:177], v[212:215], v[0:3]
	s_setprio 0
.Lmid_gemm0:
	s_add_i32 s18, 0, 0x18000
	s_add_i32 s19, 0, 0x1c000
	v_add_u32_e32 v158, s18, v145
	v_add_u32_e32 v174, s19, v145
	ds_read_b128 v[140:143], v158
	ds_read_b128 v[150:153], v158 offset:1024
	ds_read_b128 v[154:157], v158 offset:2048
	ds_read_b128 v[158:161], v158 offset:3072
	ds_read_b128 v[162:165], v174
	ds_read_b128 v[166:169], v174 offset:1024
	ds_read_b128 v[170:173], v174 offset:2048
	ds_read_b128 v[174:177], v174 offset:3072
	s_add_u32 s48, s48, 0x40000
	s_addc_u32 s49, s49, 0
	s_mov_b32 m0, s57
	v_lshl_add_u64 v[222:223], s[48:49], 0, v[130:131]
	ds_read_b128 v[184:187], v149 offset:32768
	ds_read_b128 v[188:191], v149 offset:33792
	ds_read_b128 v[192:195], v149 offset:34816
	ds_read_b128 v[196:199], v149 offset:35840
	ds_read_b128 v[200:203], v149 offset:36864
	ds_read_b128 v[204:207], v149 offset:37888
	ds_read_b128 v[208:211], v149 offset:38912
	ds_read_b128 v[212:215], v149 offset:39936
	global_load_lds_dwordx4 v[222:223], off
	v_lshl_add_u64 v[222:223], s[48:49], 0, v[128:129]
	s_mov_b32 m0, s58
	s_nop 0
	global_load_lds_dwordx4 v[222:223], off
	s_waitcnt vmcnt(8)
	s_waitcnt lgkmcnt(0)
	s_barrier
	s_setprio 1
	s_waitcnt lgkmcnt(0)
	v_mfma_f32_16x16x32_bf16 v[124:127], v[140:143], v[184:187], v[124:127]
	v_mfma_f32_16x16x32_bf16 v[124:127], v[150:153], v[188:191], v[124:127]
	v_mfma_f32_16x16x32_bf16 v[120:123], v[154:157], v[184:187], v[120:123]
	v_mfma_f32_16x16x32_bf16 v[120:123], v[158:161], v[188:191], v[120:123]
	v_mfma_f32_16x16x32_bf16 v[108:111], v[140:143], v[192:195], v[108:111]
	v_mfma_f32_16x16x32_bf16 v[108:111], v[150:153], v[196:199], v[108:111]
	v_mfma_f32_16x16x32_bf16 v[104:107], v[154:157], v[192:195], v[104:107]
	v_mfma_f32_16x16x32_bf16 v[104:107], v[158:161], v[196:199], v[104:107]
	v_mfma_f32_16x16x32_bf16 v[92:95], v[140:143], v[200:203], v[92:95]
	v_mfma_f32_16x16x32_bf16 v[92:95], v[150:153], v[204:207], v[92:95]
	v_mfma_f32_16x16x32_bf16 v[88:91], v[154:157], v[200:203], v[88:91]
	v_mfma_f32_16x16x32_bf16 v[88:91], v[158:161], v[204:207], v[88:91]
	v_mfma_f32_16x16x32_bf16 v[76:79], v[140:143], v[208:211], v[76:79]
	v_mfma_f32_16x16x32_bf16 v[76:79], v[150:153], v[212:215], v[76:79]
	v_mfma_f32_16x16x32_bf16 v[72:75], v[154:157], v[208:211], v[72:75]
	v_mfma_f32_16x16x32_bf16 v[72:75], v[158:161], v[212:215], v[72:75]
	v_mfma_f32_16x16x32_bf16 v[116:119], v[162:165], v[184:187], v[116:119]
	v_mfma_f32_16x16x32_bf16 v[116:119], v[166:169], v[188:191], v[116:119]
	v_mfma_f32_16x16x32_bf16 v[112:115], v[170:173], v[184:187], v[112:115]
	v_mfma_f32_16x16x32_bf16 v[112:115], v[174:177], v[188:191], v[112:115]
	v_mfma_f32_16x16x32_bf16 v[100:103], v[162:165], v[192:195], v[100:103]
	v_mfma_f32_16x16x32_bf16 v[100:103], v[166:169], v[196:199], v[100:103]
	v_mfma_f32_16x16x32_bf16 v[96:99], v[170:173], v[192:195], v[96:99]
	v_mfma_f32_16x16x32_bf16 v[96:99], v[174:177], v[196:199], v[96:99]
	v_mfma_f32_16x16x32_bf16 v[84:87], v[162:165], v[200:203], v[84:87]
	v_mfma_f32_16x16x32_bf16 v[84:87], v[166:169], v[204:207], v[84:87]
	v_mfma_f32_16x16x32_bf16 v[80:83], v[170:173], v[200:203], v[80:83]
	v_mfma_f32_16x16x32_bf16 v[80:83], v[174:177], v[204:207], v[80:83]
	s_setprio 2
	s_barrier
	v_mfma_f32_16x16x32_bf16 v[68:71], v[162:165], v[208:211], v[68:71]
	v_mfma_f32_16x16x32_bf16 v[68:71], v[166:169], v[212:215], v[68:71]
	v_mfma_f32_16x16x32_bf16 v[64:67], v[170:173], v[208:211], v[64:67]
	v_mfma_f32_16x16x32_bf16 v[64:67], v[174:177], v[212:215], v[64:67]
	s_setprio 0
	s_add_i32 s18, s18, s54
	v_lshl_add_u64 v[178:179], v[178:179], 0, s[6:7]
	s_mov_b32 m0, s18
	ds_read_b128 v[184:187], v149 offset:49152
	ds_read_b128 v[188:191], v149 offset:50176
	ds_read_b128 v[192:195], v149 offset:51200
	ds_read_b128 v[196:199], v149 offset:52224
	ds_read_b128 v[200:203], v149 offset:53248
	ds_read_b128 v[204:207], v149 offset:54272
	ds_read_b128 v[208:211], v149 offset:55296
	ds_read_b128 v[212:215], v149 offset:56320
	global_load_lds_dwordx4 v[178:179], off
	s_add_i32 m0, s18, 0x2000
	s_add_u32 s46, s46, 0x40080
	v_lshl_add_u64 v[178:179], v[216:217], 0, s[6:7]
	s_addc_u32 s47, s47, 0
	s_add_i32 s18, s19, s54
	global_load_lds_dwordx4 v[178:179], off
	v_lshl_add_u64 v[178:179], s[46:47], 0, v[130:131]
	s_mov_b32 m0, s18
	s_nop 0
	global_load_lds_dwordx4 v[178:179], off
	v_lshl_add_u64 v[178:179], s[46:47], 0, v[128:129]
	s_add_i32 m0, s18, 0x2000
	s_nop 0
	global_load_lds_dwordx4 v[178:179], off
	v_lshl_add_u64 v[178:179], v[218:219], 0, s[6:7]
	s_mov_b32 m0, s60
	s_nop 0
	global_load_lds_dwordx4 v[178:179], off
	v_lshl_add_u64 v[178:179], v[220:221], 0, s[6:7]
	s_mov_b32 m0, s61
	s_nop 0
	global_load_lds_dwordx4 v[178:179], off
	s_waitcnt vmcnt(8)
	s_waitcnt lgkmcnt(0)
	s_barrier
	s_setprio 1
	s_waitcnt lgkmcnt(0)
	v_mfma_f32_16x16x32_bf16 v[60:63], v[140:143], v[184:187], v[60:63]
	v_mfma_f32_16x16x32_bf16 v[60:63], v[150:153], v[188:191], v[60:63]
	v_mfma_f32_16x16x32_bf16 v[56:59], v[154:157], v[184:187], v[56:59]
	v_mfma_f32_16x16x32_bf16 v[56:59], v[158:161], v[188:191], v[56:59]
	v_mfma_f32_16x16x32_bf16 v[44:47], v[140:143], v[192:195], v[44:47]
	v_mfma_f32_16x16x32_bf16 v[44:47], v[150:153], v[196:199], v[44:47]
	v_mfma_f32_16x16x32_bf16 v[40:43], v[154:157], v[192:195], v[40:43]
	v_mfma_f32_16x16x32_bf16 v[40:43], v[158:161], v[196:199], v[40:43]
	v_mfma_f32_16x16x32_bf16 v[28:31], v[140:143], v[200:203], v[28:31]
	v_mfma_f32_16x16x32_bf16 v[28:31], v[150:153], v[204:207], v[28:31]
	v_mfma_f32_16x16x32_bf16 v[24:27], v[154:157], v[200:203], v[24:27]
	v_mfma_f32_16x16x32_bf16 v[24:27], v[158:161], v[204:207], v[24:27]
	v_mfma_f32_16x16x32_bf16 v[12:15], v[140:143], v[208:211], v[12:15]
	v_mfma_f32_16x16x32_bf16 v[12:15], v[150:153], v[212:215], v[12:15]
	v_mfma_f32_16x16x32_bf16 v[8:11], v[154:157], v[208:211], v[8:11]
	v_mfma_f32_16x16x32_bf16 v[8:11], v[158:161], v[212:215], v[8:11]
	v_mfma_f32_16x16x32_bf16 v[52:55], v[162:165], v[184:187], v[52:55]
	v_mfma_f32_16x16x32_bf16 v[52:55], v[166:169], v[188:191], v[52:55]
	v_mfma_f32_16x16x32_bf16 v[48:51], v[170:173], v[184:187], v[48:51]
	v_mfma_f32_16x16x32_bf16 v[48:51], v[174:177], v[188:191], v[48:51]
	v_mfma_f32_16x16x32_bf16 v[36:39], v[162:165], v[192:195], v[36:39]
	v_mfma_f32_16x16x32_bf16 v[36:39], v[166:169], v[196:199], v[36:39]
	v_mfma_f32_16x16x32_bf16 v[32:35], v[170:173], v[192:195], v[32:35]
	v_mfma_f32_16x16x32_bf16 v[32:35], v[174:177], v[196:199], v[32:35]
	v_mfma_f32_16x16x32_bf16 v[20:23], v[162:165], v[200:203], v[20:23]
	v_mfma_f32_16x16x32_bf16 v[20:23], v[166:169], v[204:207], v[20:23]
	v_mfma_f32_16x16x32_bf16 v[16:19], v[170:173], v[200:203], v[16:19]
	v_mfma_f32_16x16x32_bf16 v[16:19], v[174:177], v[204:207], v[16:19]
	s_setprio 2
	s_barrier
	v_mfma_f32_16x16x32_bf16 v[4:7], v[162:165], v[208:211], v[4:7]
	v_mfma_f32_16x16x32_bf16 v[4:7], v[166:169], v[212:215], v[4:7]
	v_mfma_f32_16x16x32_bf16 v[0:3], v[170:173], v[208:211], v[0:3]
	v_mfma_f32_16x16x32_bf16 v[0:3], v[174:177], v[212:215], v[0:3]
	s_setprio 0
	s_add_i32 s70, s70, 2
	s_add_u32 s44, s44, 0x100
	s_addc_u32 s45, s45, 0
	s_add_u32 s68, s68, 0x100
	s_addc_u32 s69, s69, 0
	s_cmp_gt_u32 s70, 13
	s_cbranch_scc0 .LBB0_184
	s_and_b64 vcc, exec, s[8:9]
	s_cbranch_vccz .LBB0_187
	s_barrier

.LBB0_263:
	s_add_u32 s84, s54, 0x100
	s_addc_u32 s85, s55, 0
	s_mov_b32 s86, -2
	ds_read_b128 v[152:155], v149
	ds_read_b128 v[156:159], v149 offset:1024
	ds_read_b128 v[160:163], v149 offset:2048
	ds_read_b128 v[164:167], v149 offset:3072
	ds_read_b128 v[168:171], v150
	ds_read_b128 v[172:175], v150 offset:1024
	ds_read_b128 v[176:179], v150 offset:2048
	ds_read_b128 v[184:187], v150 offset:3072
	s_add_u32 s54, s52, 0x100
	s_addc_u32 s55, s53, 0
	s_cmp_eq_u32 s86, 40
	s_cselect_b32 s59, s7, s55
	s_cselect_b32 s58, s6, s54
	s_cselect_b32 s57, s49, s85
	s_cselect_b32 s56, s48, s84
	v_lshl_add_u64 v[144:145], s[52:53], 0, v[136:137]
	s_add_i32 m0, s63, 0xc000
	ds_read_b128 v[188:191], v151
	ds_read_b128 v[192:195], v151 offset:1024
	ds_read_b128 v[196:199], v151 offset:2048
	ds_read_b128 v[200:203], v151 offset:3072
	ds_read_b128 v[204:207], v151 offset:4096
	ds_read_b128 v[208:211], v151 offset:5120
	ds_read_b128 v[212:215], v151 offset:6144
	ds_read_b128 v[216:219], v151 offset:7168
	global_load_lds_dwordx4 v[144:145], off
	v_lshl_add_u64 v[144:145], s[52:53], 0, v[138:139]
	s_add_i32 m0, s63, 0xe000
	s_nop 0
	global_load_lds_dwordx4 v[144:145], off
	s_waitcnt vmcnt(8)
	s_waitcnt lgkmcnt(0)
	s_barrier
	s_setprio 1
	s_waitcnt lgkmcnt(0)
	v_mfma_f32_16x16x32_bf16 v[124:127], v[152:155], v[188:191], 0
	v_mfma_f32_16x16x32_bf16 v[124:127], v[156:159], v[192:195], v[124:127]
	v_mfma_f32_16x16x32_bf16 v[120:123], v[160:163], v[188:191], 0
	v_mfma_f32_16x16x32_bf16 v[120:123], v[164:167], v[192:195], v[120:123]
	v_mfma_f32_16x16x32_bf16 v[116:119], v[152:155], v[196:199], 0
	v_mfma_f32_16x16x32_bf16 v[116:119], v[156:159], v[200:203], v[116:119]
	v_mfma_f32_16x16x32_bf16 v[108:111], v[160:163], v[196:199], 0
	v_mfma_f32_16x16x32_bf16 v[108:111], v[164:167], v[200:203], v[108:111]
	v_mfma_f32_16x16x32_bf16 v[100:103], v[152:155], v[204:207], 0
	v_mfma_f32_16x16x32_bf16 v[100:103], v[156:159], v[208:211], v[100:103]
	v_mfma_f32_16x16x32_bf16 v[92:95], v[160:163], v[204:207], 0
	v_mfma_f32_16x16x32_bf16 v[92:95], v[164:167], v[208:211], v[92:95]
	v_mfma_f32_16x16x32_bf16 v[84:87], v[152:155], v[212:215], 0
	v_mfma_f32_16x16x32_bf16 v[84:87], v[156:159], v[216:219], v[84:87]
	v_mfma_f32_16x16x32_bf16 v[76:79], v[160:163], v[212:215], 0
	v_mfma_f32_16x16x32_bf16 v[76:79], v[164:167], v[216:219], v[76:79]
	v_mfma_f32_16x16x32_bf16 v[112:115], v[168:171], v[188:191], 0
	v_mfma_f32_16x16x32_bf16 v[112:115], v[172:175], v[192:195], v[112:115]
	v_mfma_f32_16x16x32_bf16 v[104:107], v[176:179], v[188:191], 0
	v_mfma_f32_16x16x32_bf16 v[104:107], v[184:187], v[192:195], v[104:107]
	v_mfma_f32_16x16x32_bf16 v[96:99], v[168:171], v[196:199], 0
	v_mfma_f32_16x16x32_bf16 v[96:99], v[172:175], v[200:203], v[96:99]
	v_mfma_f32_16x16x32_bf16 v[88:91], v[176:179], v[196:199], 0
	v_mfma_f32_16x16x32_bf16 v[88:91], v[184:187], v[200:203], v[88:91]
	v_mfma_f32_16x16x32_bf16 v[80:83], v[168:171], v[204:207], 0
	v_mfma_f32_16x16x32_bf16 v[80:83], v[172:175], v[208:211], v[80:83]
	v_mfma_f32_16x16x32_bf16 v[72:75], v[176:179], v[204:207], 0
	v_mfma_f32_16x16x32_bf16 v[72:75], v[184:187], v[208:211], v[72:75]
	s_setprio 2
	s_barrier
	v_mfma_f32_16x16x32_bf16 v[68:71], v[168:171], v[212:215], 0
	v_mfma_f32_16x16x32_bf16 v[68:71], v[172:175], v[216:219], v[68:71]
	v_mfma_f32_16x16x32_bf16 v[64:67], v[176:179], v[212:215], 0
	v_mfma_f32_16x16x32_bf16 v[64:67], v[184:187], v[216:219], v[64:67]
	s_setprio 0
	s_add_i32 s18, s70, s62
	v_lshl_add_u64 v[144:145], s[56:57], 0, v[130:131]
	s_mov_b32 m0, s18
	ds_read_b128 v[188:191], v151 offset:16384
	ds_read_b128 v[192:195], v151 offset:17408
	ds_read_b128 v[196:199], v151 offset:18432
	ds_read_b128 v[200:203], v151 offset:19456
	ds_read_b128 v[204:207], v151 offset:20480
	ds_read_b128 v[208:211], v151 offset:21504
	ds_read_b128 v[212:215], v151 offset:22528
	ds_read_b128 v[216:219], v151 offset:23552
	global_load_lds_dwordx4 v[144:145], off
	s_add_i32 m0, s18, 0x2000
	s_add_u32 s52, s56, 0xb0000
	v_lshl_add_u64 v[220:221], s[56:57], 0, v[134:135]
	s_addc_u32 s53, s57, 0
	s_add_i32 s18, s71, s62
	global_load_lds_dwordx4 v[220:221], off
	v_lshl_add_u64 v[222:223], s[52:53], 0, v[130:131]
	s_mov_b32 m0, s18
	v_lshl_add_u64 v[224:225], s[58:59], 0, v[132:133]
	global_load_lds_dwordx4 v[222:223], off
	v_lshl_add_u64 v[222:223], s[52:53], 0, v[134:135]
	s_add_i32 m0, s18, 0x2000
	s_nop 0
	global_load_lds_dwordx4 v[222:223], off
	v_lshl_add_u64 v[222:223], s[58:59], 0, v[128:129]
	s_mov_b32 m0, s63
	s_nop 0
	global_load_lds_dwordx4 v[222:223], off
	s_mov_b32 m0, s64
	s_nop 0
	global_load_lds_dwordx4 v[224:225], off
	s_waitcnt vmcnt(8)
	s_waitcnt lgkmcnt(0)
	s_barrier
	s_setprio 1
	s_waitcnt lgkmcnt(0)
	v_mfma_f32_16x16x32_bf16 v[60:63], v[152:155], v[188:191], 0
	v_mfma_f32_16x16x32_bf16 v[60:63], v[156:159], v[192:195], v[60:63]
	v_mfma_f32_16x16x32_bf16 v[56:59], v[160:163], v[188:191], 0
	v_mfma_f32_16x16x32_bf16 v[56:59], v[164:167], v[192:195], v[56:59]
	v_mfma_f32_16x16x32_bf16 v[52:55], v[152:155], v[196:199], 0
	v_mfma_f32_16x16x32_bf16 v[52:55], v[156:159], v[200:203], v[52:55]
	v_mfma_f32_16x16x32_bf16 v[44:47], v[160:163], v[196:199], 0
	v_mfma_f32_16x16x32_bf16 v[44:47], v[164:167], v[200:203], v[44:47]
	v_mfma_f32_16x16x32_bf16 v[36:39], v[152:155], v[204:207], 0
	v_mfma_f32_16x16x32_bf16 v[36:39], v[156:159], v[208:211], v[36:39]
	v_mfma_f32_16x16x32_bf16 v[28:31], v[160:163], v[204:207], 0
	v_mfma_f32_16x16x32_bf16 v[28:31], v[164:167], v[208:211], v[28:31]
	v_mfma_f32_16x16x32_bf16 v[20:23], v[152:155], v[212:215], 0
	v_mfma_f32_16x16x32_bf16 v[20:23], v[156:159], v[216:219], v[20:23]
	v_mfma_f32_16x16x32_bf16 v[12:15], v[160:163], v[212:215], 0
	v_mfma_f32_16x16x32_bf16 v[12:15], v[164:167], v[216:219], v[12:15]
	v_mfma_f32_16x16x32_bf16 v[48:51], v[168:171], v[188:191], 0
	v_mfma_f32_16x16x32_bf16 v[48:51], v[172:175], v[192:195], v[48:51]
	v_mfma_f32_16x16x32_bf16 v[40:43], v[176:179], v[188:191], 0
	v_mfma_f32_16x16x32_bf16 v[40:43], v[184:187], v[192:195], v[40:43]
	v_mfma_f32_16x16x32_bf16 v[32:35], v[168:171], v[196:199], 0
	v_mfma_f32_16x16x32_bf16 v[32:35], v[172:175], v[200:203], v[32:35]
	v_mfma_f32_16x16x32_bf16 v[24:27], v[176:179], v[196:199], 0
	v_mfma_f32_16x16x32_bf16 v[24:27], v[184:187], v[200:203], v[24:27]
	v_mfma_f32_16x16x32_bf16 v[16:19], v[168:171], v[204:207], 0
	v_mfma_f32_16x16x32_bf16 v[16:19], v[172:175], v[208:211], v[16:19]
	v_mfma_f32_16x16x32_bf16 v[8:11], v[176:179], v[204:207], 0
	v_mfma_f32_16x16x32_bf16 v[8:11], v[184:187], v[208:211], v[8:11]
	s_setprio 2
	s_barrier
	v_mfma_f32_16x16x32_bf16 v[4:7], v[168:171], v[212:215], 0
	v_mfma_f32_16x16x32_bf16 v[4:7], v[172:175], v[216:219], v[4:7]
	v_mfma_f32_16x16x32_bf16 v[0:3], v[176:179], v[212:215], 0
	v_mfma_f32_16x16x32_bf16 v[0:3], v[184:187], v[216:219], v[0:3]
	s_setprio 0
	s_branch .Lmid_gemm1
.LBB0_264:
	ds_read_b128 v[152:155], v149
	ds_read_b128 v[156:159], v149 offset:1024
	ds_read_b128 v[160:163], v149 offset:2048
	ds_read_b128 v[164:167], v149 offset:3072
	ds_read_b128 v[168:171], v150
	ds_read_b128 v[172:175], v150 offset:1024
	ds_read_b128 v[176:179], v150 offset:2048
	ds_read_b128 v[184:187], v150 offset:3072
	s_add_u32 s54, s52, 0x100
	s_addc_u32 s55, s53, 0
	s_cmp_eq_u32 s86, 40
	s_cselect_b32 s59, s7, s55
	s_cselect_b32 s58, s6, s54
	s_cselect_b32 s57, s49, s85
	s_cselect_b32 s56, s48, s84
	v_lshl_add_u64 v[144:145], s[52:53], 0, v[136:137]
	s_add_i32 m0, s63, 0xc000
	ds_read_b128 v[188:191], v151
	ds_read_b128 v[192:195], v151 offset:1024
	ds_read_b128 v[196:199], v151 offset:2048
	ds_read_b128 v[200:203], v151 offset:3072
	ds_read_b128 v[204:207], v151 offset:4096
	ds_read_b128 v[208:211], v151 offset:5120
	ds_read_b128 v[212:215], v151 offset:6144
	ds_read_b128 v[216:219], v151 offset:7168
	global_load_lds_dwordx4 v[144:145], off
	v_lshl_add_u64 v[144:145], s[52:53], 0, v[138:139]
	s_add_i32 m0, s63, 0xe000
	s_nop 0
	global_load_lds_dwordx4 v[144:145], off
	s_waitcnt vmcnt(8)
	s_waitcnt lgkmcnt(0)
	s_barrier
	s_setprio 1
	s_waitcnt lgkmcnt(0)
	v_mfma_f32_16x16x32_bf16 v[124:127], v[152:155], v[188:191], v[124:127]
	v_mfma_f32_16x16x32_bf16 v[124:127], v[156:159], v[192:195], v[124:127]
	v_mfma_f32_16x16x32_bf16 v[120:123], v[160:163], v[188:191], v[120:123]
	v_mfma_f32_16x16x32_bf16 v[120:123], v[164:167], v[192:195], v[120:123]
	v_mfma_f32_16x16x32_bf16 v[116:119], v[152:155], v[196:199], v[116:119]
	v_mfma_f32_16x16x32_bf16 v[116:119], v[156:159], v[200:203], v[116:119]
	v_mfma_f32_16x16x32_bf16 v[108:111], v[160:163], v[196:199], v[108:111]
	v_mfma_f32_16x16x32_bf16 v[108:111], v[164:167], v[200:203], v[108:111]
	v_mfma_f32_16x16x32_bf16 v[100:103], v[152:155], v[204:207], v[100:103]
	v_mfma_f32_16x16x32_bf16 v[100:103], v[156:159], v[208:211], v[100:103]
	v_mfma_f32_16x16x32_bf16 v[92:95], v[160:163], v[204:207], v[92:95]
	v_mfma_f32_16x16x32_bf16 v[92:95], v[164:167], v[208:211], v[92:95]
	v_mfma_f32_16x16x32_bf16 v[84:87], v[152:155], v[212:215], v[84:87]
	v_mfma_f32_16x16x32_bf16 v[84:87], v[156:159], v[216:219], v[84:87]
	v_mfma_f32_16x16x32_bf16 v[76:79], v[160:163], v[212:215], v[76:79]
	v_mfma_f32_16x16x32_bf16 v[76:79], v[164:167], v[216:219], v[76:79]
	v_mfma_f32_16x16x32_bf16 v[112:115], v[168:171], v[188:191], v[112:115]
	v_mfma_f32_16x16x32_bf16 v[112:115], v[172:175], v[192:195], v[112:115]
	v_mfma_f32_16x16x32_bf16 v[104:107], v[176:179], v[188:191], v[104:107]
	v_mfma_f32_16x16x32_bf16 v[104:107], v[184:187], v[192:195], v[104:107]
	v_mfma_f32_16x16x32_bf16 v[96:99], v[168:171], v[196:199], v[96:99]
	v_mfma_f32_16x16x32_bf16 v[96:99], v[172:175], v[200:203], v[96:99]
	v_mfma_f32_16x16x32_bf16 v[88:91], v[176:179], v[196:199], v[88:91]
	v_mfma_f32_16x16x32_bf16 v[88:91], v[184:187], v[200:203], v[88:91]
	v_mfma_f32_16x16x32_bf16 v[80:83], v[168:171], v[204:207], v[80:83]
	v_mfma_f32_16x16x32_bf16 v[80:83], v[172:175], v[208:211], v[80:83]
	v_mfma_f32_16x16x32_bf16 v[72:75], v[176:179], v[204:207], v[72:75]
	v_mfma_f32_16x16x32_bf16 v[72:75], v[184:187], v[208:211], v[72:75]
	s_setprio 2
	s_barrier
	v_mfma_f32_16x16x32_bf16 v[68:71], v[168:171], v[212:215], v[68:71]
	v_mfma_f32_16x16x32_bf16 v[68:71], v[172:175], v[216:219], v[68:71]
	v_mfma_f32_16x16x32_bf16 v[64:67], v[176:179], v[212:215], v[64:67]
	v_mfma_f32_16x16x32_bf16 v[64:67], v[184:187], v[216:219], v[64:67]
	s_setprio 0
	s_add_i32 s18, s70, s62
	v_lshl_add_u64 v[144:145], s[56:57], 0, v[130:131]
	s_mov_b32 m0, s18
	ds_read_b128 v[188:191], v151 offset:16384
	ds_read_b128 v[192:195], v151 offset:17408
	ds_read_b128 v[196:199], v151 offset:18432
	ds_read_b128 v[200:203], v151 offset:19456
	ds_read_b128 v[204:207], v151 offset:20480
	ds_read_b128 v[208:211], v151 offset:21504
	ds_read_b128 v[212:215], v151 offset:22528
	ds_read_b128 v[216:219], v151 offset:23552
	global_load_lds_dwordx4 v[144:145], off
	s_add_i32 m0, s18, 0x2000
	s_add_u32 s52, s56, 0xb0000
	v_lshl_add_u64 v[220:221], s[56:57], 0, v[134:135]
	s_addc_u32 s53, s57, 0
	s_add_i32 s18, s71, s62
	global_load_lds_dwordx4 v[220:221], off
	v_lshl_add_u64 v[222:223], s[52:53], 0, v[130:131]
	s_mov_b32 m0, s18
	v_lshl_add_u64 v[224:225], s[58:59], 0, v[132:133]
	global_load_lds_dwordx4 v[222:223], off
	v_lshl_add_u64 v[222:223], s[52:53], 0, v[134:135]
	s_add_i32 m0, s18, 0x2000
	s_nop 0
	global_load_lds_dwordx4 v[222:223], off
	v_lshl_add_u64 v[222:223], s[58:59], 0, v[128:129]
	s_mov_b32 m0, s63
	s_nop 0
	global_load_lds_dwordx4 v[222:223], off
	s_mov_b32 m0, s64
	s_nop 0
	global_load_lds_dwordx4 v[224:225], off
	s_waitcnt vmcnt(8)
	s_waitcnt lgkmcnt(0)
	s_barrier
	s_setprio 1
	s_waitcnt lgkmcnt(0)
	v_mfma_f32_16x16x32_bf16 v[60:63], v[152:155], v[188:191], v[60:63]
	v_mfma_f32_16x16x32_bf16 v[60:63], v[156:159], v[192:195], v[60:63]
	v_mfma_f32_16x16x32_bf16 v[56:59], v[160:163], v[188:191], v[56:59]
	v_mfma_f32_16x16x32_bf16 v[56:59], v[164:167], v[192:195], v[56:59]
	v_mfma_f32_16x16x32_bf16 v[52:55], v[152:155], v[196:199], v[52:55]
	v_mfma_f32_16x16x32_bf16 v[52:55], v[156:159], v[200:203], v[52:55]
	v_mfma_f32_16x16x32_bf16 v[44:47], v[160:163], v[196:199], v[44:47]
	v_mfma_f32_16x16x32_bf16 v[44:47], v[164:167], v[200:203], v[44:47]
	v_mfma_f32_16x16x32_bf16 v[36:39], v[152:155], v[204:207], v[36:39]
	v_mfma_f32_16x16x32_bf16 v[36:39], v[156:159], v[208:211], v[36:39]
	v_mfma_f32_16x16x32_bf16 v[28:31], v[160:163], v[204:207], v[28:31]
	v_mfma_f32_16x16x32_bf16 v[28:31], v[164:167], v[208:211], v[28:31]
	v_mfma_f32_16x16x32_bf16 v[20:23], v[152:155], v[212:215], v[20:23]
	v_mfma_f32_16x16x32_bf16 v[20:23], v[156:159], v[216:219], v[20:23]
	v_mfma_f32_16x16x32_bf16 v[12:15], v[160:163], v[212:215], v[12:15]
	v_mfma_f32_16x16x32_bf16 v[12:15], v[164:167], v[216:219], v[12:15]
	v_mfma_f32_16x16x32_bf16 v[48:51], v[168:171], v[188:191], v[48:51]
	v_mfma_f32_16x16x32_bf16 v[48:51], v[172:175], v[192:195], v[48:51]
	v_mfma_f32_16x16x32_bf16 v[40:43], v[176:179], v[188:191], v[40:43]
	v_mfma_f32_16x16x32_bf16 v[40:43], v[184:187], v[192:195], v[40:43]
	v_mfma_f32_16x16x32_bf16 v[32:35], v[168:171], v[196:199], v[32:35]
	v_mfma_f32_16x16x32_bf16 v[32:35], v[172:175], v[200:203], v[32:35]
	v_mfma_f32_16x16x32_bf16 v[24:27], v[176:179], v[196:199], v[24:27]
	v_mfma_f32_16x16x32_bf16 v[24:27], v[184:187], v[200:203], v[24:27]
	v_mfma_f32_16x16x32_bf16 v[16:19], v[168:171], v[204:207], v[16:19]
	v_mfma_f32_16x16x32_bf16 v[16:19], v[172:175], v[208:211], v[16:19]
	v_mfma_f32_16x16x32_bf16 v[8:11], v[176:179], v[204:207], v[8:11]
	v_mfma_f32_16x16x32_bf16 v[8:11], v[184:187], v[208:211], v[8:11]
	s_setprio 2
	s_barrier
	v_mfma_f32_16x16x32_bf16 v[4:7], v[168:171], v[212:215], v[4:7]
	v_mfma_f32_16x16x32_bf16 v[4:7], v[172:175], v[216:219], v[4:7]
	v_mfma_f32_16x16x32_bf16 v[0:3], v[176:179], v[212:215], v[0:3]
	v_mfma_f32_16x16x32_bf16 v[0:3], v[184:187], v[216:219], v[0:3]
	s_setprio 0
.Lmid_gemm1:
	s_add_i32 s18, 0, 0x18000
	s_add_i32 s19, 0, 0x1c000
	v_add_u32_e32 v164, s18, v147
	v_add_u32_e32 v181, s19, v147
	ds_read_b128 v[152:155], v164
	ds_read_b128 v[156:159], v164 offset:1024
	ds_read_b128 v[160:163], v164 offset:2048
	ds_read_b128 v[164:167], v164 offset:3072
	ds_read_b128 v[168:171], v181
	ds_read_b128 v[172:175], v181 offset:1024
	ds_read_b128 v[176:179], v181 offset:2048
	ds_read_b128 v[184:187], v181 offset:3072
	s_add_u32 s52, s58, 0xb0000
	s_addc_u32 s53, s59, 0
	s_mov_b32 m0, s65
	v_lshl_add_u64 v[226:227], s[52:53], 0, v[128:129]
	ds_read_b128 v[188:191], v151 offset:32768
	ds_read_b128 v[192:195], v151 offset:33792
	ds_read_b128 v[196:199], v151 offset:34816
	ds_read_b128 v[200:203], v151 offset:35840
	ds_read_b128 v[204:207], v151 offset:36864
	ds_read_b128 v[208:211], v151 offset:37888
	ds_read_b128 v[212:215], v151 offset:38912
	ds_read_b128 v[216:219], v151 offset:39936
	global_load_lds_dwordx4 v[226:227], off
	v_lshl_add_u64 v[226:227], s[52:53], 0, v[132:133]
	s_mov_b32 m0, s66
	s_nop 0
	global_load_lds_dwordx4 v[226:227], off
	s_waitcnt vmcnt(8)
	s_waitcnt lgkmcnt(0)
	s_barrier
	s_setprio 1
	s_waitcnt lgkmcnt(0)
	v_mfma_f32_16x16x32_bf16 v[124:127], v[152:155], v[188:191], v[124:127]
	v_mfma_f32_16x16x32_bf16 v[124:127], v[156:159], v[192:195], v[124:127]
	v_mfma_f32_16x16x32_bf16 v[120:123], v[160:163], v[188:191], v[120:123]
	v_mfma_f32_16x16x32_bf16 v[120:123], v[164:167], v[192:195], v[120:123]
	v_mfma_f32_16x16x32_bf16 v[116:119], v[152:155], v[196:199], v[116:119]
	v_mfma_f32_16x16x32_bf16 v[116:119], v[156:159], v[200:203], v[116:119]
	v_mfma_f32_16x16x32_bf16 v[108:111], v[160:163], v[196:199], v[108:111]
	v_mfma_f32_16x16x32_bf16 v[108:111], v[164:167], v[200:203], v[108:111]
	v_mfma_f32_16x16x32_bf16 v[100:103], v[152:155], v[204:207], v[100:103]
	v_mfma_f32_16x16x32_bf16 v[100:103], v[156:159], v[208:211], v[100:103]
	v_mfma_f32_16x16x32_bf16 v[92:95], v[160:163], v[204:207], v[92:95]
	v_mfma_f32_16x16x32_bf16 v[92:95], v[164:167], v[208:211], v[92:95]
	v_mfma_f32_16x16x32_bf16 v[84:87], v[152:155], v[212:215], v[84:87]
	v_mfma_f32_16x16x32_bf16 v[84:87], v[156:159], v[216:219], v[84:87]
	v_mfma_f32_16x16x32_bf16 v[76:79], v[160:163], v[212:215], v[76:79]
	v_mfma_f32_16x16x32_bf16 v[76:79], v[164:167], v[216:219], v[76:79]
	v_mfma_f32_16x16x32_bf16 v[112:115], v[168:171], v[188:191], v[112:115]
	v_mfma_f32_16x16x32_bf16 v[112:115], v[172:175], v[192:195], v[112:115]
	v_mfma_f32_16x16x32_bf16 v[104:107], v[176:179], v[188:191], v[104:107]
	v_mfma_f32_16x16x32_bf16 v[104:107], v[184:187], v[192:195], v[104:107]
	v_mfma_f32_16x16x32_bf16 v[96:99], v[168:171], v[196:199], v[96:99]
	v_mfma_f32_16x16x32_bf16 v[96:99], v[172:175], v[200:203], v[96:99]
	v_mfma_f32_16x16x32_bf16 v[88:91], v[176:179], v[196:199], v[88:91]
	v_mfma_f32_16x16x32_bf16 v[88:91], v[184:187], v[200:203], v[88:91]
	v_mfma_f32_16x16x32_bf16 v[80:83], v[168:171], v[204:207], v[80:83]
	v_mfma_f32_16x16x32_bf16 v[80:83], v[172:175], v[208:211], v[80:83]
	v_mfma_f32_16x16x32_bf16 v[72:75], v[176:179], v[204:207], v[72:75]
	v_mfma_f32_16x16x32_bf16 v[72:75], v[184:187], v[208:211], v[72:75]
	s_setprio 2
	s_barrier
	v_mfma_f32_16x16x32_bf16 v[68:71], v[168:171], v[212:215], v[68:71]
	v_mfma_f32_16x16x32_bf16 v[68:71], v[172:175], v[216:219], v[68:71]
	v_mfma_f32_16x16x32_bf16 v[64:67], v[176:179], v[212:215], v[64:67]
	v_mfma_f32_16x16x32_bf16 v[64:67], v[184:187], v[216:219], v[64:67]
	s_setprio 0
	s_add_i32 s18, s18, s62
	v_lshl_add_u64 v[144:145], v[144:145], 0, s[8:9]
	s_mov_b32 m0, s18
	ds_read_b128 v[188:191], v151 offset:49152
	ds_read_b128 v[192:195], v151 offset:50176
	ds_read_b128 v[196:199], v151 offset:51200
	ds_read_b128 v[200:203], v151 offset:52224
	ds_read_b128 v[204:207], v151 offset:53248
	ds_read_b128 v[208:211], v151 offset:54272
	ds_read_b128 v[212:215], v151 offset:55296
	ds_read_b128 v[216:219], v151 offset:56320
	global_load_lds_dwordx4 v[144:145], off
	s_add_i32 m0, s18, 0x2000
	s_add_u32 s52, s56, 0xb0080
	v_lshl_add_u64 v[144:145], v[220:221], 0, s[8:9]
	s_addc_u32 s53, s57, 0
	s_add_i32 s18, s19, s62
	global_load_lds_dwordx4 v[144:145], off
	v_lshl_add_u64 v[144:145], s[52:53], 0, v[130:131]
	s_mov_b32 m0, s18
	s_nop 0
	global_load_lds_dwordx4 v[144:145], off
	v_lshl_add_u64 v[144:145], s[52:53], 0, v[134:135]
	s_add_i32 m0, s18, 0x2000
	s_nop 0
	global_load_lds_dwordx4 v[144:145], off
	v_lshl_add_u64 v[144:145], v[222:223], 0, s[8:9]
	s_mov_b32 m0, s68
	s_nop 0
	global_load_lds_dwordx4 v[144:145], off
	v_lshl_add_u64 v[144:145], v[224:225], 0, s[8:9]
	s_mov_b32 m0, s69
	s_nop 0
	global_load_lds_dwordx4 v[144:145], off
	s_waitcnt vmcnt(8)
	s_waitcnt lgkmcnt(0)
	s_barrier
	s_setprio 1
	s_waitcnt lgkmcnt(0)
	v_mfma_f32_16x16x32_bf16 v[60:63], v[152:155], v[188:191], v[60:63]
	v_mfma_f32_16x16x32_bf16 v[60:63], v[156:159], v[192:195], v[60:63]
	v_mfma_f32_16x16x32_bf16 v[56:59], v[160:163], v[188:191], v[56:59]
	v_mfma_f32_16x16x32_bf16 v[56:59], v[164:167], v[192:195], v[56:59]
	v_mfma_f32_16x16x32_bf16 v[52:55], v[152:155], v[196:199], v[52:55]
	v_mfma_f32_16x16x32_bf16 v[52:55], v[156:159], v[200:203], v[52:55]
	v_mfma_f32_16x16x32_bf16 v[44:47], v[160:163], v[196:199], v[44:47]
	v_mfma_f32_16x16x32_bf16 v[44:47], v[164:167], v[200:203], v[44:47]
	v_mfma_f32_16x16x32_bf16 v[36:39], v[152:155], v[204:207], v[36:39]
	v_mfma_f32_16x16x32_bf16 v[36:39], v[156:159], v[208:211], v[36:39]
	v_mfma_f32_16x16x32_bf16 v[28:31], v[160:163], v[204:207], v[28:31]
	v_mfma_f32_16x16x32_bf16 v[28:31], v[164:167], v[208:211], v[28:31]
	v_mfma_f32_16x16x32_bf16 v[20:23], v[152:155], v[212:215], v[20:23]
	v_mfma_f32_16x16x32_bf16 v[20:23], v[156:159], v[216:219], v[20:23]
	v_mfma_f32_16x16x32_bf16 v[12:15], v[160:163], v[212:215], v[12:15]
	v_mfma_f32_16x16x32_bf16 v[12:15], v[164:167], v[216:219], v[12:15]
	v_mfma_f32_16x16x32_bf16 v[48:51], v[168:171], v[188:191], v[48:51]
	v_mfma_f32_16x16x32_bf16 v[48:51], v[172:175], v[192:195], v[48:51]
	v_mfma_f32_16x16x32_bf16 v[40:43], v[176:179], v[188:191], v[40:43]
	v_mfma_f32_16x16x32_bf16 v[40:43], v[184:187], v[192:195], v[40:43]
	v_mfma_f32_16x16x32_bf16 v[32:35], v[168:171], v[196:199], v[32:35]
	v_mfma_f32_16x16x32_bf16 v[32:35], v[172:175], v[200:203], v[32:35]
	v_mfma_f32_16x16x32_bf16 v[24:27], v[176:179], v[196:199], v[24:27]
	v_mfma_f32_16x16x32_bf16 v[24:27], v[184:187], v[200:203], v[24:27]
	v_mfma_f32_16x16x32_bf16 v[16:19], v[168:171], v[204:207], v[16:19]
	v_mfma_f32_16x16x32_bf16 v[16:19], v[172:175], v[208:211], v[16:19]
	v_mfma_f32_16x16x32_bf16 v[8:11], v[176:179], v[204:207], v[8:11]
	v_mfma_f32_16x16x32_bf16 v[8:11], v[184:187], v[208:211], v[8:11]
	s_setprio 2
	s_barrier
	v_mfma_f32_16x16x32_bf16 v[4:7], v[168:171], v[212:215], v[4:7]
	v_mfma_f32_16x16x32_bf16 v[4:7], v[172:175], v[216:219], v[4:7]
	v_mfma_f32_16x16x32_bf16 v[0:3], v[176:179], v[212:215], v[0:3]
	v_mfma_f32_16x16x32_bf16 v[0:3], v[184:187], v[216:219], v[0:3]
	s_setprio 0
	s_add_i32 s86, s86, 2
	s_add_u32 s84, s84, 0x100
	s_addc_u32 s85, s85, 0
	s_cmp_gt_u32 s86, 41
	s_mov_b64 s[52:53], s[54:55]
	s_cbranch_scc0 .LBB0_264
	s_and_b64 vcc, exec, s[10:11]
	s_cbranch_vccz .LBB0_267
	s_barrier

.LBB0_386:
	s_ashr_i32 s49, s48, 31
	s_lshl_b64 s[52:53], s[48:49], 19
	s_add_u32 s52, s80, s52
	s_addc_u32 s53, s81, s53
	s_and_b64 s[54:55], s[4:5], exec
	s_cselect_b32 s49, s53, s59
	s_cselect_b32 s82, s52, s58
	s_ashr_i32 s47, s46, 31
	s_lshl_b64 s[54:55], s[46:47], 19
	s_add_u32 s54, s64, s54
	s_addc_u32 s55, s65, s55
	s_and_b64 s[62:63], s[4:5], exec
	s_cselect_b32 s47, s55, s61
	s_cselect_b32 s83, s54, s60
	s_add_u32 s58, s58, 0x40080
	s_addc_u32 s59, s59, 0
	s_add_u32 s84, s60, 0x100
	s_addc_u32 s85, s61, 0
	s_mov_b32 s86, -2
	ds_read_b128 v[152:155], v148
	ds_read_b128 v[156:159], v148 offset:1024
	ds_read_b128 v[160:163], v148 offset:2048
	ds_read_b128 v[164:167], v148 offset:3072
	ds_read_b128 v[168:171], v149
	ds_read_b128 v[172:175], v149 offset:1024
	ds_read_b128 v[176:179], v149 offset:2048
	ds_read_b128 v[184:187], v149 offset:3072
	s_add_u32 s18, s58, 0xfffc0080
	s_addc_u32 s19, s59, -1
	s_cmp_eq_u32 s86, 12
	s_cselect_b32 s63, s49, s19
	s_cselect_b32 s62, s82, s18
	s_cselect_b32 s61, s47, s85
	s_cselect_b32 s60, s83, s84
	v_lshl_add_u64 v[220:221], s[58:59], 0, v[138:139]
	s_add_i32 m0, s68, 0xc000
	ds_read_b128 v[188:191], v150
	ds_read_b128 v[192:195], v150 offset:1024
	ds_read_b128 v[196:199], v150 offset:2048
	ds_read_b128 v[200:203], v150 offset:3072
	ds_read_b128 v[204:207], v150 offset:4096
	ds_read_b128 v[208:211], v150 offset:5120
	ds_read_b128 v[212:215], v150 offset:6144
	ds_read_b128 v[216:219], v150 offset:7168
	global_load_lds_dwordx4 v[220:221], off
	v_lshl_add_u64 v[220:221], s[58:59], 0, v[140:141]
	s_add_i32 m0, s68, 0xe000
	s_nop 0
	global_load_lds_dwordx4 v[220:221], off
	s_waitcnt vmcnt(8)
	s_waitcnt lgkmcnt(0)
	s_barrier
	s_setprio 1
	s_waitcnt lgkmcnt(0)
	v_mfma_f32_16x16x32_bf16 v[124:127], v[152:155], v[188:191], 0
	v_mfma_f32_16x16x32_bf16 v[124:127], v[156:159], v[192:195], v[124:127]
	v_mfma_f32_16x16x32_bf16 v[120:123], v[160:163], v[188:191], 0
	v_mfma_f32_16x16x32_bf16 v[120:123], v[164:167], v[192:195], v[120:123]
	v_mfma_f32_16x16x32_bf16 v[116:119], v[152:155], v[196:199], 0
	v_mfma_f32_16x16x32_bf16 v[116:119], v[156:159], v[200:203], v[116:119]
	v_mfma_f32_16x16x32_bf16 v[112:115], v[160:163], v[196:199], 0
	v_mfma_f32_16x16x32_bf16 v[112:115], v[164:167], v[200:203], v[112:115]
	v_mfma_f32_16x16x32_bf16 v[108:111], v[152:155], v[204:207], 0
	v_mfma_f32_16x16x32_bf16 v[108:111], v[156:159], v[208:211], v[108:111]
	v_mfma_f32_16x16x32_bf16 v[104:107], v[160:163], v[204:207], 0
	v_mfma_f32_16x16x32_bf16 v[104:107], v[164:167], v[208:211], v[104:107]
	v_mfma_f32_16x16x32_bf16 v[100:103], v[152:155], v[212:215], 0
	v_mfma_f32_16x16x32_bf16 v[100:103], v[156:159], v[216:219], v[100:103]
	v_mfma_f32_16x16x32_bf16 v[96:99], v[160:163], v[212:215], 0
	v_mfma_f32_16x16x32_bf16 v[96:99], v[164:167], v[216:219], v[96:99]
	v_mfma_f32_16x16x32_bf16 v[68:71], v[168:171], v[188:191], 0
	v_mfma_f32_16x16x32_bf16 v[68:71], v[172:175], v[192:195], v[68:71]
	v_mfma_f32_16x16x32_bf16 v[64:67], v[176:179], v[188:191], 0
	v_mfma_f32_16x16x32_bf16 v[64:67], v[184:187], v[192:195], v[64:67]
	v_mfma_f32_16x16x32_bf16 v[52:55], v[168:171], v[196:199], 0
	v_mfma_f32_16x16x32_bf16 v[52:55], v[172:175], v[200:203], v[52:55]
	v_mfma_f32_16x16x32_bf16 v[48:51], v[176:179], v[196:199], 0
	v_mfma_f32_16x16x32_bf16 v[48:51], v[184:187], v[200:203], v[48:51]
	v_mfma_f32_16x16x32_bf16 v[44:47], v[168:171], v[204:207], 0
	v_mfma_f32_16x16x32_bf16 v[44:47], v[172:175], v[208:211], v[44:47]
	v_mfma_f32_16x16x32_bf16 v[40:43], v[176:179], v[204:207], 0
	v_mfma_f32_16x16x32_bf16 v[40:43], v[184:187], v[208:211], v[40:43]
	s_setprio 2
	s_barrier
	v_mfma_f32_16x16x32_bf16 v[36:39], v[168:171], v[212:215], 0
	v_mfma_f32_16x16x32_bf16 v[36:39], v[172:175], v[216:219], v[36:39]
	v_mfma_f32_16x16x32_bf16 v[32:35], v[176:179], v[212:215], 0
	v_mfma_f32_16x16x32_bf16 v[32:35], v[184:187], v[216:219], v[32:35]
	s_setprio 0
	s_add_i32 s18, s76, s66
	v_lshl_add_u64 v[220:221], s[60:61], 0, v[132:133]
	s_mov_b32 m0, s18
	ds_read_b128 v[188:191], v150 offset:16384
	ds_read_b128 v[192:195], v150 offset:17408
	ds_read_b128 v[196:199], v150 offset:18432
	ds_read_b128 v[200:203], v150 offset:19456
	ds_read_b128 v[204:207], v150 offset:20480
	ds_read_b128 v[208:211], v150 offset:21504
	ds_read_b128 v[212:215], v150 offset:22528
	ds_read_b128 v[216:219], v150 offset:23552
	global_load_lds_dwordx4 v[220:221], off
	s_add_i32 m0, s18, 0x2000
	s_add_u32 s88, s60, 0x40000
	v_lshl_add_u64 v[222:223], s[60:61], 0, v[128:129]
	s_addc_u32 s89, s61, 0
	s_add_i32 s18, s77, s66
	global_load_lds_dwordx4 v[222:223], off
	v_lshl_add_u64 v[224:225], s[88:89], 0, v[132:133]
	s_mov_b32 m0, s18
	v_lshl_add_u64 v[226:227], s[62:63], 0, v[130:131]
	global_load_lds_dwordx4 v[224:225], off
	v_lshl_add_u64 v[224:225], s[88:89], 0, v[128:129]
	s_add_i32 m0, s18, 0x2000
	s_nop 0
	global_load_lds_dwordx4 v[224:225], off
	v_lshl_add_u64 v[224:225], s[62:63], 0, v[134:135]
	s_mov_b32 m0, s68
	s_nop 0
	global_load_lds_dwordx4 v[224:225], off
	s_mov_b32 m0, s69
	s_nop 0
	global_load_lds_dwordx4 v[226:227], off
	s_waitcnt vmcnt(8)
	s_waitcnt lgkmcnt(0)
	s_barrier
	s_setprio 1
	s_waitcnt lgkmcnt(0)
	v_mfma_f32_16x16x32_bf16 v[92:95], v[152:155], v[188:191], 0
	v_mfma_f32_16x16x32_bf16 v[92:95], v[156:159], v[192:195], v[92:95]
	v_mfma_f32_16x16x32_bf16 v[88:91], v[160:163], v[188:191], 0
	v_mfma_f32_16x16x32_bf16 v[88:91], v[164:167], v[192:195], v[88:91]
	v_mfma_f32_16x16x32_bf16 v[84:87], v[152:155], v[196:199], 0
	v_mfma_f32_16x16x32_bf16 v[84:87], v[156:159], v[200:203], v[84:87]
	v_mfma_f32_16x16x32_bf16 v[80:83], v[160:163], v[196:199], 0
	v_mfma_f32_16x16x32_bf16 v[80:83], v[164:167], v[200:203], v[80:83]
	v_mfma_f32_16x16x32_bf16 v[76:79], v[152:155], v[204:207], 0
	v_mfma_f32_16x16x32_bf16 v[76:79], v[156:159], v[208:211], v[76:79]
	v_mfma_f32_16x16x32_bf16 v[72:75], v[160:163], v[204:207], 0
	v_mfma_f32_16x16x32_bf16 v[72:75], v[164:167], v[208:211], v[72:75]
	v_mfma_f32_16x16x32_bf16 v[60:63], v[152:155], v[212:215], 0
	v_mfma_f32_16x16x32_bf16 v[60:63], v[156:159], v[216:219], v[60:63]
	v_mfma_f32_16x16x32_bf16 v[56:59], v[160:163], v[212:215], 0
	v_mfma_f32_16x16x32_bf16 v[56:59], v[164:167], v[216:219], v[56:59]
	v_mfma_f32_16x16x32_bf16 v[28:31], v[168:171], v[188:191], 0
	v_mfma_f32_16x16x32_bf16 v[28:31], v[172:175], v[192:195], v[28:31]
	v_mfma_f32_16x16x32_bf16 v[24:27], v[176:179], v[188:191], 0
	v_mfma_f32_16x16x32_bf16 v[24:27], v[184:187], v[192:195], v[24:27]
	v_mfma_f32_16x16x32_bf16 v[20:23], v[168:171], v[196:199], 0
	v_mfma_f32_16x16x32_bf16 v[20:23], v[172:175], v[200:203], v[20:23]
	v_mfma_f32_16x16x32_bf16 v[16:19], v[176:179], v[196:199], 0
	v_mfma_f32_16x16x32_bf16 v[16:19], v[184:187], v[200:203], v[16:19]
	v_mfma_f32_16x16x32_bf16 v[12:15], v[168:171], v[204:207], 0
	v_mfma_f32_16x16x32_bf16 v[12:15], v[172:175], v[208:211], v[12:15]
	v_mfma_f32_16x16x32_bf16 v[8:11], v[176:179], v[204:207], 0
	v_mfma_f32_16x16x32_bf16 v[8:11], v[184:187], v[208:211], v[8:11]
	s_setprio 2
	s_barrier
	v_mfma_f32_16x16x32_bf16 v[4:7], v[168:171], v[212:215], 0
	v_mfma_f32_16x16x32_bf16 v[4:7], v[172:175], v[216:219], v[4:7]
	v_mfma_f32_16x16x32_bf16 v[0:3], v[176:179], v[212:215], 0
	v_mfma_f32_16x16x32_bf16 v[0:3], v[184:187], v[216:219], v[0:3]
	s_setprio 0
	s_branch .Lmid_gemm2
.LBB0_387:
	ds_read_b128 v[152:155], v148
	ds_read_b128 v[156:159], v148 offset:1024
	ds_read_b128 v[160:163], v148 offset:2048
	ds_read_b128 v[164:167], v148 offset:3072
	ds_read_b128 v[168:171], v149
	ds_read_b128 v[172:175], v149 offset:1024
	ds_read_b128 v[176:179], v149 offset:2048
	ds_read_b128 v[184:187], v149 offset:3072
	s_add_u32 s18, s58, 0xfffc0080
	s_addc_u32 s19, s59, -1
	s_cmp_eq_u32 s86, 12
	s_cselect_b32 s63, s49, s19
	s_cselect_b32 s62, s82, s18
	s_cselect_b32 s61, s47, s85
	s_cselect_b32 s60, s83, s84
	v_lshl_add_u64 v[220:221], s[58:59], 0, v[138:139]
	s_add_i32 m0, s68, 0xc000
	ds_read_b128 v[188:191], v150
	ds_read_b128 v[192:195], v150 offset:1024
	ds_read_b128 v[196:199], v150 offset:2048
	ds_read_b128 v[200:203], v150 offset:3072
	ds_read_b128 v[204:207], v150 offset:4096
	ds_read_b128 v[208:211], v150 offset:5120
	ds_read_b128 v[212:215], v150 offset:6144
	ds_read_b128 v[216:219], v150 offset:7168
	global_load_lds_dwordx4 v[220:221], off
	v_lshl_add_u64 v[220:221], s[58:59], 0, v[140:141]
	s_add_i32 m0, s68, 0xe000
	s_nop 0
	global_load_lds_dwordx4 v[220:221], off
	s_waitcnt vmcnt(8)
	s_waitcnt lgkmcnt(0)
	s_barrier
	s_setprio 1
	s_waitcnt lgkmcnt(0)
	v_mfma_f32_16x16x32_bf16 v[124:127], v[152:155], v[188:191], v[124:127]
	v_mfma_f32_16x16x32_bf16 v[124:127], v[156:159], v[192:195], v[124:127]
	v_mfma_f32_16x16x32_bf16 v[120:123], v[160:163], v[188:191], v[120:123]
	v_mfma_f32_16x16x32_bf16 v[120:123], v[164:167], v[192:195], v[120:123]
	v_mfma_f32_16x16x32_bf16 v[116:119], v[152:155], v[196:199], v[116:119]
	v_mfma_f32_16x16x32_bf16 v[116:119], v[156:159], v[200:203], v[116:119]
	v_mfma_f32_16x16x32_bf16 v[112:115], v[160:163], v[196:199], v[112:115]
	v_mfma_f32_16x16x32_bf16 v[112:115], v[164:167], v[200:203], v[112:115]
	v_mfma_f32_16x16x32_bf16 v[108:111], v[152:155], v[204:207], v[108:111]
	v_mfma_f32_16x16x32_bf16 v[108:111], v[156:159], v[208:211], v[108:111]
	v_mfma_f32_16x16x32_bf16 v[104:107], v[160:163], v[204:207], v[104:107]
	v_mfma_f32_16x16x32_bf16 v[104:107], v[164:167], v[208:211], v[104:107]
	v_mfma_f32_16x16x32_bf16 v[100:103], v[152:155], v[212:215], v[100:103]
	v_mfma_f32_16x16x32_bf16 v[100:103], v[156:159], v[216:219], v[100:103]
	v_mfma_f32_16x16x32_bf16 v[96:99], v[160:163], v[212:215], v[96:99]
	v_mfma_f32_16x16x32_bf16 v[96:99], v[164:167], v[216:219], v[96:99]
	v_mfma_f32_16x16x32_bf16 v[68:71], v[168:171], v[188:191], v[68:71]
	v_mfma_f32_16x16x32_bf16 v[68:71], v[172:175], v[192:195], v[68:71]
	v_mfma_f32_16x16x32_bf16 v[64:67], v[176:179], v[188:191], v[64:67]
	v_mfma_f32_16x16x32_bf16 v[64:67], v[184:187], v[192:195], v[64:67]
	v_mfma_f32_16x16x32_bf16 v[52:55], v[168:171], v[196:199], v[52:55]
	v_mfma_f32_16x16x32_bf16 v[52:55], v[172:175], v[200:203], v[52:55]
	v_mfma_f32_16x16x32_bf16 v[48:51], v[176:179], v[196:199], v[48:51]
	v_mfma_f32_16x16x32_bf16 v[48:51], v[184:187], v[200:203], v[48:51]
	v_mfma_f32_16x16x32_bf16 v[44:47], v[168:171], v[204:207], v[44:47]
	v_mfma_f32_16x16x32_bf16 v[44:47], v[172:175], v[208:211], v[44:47]
	v_mfma_f32_16x16x32_bf16 v[40:43], v[176:179], v[204:207], v[40:43]
	v_mfma_f32_16x16x32_bf16 v[40:43], v[184:187], v[208:211], v[40:43]
	s_setprio 2
	s_barrier
	v_mfma_f32_16x16x32_bf16 v[36:39], v[168:171], v[212:215], v[36:39]
	v_mfma_f32_16x16x32_bf16 v[36:39], v[172:175], v[216:219], v[36:39]
	v_mfma_f32_16x16x32_bf16 v[32:35], v[176:179], v[212:215], v[32:35]
	v_mfma_f32_16x16x32_bf16 v[32:35], v[184:187], v[216:219], v[32:35]
	s_setprio 0
	s_add_i32 s18, s76, s66
	v_lshl_add_u64 v[220:221], s[60:61], 0, v[132:133]
	s_mov_b32 m0, s18
	ds_read_b128 v[188:191], v150 offset:16384
	ds_read_b128 v[192:195], v150 offset:17408
	ds_read_b128 v[196:199], v150 offset:18432
	ds_read_b128 v[200:203], v150 offset:19456
	ds_read_b128 v[204:207], v150 offset:20480
	ds_read_b128 v[208:211], v150 offset:21504
	ds_read_b128 v[212:215], v150 offset:22528
	ds_read_b128 v[216:219], v150 offset:23552
	global_load_lds_dwordx4 v[220:221], off
	s_add_i32 m0, s18, 0x2000
	s_add_u32 s88, s60, 0x40000
	v_lshl_add_u64 v[222:223], s[60:61], 0, v[128:129]
	s_addc_u32 s89, s61, 0
	s_add_i32 s18, s77, s66
	global_load_lds_dwordx4 v[222:223], off
	v_lshl_add_u64 v[224:225], s[88:89], 0, v[132:133]
	s_mov_b32 m0, s18
	v_lshl_add_u64 v[226:227], s[62:63], 0, v[130:131]
	global_load_lds_dwordx4 v[224:225], off
	v_lshl_add_u64 v[224:225], s[88:89], 0, v[128:129]
	s_add_i32 m0, s18, 0x2000
	s_nop 0
	global_load_lds_dwordx4 v[224:225], off
	v_lshl_add_u64 v[224:225], s[62:63], 0, v[134:135]
	s_mov_b32 m0, s68
	s_nop 0
	global_load_lds_dwordx4 v[224:225], off
	s_mov_b32 m0, s69
	s_nop 0
	global_load_lds_dwordx4 v[226:227], off
	s_waitcnt vmcnt(8)
	s_waitcnt lgkmcnt(0)
	s_barrier
	s_setprio 1
	s_waitcnt lgkmcnt(0)
	v_mfma_f32_16x16x32_bf16 v[92:95], v[152:155], v[188:191], v[92:95]
	v_mfma_f32_16x16x32_bf16 v[92:95], v[156:159], v[192:195], v[92:95]
	v_mfma_f32_16x16x32_bf16 v[88:91], v[160:163], v[188:191], v[88:91]
	v_mfma_f32_16x16x32_bf16 v[88:91], v[164:167], v[192:195], v[88:91]
	v_mfma_f32_16x16x32_bf16 v[84:87], v[152:155], v[196:199], v[84:87]
	v_mfma_f32_16x16x32_bf16 v[84:87], v[156:159], v[200:203], v[84:87]
	v_mfma_f32_16x16x32_bf16 v[80:83], v[160:163], v[196:199], v[80:83]
	v_mfma_f32_16x16x32_bf16 v[80:83], v[164:167], v[200:203], v[80:83]
	v_mfma_f32_16x16x32_bf16 v[76:79], v[152:155], v[204:207], v[76:79]
	v_mfma_f32_16x16x32_bf16 v[76:79], v[156:159], v[208:211], v[76:79]
	v_mfma_f32_16x16x32_bf16 v[72:75], v[160:163], v[204:207], v[72:75]
	v_mfma_f32_16x16x32_bf16 v[72:75], v[164:167], v[208:211], v[72:75]
	v_mfma_f32_16x16x32_bf16 v[60:63], v[152:155], v[212:215], v[60:63]
	v_mfma_f32_16x16x32_bf16 v[60:63], v[156:159], v[216:219], v[60:63]
	v_mfma_f32_16x16x32_bf16 v[56:59], v[160:163], v[212:215], v[56:59]
	v_mfma_f32_16x16x32_bf16 v[56:59], v[164:167], v[216:219], v[56:59]
	v_mfma_f32_16x16x32_bf16 v[28:31], v[168:171], v[188:191], v[28:31]
	v_mfma_f32_16x16x32_bf16 v[28:31], v[172:175], v[192:195], v[28:31]
	v_mfma_f32_16x16x32_bf16 v[24:27], v[176:179], v[188:191], v[24:27]
	v_mfma_f32_16x16x32_bf16 v[24:27], v[184:187], v[192:195], v[24:27]
	v_mfma_f32_16x16x32_bf16 v[20:23], v[168:171], v[196:199], v[20:23]
	v_mfma_f32_16x16x32_bf16 v[20:23], v[172:175], v[200:203], v[20:23]
	v_mfma_f32_16x16x32_bf16 v[16:19], v[176:179], v[196:199], v[16:19]
	v_mfma_f32_16x16x32_bf16 v[16:19], v[184:187], v[200:203], v[16:19]
	v_mfma_f32_16x16x32_bf16 v[12:15], v[168:171], v[204:207], v[12:15]
	v_mfma_f32_16x16x32_bf16 v[12:15], v[172:175], v[208:211], v[12:15]
	v_mfma_f32_16x16x32_bf16 v[8:11], v[176:179], v[204:207], v[8:11]
	v_mfma_f32_16x16x32_bf16 v[8:11], v[184:187], v[208:211], v[8:11]
	s_setprio 2
	s_barrier
	v_mfma_f32_16x16x32_bf16 v[4:7], v[168:171], v[212:215], v[4:7]
	v_mfma_f32_16x16x32_bf16 v[4:7], v[172:175], v[216:219], v[4:7]
	v_mfma_f32_16x16x32_bf16 v[0:3], v[176:179], v[212:215], v[0:3]
	v_mfma_f32_16x16x32_bf16 v[0:3], v[184:187], v[216:219], v[0:3]
	s_setprio 0
.Lmid_gemm2:
	s_add_i32 s18, 0, 0x18000
	s_add_i32 s19, 0, 0x1c000
	v_add_u32_e32 v164, s18, v147
	v_add_u32_e32 v181, s19, v147
	ds_read_b128 v[152:155], v164
	ds_read_b128 v[156:159], v164 offset:1024
	ds_read_b128 v[160:163], v164 offset:2048
	ds_read_b128 v[164:167], v164 offset:3072
	ds_read_b128 v[168:171], v181
	ds_read_b128 v[172:175], v181 offset:1024
	ds_read_b128 v[176:179], v181 offset:2048
	ds_read_b128 v[184:187], v181 offset:3072
	s_add_u32 s62, s62, 0x40000
	s_addc_u32 s63, s63, 0
	s_mov_b32 m0, s70
	v_lshl_add_u64 v[228:229], s[62:63], 0, v[134:135]
	ds_read_b128 v[188:191], v150 offset:32768
	ds_read_b128 v[192:195], v150 offset:33792
	ds_read_b128 v[196:199], v150 offset:34816
	ds_read_b128 v[200:203], v150 offset:35840
	ds_read_b128 v[204:207], v150 offset:36864
	ds_read_b128 v[208:211], v150 offset:37888
	ds_read_b128 v[212:215], v150 offset:38912
	ds_read_b128 v[216:219], v150 offset:39936
	global_load_lds_dwordx4 v[228:229], off
	v_lshl_add_u64 v[228:229], s[62:63], 0, v[130:131]
	s_mov_b32 m0, s71
	s_nop 0
	global_load_lds_dwordx4 v[228:229], off
	s_waitcnt vmcnt(8)
	s_waitcnt lgkmcnt(0)
	s_barrier
	s_setprio 1
	s_waitcnt lgkmcnt(0)
	v_mfma_f32_16x16x32_bf16 v[124:127], v[152:155], v[188:191], v[124:127]
	v_mfma_f32_16x16x32_bf16 v[124:127], v[156:159], v[192:195], v[124:127]
	v_mfma_f32_16x16x32_bf16 v[120:123], v[160:163], v[188:191], v[120:123]
	v_mfma_f32_16x16x32_bf16 v[120:123], v[164:167], v[192:195], v[120:123]
	v_mfma_f32_16x16x32_bf16 v[116:119], v[152:155], v[196:199], v[116:119]
	v_mfma_f32_16x16x32_bf16 v[116:119], v[156:159], v[200:203], v[116:119]
	v_mfma_f32_16x16x32_bf16 v[112:115], v[160:163], v[196:199], v[112:115]
	v_mfma_f32_16x16x32_bf16 v[112:115], v[164:167], v[200:203], v[112:115]
	v_mfma_f32_16x16x32_bf16 v[108:111], v[152:155], v[204:207], v[108:111]
	v_mfma_f32_16x16x32_bf16 v[108:111], v[156:159], v[208:211], v[108:111]
	v_mfma_f32_16x16x32_bf16 v[104:107], v[160:163], v[204:207], v[104:107]
	v_mfma_f32_16x16x32_bf16 v[104:107], v[164:167], v[208:211], v[104:107]
	v_mfma_f32_16x16x32_bf16 v[100:103], v[152:155], v[212:215], v[100:103]
	v_mfma_f32_16x16x32_bf16 v[100:103], v[156:159], v[216:219], v[100:103]
	v_mfma_f32_16x16x32_bf16 v[96:99], v[160:163], v[212:215], v[96:99]
	v_mfma_f32_16x16x32_bf16 v[96:99], v[164:167], v[216:219], v[96:99]
	v_mfma_f32_16x16x32_bf16 v[68:71], v[168:171], v[188:191], v[68:71]
	v_mfma_f32_16x16x32_bf16 v[68:71], v[172:175], v[192:195], v[68:71]
	v_mfma_f32_16x16x32_bf16 v[64:67], v[176:179], v[188:191], v[64:67]
	v_mfma_f32_16x16x32_bf16 v[64:67], v[184:187], v[192:195], v[64:67]
	v_mfma_f32_16x16x32_bf16 v[52:55], v[168:171], v[196:199], v[52:55]
	v_mfma_f32_16x16x32_bf16 v[52:55], v[172:175], v[200:203], v[52:55]
	v_mfma_f32_16x16x32_bf16 v[48:51], v[176:179], v[196:199], v[48:51]
	v_mfma_f32_16x16x32_bf16 v[48:51], v[184:187], v[200:203], v[48:51]
	v_mfma_f32_16x16x32_bf16 v[44:47], v[168:171], v[204:207], v[44:47]
	v_mfma_f32_16x16x32_bf16 v[44:47], v[172:175], v[208:211], v[44:47]
	v_mfma_f32_16x16x32_bf16 v[40:43], v[176:179], v[204:207], v[40:43]
	v_mfma_f32_16x16x32_bf16 v[40:43], v[184:187], v[208:211], v[40:43]
	s_setprio 2
	s_barrier
	v_mfma_f32_16x16x32_bf16 v[36:39], v[168:171], v[212:215], v[36:39]
	v_mfma_f32_16x16x32_bf16 v[36:39], v[172:175], v[216:219], v[36:39]
	v_mfma_f32_16x16x32_bf16 v[32:35], v[176:179], v[212:215], v[32:35]
	v_mfma_f32_16x16x32_bf16 v[32:35], v[184:187], v[216:219], v[32:35]
	s_setprio 0
	s_add_i32 s18, s18, s66
	v_lshl_add_u64 v[220:221], v[220:221], 0, s[6:7]
	s_mov_b32 m0, s18
	ds_read_b128 v[188:191], v150 offset:49152
	ds_read_b128 v[192:195], v150 offset:50176
	ds_read_b128 v[196:199], v150 offset:51200
	ds_read_b128 v[200:203], v150 offset:52224
	ds_read_b128 v[204:207], v150 offset:53248
	ds_read_b128 v[208:211], v150 offset:54272
	ds_read_b128 v[212:215], v150 offset:55296
	ds_read_b128 v[216:219], v150 offset:56320
	global_load_lds_dwordx4 v[220:221], off
	s_add_i32 m0, s18, 0x2000
	s_add_u32 s60, s60, 0x40080
	v_lshl_add_u64 v[220:221], v[222:223], 0, s[6:7]
	s_addc_u32 s61, s61, 0
	s_add_i32 s18, s19, s66
	global_load_lds_dwordx4 v[220:221], off
	v_lshl_add_u64 v[220:221], s[60:61], 0, v[132:133]
	s_mov_b32 m0, s18
	s_nop 0
	global_load_lds_dwordx4 v[220:221], off
	v_lshl_add_u64 v[220:221], s[60:61], 0, v[128:129]
	s_add_i32 m0, s18, 0x2000
	s_nop 0
	global_load_lds_dwordx4 v[220:221], off
	v_lshl_add_u64 v[220:221], v[224:225], 0, s[6:7]
	s_mov_b32 m0, s74
	s_nop 0
	global_load_lds_dwordx4 v[220:221], off
	v_lshl_add_u64 v[220:221], v[226:227], 0, s[6:7]
	s_mov_b32 m0, s75
	s_nop 0
	global_load_lds_dwordx4 v[220:221], off
	s_waitcnt vmcnt(8)
	s_waitcnt lgkmcnt(0)
	s_barrier
	s_setprio 1
	s_waitcnt lgkmcnt(0)
	v_mfma_f32_16x16x32_bf16 v[92:95], v[152:155], v[188:191], v[92:95]
	v_mfma_f32_16x16x32_bf16 v[92:95], v[156:159], v[192:195], v[92:95]
	v_mfma_f32_16x16x32_bf16 v[88:91], v[160:163], v[188:191], v[88:91]
	v_mfma_f32_16x16x32_bf16 v[88:91], v[164:167], v[192:195], v[88:91]
	v_mfma_f32_16x16x32_bf16 v[84:87], v[152:155], v[196:199], v[84:87]
	v_mfma_f32_16x16x32_bf16 v[84:87], v[156:159], v[200:203], v[84:87]
	v_mfma_f32_16x16x32_bf16 v[80:83], v[160:163], v[196:199], v[80:83]
	v_mfma_f32_16x16x32_bf16 v[80:83], v[164:167], v[200:203], v[80:83]
	v_mfma_f32_16x16x32_bf16 v[76:79], v[152:155], v[204:207], v[76:79]
	v_mfma_f32_16x16x32_bf16 v[76:79], v[156:159], v[208:211], v[76:79]
	v_mfma_f32_16x16x32_bf16 v[72:75], v[160:163], v[204:207], v[72:75]
	v_mfma_f32_16x16x32_bf16 v[72:75], v[164:167], v[208:211], v[72:75]
	v_mfma_f32_16x16x32_bf16 v[60:63], v[152:155], v[212:215], v[60:63]
	v_mfma_f32_16x16x32_bf16 v[60:63], v[156:159], v[216:219], v[60:63]
	v_mfma_f32_16x16x32_bf16 v[56:59], v[160:163], v[212:215], v[56:59]
	v_mfma_f32_16x16x32_bf16 v[56:59], v[164:167], v[216:219], v[56:59]
	v_mfma_f32_16x16x32_bf16 v[28:31], v[168:171], v[188:191], v[28:31]
	v_mfma_f32_16x16x32_bf16 v[28:31], v[172:175], v[192:195], v[28:31]
	v_mfma_f32_16x16x32_bf16 v[24:27], v[176:179], v[188:191], v[24:27]
	v_mfma_f32_16x16x32_bf16 v[24:27], v[184:187], v[192:195], v[24:27]
	v_mfma_f32_16x16x32_bf16 v[20:23], v[168:171], v[196:199], v[20:23]
	v_mfma_f32_16x16x32_bf16 v[20:23], v[172:175], v[200:203], v[20:23]
	v_mfma_f32_16x16x32_bf16 v[16:19], v[176:179], v[196:199], v[16:19]
	v_mfma_f32_16x16x32_bf16 v[16:19], v[184:187], v[200:203], v[16:19]
	v_mfma_f32_16x16x32_bf16 v[12:15], v[168:171], v[204:207], v[12:15]
	v_mfma_f32_16x16x32_bf16 v[12:15], v[172:175], v[208:211], v[12:15]
	v_mfma_f32_16x16x32_bf16 v[8:11], v[176:179], v[204:207], v[8:11]
	v_mfma_f32_16x16x32_bf16 v[8:11], v[184:187], v[208:211], v[8:11]
	s_setprio 2
	s_barrier
	v_mfma_f32_16x16x32_bf16 v[4:7], v[168:171], v[212:215], v[4:7]
	v_mfma_f32_16x16x32_bf16 v[4:7], v[172:175], v[216:219], v[4:7]
	v_mfma_f32_16x16x32_bf16 v[0:3], v[176:179], v[212:215], v[0:3]
	v_mfma_f32_16x16x32_bf16 v[0:3], v[184:187], v[216:219], v[0:3]
	s_setprio 0
	s_add_i32 s86, s86, 2
	s_add_u32 s58, s58, 0x100
	s_addc_u32 s59, s59, 0
	s_add_u32 s84, s84, 0x100
	s_addc_u32 s85, s85, 0
	s_cmp_gt_u32 s86, 13
	s_cbranch_scc0 .LBB0_387
	s_and_b64 vcc, exec, s[8:9]
	s_cbranch_vccz .LBB0_390
	s_barrier

.LBB0_600:
	s_ashr_i32 s49, s48, 31
	s_lshl_b64 s[18:19], s[48:49], 19
	s_add_u32 s52, s38, s18
	s_addc_u32 s53, s39, s19
	s_and_b64 s[18:19], s[4:5], exec
	s_cselect_b32 s49, s53, s59
	s_cselect_b32 s84, s52, s58
	s_ashr_i32 s47, s46, 31
	s_lshl_b64 s[18:19], s[46:47], 19
	s_add_u32 s54, s64, s18
	s_addc_u32 s55, s65, s19
	s_and_b64 s[18:19], s[4:5], exec
	s_cselect_b32 s47, s55, s61
	s_cselect_b32 s85, s54, s60
	s_add_u32 s58, s58, 0x40080
	s_addc_u32 s59, s59, 0
	s_add_u32 s86, s60, 0x100
	s_addc_u32 s87, s61, 0
	s_mov_b32 s88, -2
	ds_read_b128 v[152:155], v149
	ds_read_b128 v[156:159], v149 offset:1024
	ds_read_b128 v[160:163], v149 offset:2048
	ds_read_b128 v[164:167], v149 offset:3072
	ds_read_b128 v[168:171], v150
	ds_read_b128 v[172:175], v150 offset:1024
	ds_read_b128 v[176:179], v150 offset:2048
	ds_read_b128 v[184:187], v150 offset:3072
	s_add_u32 s18, s58, 0xfffc0080
	s_addc_u32 s19, s59, -1
	s_cmp_eq_u32 s88, 12
	s_cselect_b32 s63, s49, s19
	s_cselect_b32 s62, s84, s18
	s_cselect_b32 s61, s47, s87
	s_cselect_b32 s60, s85, s86
	v_lshl_add_u64 v[144:145], s[58:59], 0, v[136:137]
	s_add_i32 m0, s57, 0xc000
	ds_read_b128 v[188:191], v151
	ds_read_b128 v[192:195], v151 offset:1024
	ds_read_b128 v[196:199], v151 offset:2048
	ds_read_b128 v[200:203], v151 offset:3072
	ds_read_b128 v[204:207], v151 offset:4096
	ds_read_b128 v[208:211], v151 offset:5120
	ds_read_b128 v[212:215], v151 offset:6144
	ds_read_b128 v[216:219], v151 offset:7168
	global_load_lds_dwordx4 v[144:145], off
	v_lshl_add_u64 v[144:145], s[58:59], 0, v[138:139]
	s_add_i32 m0, s57, 0xe000
	s_nop 0
	global_load_lds_dwordx4 v[144:145], off
	s_waitcnt vmcnt(8)
	s_waitcnt lgkmcnt(0)
	s_barrier
	s_setprio 1
	s_waitcnt lgkmcnt(0)
	v_mfma_f32_16x16x32_bf16 v[124:127], v[152:155], v[188:191], 0
	v_mfma_f32_16x16x32_bf16 v[124:127], v[156:159], v[192:195], v[124:127]
	v_mfma_f32_16x16x32_bf16 v[120:123], v[160:163], v[188:191], 0
	v_mfma_f32_16x16x32_bf16 v[120:123], v[164:167], v[192:195], v[120:123]
	v_mfma_f32_16x16x32_bf16 v[116:119], v[152:155], v[196:199], 0
	v_mfma_f32_16x16x32_bf16 v[116:119], v[156:159], v[200:203], v[116:119]
	v_mfma_f32_16x16x32_bf16 v[108:111], v[160:163], v[196:199], 0
	v_mfma_f32_16x16x32_bf16 v[108:111], v[164:167], v[200:203], v[108:111]
	v_mfma_f32_16x16x32_bf16 v[100:103], v[152:155], v[204:207], 0
	v_mfma_f32_16x16x32_bf16 v[100:103], v[156:159], v[208:211], v[100:103]
	v_mfma_f32_16x16x32_bf16 v[92:95], v[160:163], v[204:207], 0
	v_mfma_f32_16x16x32_bf16 v[92:95], v[164:167], v[208:211], v[92:95]
	v_mfma_f32_16x16x32_bf16 v[84:87], v[152:155], v[212:215], 0
	v_mfma_f32_16x16x32_bf16 v[84:87], v[156:159], v[216:219], v[84:87]
	v_mfma_f32_16x16x32_bf16 v[76:79], v[160:163], v[212:215], 0
	v_mfma_f32_16x16x32_bf16 v[76:79], v[164:167], v[216:219], v[76:79]
	v_mfma_f32_16x16x32_bf16 v[112:115], v[168:171], v[188:191], 0
	v_mfma_f32_16x16x32_bf16 v[112:115], v[172:175], v[192:195], v[112:115]
	v_mfma_f32_16x16x32_bf16 v[104:107], v[176:179], v[188:191], 0
	v_mfma_f32_16x16x32_bf16 v[104:107], v[184:187], v[192:195], v[104:107]
	v_mfma_f32_16x16x32_bf16 v[96:99], v[168:171], v[196:199], 0
	v_mfma_f32_16x16x32_bf16 v[96:99], v[172:175], v[200:203], v[96:99]
	v_mfma_f32_16x16x32_bf16 v[88:91], v[176:179], v[196:199], 0
	v_mfma_f32_16x16x32_bf16 v[88:91], v[184:187], v[200:203], v[88:91]
	v_mfma_f32_16x16x32_bf16 v[80:83], v[168:171], v[204:207], 0
	v_mfma_f32_16x16x32_bf16 v[80:83], v[172:175], v[208:211], v[80:83]
	v_mfma_f32_16x16x32_bf16 v[72:75], v[176:179], v[204:207], 0
	v_mfma_f32_16x16x32_bf16 v[72:75], v[184:187], v[208:211], v[72:75]
	s_setprio 2
	s_barrier
	v_mfma_f32_16x16x32_bf16 v[68:71], v[168:171], v[212:215], 0
	v_mfma_f32_16x16x32_bf16 v[68:71], v[172:175], v[216:219], v[68:71]
	v_mfma_f32_16x16x32_bf16 v[64:67], v[176:179], v[212:215], 0
	v_mfma_f32_16x16x32_bf16 v[64:67], v[184:187], v[216:219], v[64:67]
	s_setprio 0
	s_add_i32 s18, s73, s66
	v_lshl_add_u64 v[144:145], s[60:61], 0, v[130:131]
	s_mov_b32 m0, s18
	ds_read_b128 v[188:191], v151 offset:16384
	ds_read_b128 v[192:195], v151 offset:17408
	ds_read_b128 v[196:199], v151 offset:18432
	ds_read_b128 v[200:203], v151 offset:19456
	ds_read_b128 v[204:207], v151 offset:20480
	ds_read_b128 v[208:211], v151 offset:21504
	ds_read_b128 v[212:215], v151 offset:22528
	ds_read_b128 v[216:219], v151 offset:23552
	global_load_lds_dwordx4 v[144:145], off
	s_add_i32 m0, s18, 0x2000
	s_add_u32 s18, s60, 0x40000
	v_lshl_add_u64 v[220:221], s[60:61], 0, v[134:135]
	s_addc_u32 s19, s61, 0
	s_add_i32 s79, s74, s66
	global_load_lds_dwordx4 v[220:221], off
	v_lshl_add_u64 v[222:223], s[18:19], 0, v[130:131]
	s_mov_b32 m0, s79
	v_lshl_add_u64 v[224:225], s[62:63], 0, v[132:133]
	global_load_lds_dwordx4 v[222:223], off
	v_lshl_add_u64 v[222:223], s[18:19], 0, v[134:135]
	s_add_i32 m0, s79, 0x2000
	s_nop 0
	global_load_lds_dwordx4 v[222:223], off
	v_lshl_add_u64 v[222:223], s[62:63], 0, v[128:129]
	s_mov_b32 m0, s57
	s_nop 0
	global_load_lds_dwordx4 v[222:223], off
	s_mov_b32 m0, s67
	s_nop 0
	global_load_lds_dwordx4 v[224:225], off
	s_waitcnt vmcnt(8)
	s_waitcnt lgkmcnt(0)
	s_barrier
	s_setprio 1
	s_waitcnt lgkmcnt(0)
	v_mfma_f32_16x16x32_bf16 v[60:63], v[152:155], v[188:191], 0
	v_mfma_f32_16x16x32_bf16 v[60:63], v[156:159], v[192:195], v[60:63]
	v_mfma_f32_16x16x32_bf16 v[56:59], v[160:163], v[188:191], 0
	v_mfma_f32_16x16x32_bf16 v[56:59], v[164:167], v[192:195], v[56:59]
	v_mfma_f32_16x16x32_bf16 v[52:55], v[152:155], v[196:199], 0
	v_mfma_f32_16x16x32_bf16 v[52:55], v[156:159], v[200:203], v[52:55]
	v_mfma_f32_16x16x32_bf16 v[44:47], v[160:163], v[196:199], 0
	v_mfma_f32_16x16x32_bf16 v[44:47], v[164:167], v[200:203], v[44:47]
	v_mfma_f32_16x16x32_bf16 v[36:39], v[152:155], v[204:207], 0
	v_mfma_f32_16x16x32_bf16 v[36:39], v[156:159], v[208:211], v[36:39]
	v_mfma_f32_16x16x32_bf16 v[28:31], v[160:163], v[204:207], 0
	v_mfma_f32_16x16x32_bf16 v[28:31], v[164:167], v[208:211], v[28:31]
	v_mfma_f32_16x16x32_bf16 v[20:23], v[152:155], v[212:215], 0
	v_mfma_f32_16x16x32_bf16 v[20:23], v[156:159], v[216:219], v[20:23]
	v_mfma_f32_16x16x32_bf16 v[12:15], v[160:163], v[212:215], 0
	v_mfma_f32_16x16x32_bf16 v[12:15], v[164:167], v[216:219], v[12:15]
	v_mfma_f32_16x16x32_bf16 v[48:51], v[168:171], v[188:191], 0
	v_mfma_f32_16x16x32_bf16 v[48:51], v[172:175], v[192:195], v[48:51]
	v_mfma_f32_16x16x32_bf16 v[40:43], v[176:179], v[188:191], 0
	v_mfma_f32_16x16x32_bf16 v[40:43], v[184:187], v[192:195], v[40:43]
	v_mfma_f32_16x16x32_bf16 v[32:35], v[168:171], v[196:199], 0
	v_mfma_f32_16x16x32_bf16 v[32:35], v[172:175], v[200:203], v[32:35]
	v_mfma_f32_16x16x32_bf16 v[24:27], v[176:179], v[196:199], 0
	v_mfma_f32_16x16x32_bf16 v[24:27], v[184:187], v[200:203], v[24:27]
	v_mfma_f32_16x16x32_bf16 v[16:19], v[168:171], v[204:207], 0
	v_mfma_f32_16x16x32_bf16 v[16:19], v[172:175], v[208:211], v[16:19]
	v_mfma_f32_16x16x32_bf16 v[8:11], v[176:179], v[204:207], 0
	v_mfma_f32_16x16x32_bf16 v[8:11], v[184:187], v[208:211], v[8:11]
	s_setprio 2
	s_barrier
	v_mfma_f32_16x16x32_bf16 v[4:7], v[168:171], v[212:215], 0
	v_mfma_f32_16x16x32_bf16 v[4:7], v[172:175], v[216:219], v[4:7]
	v_mfma_f32_16x16x32_bf16 v[0:3], v[176:179], v[212:215], 0
	v_mfma_f32_16x16x32_bf16 v[0:3], v[184:187], v[216:219], v[0:3]
	s_setprio 0
	s_branch .Lmid_gemm3
.LBB0_601:
	ds_read_b128 v[152:155], v149
	ds_read_b128 v[156:159], v149 offset:1024
	ds_read_b128 v[160:163], v149 offset:2048
	ds_read_b128 v[164:167], v149 offset:3072
	ds_read_b128 v[168:171], v150
	ds_read_b128 v[172:175], v150 offset:1024
	ds_read_b128 v[176:179], v150 offset:2048
	ds_read_b128 v[184:187], v150 offset:3072
	s_add_u32 s18, s58, 0xfffc0080
	s_addc_u32 s19, s59, -1
	s_cmp_eq_u32 s88, 12
	s_cselect_b32 s63, s49, s19
	s_cselect_b32 s62, s84, s18
	s_cselect_b32 s61, s47, s87
	s_cselect_b32 s60, s85, s86
	v_lshl_add_u64 v[144:145], s[58:59], 0, v[136:137]
	s_add_i32 m0, s57, 0xc000
	ds_read_b128 v[188:191], v151
	ds_read_b128 v[192:195], v151 offset:1024
	ds_read_b128 v[196:199], v151 offset:2048
	ds_read_b128 v[200:203], v151 offset:3072
	ds_read_b128 v[204:207], v151 offset:4096
	ds_read_b128 v[208:211], v151 offset:5120
	ds_read_b128 v[212:215], v151 offset:6144
	ds_read_b128 v[216:219], v151 offset:7168
	global_load_lds_dwordx4 v[144:145], off
	v_lshl_add_u64 v[144:145], s[58:59], 0, v[138:139]
	s_add_i32 m0, s57, 0xe000
	s_nop 0
	global_load_lds_dwordx4 v[144:145], off
	s_waitcnt vmcnt(8)
	s_waitcnt lgkmcnt(0)
	s_barrier
	s_setprio 1
	s_waitcnt lgkmcnt(0)
	v_mfma_f32_16x16x32_bf16 v[124:127], v[152:155], v[188:191], v[124:127]
	v_mfma_f32_16x16x32_bf16 v[124:127], v[156:159], v[192:195], v[124:127]
	v_mfma_f32_16x16x32_bf16 v[120:123], v[160:163], v[188:191], v[120:123]
	v_mfma_f32_16x16x32_bf16 v[120:123], v[164:167], v[192:195], v[120:123]
	v_mfma_f32_16x16x32_bf16 v[116:119], v[152:155], v[196:199], v[116:119]
	v_mfma_f32_16x16x32_bf16 v[116:119], v[156:159], v[200:203], v[116:119]
	v_mfma_f32_16x16x32_bf16 v[108:111], v[160:163], v[196:199], v[108:111]
	v_mfma_f32_16x16x32_bf16 v[108:111], v[164:167], v[200:203], v[108:111]
	v_mfma_f32_16x16x32_bf16 v[100:103], v[152:155], v[204:207], v[100:103]
	v_mfma_f32_16x16x32_bf16 v[100:103], v[156:159], v[208:211], v[100:103]
	v_mfma_f32_16x16x32_bf16 v[92:95], v[160:163], v[204:207], v[92:95]
	v_mfma_f32_16x16x32_bf16 v[92:95], v[164:167], v[208:211], v[92:95]
	v_mfma_f32_16x16x32_bf16 v[84:87], v[152:155], v[212:215], v[84:87]
	v_mfma_f32_16x16x32_bf16 v[84:87], v[156:159], v[216:219], v[84:87]
	v_mfma_f32_16x16x32_bf16 v[76:79], v[160:163], v[212:215], v[76:79]
	v_mfma_f32_16x16x32_bf16 v[76:79], v[164:167], v[216:219], v[76:79]
	v_mfma_f32_16x16x32_bf16 v[112:115], v[168:171], v[188:191], v[112:115]
	v_mfma_f32_16x16x32_bf16 v[112:115], v[172:175], v[192:195], v[112:115]
	v_mfma_f32_16x16x32_bf16 v[104:107], v[176:179], v[188:191], v[104:107]
	v_mfma_f32_16x16x32_bf16 v[104:107], v[184:187], v[192:195], v[104:107]
	v_mfma_f32_16x16x32_bf16 v[96:99], v[168:171], v[196:199], v[96:99]
	v_mfma_f32_16x16x32_bf16 v[96:99], v[172:175], v[200:203], v[96:99]
	v_mfma_f32_16x16x32_bf16 v[88:91], v[176:179], v[196:199], v[88:91]
	v_mfma_f32_16x16x32_bf16 v[88:91], v[184:187], v[200:203], v[88:91]
	v_mfma_f32_16x16x32_bf16 v[80:83], v[168:171], v[204:207], v[80:83]
	v_mfma_f32_16x16x32_bf16 v[80:83], v[172:175], v[208:211], v[80:83]
	v_mfma_f32_16x16x32_bf16 v[72:75], v[176:179], v[204:207], v[72:75]
	v_mfma_f32_16x16x32_bf16 v[72:75], v[184:187], v[208:211], v[72:75]
	s_setprio 2
	s_barrier
	v_mfma_f32_16x16x32_bf16 v[68:71], v[168:171], v[212:215], v[68:71]
	v_mfma_f32_16x16x32_bf16 v[68:71], v[172:175], v[216:219], v[68:71]
	v_mfma_f32_16x16x32_bf16 v[64:67], v[176:179], v[212:215], v[64:67]
	v_mfma_f32_16x16x32_bf16 v[64:67], v[184:187], v[216:219], v[64:67]
	s_setprio 0
	s_add_i32 s18, s73, s66
	v_lshl_add_u64 v[144:145], s[60:61], 0, v[130:131]
	s_mov_b32 m0, s18
	ds_read_b128 v[188:191], v151 offset:16384
	ds_read_b128 v[192:195], v151 offset:17408
	ds_read_b128 v[196:199], v151 offset:18432
	ds_read_b128 v[200:203], v151 offset:19456
	ds_read_b128 v[204:207], v151 offset:20480
	ds_read_b128 v[208:211], v151 offset:21504
	ds_read_b128 v[212:215], v151 offset:22528
	ds_read_b128 v[216:219], v151 offset:23552
	global_load_lds_dwordx4 v[144:145], off
	s_add_i32 m0, s18, 0x2000
	s_add_u32 s18, s60, 0x40000
	v_lshl_add_u64 v[220:221], s[60:61], 0, v[134:135]
	s_addc_u32 s19, s61, 0
	s_add_i32 s79, s74, s66
	global_load_lds_dwordx4 v[220:221], off
	v_lshl_add_u64 v[222:223], s[18:19], 0, v[130:131]
	s_mov_b32 m0, s79
	v_lshl_add_u64 v[224:225], s[62:63], 0, v[132:133]
	global_load_lds_dwordx4 v[222:223], off
	v_lshl_add_u64 v[222:223], s[18:19], 0, v[134:135]
	s_add_i32 m0, s79, 0x2000
	s_nop 0
	global_load_lds_dwordx4 v[222:223], off
	v_lshl_add_u64 v[222:223], s[62:63], 0, v[128:129]
	s_mov_b32 m0, s57
	s_nop 0
	global_load_lds_dwordx4 v[222:223], off
	s_mov_b32 m0, s67
	s_nop 0
	global_load_lds_dwordx4 v[224:225], off
	s_waitcnt vmcnt(8)
	s_waitcnt lgkmcnt(0)
	s_barrier
	s_setprio 1
	s_waitcnt lgkmcnt(0)
	v_mfma_f32_16x16x32_bf16 v[60:63], v[152:155], v[188:191], v[60:63]
	v_mfma_f32_16x16x32_bf16 v[60:63], v[156:159], v[192:195], v[60:63]
	v_mfma_f32_16x16x32_bf16 v[56:59], v[160:163], v[188:191], v[56:59]
	v_mfma_f32_16x16x32_bf16 v[56:59], v[164:167], v[192:195], v[56:59]
	v_mfma_f32_16x16x32_bf16 v[52:55], v[152:155], v[196:199], v[52:55]
	v_mfma_f32_16x16x32_bf16 v[52:55], v[156:159], v[200:203], v[52:55]
	v_mfma_f32_16x16x32_bf16 v[44:47], v[160:163], v[196:199], v[44:47]
	v_mfma_f32_16x16x32_bf16 v[44:47], v[164:167], v[200:203], v[44:47]
	v_mfma_f32_16x16x32_bf16 v[36:39], v[152:155], v[204:207], v[36:39]
	v_mfma_f32_16x16x32_bf16 v[36:39], v[156:159], v[208:211], v[36:39]
	v_mfma_f32_16x16x32_bf16 v[28:31], v[160:163], v[204:207], v[28:31]
	v_mfma_f32_16x16x32_bf16 v[28:31], v[164:167], v[208:211], v[28:31]
	v_mfma_f32_16x16x32_bf16 v[20:23], v[152:155], v[212:215], v[20:23]
	v_mfma_f32_16x16x32_bf16 v[20:23], v[156:159], v[216:219], v[20:23]
	v_mfma_f32_16x16x32_bf16 v[12:15], v[160:163], v[212:215], v[12:15]
	v_mfma_f32_16x16x32_bf16 v[12:15], v[164:167], v[216:219], v[12:15]
	v_mfma_f32_16x16x32_bf16 v[48:51], v[168:171], v[188:191], v[48:51]
	v_mfma_f32_16x16x32_bf16 v[48:51], v[172:175], v[192:195], v[48:51]
	v_mfma_f32_16x16x32_bf16 v[40:43], v[176:179], v[188:191], v[40:43]
	v_mfma_f32_16x16x32_bf16 v[40:43], v[184:187], v[192:195], v[40:43]
	v_mfma_f32_16x16x32_bf16 v[32:35], v[168:171], v[196:199], v[32:35]
	v_mfma_f32_16x16x32_bf16 v[32:35], v[172:175], v[200:203], v[32:35]
	v_mfma_f32_16x16x32_bf16 v[24:27], v[176:179], v[196:199], v[24:27]
	v_mfma_f32_16x16x32_bf16 v[24:27], v[184:187], v[200:203], v[24:27]
	v_mfma_f32_16x16x32_bf16 v[16:19], v[168:171], v[204:207], v[16:19]
	v_mfma_f32_16x16x32_bf16 v[16:19], v[172:175], v[208:211], v[16:19]
	v_mfma_f32_16x16x32_bf16 v[8:11], v[176:179], v[204:207], v[8:11]
	v_mfma_f32_16x16x32_bf16 v[8:11], v[184:187], v[208:211], v[8:11]
	s_setprio 2
	s_barrier
	v_mfma_f32_16x16x32_bf16 v[4:7], v[168:171], v[212:215], v[4:7]
	v_mfma_f32_16x16x32_bf16 v[4:7], v[172:175], v[216:219], v[4:7]
	v_mfma_f32_16x16x32_bf16 v[0:3], v[176:179], v[212:215], v[0:3]
	v_mfma_f32_16x16x32_bf16 v[0:3], v[184:187], v[216:219], v[0:3]
	s_setprio 0
.Lmid_gemm3:
	s_add_i32 s79, 0, 0x18000
	s_add_i32 s89, 0, 0x1c000
	v_add_u32_e32 v164, s79, v147
	v_add_u32_e32 v181, s89, v147
	ds_read_b128 v[152:155], v164
	ds_read_b128 v[156:159], v164 offset:1024
	ds_read_b128 v[160:163], v164 offset:2048
	ds_read_b128 v[164:167], v164 offset:3072
	ds_read_b128 v[168:171], v181
	ds_read_b128 v[172:175], v181 offset:1024
	ds_read_b128 v[176:179], v181 offset:2048
	ds_read_b128 v[184:187], v181 offset:3072
	s_add_u32 s18, s62, 0x40000
	s_addc_u32 s19, s63, 0
	s_mov_b32 m0, s68
	v_lshl_add_u64 v[226:227], s[18:19], 0, v[128:129]
	ds_read_b128 v[188:191], v151 offset:32768
	ds_read_b128 v[192:195], v151 offset:33792
	ds_read_b128 v[196:199], v151 offset:34816
	ds_read_b128 v[200:203], v151 offset:35840
	ds_read_b128 v[204:207], v151 offset:36864
	ds_read_b128 v[208:211], v151 offset:37888
	ds_read_b128 v[212:215], v151 offset:38912
	ds_read_b128 v[216:219], v151 offset:39936
	global_load_lds_dwordx4 v[226:227], off
	v_lshl_add_u64 v[226:227], s[18:19], 0, v[132:133]
	s_mov_b32 m0, s69
	s_nop 0
	global_load_lds_dwordx4 v[226:227], off
	s_waitcnt vmcnt(8)
	s_waitcnt lgkmcnt(0)
	s_barrier
	s_setprio 1
	s_waitcnt lgkmcnt(0)
	v_mfma_f32_16x16x32_bf16 v[124:127], v[152:155], v[188:191], v[124:127]
	v_mfma_f32_16x16x32_bf16 v[124:127], v[156:159], v[192:195], v[124:127]
	v_mfma_f32_16x16x32_bf16 v[120:123], v[160:163], v[188:191], v[120:123]
	v_mfma_f32_16x16x32_bf16 v[120:123], v[164:167], v[192:195], v[120:123]
	v_mfma_f32_16x16x32_bf16 v[116:119], v[152:155], v[196:199], v[116:119]
	v_mfma_f32_16x16x32_bf16 v[116:119], v[156:159], v[200:203], v[116:119]
	v_mfma_f32_16x16x32_bf16 v[108:111], v[160:163], v[196:199], v[108:111]
	v_mfma_f32_16x16x32_bf16 v[108:111], v[164:167], v[200:203], v[108:111]
	v_mfma_f32_16x16x32_bf16 v[100:103], v[152:155], v[204:207], v[100:103]
	v_mfma_f32_16x16x32_bf16 v[100:103], v[156:159], v[208:211], v[100:103]
	v_mfma_f32_16x16x32_bf16 v[92:95], v[160:163], v[204:207], v[92:95]
	v_mfma_f32_16x16x32_bf16 v[92:95], v[164:167], v[208:211], v[92:95]
	v_mfma_f32_16x16x32_bf16 v[84:87], v[152:155], v[212:215], v[84:87]
	v_mfma_f32_16x16x32_bf16 v[84:87], v[156:159], v[216:219], v[84:87]
	v_mfma_f32_16x16x32_bf16 v[76:79], v[160:163], v[212:215], v[76:79]
	v_mfma_f32_16x16x32_bf16 v[76:79], v[164:167], v[216:219], v[76:79]
	v_mfma_f32_16x16x32_bf16 v[112:115], v[168:171], v[188:191], v[112:115]
	v_mfma_f32_16x16x32_bf16 v[112:115], v[172:175], v[192:195], v[112:115]
	v_mfma_f32_16x16x32_bf16 v[104:107], v[176:179], v[188:191], v[104:107]
	v_mfma_f32_16x16x32_bf16 v[104:107], v[184:187], v[192:195], v[104:107]
	v_mfma_f32_16x16x32_bf16 v[96:99], v[168:171], v[196:199], v[96:99]
	v_mfma_f32_16x16x32_bf16 v[96:99], v[172:175], v[200:203], v[96:99]
	v_mfma_f32_16x16x32_bf16 v[88:91], v[176:179], v[196:199], v[88:91]
	v_mfma_f32_16x16x32_bf16 v[88:91], v[184:187], v[200:203], v[88:91]
	v_mfma_f32_16x16x32_bf16 v[80:83], v[168:171], v[204:207], v[80:83]
	v_mfma_f32_16x16x32_bf16 v[80:83], v[172:175], v[208:211], v[80:83]
	v_mfma_f32_16x16x32_bf16 v[72:75], v[176:179], v[204:207], v[72:75]
	v_mfma_f32_16x16x32_bf16 v[72:75], v[184:187], v[208:211], v[72:75]
	s_setprio 2
	s_barrier
	v_mfma_f32_16x16x32_bf16 v[68:71], v[168:171], v[212:215], v[68:71]
	v_mfma_f32_16x16x32_bf16 v[68:71], v[172:175], v[216:219], v[68:71]
	v_mfma_f32_16x16x32_bf16 v[64:67], v[176:179], v[212:215], v[64:67]
	v_mfma_f32_16x16x32_bf16 v[64:67], v[184:187], v[216:219], v[64:67]
	s_setprio 0
	s_add_i32 s18, s79, s66
	v_lshl_add_u64 v[144:145], v[144:145], 0, s[10:11]
	s_mov_b32 m0, s18
	ds_read_b128 v[188:191], v151 offset:49152
	ds_read_b128 v[192:195], v151 offset:50176
	ds_read_b128 v[196:199], v151 offset:51200
	ds_read_b128 v[200:203], v151 offset:52224
	ds_read_b128 v[204:207], v151 offset:53248
	ds_read_b128 v[208:211], v151 offset:54272
	ds_read_b128 v[212:215], v151 offset:55296
	ds_read_b128 v[216:219], v151 offset:56320
	global_load_lds_dwordx4 v[144:145], off
	s_add_i32 m0, s18, 0x2000
	s_add_u32 s18, s60, 0x40080
	v_lshl_add_u64 v[144:145], v[220:221], 0, s[10:11]
	s_addc_u32 s19, s61, 0
	s_add_i32 s60, s89, s66
	global_load_lds_dwordx4 v[144:145], off
	v_lshl_add_u64 v[144:145], s[18:19], 0, v[130:131]
	s_mov_b32 m0, s60
	s_nop 0
	global_load_lds_dwordx4 v[144:145], off
	v_lshl_add_u64 v[144:145], s[18:19], 0, v[134:135]
	s_add_i32 m0, s60, 0x2000
	s_nop 0
	global_load_lds_dwordx4 v[144:145], off
	v_lshl_add_u64 v[144:145], v[222:223], 0, s[10:11]
	s_mov_b32 m0, s71
	s_nop 0
	global_load_lds_dwordx4 v[144:145], off
	v_lshl_add_u64 v[144:145], v[224:225], 0, s[10:11]
	s_mov_b32 m0, s72
	s_nop 0
	global_load_lds_dwordx4 v[144:145], off
	s_waitcnt vmcnt(8)
	s_waitcnt lgkmcnt(0)
	s_barrier
	s_setprio 1
	s_waitcnt lgkmcnt(0)
	v_mfma_f32_16x16x32_bf16 v[60:63], v[152:155], v[188:191], v[60:63]
	v_mfma_f32_16x16x32_bf16 v[60:63], v[156:159], v[192:195], v[60:63]
	v_mfma_f32_16x16x32_bf16 v[56:59], v[160:163], v[188:191], v[56:59]
	v_mfma_f32_16x16x32_bf16 v[56:59], v[164:167], v[192:195], v[56:59]
	v_mfma_f32_16x16x32_bf16 v[52:55], v[152:155], v[196:199], v[52:55]
	v_mfma_f32_16x16x32_bf16 v[52:55], v[156:159], v[200:203], v[52:55]
	v_mfma_f32_16x16x32_bf16 v[44:47], v[160:163], v[196:199], v[44:47]
	v_mfma_f32_16x16x32_bf16 v[44:47], v[164:167], v[200:203], v[44:47]
	v_mfma_f32_16x16x32_bf16 v[36:39], v[152:155], v[204:207], v[36:39]
	v_mfma_f32_16x16x32_bf16 v[36:39], v[156:159], v[208:211], v[36:39]
	v_mfma_f32_16x16x32_bf16 v[28:31], v[160:163], v[204:207], v[28:31]
	v_mfma_f32_16x16x32_bf16 v[28:31], v[164:167], v[208:211], v[28:31]
	v_mfma_f32_16x16x32_bf16 v[20:23], v[152:155], v[212:215], v[20:23]
	v_mfma_f32_16x16x32_bf16 v[20:23], v[156:159], v[216:219], v[20:23]
	v_mfma_f32_16x16x32_bf16 v[12:15], v[160:163], v[212:215], v[12:15]
	v_mfma_f32_16x16x32_bf16 v[12:15], v[164:167], v[216:219], v[12:15]
	v_mfma_f32_16x16x32_bf16 v[48:51], v[168:171], v[188:191], v[48:51]
	v_mfma_f32_16x16x32_bf16 v[48:51], v[172:175], v[192:195], v[48:51]
	v_mfma_f32_16x16x32_bf16 v[40:43], v[176:179], v[188:191], v[40:43]
	v_mfma_f32_16x16x32_bf16 v[40:43], v[184:187], v[192:195], v[40:43]
	v_mfma_f32_16x16x32_bf16 v[32:35], v[168:171], v[196:199], v[32:35]
	v_mfma_f32_16x16x32_bf16 v[32:35], v[172:175], v[200:203], v[32:35]
	v_mfma_f32_16x16x32_bf16 v[24:27], v[176:179], v[196:199], v[24:27]
	v_mfma_f32_16x16x32_bf16 v[24:27], v[184:187], v[200:203], v[24:27]
	v_mfma_f32_16x16x32_bf16 v[16:19], v[168:171], v[204:207], v[16:19]
	v_mfma_f32_16x16x32_bf16 v[16:19], v[172:175], v[208:211], v[16:19]
	v_mfma_f32_16x16x32_bf16 v[8:11], v[176:179], v[204:207], v[8:11]
	v_mfma_f32_16x16x32_bf16 v[8:11], v[184:187], v[208:211], v[8:11]
	s_setprio 2
	s_barrier
	v_mfma_f32_16x16x32_bf16 v[4:7], v[168:171], v[212:215], v[4:7]
	v_mfma_f32_16x16x32_bf16 v[4:7], v[172:175], v[216:219], v[4:7]
	v_mfma_f32_16x16x32_bf16 v[0:3], v[176:179], v[212:215], v[0:3]
	v_mfma_f32_16x16x32_bf16 v[0:3], v[184:187], v[216:219], v[0:3]
	s_setprio 0
	s_add_i32 s88, s88, 2
	s_add_u32 s58, s58, 0x100
	s_addc_u32 s59, s59, 0
	s_add_u32 s86, s86, 0x100
	s_addc_u32 s87, s87, 0
	s_cmp_gt_u32 s88, 13
	s_cbranch_scc0 .LBB0_601
	s_and_b64 vcc, exec, s[12:13]
	s_cbranch_vccz .LBB0_604
	s_barrier

.LBB0_723:
	s_ashr_i32 s31, s30, 31
	s_lshl_b64 s[36:37], s[30:31], 19
	s_add_u32 s36, s80, s36
	s_addc_u32 s37, s81, s37
	s_and_b64 s[44:45], s[10:11], exec
	s_cselect_b32 s31, s37, s49
	s_cselect_b32 s70, s36, s48
	s_ashr_i32 s19, s18, 31
	s_lshl_b64 s[44:45], s[18:19], 19
	s_add_u32 s44, s56, s44
	s_addc_u32 s45, s57, s45
	s_and_b64 s[54:55], s[10:11], exec
	s_cselect_b32 s19, s45, s53
	s_cselect_b32 s71, s44, s52
	s_add_u32 s48, s48, 0x40080
	s_addc_u32 s49, s49, 0
	s_add_u32 s72, s52, 0x100
	s_addc_u32 s73, s53, 0
	s_mov_b32 s74, -2
	ds_read_b128 v[140:143], v147
	ds_read_b128 v[150:153], v147 offset:1024
	ds_read_b128 v[154:157], v147 offset:2048
	ds_read_b128 v[158:161], v147 offset:3072
	ds_read_b128 v[162:165], v148
	ds_read_b128 v[166:169], v148 offset:1024
	ds_read_b128 v[170:173], v148 offset:2048
	ds_read_b128 v[174:177], v148 offset:3072
	s_add_u32 s52, s48, 0xfffc0080
	s_addc_u32 s53, s49, -1
	s_cmp_eq_u32 s74, 12
	s_cselect_b32 s55, s31, s53
	s_cselect_b32 s54, s70, s52
	s_cselect_b32 s53, s19, s73
	s_cselect_b32 s52, s71, s72
	v_lshl_add_u64 v[178:179], s[48:49], 0, v[132:133]
	s_add_i32 m0, s47, 0xc000
	ds_read_b128 v[184:187], v149
	ds_read_b128 v[188:191], v149 offset:1024
	ds_read_b128 v[192:195], v149 offset:2048
	ds_read_b128 v[196:199], v149 offset:3072
	ds_read_b128 v[200:203], v149 offset:4096
	ds_read_b128 v[204:207], v149 offset:5120
	ds_read_b128 v[208:211], v149 offset:6144
	ds_read_b128 v[212:215], v149 offset:7168
	global_load_lds_dwordx4 v[178:179], off
	v_lshl_add_u64 v[178:179], s[48:49], 0, v[134:135]
	s_add_i32 m0, s47, 0xe000
	s_nop 0
	global_load_lds_dwordx4 v[178:179], off
	s_waitcnt vmcnt(8)
	s_waitcnt lgkmcnt(0)
	s_barrier
	s_setprio 1
	s_waitcnt lgkmcnt(0)
	v_mfma_f32_16x16x32_bf16 v[124:127], v[140:143], v[184:187], 0
	v_mfma_f32_16x16x32_bf16 v[124:127], v[150:153], v[188:191], v[124:127]
	v_mfma_f32_16x16x32_bf16 v[120:123], v[154:157], v[184:187], 0
	v_mfma_f32_16x16x32_bf16 v[120:123], v[158:161], v[188:191], v[120:123]
	v_mfma_f32_16x16x32_bf16 v[108:111], v[140:143], v[192:195], 0
	v_mfma_f32_16x16x32_bf16 v[108:111], v[150:153], v[196:199], v[108:111]
	v_mfma_f32_16x16x32_bf16 v[104:107], v[154:157], v[192:195], 0
	v_mfma_f32_16x16x32_bf16 v[104:107], v[158:161], v[196:199], v[104:107]
	v_mfma_f32_16x16x32_bf16 v[92:95], v[140:143], v[200:203], 0
	v_mfma_f32_16x16x32_bf16 v[92:95], v[150:153], v[204:207], v[92:95]
	v_mfma_f32_16x16x32_bf16 v[88:91], v[154:157], v[200:203], 0
	v_mfma_f32_16x16x32_bf16 v[88:91], v[158:161], v[204:207], v[88:91]
	v_mfma_f32_16x16x32_bf16 v[76:79], v[140:143], v[208:211], 0
	v_mfma_f32_16x16x32_bf16 v[76:79], v[150:153], v[212:215], v[76:79]
	v_mfma_f32_16x16x32_bf16 v[72:75], v[154:157], v[208:211], 0
	v_mfma_f32_16x16x32_bf16 v[72:75], v[158:161], v[212:215], v[72:75]
	v_mfma_f32_16x16x32_bf16 v[116:119], v[162:165], v[184:187], 0
	v_mfma_f32_16x16x32_bf16 v[116:119], v[166:169], v[188:191], v[116:119]
	v_mfma_f32_16x16x32_bf16 v[112:115], v[170:173], v[184:187], 0
	v_mfma_f32_16x16x32_bf16 v[112:115], v[174:177], v[188:191], v[112:115]
	v_mfma_f32_16x16x32_bf16 v[100:103], v[162:165], v[192:195], 0
	v_mfma_f32_16x16x32_bf16 v[100:103], v[166:169], v[196:199], v[100:103]
	v_mfma_f32_16x16x32_bf16 v[96:99], v[170:173], v[192:195], 0
	v_mfma_f32_16x16x32_bf16 v[96:99], v[174:177], v[196:199], v[96:99]
	v_mfma_f32_16x16x32_bf16 v[84:87], v[162:165], v[200:203], 0
	v_mfma_f32_16x16x32_bf16 v[84:87], v[166:169], v[204:207], v[84:87]
	v_mfma_f32_16x16x32_bf16 v[80:83], v[170:173], v[200:203], 0
	v_mfma_f32_16x16x32_bf16 v[80:83], v[174:177], v[204:207], v[80:83]
	s_setprio 2
	s_barrier
	v_mfma_f32_16x16x32_bf16 v[68:71], v[162:165], v[208:211], 0
	v_mfma_f32_16x16x32_bf16 v[68:71], v[166:169], v[212:215], v[68:71]
	v_mfma_f32_16x16x32_bf16 v[64:67], v[170:173], v[208:211], 0
	v_mfma_f32_16x16x32_bf16 v[64:67], v[174:177], v[212:215], v[64:67]
	s_setprio 0
	s_add_i32 s75, s66, s58
	v_lshl_add_u64 v[178:179], s[52:53], 0, v[130:131]
	s_mov_b32 m0, s75
	ds_read_b128 v[184:187], v149 offset:16384
	ds_read_b128 v[188:191], v149 offset:17408
	ds_read_b128 v[192:195], v149 offset:18432
	ds_read_b128 v[196:199], v149 offset:19456
	ds_read_b128 v[200:203], v149 offset:20480
	ds_read_b128 v[204:207], v149 offset:21504
	ds_read_b128 v[208:211], v149 offset:22528
	ds_read_b128 v[212:215], v149 offset:23552
	global_load_lds_dwordx4 v[178:179], off
	s_add_i32 m0, s75, 0x2000
	s_add_u32 s76, s52, 0x40000
	v_lshl_add_u64 v[216:217], s[52:53], 0, v[128:129]
	s_addc_u32 s77, s53, 0
	s_add_i32 s75, s67, s58
	global_load_lds_dwordx4 v[216:217], off
	v_lshl_add_u64 v[218:219], s[76:77], 0, v[130:131]
	s_mov_b32 m0, s75
	v_lshl_add_u64 v[220:221], s[54:55], 0, v[128:129]
	global_load_lds_dwordx4 v[218:219], off
	v_lshl_add_u64 v[218:219], s[76:77], 0, v[128:129]
	s_add_i32 m0, s75, 0x2000
	s_nop 0
	global_load_lds_dwordx4 v[218:219], off
	v_lshl_add_u64 v[218:219], s[54:55], 0, v[130:131]
	s_mov_b32 m0, s47
	s_nop 0
	global_load_lds_dwordx4 v[218:219], off
	s_mov_b32 m0, s60
	s_nop 0
	global_load_lds_dwordx4 v[220:221], off
	s_waitcnt vmcnt(8)
	s_waitcnt lgkmcnt(0)
	s_barrier
	s_setprio 1
	s_waitcnt lgkmcnt(0)
	v_mfma_f32_16x16x32_bf16 v[60:63], v[140:143], v[184:187], 0
	v_mfma_f32_16x16x32_bf16 v[60:63], v[150:153], v[188:191], v[60:63]
	v_mfma_f32_16x16x32_bf16 v[56:59], v[154:157], v[184:187], 0
	v_mfma_f32_16x16x32_bf16 v[56:59], v[158:161], v[188:191], v[56:59]
	v_mfma_f32_16x16x32_bf16 v[44:47], v[140:143], v[192:195], 0
	v_mfma_f32_16x16x32_bf16 v[44:47], v[150:153], v[196:199], v[44:47]
	v_mfma_f32_16x16x32_bf16 v[40:43], v[154:157], v[192:195], 0
	v_mfma_f32_16x16x32_bf16 v[40:43], v[158:161], v[196:199], v[40:43]
	v_mfma_f32_16x16x32_bf16 v[28:31], v[140:143], v[200:203], 0
	v_mfma_f32_16x16x32_bf16 v[28:31], v[150:153], v[204:207], v[28:31]
	v_mfma_f32_16x16x32_bf16 v[24:27], v[154:157], v[200:203], 0
	v_mfma_f32_16x16x32_bf16 v[24:27], v[158:161], v[204:207], v[24:27]
	v_mfma_f32_16x16x32_bf16 v[12:15], v[140:143], v[208:211], 0
	v_mfma_f32_16x16x32_bf16 v[12:15], v[150:153], v[212:215], v[12:15]
	v_mfma_f32_16x16x32_bf16 v[8:11], v[154:157], v[208:211], 0
	v_mfma_f32_16x16x32_bf16 v[8:11], v[158:161], v[212:215], v[8:11]
	v_mfma_f32_16x16x32_bf16 v[52:55], v[162:165], v[184:187], 0
	v_mfma_f32_16x16x32_bf16 v[52:55], v[166:169], v[188:191], v[52:55]
	v_mfma_f32_16x16x32_bf16 v[48:51], v[170:173], v[184:187], 0
	v_mfma_f32_16x16x32_bf16 v[48:51], v[174:177], v[188:191], v[48:51]
	v_mfma_f32_16x16x32_bf16 v[36:39], v[162:165], v[192:195], 0
	v_mfma_f32_16x16x32_bf16 v[36:39], v[166:169], v[196:199], v[36:39]
	v_mfma_f32_16x16x32_bf16 v[32:35], v[170:173], v[192:195], 0
	v_mfma_f32_16x16x32_bf16 v[32:35], v[174:177], v[196:199], v[32:35]
	v_mfma_f32_16x16x32_bf16 v[20:23], v[162:165], v[200:203], 0
	v_mfma_f32_16x16x32_bf16 v[20:23], v[166:169], v[204:207], v[20:23]
	v_mfma_f32_16x16x32_bf16 v[16:19], v[170:173], v[200:203], 0
	v_mfma_f32_16x16x32_bf16 v[16:19], v[174:177], v[204:207], v[16:19]
	s_setprio 2
	s_barrier
	v_mfma_f32_16x16x32_bf16 v[4:7], v[162:165], v[208:211], 0
	v_mfma_f32_16x16x32_bf16 v[4:7], v[166:169], v[212:215], v[4:7]
	v_mfma_f32_16x16x32_bf16 v[0:3], v[170:173], v[208:211], 0
	v_mfma_f32_16x16x32_bf16 v[0:3], v[174:177], v[212:215], v[0:3]
	s_setprio 0
	s_branch .Lmid_gemm4
.LBB0_724:
	ds_read_b128 v[140:143], v147
	ds_read_b128 v[150:153], v147 offset:1024
	ds_read_b128 v[154:157], v147 offset:2048
	ds_read_b128 v[158:161], v147 offset:3072
	ds_read_b128 v[162:165], v148
	ds_read_b128 v[166:169], v148 offset:1024
	ds_read_b128 v[170:173], v148 offset:2048
	ds_read_b128 v[174:177], v148 offset:3072
	s_add_u32 s52, s48, 0xfffc0080
	s_addc_u32 s53, s49, -1
	s_cmp_eq_u32 s74, 12
	s_cselect_b32 s55, s31, s53
	s_cselect_b32 s54, s70, s52
	s_cselect_b32 s53, s19, s73
	s_cselect_b32 s52, s71, s72
	v_lshl_add_u64 v[178:179], s[48:49], 0, v[132:133]
	s_add_i32 m0, s47, 0xc000
	ds_read_b128 v[184:187], v149
	ds_read_b128 v[188:191], v149 offset:1024
	ds_read_b128 v[192:195], v149 offset:2048
	ds_read_b128 v[196:199], v149 offset:3072
	ds_read_b128 v[200:203], v149 offset:4096
	ds_read_b128 v[204:207], v149 offset:5120
	ds_read_b128 v[208:211], v149 offset:6144
	ds_read_b128 v[212:215], v149 offset:7168
	global_load_lds_dwordx4 v[178:179], off
	v_lshl_add_u64 v[178:179], s[48:49], 0, v[134:135]
	s_add_i32 m0, s47, 0xe000
	s_nop 0
	global_load_lds_dwordx4 v[178:179], off
	s_waitcnt vmcnt(8)
	s_waitcnt lgkmcnt(0)
	s_barrier
	s_setprio 1
	s_waitcnt lgkmcnt(0)
	v_mfma_f32_16x16x32_bf16 v[124:127], v[140:143], v[184:187], v[124:127]
	v_mfma_f32_16x16x32_bf16 v[124:127], v[150:153], v[188:191], v[124:127]
	v_mfma_f32_16x16x32_bf16 v[120:123], v[154:157], v[184:187], v[120:123]
	v_mfma_f32_16x16x32_bf16 v[120:123], v[158:161], v[188:191], v[120:123]
	v_mfma_f32_16x16x32_bf16 v[108:111], v[140:143], v[192:195], v[108:111]
	v_mfma_f32_16x16x32_bf16 v[108:111], v[150:153], v[196:199], v[108:111]
	v_mfma_f32_16x16x32_bf16 v[104:107], v[154:157], v[192:195], v[104:107]
	v_mfma_f32_16x16x32_bf16 v[104:107], v[158:161], v[196:199], v[104:107]
	v_mfma_f32_16x16x32_bf16 v[92:95], v[140:143], v[200:203], v[92:95]
	v_mfma_f32_16x16x32_bf16 v[92:95], v[150:153], v[204:207], v[92:95]
	v_mfma_f32_16x16x32_bf16 v[88:91], v[154:157], v[200:203], v[88:91]
	v_mfma_f32_16x16x32_bf16 v[88:91], v[158:161], v[204:207], v[88:91]
	v_mfma_f32_16x16x32_bf16 v[76:79], v[140:143], v[208:211], v[76:79]
	v_mfma_f32_16x16x32_bf16 v[76:79], v[150:153], v[212:215], v[76:79]
	v_mfma_f32_16x16x32_bf16 v[72:75], v[154:157], v[208:211], v[72:75]
	v_mfma_f32_16x16x32_bf16 v[72:75], v[158:161], v[212:215], v[72:75]
	v_mfma_f32_16x16x32_bf16 v[116:119], v[162:165], v[184:187], v[116:119]
	v_mfma_f32_16x16x32_bf16 v[116:119], v[166:169], v[188:191], v[116:119]
	v_mfma_f32_16x16x32_bf16 v[112:115], v[170:173], v[184:187], v[112:115]
	v_mfma_f32_16x16x32_bf16 v[112:115], v[174:177], v[188:191], v[112:115]
	v_mfma_f32_16x16x32_bf16 v[100:103], v[162:165], v[192:195], v[100:103]
	v_mfma_f32_16x16x32_bf16 v[100:103], v[166:169], v[196:199], v[100:103]
	v_mfma_f32_16x16x32_bf16 v[96:99], v[170:173], v[192:195], v[96:99]
	v_mfma_f32_16x16x32_bf16 v[96:99], v[174:177], v[196:199], v[96:99]
	v_mfma_f32_16x16x32_bf16 v[84:87], v[162:165], v[200:203], v[84:87]
	v_mfma_f32_16x16x32_bf16 v[84:87], v[166:169], v[204:207], v[84:87]
	v_mfma_f32_16x16x32_bf16 v[80:83], v[170:173], v[200:203], v[80:83]
	v_mfma_f32_16x16x32_bf16 v[80:83], v[174:177], v[204:207], v[80:83]
	s_setprio 2
	s_barrier
	v_mfma_f32_16x16x32_bf16 v[68:71], v[162:165], v[208:211], v[68:71]
	v_mfma_f32_16x16x32_bf16 v[68:71], v[166:169], v[212:215], v[68:71]
	v_mfma_f32_16x16x32_bf16 v[64:67], v[170:173], v[208:211], v[64:67]
	v_mfma_f32_16x16x32_bf16 v[64:67], v[174:177], v[212:215], v[64:67]
	s_setprio 0
	s_add_i32 s75, s66, s58
	v_lshl_add_u64 v[178:179], s[52:53], 0, v[130:131]
	s_mov_b32 m0, s75
	ds_read_b128 v[184:187], v149 offset:16384
	ds_read_b128 v[188:191], v149 offset:17408
	ds_read_b128 v[192:195], v149 offset:18432
	ds_read_b128 v[196:199], v149 offset:19456
	ds_read_b128 v[200:203], v149 offset:20480
	ds_read_b128 v[204:207], v149 offset:21504
	ds_read_b128 v[208:211], v149 offset:22528
	ds_read_b128 v[212:215], v149 offset:23552
	global_load_lds_dwordx4 v[178:179], off
	s_add_i32 m0, s75, 0x2000
	s_add_u32 s76, s52, 0x40000
	v_lshl_add_u64 v[216:217], s[52:53], 0, v[128:129]
	s_addc_u32 s77, s53, 0
	s_add_i32 s75, s67, s58
	global_load_lds_dwordx4 v[216:217], off
	v_lshl_add_u64 v[218:219], s[76:77], 0, v[130:131]
	s_mov_b32 m0, s75
	v_lshl_add_u64 v[220:221], s[54:55], 0, v[128:129]
	global_load_lds_dwordx4 v[218:219], off
	v_lshl_add_u64 v[218:219], s[76:77], 0, v[128:129]
	s_add_i32 m0, s75, 0x2000
	s_nop 0
	global_load_lds_dwordx4 v[218:219], off
	v_lshl_add_u64 v[218:219], s[54:55], 0, v[130:131]
	s_mov_b32 m0, s47
	s_nop 0
	global_load_lds_dwordx4 v[218:219], off
	s_mov_b32 m0, s60
	s_nop 0
	global_load_lds_dwordx4 v[220:221], off
	s_waitcnt vmcnt(8)
	s_waitcnt lgkmcnt(0)
	s_barrier
	s_setprio 1
	s_waitcnt lgkmcnt(0)
	v_mfma_f32_16x16x32_bf16 v[60:63], v[140:143], v[184:187], v[60:63]
	v_mfma_f32_16x16x32_bf16 v[60:63], v[150:153], v[188:191], v[60:63]
	v_mfma_f32_16x16x32_bf16 v[56:59], v[154:157], v[184:187], v[56:59]
	v_mfma_f32_16x16x32_bf16 v[56:59], v[158:161], v[188:191], v[56:59]
	v_mfma_f32_16x16x32_bf16 v[44:47], v[140:143], v[192:195], v[44:47]
	v_mfma_f32_16x16x32_bf16 v[44:47], v[150:153], v[196:199], v[44:47]
	v_mfma_f32_16x16x32_bf16 v[40:43], v[154:157], v[192:195], v[40:43]
	v_mfma_f32_16x16x32_bf16 v[40:43], v[158:161], v[196:199], v[40:43]
	v_mfma_f32_16x16x32_bf16 v[28:31], v[140:143], v[200:203], v[28:31]
	v_mfma_f32_16x16x32_bf16 v[28:31], v[150:153], v[204:207], v[28:31]
	v_mfma_f32_16x16x32_bf16 v[24:27], v[154:157], v[200:203], v[24:27]
	v_mfma_f32_16x16x32_bf16 v[24:27], v[158:161], v[204:207], v[24:27]
	v_mfma_f32_16x16x32_bf16 v[12:15], v[140:143], v[208:211], v[12:15]
	v_mfma_f32_16x16x32_bf16 v[12:15], v[150:153], v[212:215], v[12:15]
	v_mfma_f32_16x16x32_bf16 v[8:11], v[154:157], v[208:211], v[8:11]
	v_mfma_f32_16x16x32_bf16 v[8:11], v[158:161], v[212:215], v[8:11]
	v_mfma_f32_16x16x32_bf16 v[52:55], v[162:165], v[184:187], v[52:55]
	v_mfma_f32_16x16x32_bf16 v[52:55], v[166:169], v[188:191], v[52:55]
	v_mfma_f32_16x16x32_bf16 v[48:51], v[170:173], v[184:187], v[48:51]
	v_mfma_f32_16x16x32_bf16 v[48:51], v[174:177], v[188:191], v[48:51]
	v_mfma_f32_16x16x32_bf16 v[36:39], v[162:165], v[192:195], v[36:39]
	v_mfma_f32_16x16x32_bf16 v[36:39], v[166:169], v[196:199], v[36:39]
	v_mfma_f32_16x16x32_bf16 v[32:35], v[170:173], v[192:195], v[32:35]
	v_mfma_f32_16x16x32_bf16 v[32:35], v[174:177], v[196:199], v[32:35]
	v_mfma_f32_16x16x32_bf16 v[20:23], v[162:165], v[200:203], v[20:23]
	v_mfma_f32_16x16x32_bf16 v[20:23], v[166:169], v[204:207], v[20:23]
	v_mfma_f32_16x16x32_bf16 v[16:19], v[170:173], v[200:203], v[16:19]
	v_mfma_f32_16x16x32_bf16 v[16:19], v[174:177], v[204:207], v[16:19]
	s_setprio 2
	s_barrier
	v_mfma_f32_16x16x32_bf16 v[4:7], v[162:165], v[208:211], v[4:7]
	v_mfma_f32_16x16x32_bf16 v[4:7], v[166:169], v[212:215], v[4:7]
	v_mfma_f32_16x16x32_bf16 v[0:3], v[170:173], v[208:211], v[0:3]
	v_mfma_f32_16x16x32_bf16 v[0:3], v[174:177], v[212:215], v[0:3]
	s_setprio 0
.Lmid_gemm4:
	s_add_i32 s75, 0, 0x18000
	s_add_i32 s76, 0, 0x1c000
	v_add_u32_e32 v158, s75, v145
	v_add_u32_e32 v174, s76, v145
	ds_read_b128 v[140:143], v158
	ds_read_b128 v[150:153], v158 offset:1024
	ds_read_b128 v[154:157], v158 offset:2048
	ds_read_b128 v[158:161], v158 offset:3072
	ds_read_b128 v[162:165], v174
	ds_read_b128 v[166:169], v174 offset:1024
	ds_read_b128 v[170:173], v174 offset:2048
	ds_read_b128 v[174:177], v174 offset:3072
	s_add_u32 s54, s54, 0x40000
	s_addc_u32 s55, s55, 0
	s_mov_b32 m0, s61
	v_lshl_add_u64 v[222:223], s[54:55], 0, v[130:131]
	ds_read_b128 v[184:187], v149 offset:32768
	ds_read_b128 v[188:191], v149 offset:33792
	ds_read_b128 v[192:195], v149 offset:34816
	ds_read_b128 v[196:199], v149 offset:35840
	ds_read_b128 v[200:203], v149 offset:36864
	ds_read_b128 v[204:207], v149 offset:37888
	ds_read_b128 v[208:211], v149 offset:38912
	ds_read_b128 v[212:215], v149 offset:39936
	global_load_lds_dwordx4 v[222:223], off
	v_lshl_add_u64 v[222:223], s[54:55], 0, v[128:129]
	s_mov_b32 m0, s62
	s_nop 0
	global_load_lds_dwordx4 v[222:223], off
	s_waitcnt vmcnt(8)
	s_waitcnt lgkmcnt(0)
	s_barrier
	s_setprio 1
	s_waitcnt lgkmcnt(0)
	v_mfma_f32_16x16x32_bf16 v[124:127], v[140:143], v[184:187], v[124:127]
	v_mfma_f32_16x16x32_bf16 v[124:127], v[150:153], v[188:191], v[124:127]
	v_mfma_f32_16x16x32_bf16 v[120:123], v[154:157], v[184:187], v[120:123]
	v_mfma_f32_16x16x32_bf16 v[120:123], v[158:161], v[188:191], v[120:123]
	v_mfma_f32_16x16x32_bf16 v[108:111], v[140:143], v[192:195], v[108:111]
	v_mfma_f32_16x16x32_bf16 v[108:111], v[150:153], v[196:199], v[108:111]
	v_mfma_f32_16x16x32_bf16 v[104:107], v[154:157], v[192:195], v[104:107]
	v_mfma_f32_16x16x32_bf16 v[104:107], v[158:161], v[196:199], v[104:107]
	v_mfma_f32_16x16x32_bf16 v[92:95], v[140:143], v[200:203], v[92:95]
	v_mfma_f32_16x16x32_bf16 v[92:95], v[150:153], v[204:207], v[92:95]
	v_mfma_f32_16x16x32_bf16 v[88:91], v[154:157], v[200:203], v[88:91]
	v_mfma_f32_16x16x32_bf16 v[88:91], v[158:161], v[204:207], v[88:91]
	v_mfma_f32_16x16x32_bf16 v[76:79], v[140:143], v[208:211], v[76:79]
	v_mfma_f32_16x16x32_bf16 v[76:79], v[150:153], v[212:215], v[76:79]
	v_mfma_f32_16x16x32_bf16 v[72:75], v[154:157], v[208:211], v[72:75]
	v_mfma_f32_16x16x32_bf16 v[72:75], v[158:161], v[212:215], v[72:75]
	v_mfma_f32_16x16x32_bf16 v[116:119], v[162:165], v[184:187], v[116:119]
	v_mfma_f32_16x16x32_bf16 v[116:119], v[166:169], v[188:191], v[116:119]
	v_mfma_f32_16x16x32_bf16 v[112:115], v[170:173], v[184:187], v[112:115]
	v_mfma_f32_16x16x32_bf16 v[112:115], v[174:177], v[188:191], v[112:115]
	v_mfma_f32_16x16x32_bf16 v[100:103], v[162:165], v[192:195], v[100:103]
	v_mfma_f32_16x16x32_bf16 v[100:103], v[166:169], v[196:199], v[100:103]
	v_mfma_f32_16x16x32_bf16 v[96:99], v[170:173], v[192:195], v[96:99]
	v_mfma_f32_16x16x32_bf16 v[96:99], v[174:177], v[196:199], v[96:99]
	v_mfma_f32_16x16x32_bf16 v[84:87], v[162:165], v[200:203], v[84:87]
	v_mfma_f32_16x16x32_bf16 v[84:87], v[166:169], v[204:207], v[84:87]
	v_mfma_f32_16x16x32_bf16 v[80:83], v[170:173], v[200:203], v[80:83]
	v_mfma_f32_16x16x32_bf16 v[80:83], v[174:177], v[204:207], v[80:83]
	s_setprio 2
	s_barrier
	v_mfma_f32_16x16x32_bf16 v[68:71], v[162:165], v[208:211], v[68:71]
	v_mfma_f32_16x16x32_bf16 v[68:71], v[166:169], v[212:215], v[68:71]
	v_mfma_f32_16x16x32_bf16 v[64:67], v[170:173], v[208:211], v[64:67]
	v_mfma_f32_16x16x32_bf16 v[64:67], v[174:177], v[212:215], v[64:67]
	s_setprio 0
	s_add_i32 s54, s75, s58
	v_lshl_add_u64 v[178:179], v[178:179], 0, s[12:13]
	s_mov_b32 m0, s54
	ds_read_b128 v[184:187], v149 offset:49152
	ds_read_b128 v[188:191], v149 offset:50176
	ds_read_b128 v[192:195], v149 offset:51200
	ds_read_b128 v[196:199], v149 offset:52224
	ds_read_b128 v[200:203], v149 offset:53248
	ds_read_b128 v[204:207], v149 offset:54272
	ds_read_b128 v[208:211], v149 offset:55296
	ds_read_b128 v[212:215], v149 offset:56320
	global_load_lds_dwordx4 v[178:179], off
	s_add_i32 m0, s54, 0x2000
	s_add_u32 s52, s52, 0x40080
	v_lshl_add_u64 v[178:179], v[216:217], 0, s[12:13]
	s_addc_u32 s53, s53, 0
	s_add_i32 s54, s76, s58
	global_load_lds_dwordx4 v[178:179], off
	v_lshl_add_u64 v[178:179], s[52:53], 0, v[130:131]
	s_mov_b32 m0, s54
	s_nop 0
	global_load_lds_dwordx4 v[178:179], off
	v_lshl_add_u64 v[178:179], s[52:53], 0, v[128:129]
	s_add_i32 m0, s54, 0x2000
	s_nop 0
	global_load_lds_dwordx4 v[178:179], off
	v_lshl_add_u64 v[178:179], v[218:219], 0, s[12:13]
	s_mov_b32 m0, s64
	s_nop 0
	global_load_lds_dwordx4 v[178:179], off
	v_lshl_add_u64 v[178:179], v[220:221], 0, s[12:13]
	s_mov_b32 m0, s65
	s_nop 0
	global_load_lds_dwordx4 v[178:179], off
	s_waitcnt vmcnt(8)
	s_waitcnt lgkmcnt(0)
	s_barrier
	s_setprio 1
	s_waitcnt lgkmcnt(0)
	v_mfma_f32_16x16x32_bf16 v[60:63], v[140:143], v[184:187], v[60:63]
	v_mfma_f32_16x16x32_bf16 v[60:63], v[150:153], v[188:191], v[60:63]
	v_mfma_f32_16x16x32_bf16 v[56:59], v[154:157], v[184:187], v[56:59]
	v_mfma_f32_16x16x32_bf16 v[56:59], v[158:161], v[188:191], v[56:59]
	v_mfma_f32_16x16x32_bf16 v[44:47], v[140:143], v[192:195], v[44:47]
	v_mfma_f32_16x16x32_bf16 v[44:47], v[150:153], v[196:199], v[44:47]
	v_mfma_f32_16x16x32_bf16 v[40:43], v[154:157], v[192:195], v[40:43]
	v_mfma_f32_16x16x32_bf16 v[40:43], v[158:161], v[196:199], v[40:43]
	v_mfma_f32_16x16x32_bf16 v[28:31], v[140:143], v[200:203], v[28:31]
	v_mfma_f32_16x16x32_bf16 v[28:31], v[150:153], v[204:207], v[28:31]
	v_mfma_f32_16x16x32_bf16 v[24:27], v[154:157], v[200:203], v[24:27]
	v_mfma_f32_16x16x32_bf16 v[24:27], v[158:161], v[204:207], v[24:27]
	v_mfma_f32_16x16x32_bf16 v[12:15], v[140:143], v[208:211], v[12:15]
	v_mfma_f32_16x16x32_bf16 v[12:15], v[150:153], v[212:215], v[12:15]
	v_mfma_f32_16x16x32_bf16 v[8:11], v[154:157], v[208:211], v[8:11]
	v_mfma_f32_16x16x32_bf16 v[8:11], v[158:161], v[212:215], v[8:11]
	v_mfma_f32_16x16x32_bf16 v[52:55], v[162:165], v[184:187], v[52:55]
	v_mfma_f32_16x16x32_bf16 v[52:55], v[166:169], v[188:191], v[52:55]
	v_mfma_f32_16x16x32_bf16 v[48:51], v[170:173], v[184:187], v[48:51]
	v_mfma_f32_16x16x32_bf16 v[48:51], v[174:177], v[188:191], v[48:51]
	v_mfma_f32_16x16x32_bf16 v[36:39], v[162:165], v[192:195], v[36:39]
	v_mfma_f32_16x16x32_bf16 v[36:39], v[166:169], v[196:199], v[36:39]
	v_mfma_f32_16x16x32_bf16 v[32:35], v[170:173], v[192:195], v[32:35]
	v_mfma_f32_16x16x32_bf16 v[32:35], v[174:177], v[196:199], v[32:35]
	v_mfma_f32_16x16x32_bf16 v[20:23], v[162:165], v[200:203], v[20:23]
	v_mfma_f32_16x16x32_bf16 v[20:23], v[166:169], v[204:207], v[20:23]
	v_mfma_f32_16x16x32_bf16 v[16:19], v[170:173], v[200:203], v[16:19]
	v_mfma_f32_16x16x32_bf16 v[16:19], v[174:177], v[204:207], v[16:19]
	s_setprio 2
	s_barrier
	v_mfma_f32_16x16x32_bf16 v[4:7], v[162:165], v[208:211], v[4:7]
	v_mfma_f32_16x16x32_bf16 v[4:7], v[166:169], v[212:215], v[4:7]
	v_mfma_f32_16x16x32_bf16 v[0:3], v[170:173], v[208:211], v[0:3]
	v_mfma_f32_16x16x32_bf16 v[0:3], v[174:177], v[212:215], v[0:3]
	s_setprio 0
	s_add_i32 s74, s74, 2
	s_add_u32 s48, s48, 0x100
	s_addc_u32 s49, s49, 0
	s_add_u32 s72, s72, 0x100
	s_addc_u32 s73, s73, 0
	s_cmp_gt_u32 s74, 13
	s_cbranch_scc0 .LBB0_724
	s_and_b64 vcc, exec, s[16:17]
	s_cbranch_vccz .LBB0_727
	s_barrier

.LBB0_803:
	s_add_u32 s84, s54, 0x100
	s_addc_u32 s85, s55, 0
	s_mov_b32 s86, -2
	ds_read_b128 v[152:155], v149
	ds_read_b128 v[156:159], v149 offset:1024
	ds_read_b128 v[160:163], v149 offset:2048
	ds_read_b128 v[164:167], v149 offset:3072
	ds_read_b128 v[168:171], v150
	ds_read_b128 v[172:175], v150 offset:1024
	ds_read_b128 v[176:179], v150 offset:2048
	ds_read_b128 v[184:187], v150 offset:3072
	s_add_u32 s54, s52, 0x100
	s_addc_u32 s55, s53, 0
	s_cmp_eq_u32 s86, 40
	s_cselect_b32 s59, s13, s55
	s_cselect_b32 s58, s12, s54
	s_cselect_b32 s57, s49, s85
	s_cselect_b32 s56, s48, s84
	v_lshl_add_u64 v[144:145], s[52:53], 0, v[136:137]
	s_add_i32 m0, s63, 0xc000
	ds_read_b128 v[188:191], v151
	ds_read_b128 v[192:195], v151 offset:1024
	ds_read_b128 v[196:199], v151 offset:2048
	ds_read_b128 v[200:203], v151 offset:3072
	ds_read_b128 v[204:207], v151 offset:4096
	ds_read_b128 v[208:211], v151 offset:5120
	ds_read_b128 v[212:215], v151 offset:6144
	ds_read_b128 v[216:219], v151 offset:7168
	global_load_lds_dwordx4 v[144:145], off
	v_lshl_add_u64 v[144:145], s[52:53], 0, v[138:139]
	s_add_i32 m0, s63, 0xe000
	s_nop 0
	global_load_lds_dwordx4 v[144:145], off
	s_waitcnt vmcnt(8)
	s_waitcnt lgkmcnt(0)
	s_barrier
	s_setprio 1
	s_waitcnt lgkmcnt(0)
	v_mfma_f32_16x16x32_bf16 v[124:127], v[152:155], v[188:191], 0
	v_mfma_f32_16x16x32_bf16 v[124:127], v[156:159], v[192:195], v[124:127]
	v_mfma_f32_16x16x32_bf16 v[120:123], v[160:163], v[188:191], 0
	v_mfma_f32_16x16x32_bf16 v[120:123], v[164:167], v[192:195], v[120:123]
	v_mfma_f32_16x16x32_bf16 v[116:119], v[152:155], v[196:199], 0
	v_mfma_f32_16x16x32_bf16 v[116:119], v[156:159], v[200:203], v[116:119]
	v_mfma_f32_16x16x32_bf16 v[108:111], v[160:163], v[196:199], 0
	v_mfma_f32_16x16x32_bf16 v[108:111], v[164:167], v[200:203], v[108:111]
	v_mfma_f32_16x16x32_bf16 v[100:103], v[152:155], v[204:207], 0
	v_mfma_f32_16x16x32_bf16 v[100:103], v[156:159], v[208:211], v[100:103]
	v_mfma_f32_16x16x32_bf16 v[92:95], v[160:163], v[204:207], 0
	v_mfma_f32_16x16x32_bf16 v[92:95], v[164:167], v[208:211], v[92:95]
	v_mfma_f32_16x16x32_bf16 v[84:87], v[152:155], v[212:215], 0
	v_mfma_f32_16x16x32_bf16 v[84:87], v[156:159], v[216:219], v[84:87]
	v_mfma_f32_16x16x32_bf16 v[76:79], v[160:163], v[212:215], 0
	v_mfma_f32_16x16x32_bf16 v[76:79], v[164:167], v[216:219], v[76:79]
	v_mfma_f32_16x16x32_bf16 v[112:115], v[168:171], v[188:191], 0
	v_mfma_f32_16x16x32_bf16 v[112:115], v[172:175], v[192:195], v[112:115]
	v_mfma_f32_16x16x32_bf16 v[104:107], v[176:179], v[188:191], 0
	v_mfma_f32_16x16x32_bf16 v[104:107], v[184:187], v[192:195], v[104:107]
	v_mfma_f32_16x16x32_bf16 v[96:99], v[168:171], v[196:199], 0
	v_mfma_f32_16x16x32_bf16 v[96:99], v[172:175], v[200:203], v[96:99]
	v_mfma_f32_16x16x32_bf16 v[88:91], v[176:179], v[196:199], 0
	v_mfma_f32_16x16x32_bf16 v[88:91], v[184:187], v[200:203], v[88:91]
	v_mfma_f32_16x16x32_bf16 v[80:83], v[168:171], v[204:207], 0
	v_mfma_f32_16x16x32_bf16 v[80:83], v[172:175], v[208:211], v[80:83]
	v_mfma_f32_16x16x32_bf16 v[72:75], v[176:179], v[204:207], 0
	v_mfma_f32_16x16x32_bf16 v[72:75], v[184:187], v[208:211], v[72:75]
	s_setprio 2
	s_barrier
	v_mfma_f32_16x16x32_bf16 v[68:71], v[168:171], v[212:215], 0
	v_mfma_f32_16x16x32_bf16 v[68:71], v[172:175], v[216:219], v[68:71]
	v_mfma_f32_16x16x32_bf16 v[64:67], v[176:179], v[212:215], 0
	v_mfma_f32_16x16x32_bf16 v[64:67], v[184:187], v[216:219], v[64:67]
	s_setprio 0
	s_add_i32 s52, s70, s62
	v_lshl_add_u64 v[144:145], s[56:57], 0, v[130:131]
	s_mov_b32 m0, s52
	ds_read_b128 v[188:191], v151 offset:16384
	ds_read_b128 v[192:195], v151 offset:17408
	ds_read_b128 v[196:199], v151 offset:18432
	ds_read_b128 v[200:203], v151 offset:19456
	ds_read_b128 v[204:207], v151 offset:20480
	ds_read_b128 v[208:211], v151 offset:21504
	ds_read_b128 v[212:215], v151 offset:22528
	ds_read_b128 v[216:219], v151 offset:23552
	global_load_lds_dwordx4 v[144:145], off
	s_add_i32 m0, s52, 0x2000
	s_add_u32 s52, s56, 0xb0000
	v_lshl_add_u64 v[220:221], s[56:57], 0, v[134:135]
	s_addc_u32 s53, s57, 0
	s_add_i32 s79, s71, s62
	global_load_lds_dwordx4 v[220:221], off
	v_lshl_add_u64 v[222:223], s[52:53], 0, v[130:131]
	s_mov_b32 m0, s79
	v_lshl_add_u64 v[224:225], s[58:59], 0, v[132:133]
	global_load_lds_dwordx4 v[222:223], off
	v_lshl_add_u64 v[222:223], s[52:53], 0, v[134:135]
	s_add_i32 m0, s79, 0x2000
	s_nop 0
	global_load_lds_dwordx4 v[222:223], off
	v_lshl_add_u64 v[222:223], s[58:59], 0, v[128:129]
	s_mov_b32 m0, s63
	s_nop 0
	global_load_lds_dwordx4 v[222:223], off
	s_mov_b32 m0, s64
	s_nop 0
	global_load_lds_dwordx4 v[224:225], off
	s_waitcnt vmcnt(8)
	s_waitcnt lgkmcnt(0)
	s_barrier
	s_setprio 1
	s_waitcnt lgkmcnt(0)
	v_mfma_f32_16x16x32_bf16 v[60:63], v[152:155], v[188:191], 0
	v_mfma_f32_16x16x32_bf16 v[60:63], v[156:159], v[192:195], v[60:63]
	v_mfma_f32_16x16x32_bf16 v[56:59], v[160:163], v[188:191], 0
	v_mfma_f32_16x16x32_bf16 v[56:59], v[164:167], v[192:195], v[56:59]
	v_mfma_f32_16x16x32_bf16 v[52:55], v[152:155], v[196:199], 0
	v_mfma_f32_16x16x32_bf16 v[52:55], v[156:159], v[200:203], v[52:55]
	v_mfma_f32_16x16x32_bf16 v[44:47], v[160:163], v[196:199], 0
	v_mfma_f32_16x16x32_bf16 v[44:47], v[164:167], v[200:203], v[44:47]
	v_mfma_f32_16x16x32_bf16 v[36:39], v[152:155], v[204:207], 0
	v_mfma_f32_16x16x32_bf16 v[36:39], v[156:159], v[208:211], v[36:39]
	v_mfma_f32_16x16x32_bf16 v[28:31], v[160:163], v[204:207], 0
	v_mfma_f32_16x16x32_bf16 v[28:31], v[164:167], v[208:211], v[28:31]
	v_mfma_f32_16x16x32_bf16 v[20:23], v[152:155], v[212:215], 0
	v_mfma_f32_16x16x32_bf16 v[20:23], v[156:159], v[216:219], v[20:23]
	v_mfma_f32_16x16x32_bf16 v[12:15], v[160:163], v[212:215], 0
	v_mfma_f32_16x16x32_bf16 v[12:15], v[164:167], v[216:219], v[12:15]
	v_mfma_f32_16x16x32_bf16 v[48:51], v[168:171], v[188:191], 0
	v_mfma_f32_16x16x32_bf16 v[48:51], v[172:175], v[192:195], v[48:51]
	v_mfma_f32_16x16x32_bf16 v[40:43], v[176:179], v[188:191], 0
	v_mfma_f32_16x16x32_bf16 v[40:43], v[184:187], v[192:195], v[40:43]
	v_mfma_f32_16x16x32_bf16 v[32:35], v[168:171], v[196:199], 0
	v_mfma_f32_16x16x32_bf16 v[32:35], v[172:175], v[200:203], v[32:35]
	v_mfma_f32_16x16x32_bf16 v[24:27], v[176:179], v[196:199], 0
	v_mfma_f32_16x16x32_bf16 v[24:27], v[184:187], v[200:203], v[24:27]
	v_mfma_f32_16x16x32_bf16 v[16:19], v[168:171], v[204:207], 0
	v_mfma_f32_16x16x32_bf16 v[16:19], v[172:175], v[208:211], v[16:19]
	v_mfma_f32_16x16x32_bf16 v[8:11], v[176:179], v[204:207], 0
	v_mfma_f32_16x16x32_bf16 v[8:11], v[184:187], v[208:211], v[8:11]
	s_setprio 2
	s_barrier
	v_mfma_f32_16x16x32_bf16 v[4:7], v[168:171], v[212:215], 0
	v_mfma_f32_16x16x32_bf16 v[4:7], v[172:175], v[216:219], v[4:7]
	v_mfma_f32_16x16x32_bf16 v[0:3], v[176:179], v[212:215], 0
	v_mfma_f32_16x16x32_bf16 v[0:3], v[184:187], v[216:219], v[0:3]
	s_setprio 0
	s_branch .Lmid_gemm5
.LBB0_804:
	ds_read_b128 v[152:155], v149
	ds_read_b128 v[156:159], v149 offset:1024
	ds_read_b128 v[160:163], v149 offset:2048
	ds_read_b128 v[164:167], v149 offset:3072
	ds_read_b128 v[168:171], v150
	ds_read_b128 v[172:175], v150 offset:1024
	ds_read_b128 v[176:179], v150 offset:2048
	ds_read_b128 v[184:187], v150 offset:3072
	s_add_u32 s54, s52, 0x100
	s_addc_u32 s55, s53, 0
	s_cmp_eq_u32 s86, 40
	s_cselect_b32 s59, s13, s55
	s_cselect_b32 s58, s12, s54
	s_cselect_b32 s57, s49, s85
	s_cselect_b32 s56, s48, s84
	v_lshl_add_u64 v[144:145], s[52:53], 0, v[136:137]
	s_add_i32 m0, s63, 0xc000
	ds_read_b128 v[188:191], v151
	ds_read_b128 v[192:195], v151 offset:1024
	ds_read_b128 v[196:199], v151 offset:2048
	ds_read_b128 v[200:203], v151 offset:3072
	ds_read_b128 v[204:207], v151 offset:4096
	ds_read_b128 v[208:211], v151 offset:5120
	ds_read_b128 v[212:215], v151 offset:6144
	ds_read_b128 v[216:219], v151 offset:7168
	global_load_lds_dwordx4 v[144:145], off
	v_lshl_add_u64 v[144:145], s[52:53], 0, v[138:139]
	s_add_i32 m0, s63, 0xe000
	s_nop 0
	global_load_lds_dwordx4 v[144:145], off
	s_waitcnt vmcnt(8)
	s_waitcnt lgkmcnt(0)
	s_barrier
	s_setprio 1
	s_waitcnt lgkmcnt(0)
	v_mfma_f32_16x16x32_bf16 v[124:127], v[152:155], v[188:191], v[124:127]
	v_mfma_f32_16x16x32_bf16 v[124:127], v[156:159], v[192:195], v[124:127]
	v_mfma_f32_16x16x32_bf16 v[120:123], v[160:163], v[188:191], v[120:123]
	v_mfma_f32_16x16x32_bf16 v[120:123], v[164:167], v[192:195], v[120:123]
	v_mfma_f32_16x16x32_bf16 v[116:119], v[152:155], v[196:199], v[116:119]
	v_mfma_f32_16x16x32_bf16 v[116:119], v[156:159], v[200:203], v[116:119]
	v_mfma_f32_16x16x32_bf16 v[108:111], v[160:163], v[196:199], v[108:111]
	v_mfma_f32_16x16x32_bf16 v[108:111], v[164:167], v[200:203], v[108:111]
	v_mfma_f32_16x16x32_bf16 v[100:103], v[152:155], v[204:207], v[100:103]
	v_mfma_f32_16x16x32_bf16 v[100:103], v[156:159], v[208:211], v[100:103]
	v_mfma_f32_16x16x32_bf16 v[92:95], v[160:163], v[204:207], v[92:95]
	v_mfma_f32_16x16x32_bf16 v[92:95], v[164:167], v[208:211], v[92:95]
	v_mfma_f32_16x16x32_bf16 v[84:87], v[152:155], v[212:215], v[84:87]
	v_mfma_f32_16x16x32_bf16 v[84:87], v[156:159], v[216:219], v[84:87]
	v_mfma_f32_16x16x32_bf16 v[76:79], v[160:163], v[212:215], v[76:79]
	v_mfma_f32_16x16x32_bf16 v[76:79], v[164:167], v[216:219], v[76:79]
	v_mfma_f32_16x16x32_bf16 v[112:115], v[168:171], v[188:191], v[112:115]
	v_mfma_f32_16x16x32_bf16 v[112:115], v[172:175], v[192:195], v[112:115]
	v_mfma_f32_16x16x32_bf16 v[104:107], v[176:179], v[188:191], v[104:107]
	v_mfma_f32_16x16x32_bf16 v[104:107], v[184:187], v[192:195], v[104:107]
	v_mfma_f32_16x16x32_bf16 v[96:99], v[168:171], v[196:199], v[96:99]
	v_mfma_f32_16x16x32_bf16 v[96:99], v[172:175], v[200:203], v[96:99]
	v_mfma_f32_16x16x32_bf16 v[88:91], v[176:179], v[196:199], v[88:91]
	v_mfma_f32_16x16x32_bf16 v[88:91], v[184:187], v[200:203], v[88:91]
	v_mfma_f32_16x16x32_bf16 v[80:83], v[168:171], v[204:207], v[80:83]
	v_mfma_f32_16x16x32_bf16 v[80:83], v[172:175], v[208:211], v[80:83]
	v_mfma_f32_16x16x32_bf16 v[72:75], v[176:179], v[204:207], v[72:75]
	v_mfma_f32_16x16x32_bf16 v[72:75], v[184:187], v[208:211], v[72:75]
	s_setprio 2
	s_barrier
	v_mfma_f32_16x16x32_bf16 v[68:71], v[168:171], v[212:215], v[68:71]
	v_mfma_f32_16x16x32_bf16 v[68:71], v[172:175], v[216:219], v[68:71]
	v_mfma_f32_16x16x32_bf16 v[64:67], v[176:179], v[212:215], v[64:67]
	v_mfma_f32_16x16x32_bf16 v[64:67], v[184:187], v[216:219], v[64:67]
	s_setprio 0
	s_add_i32 s52, s70, s62
	v_lshl_add_u64 v[144:145], s[56:57], 0, v[130:131]
	s_mov_b32 m0, s52
	ds_read_b128 v[188:191], v151 offset:16384
	ds_read_b128 v[192:195], v151 offset:17408
	ds_read_b128 v[196:199], v151 offset:18432
	ds_read_b128 v[200:203], v151 offset:19456
	ds_read_b128 v[204:207], v151 offset:20480
	ds_read_b128 v[208:211], v151 offset:21504
	ds_read_b128 v[212:215], v151 offset:22528
	ds_read_b128 v[216:219], v151 offset:23552
	global_load_lds_dwordx4 v[144:145], off
	s_add_i32 m0, s52, 0x2000
	s_add_u32 s52, s56, 0xb0000
	v_lshl_add_u64 v[220:221], s[56:57], 0, v[134:135]
	s_addc_u32 s53, s57, 0
	s_add_i32 s79, s71, s62
	global_load_lds_dwordx4 v[220:221], off
	v_lshl_add_u64 v[222:223], s[52:53], 0, v[130:131]
	s_mov_b32 m0, s79
	v_lshl_add_u64 v[224:225], s[58:59], 0, v[132:133]
	global_load_lds_dwordx4 v[222:223], off
	v_lshl_add_u64 v[222:223], s[52:53], 0, v[134:135]
	s_add_i32 m0, s79, 0x2000
	s_nop 0
	global_load_lds_dwordx4 v[222:223], off
	v_lshl_add_u64 v[222:223], s[58:59], 0, v[128:129]
	s_mov_b32 m0, s63
	s_nop 0
	global_load_lds_dwordx4 v[222:223], off
	s_mov_b32 m0, s64
	s_nop 0
	global_load_lds_dwordx4 v[224:225], off
	s_waitcnt vmcnt(8)
	s_waitcnt lgkmcnt(0)
	s_barrier
	s_setprio 1
	s_waitcnt lgkmcnt(0)
	v_mfma_f32_16x16x32_bf16 v[60:63], v[152:155], v[188:191], v[60:63]
	v_mfma_f32_16x16x32_bf16 v[60:63], v[156:159], v[192:195], v[60:63]
	v_mfma_f32_16x16x32_bf16 v[56:59], v[160:163], v[188:191], v[56:59]
	v_mfma_f32_16x16x32_bf16 v[56:59], v[164:167], v[192:195], v[56:59]
	v_mfma_f32_16x16x32_bf16 v[52:55], v[152:155], v[196:199], v[52:55]
	v_mfma_f32_16x16x32_bf16 v[52:55], v[156:159], v[200:203], v[52:55]
	v_mfma_f32_16x16x32_bf16 v[44:47], v[160:163], v[196:199], v[44:47]
	v_mfma_f32_16x16x32_bf16 v[44:47], v[164:167], v[200:203], v[44:47]
	v_mfma_f32_16x16x32_bf16 v[36:39], v[152:155], v[204:207], v[36:39]
	v_mfma_f32_16x16x32_bf16 v[36:39], v[156:159], v[208:211], v[36:39]
	v_mfma_f32_16x16x32_bf16 v[28:31], v[160:163], v[204:207], v[28:31]
	v_mfma_f32_16x16x32_bf16 v[28:31], v[164:167], v[208:211], v[28:31]
	v_mfma_f32_16x16x32_bf16 v[20:23], v[152:155], v[212:215], v[20:23]
	v_mfma_f32_16x16x32_bf16 v[20:23], v[156:159], v[216:219], v[20:23]
	v_mfma_f32_16x16x32_bf16 v[12:15], v[160:163], v[212:215], v[12:15]
	v_mfma_f32_16x16x32_bf16 v[12:15], v[164:167], v[216:219], v[12:15]
	v_mfma_f32_16x16x32_bf16 v[48:51], v[168:171], v[188:191], v[48:51]
	v_mfma_f32_16x16x32_bf16 v[48:51], v[172:175], v[192:195], v[48:51]
	v_mfma_f32_16x16x32_bf16 v[40:43], v[176:179], v[188:191], v[40:43]
	v_mfma_f32_16x16x32_bf16 v[40:43], v[184:187], v[192:195], v[40:43]
	v_mfma_f32_16x16x32_bf16 v[32:35], v[168:171], v[196:199], v[32:35]
	v_mfma_f32_16x16x32_bf16 v[32:35], v[172:175], v[200:203], v[32:35]
	v_mfma_f32_16x16x32_bf16 v[24:27], v[176:179], v[196:199], v[24:27]
	v_mfma_f32_16x16x32_bf16 v[24:27], v[184:187], v[200:203], v[24:27]
	v_mfma_f32_16x16x32_bf16 v[16:19], v[168:171], v[204:207], v[16:19]
	v_mfma_f32_16x16x32_bf16 v[16:19], v[172:175], v[208:211], v[16:19]
	v_mfma_f32_16x16x32_bf16 v[8:11], v[176:179], v[204:207], v[8:11]
	v_mfma_f32_16x16x32_bf16 v[8:11], v[184:187], v[208:211], v[8:11]
	s_setprio 2
	s_barrier
	v_mfma_f32_16x16x32_bf16 v[4:7], v[168:171], v[212:215], v[4:7]
	v_mfma_f32_16x16x32_bf16 v[4:7], v[172:175], v[216:219], v[4:7]
	v_mfma_f32_16x16x32_bf16 v[0:3], v[176:179], v[212:215], v[0:3]
	v_mfma_f32_16x16x32_bf16 v[0:3], v[184:187], v[216:219], v[0:3]
	s_setprio 0
.Lmid_gemm5:
	s_add_i32 s79, 0, 0x18000
	s_add_i32 s87, 0, 0x1c000
	v_add_u32_e32 v164, s79, v147
	v_add_u32_e32 v181, s87, v147
	ds_read_b128 v[152:155], v164
	ds_read_b128 v[156:159], v164 offset:1024
	ds_read_b128 v[160:163], v164 offset:2048
	ds_read_b128 v[164:167], v164 offset:3072
	ds_read_b128 v[168:171], v181
	ds_read_b128 v[172:175], v181 offset:1024
	ds_read_b128 v[176:179], v181 offset:2048
	ds_read_b128 v[184:187], v181 offset:3072
	s_add_u32 s52, s58, 0xb0000
	s_addc_u32 s53, s59, 0
	s_mov_b32 m0, s65
	v_lshl_add_u64 v[226:227], s[52:53], 0, v[128:129]
	ds_read_b128 v[188:191], v151 offset:32768
	ds_read_b128 v[192:195], v151 offset:33792
	ds_read_b128 v[196:199], v151 offset:34816
	ds_read_b128 v[200:203], v151 offset:35840
	ds_read_b128 v[204:207], v151 offset:36864
	ds_read_b128 v[208:211], v151 offset:37888
	ds_read_b128 v[212:215], v151 offset:38912
	ds_read_b128 v[216:219], v151 offset:39936
	global_load_lds_dwordx4 v[226:227], off
	v_lshl_add_u64 v[226:227], s[52:53], 0, v[132:133]
	s_mov_b32 m0, s66
	s_nop 0
	global_load_lds_dwordx4 v[226:227], off
	s_waitcnt vmcnt(8)
	s_waitcnt lgkmcnt(0)
	s_barrier
	s_setprio 1
	s_waitcnt lgkmcnt(0)
	v_mfma_f32_16x16x32_bf16 v[124:127], v[152:155], v[188:191], v[124:127]
	v_mfma_f32_16x16x32_bf16 v[124:127], v[156:159], v[192:195], v[124:127]
	v_mfma_f32_16x16x32_bf16 v[120:123], v[160:163], v[188:191], v[120:123]
	v_mfma_f32_16x16x32_bf16 v[120:123], v[164:167], v[192:195], v[120:123]
	v_mfma_f32_16x16x32_bf16 v[116:119], v[152:155], v[196:199], v[116:119]
	v_mfma_f32_16x16x32_bf16 v[116:119], v[156:159], v[200:203], v[116:119]
	v_mfma_f32_16x16x32_bf16 v[108:111], v[160:163], v[196:199], v[108:111]
	v_mfma_f32_16x16x32_bf16 v[108:111], v[164:167], v[200:203], v[108:111]
	v_mfma_f32_16x16x32_bf16 v[100:103], v[152:155], v[204:207], v[100:103]
	v_mfma_f32_16x16x32_bf16 v[100:103], v[156:159], v[208:211], v[100:103]
	v_mfma_f32_16x16x32_bf16 v[92:95], v[160:163], v[204:207], v[92:95]
	v_mfma_f32_16x16x32_bf16 v[92:95], v[164:167], v[208:211], v[92:95]
	v_mfma_f32_16x16x32_bf16 v[84:87], v[152:155], v[212:215], v[84:87]
	v_mfma_f32_16x16x32_bf16 v[84:87], v[156:159], v[216:219], v[84:87]
	v_mfma_f32_16x16x32_bf16 v[76:79], v[160:163], v[212:215], v[76:79]
	v_mfma_f32_16x16x32_bf16 v[76:79], v[164:167], v[216:219], v[76:79]
	v_mfma_f32_16x16x32_bf16 v[112:115], v[168:171], v[188:191], v[112:115]
	v_mfma_f32_16x16x32_bf16 v[112:115], v[172:175], v[192:195], v[112:115]
	v_mfma_f32_16x16x32_bf16 v[104:107], v[176:179], v[188:191], v[104:107]
	v_mfma_f32_16x16x32_bf16 v[104:107], v[184:187], v[192:195], v[104:107]
	v_mfma_f32_16x16x32_bf16 v[96:99], v[168:171], v[196:199], v[96:99]
	v_mfma_f32_16x16x32_bf16 v[96:99], v[172:175], v[200:203], v[96:99]
	v_mfma_f32_16x16x32_bf16 v[88:91], v[176:179], v[196:199], v[88:91]
	v_mfma_f32_16x16x32_bf16 v[88:91], v[184:187], v[200:203], v[88:91]
	v_mfma_f32_16x16x32_bf16 v[80:83], v[168:171], v[204:207], v[80:83]
	v_mfma_f32_16x16x32_bf16 v[80:83], v[172:175], v[208:211], v[80:83]
	v_mfma_f32_16x16x32_bf16 v[72:75], v[176:179], v[204:207], v[72:75]
	v_mfma_f32_16x16x32_bf16 v[72:75], v[184:187], v[208:211], v[72:75]
	s_setprio 2
	s_barrier
	v_mfma_f32_16x16x32_bf16 v[68:71], v[168:171], v[212:215], v[68:71]
	v_mfma_f32_16x16x32_bf16 v[68:71], v[172:175], v[216:219], v[68:71]
	v_mfma_f32_16x16x32_bf16 v[64:67], v[176:179], v[212:215], v[64:67]
	v_mfma_f32_16x16x32_bf16 v[64:67], v[184:187], v[216:219], v[64:67]
	s_setprio 0
	s_add_i32 s52, s79, s62
	v_lshl_add_u64 v[144:145], v[144:145], 0, s[16:17]
	s_mov_b32 m0, s52
	ds_read_b128 v[188:191], v151 offset:49152
	ds_read_b128 v[192:195], v151 offset:50176
	ds_read_b128 v[196:199], v151 offset:51200
	ds_read_b128 v[200:203], v151 offset:52224
	ds_read_b128 v[204:207], v151 offset:53248
	ds_read_b128 v[208:211], v151 offset:54272
	ds_read_b128 v[212:215], v151 offset:55296
	ds_read_b128 v[216:219], v151 offset:56320
	global_load_lds_dwordx4 v[144:145], off
	s_add_i32 m0, s52, 0x2000
	s_add_u32 s52, s56, 0xb0080
	v_lshl_add_u64 v[144:145], v[220:221], 0, s[16:17]
	s_addc_u32 s53, s57, 0
	s_add_i32 s56, s87, s62
	global_load_lds_dwordx4 v[144:145], off
	v_lshl_add_u64 v[144:145], s[52:53], 0, v[130:131]
	s_mov_b32 m0, s56
	s_nop 0
	global_load_lds_dwordx4 v[144:145], off
	v_lshl_add_u64 v[144:145], s[52:53], 0, v[134:135]
	s_add_i32 m0, s56, 0x2000
	s_nop 0
	global_load_lds_dwordx4 v[144:145], off
	v_lshl_add_u64 v[144:145], v[222:223], 0, s[16:17]
	s_mov_b32 m0, s68
	s_nop 0
	global_load_lds_dwordx4 v[144:145], off
	v_lshl_add_u64 v[144:145], v[224:225], 0, s[16:17]
	s_mov_b32 m0, s69
	s_nop 0
	global_load_lds_dwordx4 v[144:145], off
	s_waitcnt vmcnt(8)
	s_waitcnt lgkmcnt(0)
	s_barrier
	s_setprio 1
	s_waitcnt lgkmcnt(0)
	v_mfma_f32_16x16x32_bf16 v[60:63], v[152:155], v[188:191], v[60:63]
	v_mfma_f32_16x16x32_bf16 v[60:63], v[156:159], v[192:195], v[60:63]
	v_mfma_f32_16x16x32_bf16 v[56:59], v[160:163], v[188:191], v[56:59]
	v_mfma_f32_16x16x32_bf16 v[56:59], v[164:167], v[192:195], v[56:59]
	v_mfma_f32_16x16x32_bf16 v[52:55], v[152:155], v[196:199], v[52:55]
	v_mfma_f32_16x16x32_bf16 v[52:55], v[156:159], v[200:203], v[52:55]
	v_mfma_f32_16x16x32_bf16 v[44:47], v[160:163], v[196:199], v[44:47]
	v_mfma_f32_16x16x32_bf16 v[44:47], v[164:167], v[200:203], v[44:47]
	v_mfma_f32_16x16x32_bf16 v[36:39], v[152:155], v[204:207], v[36:39]
	v_mfma_f32_16x16x32_bf16 v[36:39], v[156:159], v[208:211], v[36:39]
	v_mfma_f32_16x16x32_bf16 v[28:31], v[160:163], v[204:207], v[28:31]
	v_mfma_f32_16x16x32_bf16 v[28:31], v[164:167], v[208:211], v[28:31]
	v_mfma_f32_16x16x32_bf16 v[20:23], v[152:155], v[212:215], v[20:23]
	v_mfma_f32_16x16x32_bf16 v[20:23], v[156:159], v[216:219], v[20:23]
	v_mfma_f32_16x16x32_bf16 v[12:15], v[160:163], v[212:215], v[12:15]
	v_mfma_f32_16x16x32_bf16 v[12:15], v[164:167], v[216:219], v[12:15]
	v_mfma_f32_16x16x32_bf16 v[48:51], v[168:171], v[188:191], v[48:51]
	v_mfma_f32_16x16x32_bf16 v[48:51], v[172:175], v[192:195], v[48:51]
	v_mfma_f32_16x16x32_bf16 v[40:43], v[176:179], v[188:191], v[40:43]
	v_mfma_f32_16x16x32_bf16 v[40:43], v[184:187], v[192:195], v[40:43]
	v_mfma_f32_16x16x32_bf16 v[32:35], v[168:171], v[196:199], v[32:35]
	v_mfma_f32_16x16x32_bf16 v[32:35], v[172:175], v[200:203], v[32:35]
	v_mfma_f32_16x16x32_bf16 v[24:27], v[176:179], v[196:199], v[24:27]
	v_mfma_f32_16x16x32_bf16 v[24:27], v[184:187], v[200:203], v[24:27]
	v_mfma_f32_16x16x32_bf16 v[16:19], v[168:171], v[204:207], v[16:19]
	v_mfma_f32_16x16x32_bf16 v[16:19], v[172:175], v[208:211], v[16:19]
	v_mfma_f32_16x16x32_bf16 v[8:11], v[176:179], v[204:207], v[8:11]
	v_mfma_f32_16x16x32_bf16 v[8:11], v[184:187], v[208:211], v[8:11]
	s_setprio 2
	s_barrier
	v_mfma_f32_16x16x32_bf16 v[4:7], v[168:171], v[212:215], v[4:7]
	v_mfma_f32_16x16x32_bf16 v[4:7], v[172:175], v[216:219], v[4:7]
	v_mfma_f32_16x16x32_bf16 v[0:3], v[176:179], v[212:215], v[0:3]
	v_mfma_f32_16x16x32_bf16 v[0:3], v[184:187], v[216:219], v[0:3]
	s_setprio 0
	s_add_i32 s86, s86, 2
	s_add_u32 s84, s84, 0x100
	s_addc_u32 s85, s85, 0
	s_cmp_gt_u32 s86, 41
	s_mov_b64 s[52:53], s[54:55]
	s_cbranch_scc0 .LBB0_804
	s_and_b64 vcc, exec, s[18:19]
	s_cbranch_vccz .LBB0_807
	s_barrier

.LBB0_934:
	s_ashr_i32 s53, s52, 31
	s_lshl_b64 s[54:55], s[52:53], 19
	s_add_u32 s54, s80, s54
	s_addc_u32 s55, s81, s55
	s_and_b64 s[56:57], s[10:11], exec
	s_cselect_b32 s53, s55, s61
	s_cselect_b32 s83, s54, s60
	s_ashr_i32 s49, s48, 31
	s_lshl_b64 s[56:57], s[48:49], 19
	s_add_u32 s56, s66, s56
	s_addc_u32 s57, s67, s57
	s_and_b64 s[64:65], s[10:11], exec
	s_cselect_b32 s49, s57, s63
	s_cselect_b32 s84, s56, s62
	s_add_u32 s60, s60, 0x40080
	s_addc_u32 s61, s61, 0
	s_add_u32 s85, s62, 0x100
	s_addc_u32 s86, s63, 0
	s_mov_b32 s87, -2
	ds_read_b128 v[152:155], v148
	ds_read_b128 v[156:159], v148 offset:1024
	ds_read_b128 v[160:163], v148 offset:2048
	ds_read_b128 v[164:167], v148 offset:3072
	ds_read_b128 v[168:171], v149
	ds_read_b128 v[172:175], v149 offset:1024
	ds_read_b128 v[176:179], v149 offset:2048
	ds_read_b128 v[184:187], v149 offset:3072
	s_add_u32 s62, s60, 0xfffc0080
	s_addc_u32 s63, s61, -1
	s_cmp_eq_u32 s87, 12
	s_cselect_b32 s65, s53, s63
	s_cselect_b32 s64, s83, s62
	s_cselect_b32 s63, s49, s86
	s_cselect_b32 s62, s84, s85
	v_lshl_add_u64 v[220:221], s[60:61], 0, v[138:139]
	s_add_i32 m0, s69, 0xc000
	ds_read_b128 v[188:191], v150
	ds_read_b128 v[192:195], v150 offset:1024
	ds_read_b128 v[196:199], v150 offset:2048
	ds_read_b128 v[200:203], v150 offset:3072
	ds_read_b128 v[204:207], v150 offset:4096
	ds_read_b128 v[208:211], v150 offset:5120
	ds_read_b128 v[212:215], v150 offset:6144
	ds_read_b128 v[216:219], v150 offset:7168
	global_load_lds_dwordx4 v[220:221], off
	v_lshl_add_u64 v[220:221], s[60:61], 0, v[140:141]
	s_add_i32 m0, s69, 0xe000
	s_nop 0
	global_load_lds_dwordx4 v[220:221], off
	s_waitcnt vmcnt(8)
	s_waitcnt lgkmcnt(0)
	s_barrier
	s_setprio 1
	s_waitcnt lgkmcnt(0)
	v_mfma_f32_16x16x32_bf16 v[124:127], v[152:155], v[188:191], 0
	v_mfma_f32_16x16x32_bf16 v[124:127], v[156:159], v[192:195], v[124:127]
	v_mfma_f32_16x16x32_bf16 v[120:123], v[160:163], v[188:191], 0
	v_mfma_f32_16x16x32_bf16 v[120:123], v[164:167], v[192:195], v[120:123]
	v_mfma_f32_16x16x32_bf16 v[116:119], v[152:155], v[196:199], 0
	v_mfma_f32_16x16x32_bf16 v[116:119], v[156:159], v[200:203], v[116:119]
	v_mfma_f32_16x16x32_bf16 v[112:115], v[160:163], v[196:199], 0
	v_mfma_f32_16x16x32_bf16 v[112:115], v[164:167], v[200:203], v[112:115]
	v_mfma_f32_16x16x32_bf16 v[108:111], v[152:155], v[204:207], 0
	v_mfma_f32_16x16x32_bf16 v[108:111], v[156:159], v[208:211], v[108:111]
	v_mfma_f32_16x16x32_bf16 v[104:107], v[160:163], v[204:207], 0
	v_mfma_f32_16x16x32_bf16 v[104:107], v[164:167], v[208:211], v[104:107]
	v_mfma_f32_16x16x32_bf16 v[100:103], v[152:155], v[212:215], 0
	v_mfma_f32_16x16x32_bf16 v[100:103], v[156:159], v[216:219], v[100:103]
	v_mfma_f32_16x16x32_bf16 v[96:99], v[160:163], v[212:215], 0
	v_mfma_f32_16x16x32_bf16 v[96:99], v[164:167], v[216:219], v[96:99]
	v_mfma_f32_16x16x32_bf16 v[76:79], v[168:171], v[188:191], 0
	v_mfma_f32_16x16x32_bf16 v[76:79], v[172:175], v[192:195], v[76:79]
	v_mfma_f32_16x16x32_bf16 v[68:71], v[176:179], v[188:191], 0
	v_mfma_f32_16x16x32_bf16 v[68:71], v[184:187], v[192:195], v[68:71]
	v_mfma_f32_16x16x32_bf16 v[60:63], v[168:171], v[196:199], 0
	v_mfma_f32_16x16x32_bf16 v[60:63], v[172:175], v[200:203], v[60:63]
	v_mfma_f32_16x16x32_bf16 v[52:55], v[176:179], v[196:199], 0
	v_mfma_f32_16x16x32_bf16 v[52:55], v[184:187], v[200:203], v[52:55]
	v_mfma_f32_16x16x32_bf16 v[44:47], v[168:171], v[204:207], 0
	v_mfma_f32_16x16x32_bf16 v[44:47], v[172:175], v[208:211], v[44:47]
	v_mfma_f32_16x16x32_bf16 v[40:43], v[176:179], v[204:207], 0
	v_mfma_f32_16x16x32_bf16 v[40:43], v[184:187], v[208:211], v[40:43]
	s_setprio 2
	s_barrier
	v_mfma_f32_16x16x32_bf16 v[36:39], v[168:171], v[212:215], 0
	v_mfma_f32_16x16x32_bf16 v[36:39], v[172:175], v[216:219], v[36:39]
	v_mfma_f32_16x16x32_bf16 v[32:35], v[176:179], v[212:215], 0
	v_mfma_f32_16x16x32_bf16 v[32:35], v[184:187], v[216:219], v[32:35]
	s_setprio 0
	s_add_i32 s79, s77, s68
	v_lshl_add_u64 v[220:221], s[62:63], 0, v[130:131]
	s_mov_b32 m0, s79
	ds_read_b128 v[188:191], v150 offset:16384
	ds_read_b128 v[192:195], v150 offset:17408
	ds_read_b128 v[196:199], v150 offset:18432
	ds_read_b128 v[200:203], v150 offset:19456
	ds_read_b128 v[204:207], v150 offset:20480
	ds_read_b128 v[208:211], v150 offset:21504
	ds_read_b128 v[212:215], v150 offset:22528
	ds_read_b128 v[216:219], v150 offset:23552
	global_load_lds_dwordx4 v[220:221], off
	s_add_i32 m0, s79, 0x2000
	s_add_u32 s88, s62, 0x40000
	v_lshl_add_u64 v[222:223], s[62:63], 0, v[134:135]
	s_addc_u32 s89, s63, 0
	s_add_i32 s79, s82, s68
	global_load_lds_dwordx4 v[222:223], off
	v_lshl_add_u64 v[224:225], s[88:89], 0, v[130:131]
	s_mov_b32 m0, s79
	v_lshl_add_u64 v[226:227], s[64:65], 0, v[132:133]
	global_load_lds_dwordx4 v[224:225], off
	v_lshl_add_u64 v[224:225], s[88:89], 0, v[134:135]
	s_add_i32 m0, s79, 0x2000
	s_nop 0
	global_load_lds_dwordx4 v[224:225], off
	v_lshl_add_u64 v[224:225], s[64:65], 0, v[128:129]
	s_mov_b32 m0, s69
	s_nop 0
	global_load_lds_dwordx4 v[224:225], off
	s_mov_b32 m0, s70
	s_nop 0
	global_load_lds_dwordx4 v[226:227], off
	s_waitcnt vmcnt(8)
	s_waitcnt lgkmcnt(0)
	s_barrier
	s_setprio 1
	s_waitcnt lgkmcnt(0)
	v_mfma_f32_16x16x32_bf16 v[92:95], v[152:155], v[188:191], 0
	v_mfma_f32_16x16x32_bf16 v[92:95], v[156:159], v[192:195], v[92:95]
	v_mfma_f32_16x16x32_bf16 v[88:91], v[160:163], v[188:191], 0
	v_mfma_f32_16x16x32_bf16 v[88:91], v[164:167], v[192:195], v[88:91]
	v_mfma_f32_16x16x32_bf16 v[84:87], v[152:155], v[196:199], 0
	v_mfma_f32_16x16x32_bf16 v[84:87], v[156:159], v[200:203], v[84:87]
	v_mfma_f32_16x16x32_bf16 v[80:83], v[160:163], v[196:199], 0
	v_mfma_f32_16x16x32_bf16 v[80:83], v[164:167], v[200:203], v[80:83]
	v_mfma_f32_16x16x32_bf16 v[72:75], v[152:155], v[204:207], 0
	v_mfma_f32_16x16x32_bf16 v[72:75], v[156:159], v[208:211], v[72:75]
	v_mfma_f32_16x16x32_bf16 v[64:67], v[160:163], v[204:207], 0
	v_mfma_f32_16x16x32_bf16 v[64:67], v[164:167], v[208:211], v[64:67]
	v_mfma_f32_16x16x32_bf16 v[56:59], v[152:155], v[212:215], 0
	v_mfma_f32_16x16x32_bf16 v[56:59], v[156:159], v[216:219], v[56:59]
	v_mfma_f32_16x16x32_bf16 v[48:51], v[160:163], v[212:215], 0
	v_mfma_f32_16x16x32_bf16 v[48:51], v[164:167], v[216:219], v[48:51]
	v_mfma_f32_16x16x32_bf16 v[28:31], v[168:171], v[188:191], 0
	v_mfma_f32_16x16x32_bf16 v[28:31], v[172:175], v[192:195], v[28:31]
	v_mfma_f32_16x16x32_bf16 v[24:27], v[176:179], v[188:191], 0
	v_mfma_f32_16x16x32_bf16 v[24:27], v[184:187], v[192:195], v[24:27]
	v_mfma_f32_16x16x32_bf16 v[20:23], v[168:171], v[196:199], 0
	v_mfma_f32_16x16x32_bf16 v[20:23], v[172:175], v[200:203], v[20:23]
	v_mfma_f32_16x16x32_bf16 v[16:19], v[176:179], v[196:199], 0
	v_mfma_f32_16x16x32_bf16 v[16:19], v[184:187], v[200:203], v[16:19]
	v_mfma_f32_16x16x32_bf16 v[12:15], v[168:171], v[204:207], 0
	v_mfma_f32_16x16x32_bf16 v[12:15], v[172:175], v[208:211], v[12:15]
	v_mfma_f32_16x16x32_bf16 v[8:11], v[176:179], v[204:207], 0
	v_mfma_f32_16x16x32_bf16 v[8:11], v[184:187], v[208:211], v[8:11]
	s_setprio 2
	s_barrier
	v_mfma_f32_16x16x32_bf16 v[4:7], v[168:171], v[212:215], 0
	v_mfma_f32_16x16x32_bf16 v[4:7], v[172:175], v[216:219], v[4:7]
	v_mfma_f32_16x16x32_bf16 v[0:3], v[176:179], v[212:215], 0
	v_mfma_f32_16x16x32_bf16 v[0:3], v[184:187], v[216:219], v[0:3]
	s_setprio 0
	s_branch .Lmid_gemm6
.LBB0_935:
	ds_read_b128 v[152:155], v148
	ds_read_b128 v[156:159], v148 offset:1024
	ds_read_b128 v[160:163], v148 offset:2048
	ds_read_b128 v[164:167], v148 offset:3072
	ds_read_b128 v[168:171], v149
	ds_read_b128 v[172:175], v149 offset:1024
	ds_read_b128 v[176:179], v149 offset:2048
	ds_read_b128 v[184:187], v149 offset:3072
	s_add_u32 s62, s60, 0xfffc0080
	s_addc_u32 s63, s61, -1
	s_cmp_eq_u32 s87, 12
	s_cselect_b32 s65, s53, s63
	s_cselect_b32 s64, s83, s62
	s_cselect_b32 s63, s49, s86
	s_cselect_b32 s62, s84, s85
	v_lshl_add_u64 v[220:221], s[60:61], 0, v[138:139]
	s_add_i32 m0, s69, 0xc000
	ds_read_b128 v[188:191], v150
	ds_read_b128 v[192:195], v150 offset:1024
	ds_read_b128 v[196:199], v150 offset:2048
	ds_read_b128 v[200:203], v150 offset:3072
	ds_read_b128 v[204:207], v150 offset:4096
	ds_read_b128 v[208:211], v150 offset:5120
	ds_read_b128 v[212:215], v150 offset:6144
	ds_read_b128 v[216:219], v150 offset:7168
	global_load_lds_dwordx4 v[220:221], off
	v_lshl_add_u64 v[220:221], s[60:61], 0, v[140:141]
	s_add_i32 m0, s69, 0xe000
	s_nop 0
	global_load_lds_dwordx4 v[220:221], off
	s_waitcnt vmcnt(8)
	s_waitcnt lgkmcnt(0)
	s_barrier
	s_setprio 1
	s_waitcnt lgkmcnt(0)
	v_mfma_f32_16x16x32_bf16 v[124:127], v[152:155], v[188:191], v[124:127]
	v_mfma_f32_16x16x32_bf16 v[124:127], v[156:159], v[192:195], v[124:127]
	v_mfma_f32_16x16x32_bf16 v[120:123], v[160:163], v[188:191], v[120:123]
	v_mfma_f32_16x16x32_bf16 v[120:123], v[164:167], v[192:195], v[120:123]
	v_mfma_f32_16x16x32_bf16 v[116:119], v[152:155], v[196:199], v[116:119]
	v_mfma_f32_16x16x32_bf16 v[116:119], v[156:159], v[200:203], v[116:119]
	v_mfma_f32_16x16x32_bf16 v[112:115], v[160:163], v[196:199], v[112:115]
	v_mfma_f32_16x16x32_bf16 v[112:115], v[164:167], v[200:203], v[112:115]
	v_mfma_f32_16x16x32_bf16 v[108:111], v[152:155], v[204:207], v[108:111]
	v_mfma_f32_16x16x32_bf16 v[108:111], v[156:159], v[208:211], v[108:111]
	v_mfma_f32_16x16x32_bf16 v[104:107], v[160:163], v[204:207], v[104:107]
	v_mfma_f32_16x16x32_bf16 v[104:107], v[164:167], v[208:211], v[104:107]
	v_mfma_f32_16x16x32_bf16 v[100:103], v[152:155], v[212:215], v[100:103]
	v_mfma_f32_16x16x32_bf16 v[100:103], v[156:159], v[216:219], v[100:103]
	v_mfma_f32_16x16x32_bf16 v[96:99], v[160:163], v[212:215], v[96:99]
	v_mfma_f32_16x16x32_bf16 v[96:99], v[164:167], v[216:219], v[96:99]
	v_mfma_f32_16x16x32_bf16 v[76:79], v[168:171], v[188:191], v[76:79]
	v_mfma_f32_16x16x32_bf16 v[76:79], v[172:175], v[192:195], v[76:79]
	v_mfma_f32_16x16x32_bf16 v[68:71], v[176:179], v[188:191], v[68:71]
	v_mfma_f32_16x16x32_bf16 v[68:71], v[184:187], v[192:195], v[68:71]
	v_mfma_f32_16x16x32_bf16 v[60:63], v[168:171], v[196:199], v[60:63]
	v_mfma_f32_16x16x32_bf16 v[60:63], v[172:175], v[200:203], v[60:63]
	v_mfma_f32_16x16x32_bf16 v[52:55], v[176:179], v[196:199], v[52:55]
	v_mfma_f32_16x16x32_bf16 v[52:55], v[184:187], v[200:203], v[52:55]
	v_mfma_f32_16x16x32_bf16 v[44:47], v[168:171], v[204:207], v[44:47]
	v_mfma_f32_16x16x32_bf16 v[44:47], v[172:175], v[208:211], v[44:47]
	v_mfma_f32_16x16x32_bf16 v[40:43], v[176:179], v[204:207], v[40:43]
	v_mfma_f32_16x16x32_bf16 v[40:43], v[184:187], v[208:211], v[40:43]
	s_setprio 2
	s_barrier
	v_mfma_f32_16x16x32_bf16 v[36:39], v[168:171], v[212:215], v[36:39]
	v_mfma_f32_16x16x32_bf16 v[36:39], v[172:175], v[216:219], v[36:39]
	v_mfma_f32_16x16x32_bf16 v[32:35], v[176:179], v[212:215], v[32:35]
	v_mfma_f32_16x16x32_bf16 v[32:35], v[184:187], v[216:219], v[32:35]
	s_setprio 0
	s_add_i32 s79, s77, s68
	v_lshl_add_u64 v[220:221], s[62:63], 0, v[130:131]
	s_mov_b32 m0, s79
	ds_read_b128 v[188:191], v150 offset:16384
	ds_read_b128 v[192:195], v150 offset:17408
	ds_read_b128 v[196:199], v150 offset:18432
	ds_read_b128 v[200:203], v150 offset:19456
	ds_read_b128 v[204:207], v150 offset:20480
	ds_read_b128 v[208:211], v150 offset:21504
	ds_read_b128 v[212:215], v150 offset:22528
	ds_read_b128 v[216:219], v150 offset:23552
	global_load_lds_dwordx4 v[220:221], off
	s_add_i32 m0, s79, 0x2000
	s_add_u32 s88, s62, 0x40000
	v_lshl_add_u64 v[222:223], s[62:63], 0, v[134:135]
	s_addc_u32 s89, s63, 0
	s_add_i32 s79, s82, s68
	global_load_lds_dwordx4 v[222:223], off
	v_lshl_add_u64 v[224:225], s[88:89], 0, v[130:131]
	s_mov_b32 m0, s79
	v_lshl_add_u64 v[226:227], s[64:65], 0, v[132:133]
	global_load_lds_dwordx4 v[224:225], off
	v_lshl_add_u64 v[224:225], s[88:89], 0, v[134:135]
	s_add_i32 m0, s79, 0x2000
	s_nop 0
	global_load_lds_dwordx4 v[224:225], off
	v_lshl_add_u64 v[224:225], s[64:65], 0, v[128:129]
	s_mov_b32 m0, s69
	s_nop 0
	global_load_lds_dwordx4 v[224:225], off
	s_mov_b32 m0, s70
	s_nop 0
	global_load_lds_dwordx4 v[226:227], off
	s_waitcnt vmcnt(8)
	s_waitcnt lgkmcnt(0)
	s_barrier
	s_setprio 1
	s_waitcnt lgkmcnt(0)
	v_mfma_f32_16x16x32_bf16 v[92:95], v[152:155], v[188:191], v[92:95]
	v_mfma_f32_16x16x32_bf16 v[92:95], v[156:159], v[192:195], v[92:95]
	v_mfma_f32_16x16x32_bf16 v[88:91], v[160:163], v[188:191], v[88:91]
	v_mfma_f32_16x16x32_bf16 v[88:91], v[164:167], v[192:195], v[88:91]
	v_mfma_f32_16x16x32_bf16 v[84:87], v[152:155], v[196:199], v[84:87]
	v_mfma_f32_16x16x32_bf16 v[84:87], v[156:159], v[200:203], v[84:87]
	v_mfma_f32_16x16x32_bf16 v[80:83], v[160:163], v[196:199], v[80:83]
	v_mfma_f32_16x16x32_bf16 v[80:83], v[164:167], v[200:203], v[80:83]
	v_mfma_f32_16x16x32_bf16 v[72:75], v[152:155], v[204:207], v[72:75]
	v_mfma_f32_16x16x32_bf16 v[72:75], v[156:159], v[208:211], v[72:75]
	v_mfma_f32_16x16x32_bf16 v[64:67], v[160:163], v[204:207], v[64:67]
	v_mfma_f32_16x16x32_bf16 v[64:67], v[164:167], v[208:211], v[64:67]
	v_mfma_f32_16x16x32_bf16 v[56:59], v[152:155], v[212:215], v[56:59]
	v_mfma_f32_16x16x32_bf16 v[56:59], v[156:159], v[216:219], v[56:59]
	v_mfma_f32_16x16x32_bf16 v[48:51], v[160:163], v[212:215], v[48:51]
	v_mfma_f32_16x16x32_bf16 v[48:51], v[164:167], v[216:219], v[48:51]
	v_mfma_f32_16x16x32_bf16 v[28:31], v[168:171], v[188:191], v[28:31]
	v_mfma_f32_16x16x32_bf16 v[28:31], v[172:175], v[192:195], v[28:31]
	v_mfma_f32_16x16x32_bf16 v[24:27], v[176:179], v[188:191], v[24:27]
	v_mfma_f32_16x16x32_bf16 v[24:27], v[184:187], v[192:195], v[24:27]
	v_mfma_f32_16x16x32_bf16 v[20:23], v[168:171], v[196:199], v[20:23]
	v_mfma_f32_16x16x32_bf16 v[20:23], v[172:175], v[200:203], v[20:23]
	v_mfma_f32_16x16x32_bf16 v[16:19], v[176:179], v[196:199], v[16:19]
	v_mfma_f32_16x16x32_bf16 v[16:19], v[184:187], v[200:203], v[16:19]
	v_mfma_f32_16x16x32_bf16 v[12:15], v[168:171], v[204:207], v[12:15]
	v_mfma_f32_16x16x32_bf16 v[12:15], v[172:175], v[208:211], v[12:15]
	v_mfma_f32_16x16x32_bf16 v[8:11], v[176:179], v[204:207], v[8:11]
	v_mfma_f32_16x16x32_bf16 v[8:11], v[184:187], v[208:211], v[8:11]
	s_setprio 2
	s_barrier
	v_mfma_f32_16x16x32_bf16 v[4:7], v[168:171], v[212:215], v[4:7]
	v_mfma_f32_16x16x32_bf16 v[4:7], v[172:175], v[216:219], v[4:7]
	v_mfma_f32_16x16x32_bf16 v[0:3], v[176:179], v[212:215], v[0:3]
	v_mfma_f32_16x16x32_bf16 v[0:3], v[184:187], v[216:219], v[0:3]
	s_setprio 0
.Lmid_gemm6:
	s_add_i32 s79, 0, 0x18000
	v_add_u32_e32 v151, s79, v147
	s_add_i32 s88, 0, 0x1c000
	ds_read_b128 v[152:155], v151
	ds_read_b128 v[156:159], v151 offset:1024
	ds_read_b128 v[160:163], v151 offset:2048
	ds_read_b128 v[164:167], v151 offset:3072
	v_add_u32_e32 v151, s88, v147
	ds_read_b128 v[168:171], v151
	ds_read_b128 v[172:175], v151 offset:1024
	ds_read_b128 v[176:179], v151 offset:2048
	ds_read_b128 v[184:187], v151 offset:3072
	s_add_u32 s64, s64, 0x40000
	s_addc_u32 s65, s65, 0
	s_mov_b32 m0, s71
	v_lshl_add_u64 v[228:229], s[64:65], 0, v[128:129]
	ds_read_b128 v[188:191], v150 offset:32768
	ds_read_b128 v[192:195], v150 offset:33792
	ds_read_b128 v[196:199], v150 offset:34816
	ds_read_b128 v[200:203], v150 offset:35840
	ds_read_b128 v[204:207], v150 offset:36864
	ds_read_b128 v[208:211], v150 offset:37888
	ds_read_b128 v[212:215], v150 offset:38912
	ds_read_b128 v[216:219], v150 offset:39936
	global_load_lds_dwordx4 v[228:229], off
	v_lshl_add_u64 v[228:229], s[64:65], 0, v[132:133]
	s_mov_b32 m0, s72
	s_nop 0
	global_load_lds_dwordx4 v[228:229], off
	s_waitcnt vmcnt(8)
	s_waitcnt lgkmcnt(0)
	s_barrier
	s_setprio 1
	s_waitcnt lgkmcnt(0)
	v_mfma_f32_16x16x32_bf16 v[124:127], v[152:155], v[188:191], v[124:127]
	v_mfma_f32_16x16x32_bf16 v[124:127], v[156:159], v[192:195], v[124:127]
	v_mfma_f32_16x16x32_bf16 v[120:123], v[160:163], v[188:191], v[120:123]
	v_mfma_f32_16x16x32_bf16 v[120:123], v[164:167], v[192:195], v[120:123]
	v_mfma_f32_16x16x32_bf16 v[116:119], v[152:155], v[196:199], v[116:119]
	v_mfma_f32_16x16x32_bf16 v[116:119], v[156:159], v[200:203], v[116:119]
	v_mfma_f32_16x16x32_bf16 v[112:115], v[160:163], v[196:199], v[112:115]
	v_mfma_f32_16x16x32_bf16 v[112:115], v[164:167], v[200:203], v[112:115]
	v_mfma_f32_16x16x32_bf16 v[108:111], v[152:155], v[204:207], v[108:111]
	v_mfma_f32_16x16x32_bf16 v[108:111], v[156:159], v[208:211], v[108:111]
	v_mfma_f32_16x16x32_bf16 v[104:107], v[160:163], v[204:207], v[104:107]
	v_mfma_f32_16x16x32_bf16 v[104:107], v[164:167], v[208:211], v[104:107]
	v_mfma_f32_16x16x32_bf16 v[100:103], v[152:155], v[212:215], v[100:103]
	v_mfma_f32_16x16x32_bf16 v[100:103], v[156:159], v[216:219], v[100:103]
	v_mfma_f32_16x16x32_bf16 v[96:99], v[160:163], v[212:215], v[96:99]
	v_mfma_f32_16x16x32_bf16 v[96:99], v[164:167], v[216:219], v[96:99]
	v_mfma_f32_16x16x32_bf16 v[76:79], v[168:171], v[188:191], v[76:79]
	v_mfma_f32_16x16x32_bf16 v[76:79], v[172:175], v[192:195], v[76:79]
	v_mfma_f32_16x16x32_bf16 v[68:71], v[176:179], v[188:191], v[68:71]
	v_mfma_f32_16x16x32_bf16 v[68:71], v[184:187], v[192:195], v[68:71]
	v_mfma_f32_16x16x32_bf16 v[60:63], v[168:171], v[196:199], v[60:63]
	v_mfma_f32_16x16x32_bf16 v[60:63], v[172:175], v[200:203], v[60:63]
	v_mfma_f32_16x16x32_bf16 v[52:55], v[176:179], v[196:199], v[52:55]
	v_mfma_f32_16x16x32_bf16 v[52:55], v[184:187], v[200:203], v[52:55]
	v_mfma_f32_16x16x32_bf16 v[44:47], v[168:171], v[204:207], v[44:47]
	v_mfma_f32_16x16x32_bf16 v[44:47], v[172:175], v[208:211], v[44:47]
	v_mfma_f32_16x16x32_bf16 v[40:43], v[176:179], v[204:207], v[40:43]
	v_mfma_f32_16x16x32_bf16 v[40:43], v[184:187], v[208:211], v[40:43]
	s_setprio 2
	s_barrier
	v_mfma_f32_16x16x32_bf16 v[36:39], v[168:171], v[212:215], v[36:39]
	v_mfma_f32_16x16x32_bf16 v[36:39], v[172:175], v[216:219], v[36:39]
	v_mfma_f32_16x16x32_bf16 v[32:35], v[176:179], v[212:215], v[32:35]
	v_mfma_f32_16x16x32_bf16 v[32:35], v[184:187], v[216:219], v[32:35]
	s_setprio 0
	s_add_i32 s64, s79, s68
	v_lshl_add_u64 v[220:221], v[220:221], 0, s[12:13]
	s_mov_b32 m0, s64
	ds_read_b128 v[188:191], v150 offset:49152
	ds_read_b128 v[192:195], v150 offset:50176
	ds_read_b128 v[196:199], v150 offset:51200
	ds_read_b128 v[200:203], v150 offset:52224
	ds_read_b128 v[204:207], v150 offset:53248
	ds_read_b128 v[208:211], v150 offset:54272
	ds_read_b128 v[212:215], v150 offset:55296
	ds_read_b128 v[216:219], v150 offset:56320
	global_load_lds_dwordx4 v[220:221], off
	s_add_i32 m0, s64, 0x2000
	s_add_u32 s62, s62, 0x40080
	v_lshl_add_u64 v[220:221], v[222:223], 0, s[12:13]
	s_addc_u32 s63, s63, 0
	s_add_i32 s64, s88, s68
	global_load_lds_dwordx4 v[220:221], off
	v_lshl_add_u64 v[220:221], s[62:63], 0, v[130:131]
	s_mov_b32 m0, s64
	s_nop 0
	global_load_lds_dwordx4 v[220:221], off
	v_lshl_add_u64 v[220:221], s[62:63], 0, v[134:135]
	s_add_i32 m0, s64, 0x2000
	s_nop 0
	global_load_lds_dwordx4 v[220:221], off
	v_lshl_add_u64 v[220:221], v[224:225], 0, s[12:13]
	s_mov_b32 m0, s75
	s_nop 0
	global_load_lds_dwordx4 v[220:221], off
	v_lshl_add_u64 v[220:221], v[226:227], 0, s[12:13]
	s_mov_b32 m0, s76
	s_nop 0
	global_load_lds_dwordx4 v[220:221], off
	s_waitcnt vmcnt(8)
	s_waitcnt lgkmcnt(0)
	s_barrier
	s_setprio 1
	s_waitcnt lgkmcnt(0)
	v_mfma_f32_16x16x32_bf16 v[92:95], v[152:155], v[188:191], v[92:95]
	v_mfma_f32_16x16x32_bf16 v[92:95], v[156:159], v[192:195], v[92:95]
	v_mfma_f32_16x16x32_bf16 v[88:91], v[160:163], v[188:191], v[88:91]
	v_mfma_f32_16x16x32_bf16 v[88:91], v[164:167], v[192:195], v[88:91]
	v_mfma_f32_16x16x32_bf16 v[84:87], v[152:155], v[196:199], v[84:87]
	v_mfma_f32_16x16x32_bf16 v[84:87], v[156:159], v[200:203], v[84:87]
	v_mfma_f32_16x16x32_bf16 v[80:83], v[160:163], v[196:199], v[80:83]
	v_mfma_f32_16x16x32_bf16 v[80:83], v[164:167], v[200:203], v[80:83]
	v_mfma_f32_16x16x32_bf16 v[72:75], v[152:155], v[204:207], v[72:75]
	v_mfma_f32_16x16x32_bf16 v[72:75], v[156:159], v[208:211], v[72:75]
	v_mfma_f32_16x16x32_bf16 v[64:67], v[160:163], v[204:207], v[64:67]
	v_mfma_f32_16x16x32_bf16 v[64:67], v[164:167], v[208:211], v[64:67]
	v_mfma_f32_16x16x32_bf16 v[56:59], v[152:155], v[212:215], v[56:59]
	v_mfma_f32_16x16x32_bf16 v[56:59], v[156:159], v[216:219], v[56:59]
	v_mfma_f32_16x16x32_bf16 v[48:51], v[160:163], v[212:215], v[48:51]
	v_mfma_f32_16x16x32_bf16 v[48:51], v[164:167], v[216:219], v[48:51]
	v_mfma_f32_16x16x32_bf16 v[28:31], v[168:171], v[188:191], v[28:31]
	v_mfma_f32_16x16x32_bf16 v[28:31], v[172:175], v[192:195], v[28:31]
	v_mfma_f32_16x16x32_bf16 v[24:27], v[176:179], v[188:191], v[24:27]
	v_mfma_f32_16x16x32_bf16 v[24:27], v[184:187], v[192:195], v[24:27]
	v_mfma_f32_16x16x32_bf16 v[20:23], v[168:171], v[196:199], v[20:23]
	v_mfma_f32_16x16x32_bf16 v[20:23], v[172:175], v[200:203], v[20:23]
	v_mfma_f32_16x16x32_bf16 v[16:19], v[176:179], v[196:199], v[16:19]
	v_mfma_f32_16x16x32_bf16 v[16:19], v[184:187], v[200:203], v[16:19]
	v_mfma_f32_16x16x32_bf16 v[12:15], v[168:171], v[204:207], v[12:15]
	v_mfma_f32_16x16x32_bf16 v[12:15], v[172:175], v[208:211], v[12:15]
	v_mfma_f32_16x16x32_bf16 v[8:11], v[176:179], v[204:207], v[8:11]
	v_mfma_f32_16x16x32_bf16 v[8:11], v[184:187], v[208:211], v[8:11]
	s_setprio 2
	s_barrier
	v_mfma_f32_16x16x32_bf16 v[4:7], v[168:171], v[212:215], v[4:7]
	v_mfma_f32_16x16x32_bf16 v[4:7], v[172:175], v[216:219], v[4:7]
	v_mfma_f32_16x16x32_bf16 v[0:3], v[176:179], v[212:215], v[0:3]
	v_mfma_f32_16x16x32_bf16 v[0:3], v[184:187], v[216:219], v[0:3]
	s_setprio 0
	s_add_i32 s87, s87, 2
	s_add_u32 s60, s60, 0x100
	s_addc_u32 s61, s61, 0
	s_add_u32 s85, s85, 0x100
	s_addc_u32 s86, s86, 0
	s_cmp_gt_u32 s87, 13
	s_cbranch_scc0 .LBB0_935
	s_and_b64 vcc, exec, s[16:17]
	s_cbranch_vccz .LBB0_938
	s_barrier

.LBB0_950:
	s_ashr_i32 s37, s36, 31
	s_lshl_b64 s[44:45], s[36:37], 19
	s_add_u32 s44, s80, s44
	s_addc_u32 s45, s81, s45
	s_and_b64 s[46:47], s[10:11], exec
	s_cselect_b32 s37, s45, s53
	s_cselect_b32 s72, s44, s52
	s_ashr_i32 s19, s18, 31
	s_lshl_b64 s[46:47], s[18:19], 19
	s_add_u32 s46, s58, s46
	s_addc_u32 s47, s59, s47
	s_and_b64 s[56:57], s[10:11], exec
	s_cselect_b32 s19, s47, s55
	s_cselect_b32 s73, s46, s54
	s_add_u32 s52, s52, 0x40080
	s_addc_u32 s53, s53, 0
	s_add_u32 s74, s54, 0x100
	s_addc_u32 s75, s55, 0
	s_mov_b32 s76, -2
	ds_read_b128 v[140:143], v147
	ds_read_b128 v[150:153], v147 offset:1024
	ds_read_b128 v[154:157], v147 offset:2048
	ds_read_b128 v[158:161], v147 offset:3072
	ds_read_b128 v[162:165], v148
	ds_read_b128 v[166:169], v148 offset:1024
	ds_read_b128 v[170:173], v148 offset:2048
	ds_read_b128 v[174:177], v148 offset:3072
	s_add_u32 s54, s52, 0xfffc0080
	s_addc_u32 s55, s53, -1
	s_cmp_eq_u32 s76, 12
	s_cselect_b32 s57, s37, s55
	s_cselect_b32 s56, s72, s54
	s_cselect_b32 s55, s19, s75
	s_cselect_b32 s54, s73, s74
	v_lshl_add_u64 v[178:179], s[52:53], 0, v[132:133]
	s_add_i32 m0, s49, 0xc000
	ds_read_b128 v[184:187], v149
	ds_read_b128 v[188:191], v149 offset:1024
	ds_read_b128 v[192:195], v149 offset:2048
	ds_read_b128 v[196:199], v149 offset:3072
	ds_read_b128 v[200:203], v149 offset:4096
	ds_read_b128 v[204:207], v149 offset:5120
	ds_read_b128 v[208:211], v149 offset:6144
	ds_read_b128 v[212:215], v149 offset:7168
	global_load_lds_dwordx4 v[178:179], off
	v_lshl_add_u64 v[178:179], s[52:53], 0, v[134:135]
	s_add_i32 m0, s49, 0xe000
	s_nop 0
	global_load_lds_dwordx4 v[178:179], off
	s_waitcnt vmcnt(8)
	s_waitcnt lgkmcnt(0)
	s_barrier
	s_setprio 1
	s_waitcnt lgkmcnt(0)
	v_mfma_f32_16x16x32_bf16 v[124:127], v[140:143], v[184:187], 0
	v_mfma_f32_16x16x32_bf16 v[124:127], v[150:153], v[188:191], v[124:127]
	v_mfma_f32_16x16x32_bf16 v[120:123], v[154:157], v[184:187], 0
	v_mfma_f32_16x16x32_bf16 v[120:123], v[158:161], v[188:191], v[120:123]
	v_mfma_f32_16x16x32_bf16 v[108:111], v[140:143], v[192:195], 0
	v_mfma_f32_16x16x32_bf16 v[108:111], v[150:153], v[196:199], v[108:111]
	v_mfma_f32_16x16x32_bf16 v[104:107], v[154:157], v[192:195], 0
	v_mfma_f32_16x16x32_bf16 v[104:107], v[158:161], v[196:199], v[104:107]
	v_mfma_f32_16x16x32_bf16 v[92:95], v[140:143], v[200:203], 0
	v_mfma_f32_16x16x32_bf16 v[92:95], v[150:153], v[204:207], v[92:95]
	v_mfma_f32_16x16x32_bf16 v[88:91], v[154:157], v[200:203], 0
	v_mfma_f32_16x16x32_bf16 v[88:91], v[158:161], v[204:207], v[88:91]
	v_mfma_f32_16x16x32_bf16 v[76:79], v[140:143], v[208:211], 0
	v_mfma_f32_16x16x32_bf16 v[76:79], v[150:153], v[212:215], v[76:79]
	v_mfma_f32_16x16x32_bf16 v[72:75], v[154:157], v[208:211], 0
	v_mfma_f32_16x16x32_bf16 v[72:75], v[158:161], v[212:215], v[72:75]
	v_mfma_f32_16x16x32_bf16 v[116:119], v[162:165], v[184:187], 0
	v_mfma_f32_16x16x32_bf16 v[116:119], v[166:169], v[188:191], v[116:119]
	v_mfma_f32_16x16x32_bf16 v[112:115], v[170:173], v[184:187], 0
	v_mfma_f32_16x16x32_bf16 v[112:115], v[174:177], v[188:191], v[112:115]
	v_mfma_f32_16x16x32_bf16 v[100:103], v[162:165], v[192:195], 0
	v_mfma_f32_16x16x32_bf16 v[100:103], v[166:169], v[196:199], v[100:103]
	v_mfma_f32_16x16x32_bf16 v[96:99], v[170:173], v[192:195], 0
	v_mfma_f32_16x16x32_bf16 v[96:99], v[174:177], v[196:199], v[96:99]
	v_mfma_f32_16x16x32_bf16 v[84:87], v[162:165], v[200:203], 0
	v_mfma_f32_16x16x32_bf16 v[84:87], v[166:169], v[204:207], v[84:87]
	v_mfma_f32_16x16x32_bf16 v[80:83], v[170:173], v[200:203], 0
	v_mfma_f32_16x16x32_bf16 v[80:83], v[174:177], v[204:207], v[80:83]
	s_setprio 2
	s_barrier
	v_mfma_f32_16x16x32_bf16 v[68:71], v[162:165], v[208:211], 0
	v_mfma_f32_16x16x32_bf16 v[68:71], v[166:169], v[212:215], v[68:71]
	v_mfma_f32_16x16x32_bf16 v[64:67], v[170:173], v[208:211], 0
	v_mfma_f32_16x16x32_bf16 v[64:67], v[174:177], v[212:215], v[64:67]
	s_setprio 0
	s_add_i32 s77, s68, s60
	v_lshl_add_u64 v[178:179], s[54:55], 0, v[130:131]
	s_mov_b32 m0, s77
	ds_read_b128 v[184:187], v149 offset:16384
	ds_read_b128 v[188:191], v149 offset:17408
	ds_read_b128 v[192:195], v149 offset:18432
	ds_read_b128 v[196:199], v149 offset:19456
	ds_read_b128 v[200:203], v149 offset:20480
	ds_read_b128 v[204:207], v149 offset:21504
	ds_read_b128 v[208:211], v149 offset:22528
	ds_read_b128 v[212:215], v149 offset:23552
	global_load_lds_dwordx4 v[178:179], off
	s_add_i32 m0, s77, 0x2000
	s_add_u32 s82, s54, 0x40000
	v_lshl_add_u64 v[216:217], s[54:55], 0, v[128:129]
	s_addc_u32 s83, s55, 0
	s_add_i32 s77, s69, s60
	global_load_lds_dwordx4 v[216:217], off
	v_lshl_add_u64 v[218:219], s[82:83], 0, v[130:131]
	s_mov_b32 m0, s77
	v_lshl_add_u64 v[220:221], s[56:57], 0, v[128:129]
	global_load_lds_dwordx4 v[218:219], off
	v_lshl_add_u64 v[218:219], s[82:83], 0, v[128:129]
	s_add_i32 m0, s77, 0x2000
	s_nop 0
	global_load_lds_dwordx4 v[218:219], off
	v_lshl_add_u64 v[218:219], s[56:57], 0, v[130:131]
	s_mov_b32 m0, s49
	s_nop 0
	global_load_lds_dwordx4 v[218:219], off
	s_mov_b32 m0, s62
	s_nop 0
	global_load_lds_dwordx4 v[220:221], off
	s_waitcnt vmcnt(8)
	s_waitcnt lgkmcnt(0)
	s_barrier
	s_setprio 1
	s_waitcnt lgkmcnt(0)
	v_mfma_f32_16x16x32_bf16 v[60:63], v[140:143], v[184:187], 0
	v_mfma_f32_16x16x32_bf16 v[60:63], v[150:153], v[188:191], v[60:63]
	v_mfma_f32_16x16x32_bf16 v[56:59], v[154:157], v[184:187], 0
	v_mfma_f32_16x16x32_bf16 v[56:59], v[158:161], v[188:191], v[56:59]
	v_mfma_f32_16x16x32_bf16 v[44:47], v[140:143], v[192:195], 0
	v_mfma_f32_16x16x32_bf16 v[44:47], v[150:153], v[196:199], v[44:47]
	v_mfma_f32_16x16x32_bf16 v[40:43], v[154:157], v[192:195], 0
	v_mfma_f32_16x16x32_bf16 v[40:43], v[158:161], v[196:199], v[40:43]
	v_mfma_f32_16x16x32_bf16 v[28:31], v[140:143], v[200:203], 0
	v_mfma_f32_16x16x32_bf16 v[28:31], v[150:153], v[204:207], v[28:31]
	v_mfma_f32_16x16x32_bf16 v[24:27], v[154:157], v[200:203], 0
	v_mfma_f32_16x16x32_bf16 v[24:27], v[158:161], v[204:207], v[24:27]
	v_mfma_f32_16x16x32_bf16 v[12:15], v[140:143], v[208:211], 0
	v_mfma_f32_16x16x32_bf16 v[12:15], v[150:153], v[212:215], v[12:15]
	v_mfma_f32_16x16x32_bf16 v[8:11], v[154:157], v[208:211], 0
	v_mfma_f32_16x16x32_bf16 v[8:11], v[158:161], v[212:215], v[8:11]
	v_mfma_f32_16x16x32_bf16 v[52:55], v[162:165], v[184:187], 0
	v_mfma_f32_16x16x32_bf16 v[52:55], v[166:169], v[188:191], v[52:55]
	v_mfma_f32_16x16x32_bf16 v[48:51], v[170:173], v[184:187], 0
	v_mfma_f32_16x16x32_bf16 v[48:51], v[174:177], v[188:191], v[48:51]
	v_mfma_f32_16x16x32_bf16 v[36:39], v[162:165], v[192:195], 0
	v_mfma_f32_16x16x32_bf16 v[36:39], v[166:169], v[196:199], v[36:39]
	v_mfma_f32_16x16x32_bf16 v[32:35], v[170:173], v[192:195], 0
	v_mfma_f32_16x16x32_bf16 v[32:35], v[174:177], v[196:199], v[32:35]
	v_mfma_f32_16x16x32_bf16 v[20:23], v[162:165], v[200:203], 0
	v_mfma_f32_16x16x32_bf16 v[20:23], v[166:169], v[204:207], v[20:23]
	v_mfma_f32_16x16x32_bf16 v[16:19], v[170:173], v[200:203], 0
	v_mfma_f32_16x16x32_bf16 v[16:19], v[174:177], v[204:207], v[16:19]
	s_setprio 2
	s_barrier
	v_mfma_f32_16x16x32_bf16 v[4:7], v[162:165], v[208:211], 0
	v_mfma_f32_16x16x32_bf16 v[4:7], v[166:169], v[212:215], v[4:7]
	v_mfma_f32_16x16x32_bf16 v[0:3], v[170:173], v[208:211], 0
	v_mfma_f32_16x16x32_bf16 v[0:3], v[174:177], v[212:215], v[0:3]
	s_setprio 0
	s_branch .Lmid_gemm7
.LBB0_951:
	ds_read_b128 v[140:143], v147
	ds_read_b128 v[150:153], v147 offset:1024
	ds_read_b128 v[154:157], v147 offset:2048
	ds_read_b128 v[158:161], v147 offset:3072
	ds_read_b128 v[162:165], v148
	ds_read_b128 v[166:169], v148 offset:1024
	ds_read_b128 v[170:173], v148 offset:2048
	ds_read_b128 v[174:177], v148 offset:3072
	s_add_u32 s54, s52, 0xfffc0080
	s_addc_u32 s55, s53, -1
	s_cmp_eq_u32 s76, 12
	s_cselect_b32 s57, s37, s55
	s_cselect_b32 s56, s72, s54
	s_cselect_b32 s55, s19, s75
	s_cselect_b32 s54, s73, s74
	v_lshl_add_u64 v[178:179], s[52:53], 0, v[132:133]
	s_add_i32 m0, s49, 0xc000
	ds_read_b128 v[184:187], v149
	ds_read_b128 v[188:191], v149 offset:1024
	ds_read_b128 v[192:195], v149 offset:2048
	ds_read_b128 v[196:199], v149 offset:3072
	ds_read_b128 v[200:203], v149 offset:4096
	ds_read_b128 v[204:207], v149 offset:5120
	ds_read_b128 v[208:211], v149 offset:6144
	ds_read_b128 v[212:215], v149 offset:7168
	global_load_lds_dwordx4 v[178:179], off
	v_lshl_add_u64 v[178:179], s[52:53], 0, v[134:135]
	s_add_i32 m0, s49, 0xe000
	s_nop 0
	global_load_lds_dwordx4 v[178:179], off
	s_waitcnt vmcnt(8)
	s_waitcnt lgkmcnt(0)
	s_barrier
	s_setprio 1
	s_waitcnt lgkmcnt(0)
	v_mfma_f32_16x16x32_bf16 v[124:127], v[140:143], v[184:187], v[124:127]
	v_mfma_f32_16x16x32_bf16 v[124:127], v[150:153], v[188:191], v[124:127]
	v_mfma_f32_16x16x32_bf16 v[120:123], v[154:157], v[184:187], v[120:123]
	v_mfma_f32_16x16x32_bf16 v[120:123], v[158:161], v[188:191], v[120:123]
	v_mfma_f32_16x16x32_bf16 v[108:111], v[140:143], v[192:195], v[108:111]
	v_mfma_f32_16x16x32_bf16 v[108:111], v[150:153], v[196:199], v[108:111]
	v_mfma_f32_16x16x32_bf16 v[104:107], v[154:157], v[192:195], v[104:107]
	v_mfma_f32_16x16x32_bf16 v[104:107], v[158:161], v[196:199], v[104:107]
	v_mfma_f32_16x16x32_bf16 v[92:95], v[140:143], v[200:203], v[92:95]
	v_mfma_f32_16x16x32_bf16 v[92:95], v[150:153], v[204:207], v[92:95]
	v_mfma_f32_16x16x32_bf16 v[88:91], v[154:157], v[200:203], v[88:91]
	v_mfma_f32_16x16x32_bf16 v[88:91], v[158:161], v[204:207], v[88:91]
	v_mfma_f32_16x16x32_bf16 v[76:79], v[140:143], v[208:211], v[76:79]
	v_mfma_f32_16x16x32_bf16 v[76:79], v[150:153], v[212:215], v[76:79]
	v_mfma_f32_16x16x32_bf16 v[72:75], v[154:157], v[208:211], v[72:75]
	v_mfma_f32_16x16x32_bf16 v[72:75], v[158:161], v[212:215], v[72:75]
	v_mfma_f32_16x16x32_bf16 v[116:119], v[162:165], v[184:187], v[116:119]
	v_mfma_f32_16x16x32_bf16 v[116:119], v[166:169], v[188:191], v[116:119]
	v_mfma_f32_16x16x32_bf16 v[112:115], v[170:173], v[184:187], v[112:115]
	v_mfma_f32_16x16x32_bf16 v[112:115], v[174:177], v[188:191], v[112:115]
	v_mfma_f32_16x16x32_bf16 v[100:103], v[162:165], v[192:195], v[100:103]
	v_mfma_f32_16x16x32_bf16 v[100:103], v[166:169], v[196:199], v[100:103]
	v_mfma_f32_16x16x32_bf16 v[96:99], v[170:173], v[192:195], v[96:99]
	v_mfma_f32_16x16x32_bf16 v[96:99], v[174:177], v[196:199], v[96:99]
	v_mfma_f32_16x16x32_bf16 v[84:87], v[162:165], v[200:203], v[84:87]
	v_mfma_f32_16x16x32_bf16 v[84:87], v[166:169], v[204:207], v[84:87]
	v_mfma_f32_16x16x32_bf16 v[80:83], v[170:173], v[200:203], v[80:83]
	v_mfma_f32_16x16x32_bf16 v[80:83], v[174:177], v[204:207], v[80:83]
	s_setprio 2
	s_barrier
	v_mfma_f32_16x16x32_bf16 v[68:71], v[162:165], v[208:211], v[68:71]
	v_mfma_f32_16x16x32_bf16 v[68:71], v[166:169], v[212:215], v[68:71]
	v_mfma_f32_16x16x32_bf16 v[64:67], v[170:173], v[208:211], v[64:67]
	v_mfma_f32_16x16x32_bf16 v[64:67], v[174:177], v[212:215], v[64:67]
	s_setprio 0
	s_add_i32 s77, s68, s60
	v_lshl_add_u64 v[178:179], s[54:55], 0, v[130:131]
	s_mov_b32 m0, s77
	ds_read_b128 v[184:187], v149 offset:16384
	ds_read_b128 v[188:191], v149 offset:17408
	ds_read_b128 v[192:195], v149 offset:18432
	ds_read_b128 v[196:199], v149 offset:19456
	ds_read_b128 v[200:203], v149 offset:20480
	ds_read_b128 v[204:207], v149 offset:21504
	ds_read_b128 v[208:211], v149 offset:22528
	ds_read_b128 v[212:215], v149 offset:23552
	global_load_lds_dwordx4 v[178:179], off
	s_add_i32 m0, s77, 0x2000
	s_add_u32 s82, s54, 0x40000
	v_lshl_add_u64 v[216:217], s[54:55], 0, v[128:129]
	s_addc_u32 s83, s55, 0
	s_add_i32 s77, s69, s60
	global_load_lds_dwordx4 v[216:217], off
	v_lshl_add_u64 v[218:219], s[82:83], 0, v[130:131]
	s_mov_b32 m0, s77
	v_lshl_add_u64 v[220:221], s[56:57], 0, v[128:129]
	global_load_lds_dwordx4 v[218:219], off
	v_lshl_add_u64 v[218:219], s[82:83], 0, v[128:129]
	s_add_i32 m0, s77, 0x2000
	s_nop 0
	global_load_lds_dwordx4 v[218:219], off
	v_lshl_add_u64 v[218:219], s[56:57], 0, v[130:131]
	s_mov_b32 m0, s49
	s_nop 0
	global_load_lds_dwordx4 v[218:219], off
	s_mov_b32 m0, s62
	s_nop 0
	global_load_lds_dwordx4 v[220:221], off
	s_waitcnt vmcnt(8)
	s_waitcnt lgkmcnt(0)
	s_barrier
	s_setprio 1
	s_waitcnt lgkmcnt(0)
	v_mfma_f32_16x16x32_bf16 v[60:63], v[140:143], v[184:187], v[60:63]
	v_mfma_f32_16x16x32_bf16 v[60:63], v[150:153], v[188:191], v[60:63]
	v_mfma_f32_16x16x32_bf16 v[56:59], v[154:157], v[184:187], v[56:59]
	v_mfma_f32_16x16x32_bf16 v[56:59], v[158:161], v[188:191], v[56:59]
	v_mfma_f32_16x16x32_bf16 v[44:47], v[140:143], v[192:195], v[44:47]
	v_mfma_f32_16x16x32_bf16 v[44:47], v[150:153], v[196:199], v[44:47]
	v_mfma_f32_16x16x32_bf16 v[40:43], v[154:157], v[192:195], v[40:43]
	v_mfma_f32_16x16x32_bf16 v[40:43], v[158:161], v[196:199], v[40:43]
	v_mfma_f32_16x16x32_bf16 v[28:31], v[140:143], v[200:203], v[28:31]
	v_mfma_f32_16x16x32_bf16 v[28:31], v[150:153], v[204:207], v[28:31]
	v_mfma_f32_16x16x32_bf16 v[24:27], v[154:157], v[200:203], v[24:27]
	v_mfma_f32_16x16x32_bf16 v[24:27], v[158:161], v[204:207], v[24:27]
	v_mfma_f32_16x16x32_bf16 v[12:15], v[140:143], v[208:211], v[12:15]
	v_mfma_f32_16x16x32_bf16 v[12:15], v[150:153], v[212:215], v[12:15]
	v_mfma_f32_16x16x32_bf16 v[8:11], v[154:157], v[208:211], v[8:11]
	v_mfma_f32_16x16x32_bf16 v[8:11], v[158:161], v[212:215], v[8:11]
	v_mfma_f32_16x16x32_bf16 v[52:55], v[162:165], v[184:187], v[52:55]
	v_mfma_f32_16x16x32_bf16 v[52:55], v[166:169], v[188:191], v[52:55]
	v_mfma_f32_16x16x32_bf16 v[48:51], v[170:173], v[184:187], v[48:51]
	v_mfma_f32_16x16x32_bf16 v[48:51], v[174:177], v[188:191], v[48:51]
	v_mfma_f32_16x16x32_bf16 v[36:39], v[162:165], v[192:195], v[36:39]
	v_mfma_f32_16x16x32_bf16 v[36:39], v[166:169], v[196:199], v[36:39]
	v_mfma_f32_16x16x32_bf16 v[32:35], v[170:173], v[192:195], v[32:35]
	v_mfma_f32_16x16x32_bf16 v[32:35], v[174:177], v[196:199], v[32:35]
	v_mfma_f32_16x16x32_bf16 v[20:23], v[162:165], v[200:203], v[20:23]
	v_mfma_f32_16x16x32_bf16 v[20:23], v[166:169], v[204:207], v[20:23]
	v_mfma_f32_16x16x32_bf16 v[16:19], v[170:173], v[200:203], v[16:19]
	v_mfma_f32_16x16x32_bf16 v[16:19], v[174:177], v[204:207], v[16:19]
	s_setprio 2
	s_barrier
	v_mfma_f32_16x16x32_bf16 v[4:7], v[162:165], v[208:211], v[4:7]
	v_mfma_f32_16x16x32_bf16 v[4:7], v[166:169], v[212:215], v[4:7]
	v_mfma_f32_16x16x32_bf16 v[0:3], v[170:173], v[208:211], v[0:3]
	v_mfma_f32_16x16x32_bf16 v[0:3], v[174:177], v[212:215], v[0:3]
	s_setprio 0
.Lmid_gemm7:
	s_add_i32 s77, 0, 0x18000
	s_add_i32 s79, 0, 0x1c000
	v_add_u32_e32 v158, s77, v145
	v_add_u32_e32 v174, s79, v145
	ds_read_b128 v[140:143], v158
	ds_read_b128 v[150:153], v158 offset:1024
	ds_read_b128 v[154:157], v158 offset:2048
	ds_read_b128 v[158:161], v158 offset:3072
	ds_read_b128 v[162:165], v174
	ds_read_b128 v[166:169], v174 offset:1024
	ds_read_b128 v[170:173], v174 offset:2048
	ds_read_b128 v[174:177], v174 offset:3072
	s_add_u32 s56, s56, 0x40000
	s_addc_u32 s57, s57, 0
	s_mov_b32 m0, s63
	v_lshl_add_u64 v[222:223], s[56:57], 0, v[130:131]
	ds_read_b128 v[184:187], v149 offset:32768
	ds_read_b128 v[188:191], v149 offset:33792
	ds_read_b128 v[192:195], v149 offset:34816
	ds_read_b128 v[196:199], v149 offset:35840
	ds_read_b128 v[200:203], v149 offset:36864
	ds_read_b128 v[204:207], v149 offset:37888
	ds_read_b128 v[208:211], v149 offset:38912
	ds_read_b128 v[212:215], v149 offset:39936
	global_load_lds_dwordx4 v[222:223], off
	v_lshl_add_u64 v[222:223], s[56:57], 0, v[128:129]
	s_mov_b32 m0, s64
	s_nop 0
	global_load_lds_dwordx4 v[222:223], off
	s_waitcnt vmcnt(8)
	s_waitcnt lgkmcnt(0)
	s_barrier
	s_setprio 1
	s_waitcnt lgkmcnt(0)
	v_mfma_f32_16x16x32_bf16 v[124:127], v[140:143], v[184:187], v[124:127]
	v_mfma_f32_16x16x32_bf16 v[124:127], v[150:153], v[188:191], v[124:127]
	v_mfma_f32_16x16x32_bf16 v[120:123], v[154:157], v[184:187], v[120:123]
	v_mfma_f32_16x16x32_bf16 v[120:123], v[158:161], v[188:191], v[120:123]
	v_mfma_f32_16x16x32_bf16 v[108:111], v[140:143], v[192:195], v[108:111]
	v_mfma_f32_16x16x32_bf16 v[108:111], v[150:153], v[196:199], v[108:111]
	v_mfma_f32_16x16x32_bf16 v[104:107], v[154:157], v[192:195], v[104:107]
	v_mfma_f32_16x16x32_bf16 v[104:107], v[158:161], v[196:199], v[104:107]
	v_mfma_f32_16x16x32_bf16 v[92:95], v[140:143], v[200:203], v[92:95]
	v_mfma_f32_16x16x32_bf16 v[92:95], v[150:153], v[204:207], v[92:95]
	v_mfma_f32_16x16x32_bf16 v[88:91], v[154:157], v[200:203], v[88:91]
	v_mfma_f32_16x16x32_bf16 v[88:91], v[158:161], v[204:207], v[88:91]
	v_mfma_f32_16x16x32_bf16 v[76:79], v[140:143], v[208:211], v[76:79]
	v_mfma_f32_16x16x32_bf16 v[76:79], v[150:153], v[212:215], v[76:79]
	v_mfma_f32_16x16x32_bf16 v[72:75], v[154:157], v[208:211], v[72:75]
	v_mfma_f32_16x16x32_bf16 v[72:75], v[158:161], v[212:215], v[72:75]
	v_mfma_f32_16x16x32_bf16 v[116:119], v[162:165], v[184:187], v[116:119]
	v_mfma_f32_16x16x32_bf16 v[116:119], v[166:169], v[188:191], v[116:119]
	v_mfma_f32_16x16x32_bf16 v[112:115], v[170:173], v[184:187], v[112:115]
	v_mfma_f32_16x16x32_bf16 v[112:115], v[174:177], v[188:191], v[112:115]
	v_mfma_f32_16x16x32_bf16 v[100:103], v[162:165], v[192:195], v[100:103]
	v_mfma_f32_16x16x32_bf16 v[100:103], v[166:169], v[196:199], v[100:103]
	v_mfma_f32_16x16x32_bf16 v[96:99], v[170:173], v[192:195], v[96:99]
	v_mfma_f32_16x16x32_bf16 v[96:99], v[174:177], v[196:199], v[96:99]
	v_mfma_f32_16x16x32_bf16 v[84:87], v[162:165], v[200:203], v[84:87]
	v_mfma_f32_16x16x32_bf16 v[84:87], v[166:169], v[204:207], v[84:87]
	v_mfma_f32_16x16x32_bf16 v[80:83], v[170:173], v[200:203], v[80:83]
	v_mfma_f32_16x16x32_bf16 v[80:83], v[174:177], v[204:207], v[80:83]
	s_setprio 2
	s_barrier
	v_mfma_f32_16x16x32_bf16 v[68:71], v[162:165], v[208:211], v[68:71]
	v_mfma_f32_16x16x32_bf16 v[68:71], v[166:169], v[212:215], v[68:71]
	v_mfma_f32_16x16x32_bf16 v[64:67], v[170:173], v[208:211], v[64:67]
	v_mfma_f32_16x16x32_bf16 v[64:67], v[174:177], v[212:215], v[64:67]
	s_setprio 0
	s_add_i32 s56, s77, s60
	v_lshl_add_u64 v[178:179], v[178:179], 0, s[12:13]
	s_mov_b32 m0, s56
	ds_read_b128 v[184:187], v149 offset:49152
	ds_read_b128 v[188:191], v149 offset:50176
	ds_read_b128 v[192:195], v149 offset:51200
	ds_read_b128 v[196:199], v149 offset:52224
	ds_read_b128 v[200:203], v149 offset:53248
	ds_read_b128 v[204:207], v149 offset:54272
	ds_read_b128 v[208:211], v149 offset:55296
	ds_read_b128 v[212:215], v149 offset:56320
	global_load_lds_dwordx4 v[178:179], off
	s_add_i32 m0, s56, 0x2000
	s_add_u32 s54, s54, 0x40080
	v_lshl_add_u64 v[178:179], v[216:217], 0, s[12:13]
	s_addc_u32 s55, s55, 0
	s_add_i32 s56, s79, s60
	global_load_lds_dwordx4 v[178:179], off
	v_lshl_add_u64 v[178:179], s[54:55], 0, v[130:131]
	s_mov_b32 m0, s56
	s_nop 0
	global_load_lds_dwordx4 v[178:179], off
	v_lshl_add_u64 v[178:179], s[54:55], 0, v[128:129]
	s_add_i32 m0, s56, 0x2000
	s_nop 0
	global_load_lds_dwordx4 v[178:179], off
	v_lshl_add_u64 v[178:179], v[218:219], 0, s[12:13]
	s_mov_b32 m0, s66
	s_nop 0
	global_load_lds_dwordx4 v[178:179], off
	v_lshl_add_u64 v[178:179], v[220:221], 0, s[12:13]
	s_mov_b32 m0, s67
	s_nop 0
	global_load_lds_dwordx4 v[178:179], off
	s_waitcnt vmcnt(8)
	s_waitcnt lgkmcnt(0)
	s_barrier
	s_setprio 1
	s_waitcnt lgkmcnt(0)
	v_mfma_f32_16x16x32_bf16 v[60:63], v[140:143], v[184:187], v[60:63]
	v_mfma_f32_16x16x32_bf16 v[60:63], v[150:153], v[188:191], v[60:63]
	v_mfma_f32_16x16x32_bf16 v[56:59], v[154:157], v[184:187], v[56:59]
	v_mfma_f32_16x16x32_bf16 v[56:59], v[158:161], v[188:191], v[56:59]
	v_mfma_f32_16x16x32_bf16 v[44:47], v[140:143], v[192:195], v[44:47]
	v_mfma_f32_16x16x32_bf16 v[44:47], v[150:153], v[196:199], v[44:47]
	v_mfma_f32_16x16x32_bf16 v[40:43], v[154:157], v[192:195], v[40:43]
	v_mfma_f32_16x16x32_bf16 v[40:43], v[158:161], v[196:199], v[40:43]
	v_mfma_f32_16x16x32_bf16 v[28:31], v[140:143], v[200:203], v[28:31]
	v_mfma_f32_16x16x32_bf16 v[28:31], v[150:153], v[204:207], v[28:31]
	v_mfma_f32_16x16x32_bf16 v[24:27], v[154:157], v[200:203], v[24:27]
	v_mfma_f32_16x16x32_bf16 v[24:27], v[158:161], v[204:207], v[24:27]
	v_mfma_f32_16x16x32_bf16 v[12:15], v[140:143], v[208:211], v[12:15]
	v_mfma_f32_16x16x32_bf16 v[12:15], v[150:153], v[212:215], v[12:15]
	v_mfma_f32_16x16x32_bf16 v[8:11], v[154:157], v[208:211], v[8:11]
	v_mfma_f32_16x16x32_bf16 v[8:11], v[158:161], v[212:215], v[8:11]
	v_mfma_f32_16x16x32_bf16 v[52:55], v[162:165], v[184:187], v[52:55]
	v_mfma_f32_16x16x32_bf16 v[52:55], v[166:169], v[188:191], v[52:55]
	v_mfma_f32_16x16x32_bf16 v[48:51], v[170:173], v[184:187], v[48:51]
	v_mfma_f32_16x16x32_bf16 v[48:51], v[174:177], v[188:191], v[48:51]
	v_mfma_f32_16x16x32_bf16 v[36:39], v[162:165], v[192:195], v[36:39]
	v_mfma_f32_16x16x32_bf16 v[36:39], v[166:169], v[196:199], v[36:39]
	v_mfma_f32_16x16x32_bf16 v[32:35], v[170:173], v[192:195], v[32:35]
	v_mfma_f32_16x16x32_bf16 v[32:35], v[174:177], v[196:199], v[32:35]
	v_mfma_f32_16x16x32_bf16 v[20:23], v[162:165], v[200:203], v[20:23]
	v_mfma_f32_16x16x32_bf16 v[20:23], v[166:169], v[204:207], v[20:23]
	v_mfma_f32_16x16x32_bf16 v[16:19], v[170:173], v[200:203], v[16:19]
	v_mfma_f32_16x16x32_bf16 v[16:19], v[174:177], v[204:207], v[16:19]
	s_setprio 2
	s_barrier
	v_mfma_f32_16x16x32_bf16 v[4:7], v[162:165], v[208:211], v[4:7]
	v_mfma_f32_16x16x32_bf16 v[4:7], v[166:169], v[212:215], v[4:7]
	v_mfma_f32_16x16x32_bf16 v[0:3], v[170:173], v[208:211], v[0:3]
	v_mfma_f32_16x16x32_bf16 v[0:3], v[174:177], v[212:215], v[0:3]
	s_setprio 0
	s_add_i32 s76, s76, 2
	s_add_u32 s52, s52, 0x100
	s_addc_u32 s53, s53, 0
	s_add_u32 s74, s74, 0x100
	s_addc_u32 s75, s75, 0
	s_cmp_gt_u32 s76, 13
	s_cbranch_scc0 .LBB0_951
	s_and_b64 vcc, exec, s[16:17]
	s_cbranch_vccz .LBB0_954
	s_barrier

.LBB0_1030:
	s_add_u32 s86, s56, 0x100
	s_addc_u32 s87, s57, 0
	s_mov_b32 s88, -2
	ds_read_b128 v[152:155], v149
	ds_read_b128 v[156:159], v149 offset:1024
	ds_read_b128 v[160:163], v149 offset:2048
	ds_read_b128 v[164:167], v149 offset:3072
	ds_read_b128 v[168:171], v150
	ds_read_b128 v[172:175], v150 offset:1024
	ds_read_b128 v[176:179], v150 offset:2048
	ds_read_b128 v[184:187], v150 offset:3072
	s_add_u32 s56, s54, 0x100
	s_addc_u32 s57, s55, 0
	s_cmp_eq_u32 s88, 40
	s_cselect_b32 s61, s13, s57
	s_cselect_b32 s60, s12, s56
	s_cselect_b32 s59, s53, s87
	s_cselect_b32 s58, s52, s86
	v_lshl_add_u64 v[144:145], s[54:55], 0, v[136:137]
	s_add_i32 m0, s65, 0xc000
	ds_read_b128 v[188:191], v151
	ds_read_b128 v[192:195], v151 offset:1024
	ds_read_b128 v[196:199], v151 offset:2048
	ds_read_b128 v[200:203], v151 offset:3072
	ds_read_b128 v[204:207], v151 offset:4096
	ds_read_b128 v[208:211], v151 offset:5120
	ds_read_b128 v[212:215], v151 offset:6144
	ds_read_b128 v[216:219], v151 offset:7168
	global_load_lds_dwordx4 v[144:145], off
	v_lshl_add_u64 v[144:145], s[54:55], 0, v[138:139]
	s_add_i32 m0, s65, 0xe000
	s_nop 0
	global_load_lds_dwordx4 v[144:145], off
	s_waitcnt vmcnt(8)
	s_waitcnt lgkmcnt(0)
	s_barrier
	s_setprio 1
	s_waitcnt lgkmcnt(0)
	v_mfma_f32_16x16x32_bf16 v[124:127], v[152:155], v[188:191], 0
	v_mfma_f32_16x16x32_bf16 v[124:127], v[156:159], v[192:195], v[124:127]
	v_mfma_f32_16x16x32_bf16 v[120:123], v[160:163], v[188:191], 0
	v_mfma_f32_16x16x32_bf16 v[120:123], v[164:167], v[192:195], v[120:123]
	v_mfma_f32_16x16x32_bf16 v[116:119], v[152:155], v[196:199], 0
	v_mfma_f32_16x16x32_bf16 v[116:119], v[156:159], v[200:203], v[116:119]
	v_mfma_f32_16x16x32_bf16 v[108:111], v[160:163], v[196:199], 0
	v_mfma_f32_16x16x32_bf16 v[108:111], v[164:167], v[200:203], v[108:111]
	v_mfma_f32_16x16x32_bf16 v[100:103], v[152:155], v[204:207], 0
	v_mfma_f32_16x16x32_bf16 v[100:103], v[156:159], v[208:211], v[100:103]
	v_mfma_f32_16x16x32_bf16 v[92:95], v[160:163], v[204:207], 0
	v_mfma_f32_16x16x32_bf16 v[92:95], v[164:167], v[208:211], v[92:95]
	v_mfma_f32_16x16x32_bf16 v[84:87], v[152:155], v[212:215], 0
	v_mfma_f32_16x16x32_bf16 v[84:87], v[156:159], v[216:219], v[84:87]
	v_mfma_f32_16x16x32_bf16 v[76:79], v[160:163], v[212:215], 0
	v_mfma_f32_16x16x32_bf16 v[76:79], v[164:167], v[216:219], v[76:79]
	v_mfma_f32_16x16x32_bf16 v[112:115], v[168:171], v[188:191], 0
	v_mfma_f32_16x16x32_bf16 v[112:115], v[172:175], v[192:195], v[112:115]
	v_mfma_f32_16x16x32_bf16 v[104:107], v[176:179], v[188:191], 0
	v_mfma_f32_16x16x32_bf16 v[104:107], v[184:187], v[192:195], v[104:107]
	v_mfma_f32_16x16x32_bf16 v[96:99], v[168:171], v[196:199], 0
	v_mfma_f32_16x16x32_bf16 v[96:99], v[172:175], v[200:203], v[96:99]
	v_mfma_f32_16x16x32_bf16 v[88:91], v[176:179], v[196:199], 0
	v_mfma_f32_16x16x32_bf16 v[88:91], v[184:187], v[200:203], v[88:91]
	v_mfma_f32_16x16x32_bf16 v[80:83], v[168:171], v[204:207], 0
	v_mfma_f32_16x16x32_bf16 v[80:83], v[172:175], v[208:211], v[80:83]
	v_mfma_f32_16x16x32_bf16 v[72:75], v[176:179], v[204:207], 0
	v_mfma_f32_16x16x32_bf16 v[72:75], v[184:187], v[208:211], v[72:75]
	s_setprio 2
	s_barrier
	v_mfma_f32_16x16x32_bf16 v[68:71], v[168:171], v[212:215], 0
	v_mfma_f32_16x16x32_bf16 v[68:71], v[172:175], v[216:219], v[68:71]
	v_mfma_f32_16x16x32_bf16 v[64:67], v[176:179], v[212:215], 0
	v_mfma_f32_16x16x32_bf16 v[64:67], v[184:187], v[216:219], v[64:67]
	s_setprio 0
	s_add_i32 s54, s72, s64
	v_lshl_add_u64 v[144:145], s[58:59], 0, v[130:131]
	s_mov_b32 m0, s54
	ds_read_b128 v[188:191], v151 offset:16384
	ds_read_b128 v[192:195], v151 offset:17408
	ds_read_b128 v[196:199], v151 offset:18432
	ds_read_b128 v[200:203], v151 offset:19456
	ds_read_b128 v[204:207], v151 offset:20480
	ds_read_b128 v[208:211], v151 offset:21504
	ds_read_b128 v[212:215], v151 offset:22528
	ds_read_b128 v[216:219], v151 offset:23552
	global_load_lds_dwordx4 v[144:145], off
	s_add_i32 m0, s54, 0x2000
	s_add_u32 s54, s58, 0xb0000
	v_lshl_add_u64 v[220:221], s[58:59], 0, v[134:135]
	s_addc_u32 s55, s59, 0
	s_add_i32 s79, s73, s64
	global_load_lds_dwordx4 v[220:221], off
	v_lshl_add_u64 v[222:223], s[54:55], 0, v[130:131]
	s_mov_b32 m0, s79
	v_lshl_add_u64 v[224:225], s[60:61], 0, v[132:133]
	global_load_lds_dwordx4 v[222:223], off
	v_lshl_add_u64 v[222:223], s[54:55], 0, v[134:135]
	s_add_i32 m0, s79, 0x2000
	s_nop 0
	global_load_lds_dwordx4 v[222:223], off
	v_lshl_add_u64 v[222:223], s[60:61], 0, v[128:129]
	s_mov_b32 m0, s65
	s_nop 0
	global_load_lds_dwordx4 v[222:223], off
	s_mov_b32 m0, s66
	s_nop 0
	global_load_lds_dwordx4 v[224:225], off
	s_waitcnt vmcnt(8)
	s_waitcnt lgkmcnt(0)
	s_barrier
	s_setprio 1
	s_waitcnt lgkmcnt(0)
	v_mfma_f32_16x16x32_bf16 v[60:63], v[152:155], v[188:191], 0
	v_mfma_f32_16x16x32_bf16 v[60:63], v[156:159], v[192:195], v[60:63]
	v_mfma_f32_16x16x32_bf16 v[56:59], v[160:163], v[188:191], 0
	v_mfma_f32_16x16x32_bf16 v[56:59], v[164:167], v[192:195], v[56:59]
	v_mfma_f32_16x16x32_bf16 v[52:55], v[152:155], v[196:199], 0
	v_mfma_f32_16x16x32_bf16 v[52:55], v[156:159], v[200:203], v[52:55]
	v_mfma_f32_16x16x32_bf16 v[44:47], v[160:163], v[196:199], 0
	v_mfma_f32_16x16x32_bf16 v[44:47], v[164:167], v[200:203], v[44:47]
	v_mfma_f32_16x16x32_bf16 v[36:39], v[152:155], v[204:207], 0
	v_mfma_f32_16x16x32_bf16 v[36:39], v[156:159], v[208:211], v[36:39]
	v_mfma_f32_16x16x32_bf16 v[28:31], v[160:163], v[204:207], 0
	v_mfma_f32_16x16x32_bf16 v[28:31], v[164:167], v[208:211], v[28:31]
	v_mfma_f32_16x16x32_bf16 v[20:23], v[152:155], v[212:215], 0
	v_mfma_f32_16x16x32_bf16 v[20:23], v[156:159], v[216:219], v[20:23]
	v_mfma_f32_16x16x32_bf16 v[12:15], v[160:163], v[212:215], 0
	v_mfma_f32_16x16x32_bf16 v[12:15], v[164:167], v[216:219], v[12:15]
	v_mfma_f32_16x16x32_bf16 v[48:51], v[168:171], v[188:191], 0
	v_mfma_f32_16x16x32_bf16 v[48:51], v[172:175], v[192:195], v[48:51]
	v_mfma_f32_16x16x32_bf16 v[40:43], v[176:179], v[188:191], 0
	v_mfma_f32_16x16x32_bf16 v[40:43], v[184:187], v[192:195], v[40:43]
	v_mfma_f32_16x16x32_bf16 v[32:35], v[168:171], v[196:199], 0
	v_mfma_f32_16x16x32_bf16 v[32:35], v[172:175], v[200:203], v[32:35]
	v_mfma_f32_16x16x32_bf16 v[24:27], v[176:179], v[196:199], 0
	v_mfma_f32_16x16x32_bf16 v[24:27], v[184:187], v[200:203], v[24:27]
	v_mfma_f32_16x16x32_bf16 v[16:19], v[168:171], v[204:207], 0
	v_mfma_f32_16x16x32_bf16 v[16:19], v[172:175], v[208:211], v[16:19]
	v_mfma_f32_16x16x32_bf16 v[8:11], v[176:179], v[204:207], 0
	v_mfma_f32_16x16x32_bf16 v[8:11], v[184:187], v[208:211], v[8:11]
	s_setprio 2
	s_barrier
	v_mfma_f32_16x16x32_bf16 v[4:7], v[168:171], v[212:215], 0
	v_mfma_f32_16x16x32_bf16 v[4:7], v[172:175], v[216:219], v[4:7]
	v_mfma_f32_16x16x32_bf16 v[0:3], v[176:179], v[212:215], 0
	v_mfma_f32_16x16x32_bf16 v[0:3], v[184:187], v[216:219], v[0:3]
	s_setprio 0
	s_branch .Lmid_gemm8
.LBB0_1031:
	ds_read_b128 v[152:155], v149
	ds_read_b128 v[156:159], v149 offset:1024
	ds_read_b128 v[160:163], v149 offset:2048
	ds_read_b128 v[164:167], v149 offset:3072
	ds_read_b128 v[168:171], v150
	ds_read_b128 v[172:175], v150 offset:1024
	ds_read_b128 v[176:179], v150 offset:2048
	ds_read_b128 v[184:187], v150 offset:3072
	s_add_u32 s56, s54, 0x100
	s_addc_u32 s57, s55, 0
	s_cmp_eq_u32 s88, 40
	s_cselect_b32 s61, s13, s57
	s_cselect_b32 s60, s12, s56
	s_cselect_b32 s59, s53, s87
	s_cselect_b32 s58, s52, s86
	v_lshl_add_u64 v[144:145], s[54:55], 0, v[136:137]
	s_add_i32 m0, s65, 0xc000
	ds_read_b128 v[188:191], v151
	ds_read_b128 v[192:195], v151 offset:1024
	ds_read_b128 v[196:199], v151 offset:2048
	ds_read_b128 v[200:203], v151 offset:3072
	ds_read_b128 v[204:207], v151 offset:4096
	ds_read_b128 v[208:211], v151 offset:5120
	ds_read_b128 v[212:215], v151 offset:6144
	ds_read_b128 v[216:219], v151 offset:7168
	global_load_lds_dwordx4 v[144:145], off
	v_lshl_add_u64 v[144:145], s[54:55], 0, v[138:139]
	s_add_i32 m0, s65, 0xe000
	s_nop 0
	global_load_lds_dwordx4 v[144:145], off
	s_waitcnt vmcnt(8)
	s_waitcnt lgkmcnt(0)
	s_barrier
	s_setprio 1
	s_waitcnt lgkmcnt(0)
	v_mfma_f32_16x16x32_bf16 v[124:127], v[152:155], v[188:191], v[124:127]
	v_mfma_f32_16x16x32_bf16 v[124:127], v[156:159], v[192:195], v[124:127]
	v_mfma_f32_16x16x32_bf16 v[120:123], v[160:163], v[188:191], v[120:123]
	v_mfma_f32_16x16x32_bf16 v[120:123], v[164:167], v[192:195], v[120:123]
	v_mfma_f32_16x16x32_bf16 v[116:119], v[152:155], v[196:199], v[116:119]
	v_mfma_f32_16x16x32_bf16 v[116:119], v[156:159], v[200:203], v[116:119]
	v_mfma_f32_16x16x32_bf16 v[108:111], v[160:163], v[196:199], v[108:111]
	v_mfma_f32_16x16x32_bf16 v[108:111], v[164:167], v[200:203], v[108:111]
	v_mfma_f32_16x16x32_bf16 v[100:103], v[152:155], v[204:207], v[100:103]
	v_mfma_f32_16x16x32_bf16 v[100:103], v[156:159], v[208:211], v[100:103]
	v_mfma_f32_16x16x32_bf16 v[92:95], v[160:163], v[204:207], v[92:95]
	v_mfma_f32_16x16x32_bf16 v[92:95], v[164:167], v[208:211], v[92:95]
	v_mfma_f32_16x16x32_bf16 v[84:87], v[152:155], v[212:215], v[84:87]
	v_mfma_f32_16x16x32_bf16 v[84:87], v[156:159], v[216:219], v[84:87]
	v_mfma_f32_16x16x32_bf16 v[76:79], v[160:163], v[212:215], v[76:79]
	v_mfma_f32_16x16x32_bf16 v[76:79], v[164:167], v[216:219], v[76:79]
	v_mfma_f32_16x16x32_bf16 v[112:115], v[168:171], v[188:191], v[112:115]
	v_mfma_f32_16x16x32_bf16 v[112:115], v[172:175], v[192:195], v[112:115]
	v_mfma_f32_16x16x32_bf16 v[104:107], v[176:179], v[188:191], v[104:107]
	v_mfma_f32_16x16x32_bf16 v[104:107], v[184:187], v[192:195], v[104:107]
	v_mfma_f32_16x16x32_bf16 v[96:99], v[168:171], v[196:199], v[96:99]
	v_mfma_f32_16x16x32_bf16 v[96:99], v[172:175], v[200:203], v[96:99]
	v_mfma_f32_16x16x32_bf16 v[88:91], v[176:179], v[196:199], v[88:91]
	v_mfma_f32_16x16x32_bf16 v[88:91], v[184:187], v[200:203], v[88:91]
	v_mfma_f32_16x16x32_bf16 v[80:83], v[168:171], v[204:207], v[80:83]
	v_mfma_f32_16x16x32_bf16 v[80:83], v[172:175], v[208:211], v[80:83]
	v_mfma_f32_16x16x32_bf16 v[72:75], v[176:179], v[204:207], v[72:75]
	v_mfma_f32_16x16x32_bf16 v[72:75], v[184:187], v[208:211], v[72:75]
	s_setprio 2
	s_barrier
	v_mfma_f32_16x16x32_bf16 v[68:71], v[168:171], v[212:215], v[68:71]
	v_mfma_f32_16x16x32_bf16 v[68:71], v[172:175], v[216:219], v[68:71]
	v_mfma_f32_16x16x32_bf16 v[64:67], v[176:179], v[212:215], v[64:67]
	v_mfma_f32_16x16x32_bf16 v[64:67], v[184:187], v[216:219], v[64:67]
	s_setprio 0
	s_add_i32 s54, s72, s64
	v_lshl_add_u64 v[144:145], s[58:59], 0, v[130:131]
	s_mov_b32 m0, s54
	ds_read_b128 v[188:191], v151 offset:16384
	ds_read_b128 v[192:195], v151 offset:17408
	ds_read_b128 v[196:199], v151 offset:18432
	ds_read_b128 v[200:203], v151 offset:19456
	ds_read_b128 v[204:207], v151 offset:20480
	ds_read_b128 v[208:211], v151 offset:21504
	ds_read_b128 v[212:215], v151 offset:22528
	ds_read_b128 v[216:219], v151 offset:23552
	global_load_lds_dwordx4 v[144:145], off
	s_add_i32 m0, s54, 0x2000
	s_add_u32 s54, s58, 0xb0000
	v_lshl_add_u64 v[220:221], s[58:59], 0, v[134:135]
	s_addc_u32 s55, s59, 0
	s_add_i32 s79, s73, s64
	global_load_lds_dwordx4 v[220:221], off
	v_lshl_add_u64 v[222:223], s[54:55], 0, v[130:131]
	s_mov_b32 m0, s79
	v_lshl_add_u64 v[224:225], s[60:61], 0, v[132:133]
	global_load_lds_dwordx4 v[222:223], off
	v_lshl_add_u64 v[222:223], s[54:55], 0, v[134:135]
	s_add_i32 m0, s79, 0x2000
	s_nop 0
	global_load_lds_dwordx4 v[222:223], off
	v_lshl_add_u64 v[222:223], s[60:61], 0, v[128:129]
	s_mov_b32 m0, s65
	s_nop 0
	global_load_lds_dwordx4 v[222:223], off
	s_mov_b32 m0, s66
	s_nop 0
	global_load_lds_dwordx4 v[224:225], off
	s_waitcnt vmcnt(8)
	s_waitcnt lgkmcnt(0)
	s_barrier
	s_setprio 1
	s_waitcnt lgkmcnt(0)
	v_mfma_f32_16x16x32_bf16 v[60:63], v[152:155], v[188:191], v[60:63]
	v_mfma_f32_16x16x32_bf16 v[60:63], v[156:159], v[192:195], v[60:63]
	v_mfma_f32_16x16x32_bf16 v[56:59], v[160:163], v[188:191], v[56:59]
	v_mfma_f32_16x16x32_bf16 v[56:59], v[164:167], v[192:195], v[56:59]
	v_mfma_f32_16x16x32_bf16 v[52:55], v[152:155], v[196:199], v[52:55]
	v_mfma_f32_16x16x32_bf16 v[52:55], v[156:159], v[200:203], v[52:55]
	v_mfma_f32_16x16x32_bf16 v[44:47], v[160:163], v[196:199], v[44:47]
	v_mfma_f32_16x16x32_bf16 v[44:47], v[164:167], v[200:203], v[44:47]
	v_mfma_f32_16x16x32_bf16 v[36:39], v[152:155], v[204:207], v[36:39]
	v_mfma_f32_16x16x32_bf16 v[36:39], v[156:159], v[208:211], v[36:39]
	v_mfma_f32_16x16x32_bf16 v[28:31], v[160:163], v[204:207], v[28:31]
	v_mfma_f32_16x16x32_bf16 v[28:31], v[164:167], v[208:211], v[28:31]
	v_mfma_f32_16x16x32_bf16 v[20:23], v[152:155], v[212:215], v[20:23]
	v_mfma_f32_16x16x32_bf16 v[20:23], v[156:159], v[216:219], v[20:23]
	v_mfma_f32_16x16x32_bf16 v[12:15], v[160:163], v[212:215], v[12:15]
	v_mfma_f32_16x16x32_bf16 v[12:15], v[164:167], v[216:219], v[12:15]
	v_mfma_f32_16x16x32_bf16 v[48:51], v[168:171], v[188:191], v[48:51]
	v_mfma_f32_16x16x32_bf16 v[48:51], v[172:175], v[192:195], v[48:51]
	v_mfma_f32_16x16x32_bf16 v[40:43], v[176:179], v[188:191], v[40:43]
	v_mfma_f32_16x16x32_bf16 v[40:43], v[184:187], v[192:195], v[40:43]
	v_mfma_f32_16x16x32_bf16 v[32:35], v[168:171], v[196:199], v[32:35]
	v_mfma_f32_16x16x32_bf16 v[32:35], v[172:175], v[200:203], v[32:35]
	v_mfma_f32_16x16x32_bf16 v[24:27], v[176:179], v[196:199], v[24:27]
	v_mfma_f32_16x16x32_bf16 v[24:27], v[184:187], v[200:203], v[24:27]
	v_mfma_f32_16x16x32_bf16 v[16:19], v[168:171], v[204:207], v[16:19]
	v_mfma_f32_16x16x32_bf16 v[16:19], v[172:175], v[208:211], v[16:19]
	v_mfma_f32_16x16x32_bf16 v[8:11], v[176:179], v[204:207], v[8:11]
	v_mfma_f32_16x16x32_bf16 v[8:11], v[184:187], v[208:211], v[8:11]
	s_setprio 2
	s_barrier
	v_mfma_f32_16x16x32_bf16 v[4:7], v[168:171], v[212:215], v[4:7]
	v_mfma_f32_16x16x32_bf16 v[4:7], v[172:175], v[216:219], v[4:7]
	v_mfma_f32_16x16x32_bf16 v[0:3], v[176:179], v[212:215], v[0:3]
	v_mfma_f32_16x16x32_bf16 v[0:3], v[184:187], v[216:219], v[0:3]
	s_setprio 0
.Lmid_gemm8:
	s_add_i32 s79, 0, 0x18000
	s_add_i32 s89, 0, 0x1c000
	v_add_u32_e32 v164, s79, v147
	v_add_u32_e32 v181, s89, v147
	ds_read_b128 v[152:155], v164
	ds_read_b128 v[156:159], v164 offset:1024
	ds_read_b128 v[160:163], v164 offset:2048
	ds_read_b128 v[164:167], v164 offset:3072
	ds_read_b128 v[168:171], v181
	ds_read_b128 v[172:175], v181 offset:1024
	ds_read_b128 v[176:179], v181 offset:2048
	ds_read_b128 v[184:187], v181 offset:3072
	s_add_u32 s54, s60, 0xb0000
	s_addc_u32 s55, s61, 0
	s_mov_b32 m0, s67
	v_lshl_add_u64 v[226:227], s[54:55], 0, v[128:129]
	ds_read_b128 v[188:191], v151 offset:32768
	ds_read_b128 v[192:195], v151 offset:33792
	ds_read_b128 v[196:199], v151 offset:34816
	ds_read_b128 v[200:203], v151 offset:35840
	ds_read_b128 v[204:207], v151 offset:36864
	ds_read_b128 v[208:211], v151 offset:37888
	ds_read_b128 v[212:215], v151 offset:38912
	ds_read_b128 v[216:219], v151 offset:39936
	global_load_lds_dwordx4 v[226:227], off
	v_lshl_add_u64 v[226:227], s[54:55], 0, v[132:133]
	s_mov_b32 m0, s68
	s_nop 0
	global_load_lds_dwordx4 v[226:227], off
	s_waitcnt vmcnt(8)
	s_waitcnt lgkmcnt(0)
	s_barrier
	s_setprio 1
	s_waitcnt lgkmcnt(0)
	v_mfma_f32_16x16x32_bf16 v[124:127], v[152:155], v[188:191], v[124:127]
	v_mfma_f32_16x16x32_bf16 v[124:127], v[156:159], v[192:195], v[124:127]
	v_mfma_f32_16x16x32_bf16 v[120:123], v[160:163], v[188:191], v[120:123]
	v_mfma_f32_16x16x32_bf16 v[120:123], v[164:167], v[192:195], v[120:123]
	v_mfma_f32_16x16x32_bf16 v[116:119], v[152:155], v[196:199], v[116:119]
	v_mfma_f32_16x16x32_bf16 v[116:119], v[156:159], v[200:203], v[116:119]
	v_mfma_f32_16x16x32_bf16 v[108:111], v[160:163], v[196:199], v[108:111]
	v_mfma_f32_16x16x32_bf16 v[108:111], v[164:167], v[200:203], v[108:111]
	v_mfma_f32_16x16x32_bf16 v[100:103], v[152:155], v[204:207], v[100:103]
	v_mfma_f32_16x16x32_bf16 v[100:103], v[156:159], v[208:211], v[100:103]
	v_mfma_f32_16x16x32_bf16 v[92:95], v[160:163], v[204:207], v[92:95]
	v_mfma_f32_16x16x32_bf16 v[92:95], v[164:167], v[208:211], v[92:95]
	v_mfma_f32_16x16x32_bf16 v[84:87], v[152:155], v[212:215], v[84:87]
	v_mfma_f32_16x16x32_bf16 v[84:87], v[156:159], v[216:219], v[84:87]
	v_mfma_f32_16x16x32_bf16 v[76:79], v[160:163], v[212:215], v[76:79]
	v_mfma_f32_16x16x32_bf16 v[76:79], v[164:167], v[216:219], v[76:79]
	v_mfma_f32_16x16x32_bf16 v[112:115], v[168:171], v[188:191], v[112:115]
	v_mfma_f32_16x16x32_bf16 v[112:115], v[172:175], v[192:195], v[112:115]
	v_mfma_f32_16x16x32_bf16 v[104:107], v[176:179], v[188:191], v[104:107]
	v_mfma_f32_16x16x32_bf16 v[104:107], v[184:187], v[192:195], v[104:107]
	v_mfma_f32_16x16x32_bf16 v[96:99], v[168:171], v[196:199], v[96:99]
	v_mfma_f32_16x16x32_bf16 v[96:99], v[172:175], v[200:203], v[96:99]
	v_mfma_f32_16x16x32_bf16 v[88:91], v[176:179], v[196:199], v[88:91]
	v_mfma_f32_16x16x32_bf16 v[88:91], v[184:187], v[200:203], v[88:91]
	v_mfma_f32_16x16x32_bf16 v[80:83], v[168:171], v[204:207], v[80:83]
	v_mfma_f32_16x16x32_bf16 v[80:83], v[172:175], v[208:211], v[80:83]
	v_mfma_f32_16x16x32_bf16 v[72:75], v[176:179], v[204:207], v[72:75]
	v_mfma_f32_16x16x32_bf16 v[72:75], v[184:187], v[208:211], v[72:75]
	s_setprio 2
	s_barrier
	v_mfma_f32_16x16x32_bf16 v[68:71], v[168:171], v[212:215], v[68:71]
	v_mfma_f32_16x16x32_bf16 v[68:71], v[172:175], v[216:219], v[68:71]
	v_mfma_f32_16x16x32_bf16 v[64:67], v[176:179], v[212:215], v[64:67]
	v_mfma_f32_16x16x32_bf16 v[64:67], v[184:187], v[216:219], v[64:67]
	s_setprio 0
	s_add_i32 s54, s79, s64
	v_lshl_add_u64 v[144:145], v[144:145], 0, s[16:17]
	s_mov_b32 m0, s54
	ds_read_b128 v[188:191], v151 offset:49152
	ds_read_b128 v[192:195], v151 offset:50176
	ds_read_b128 v[196:199], v151 offset:51200
	ds_read_b128 v[200:203], v151 offset:52224
	ds_read_b128 v[204:207], v151 offset:53248
	ds_read_b128 v[208:211], v151 offset:54272
	ds_read_b128 v[212:215], v151 offset:55296
	ds_read_b128 v[216:219], v151 offset:56320
	global_load_lds_dwordx4 v[144:145], off
	s_add_i32 m0, s54, 0x2000
	s_add_u32 s54, s58, 0xb0080
	v_lshl_add_u64 v[144:145], v[220:221], 0, s[16:17]
	s_addc_u32 s55, s59, 0
	s_add_i32 s58, s89, s64
	global_load_lds_dwordx4 v[144:145], off
	v_lshl_add_u64 v[144:145], s[54:55], 0, v[130:131]
	s_mov_b32 m0, s58
	s_nop 0
	global_load_lds_dwordx4 v[144:145], off
	v_lshl_add_u64 v[144:145], s[54:55], 0, v[134:135]
	s_add_i32 m0, s58, 0x2000
	s_nop 0
	global_load_lds_dwordx4 v[144:145], off
	v_lshl_add_u64 v[144:145], v[222:223], 0, s[16:17]
	s_mov_b32 m0, s70
	s_nop 0
	global_load_lds_dwordx4 v[144:145], off
	v_lshl_add_u64 v[144:145], v[224:225], 0, s[16:17]
	s_mov_b32 m0, s71
	s_nop 0
	global_load_lds_dwordx4 v[144:145], off
	s_waitcnt vmcnt(8)
	s_waitcnt lgkmcnt(0)
	s_barrier
	s_setprio 1
	s_waitcnt lgkmcnt(0)
	v_mfma_f32_16x16x32_bf16 v[60:63], v[152:155], v[188:191], v[60:63]
	v_mfma_f32_16x16x32_bf16 v[60:63], v[156:159], v[192:195], v[60:63]
	v_mfma_f32_16x16x32_bf16 v[56:59], v[160:163], v[188:191], v[56:59]
	v_mfma_f32_16x16x32_bf16 v[56:59], v[164:167], v[192:195], v[56:59]
	v_mfma_f32_16x16x32_bf16 v[52:55], v[152:155], v[196:199], v[52:55]
	v_mfma_f32_16x16x32_bf16 v[52:55], v[156:159], v[200:203], v[52:55]
	v_mfma_f32_16x16x32_bf16 v[44:47], v[160:163], v[196:199], v[44:47]
	v_mfma_f32_16x16x32_bf16 v[44:47], v[164:167], v[200:203], v[44:47]
	v_mfma_f32_16x16x32_bf16 v[36:39], v[152:155], v[204:207], v[36:39]
	v_mfma_f32_16x16x32_bf16 v[36:39], v[156:159], v[208:211], v[36:39]
	v_mfma_f32_16x16x32_bf16 v[28:31], v[160:163], v[204:207], v[28:31]
	v_mfma_f32_16x16x32_bf16 v[28:31], v[164:167], v[208:211], v[28:31]
	v_mfma_f32_16x16x32_bf16 v[20:23], v[152:155], v[212:215], v[20:23]
	v_mfma_f32_16x16x32_bf16 v[20:23], v[156:159], v[216:219], v[20:23]
	v_mfma_f32_16x16x32_bf16 v[12:15], v[160:163], v[212:215], v[12:15]
	v_mfma_f32_16x16x32_bf16 v[12:15], v[164:167], v[216:219], v[12:15]
	v_mfma_f32_16x16x32_bf16 v[48:51], v[168:171], v[188:191], v[48:51]
	v_mfma_f32_16x16x32_bf16 v[48:51], v[172:175], v[192:195], v[48:51]
	v_mfma_f32_16x16x32_bf16 v[40:43], v[176:179], v[188:191], v[40:43]
	v_mfma_f32_16x16x32_bf16 v[40:43], v[184:187], v[192:195], v[40:43]
	v_mfma_f32_16x16x32_bf16 v[32:35], v[168:171], v[196:199], v[32:35]
	v_mfma_f32_16x16x32_bf16 v[32:35], v[172:175], v[200:203], v[32:35]
	v_mfma_f32_16x16x32_bf16 v[24:27], v[176:179], v[196:199], v[24:27]
	v_mfma_f32_16x16x32_bf16 v[24:27], v[184:187], v[200:203], v[24:27]
	v_mfma_f32_16x16x32_bf16 v[16:19], v[168:171], v[204:207], v[16:19]
	v_mfma_f32_16x16x32_bf16 v[16:19], v[172:175], v[208:211], v[16:19]
	v_mfma_f32_16x16x32_bf16 v[8:11], v[176:179], v[204:207], v[8:11]
	v_mfma_f32_16x16x32_bf16 v[8:11], v[184:187], v[208:211], v[8:11]
	s_setprio 2
	s_barrier
	v_mfma_f32_16x16x32_bf16 v[4:7], v[168:171], v[212:215], v[4:7]
	v_mfma_f32_16x16x32_bf16 v[4:7], v[172:175], v[216:219], v[4:7]
	v_mfma_f32_16x16x32_bf16 v[0:3], v[176:179], v[212:215], v[0:3]
	v_mfma_f32_16x16x32_bf16 v[0:3], v[184:187], v[216:219], v[0:3]
	s_setprio 0
	s_add_i32 s88, s88, 2
	s_add_u32 s86, s86, 0x100
	s_addc_u32 s87, s87, 0
	s_cmp_gt_u32 s88, 41
	s_mov_b64 s[54:55], s[56:57]
	s_cbranch_scc0 .LBB0_1031
	s_and_b64 vcc, exec, s[18:19]
	s_cbranch_vccz .LBB0_1034
	s_barrier

.LBB0_1161:
	s_ashr_i32 s53, s52, 31
	s_lshl_b64 s[54:55], s[52:53], 19
	s_add_u32 s54, s80, s54
	s_addc_u32 s55, s81, s55
	s_and_b64 s[56:57], s[10:11], exec
	s_cselect_b32 s53, s55, s61
	s_cselect_b32 s83, s54, s60
	s_ashr_i32 s49, s48, 31
	s_lshl_b64 s[56:57], s[48:49], 19
	s_add_u32 s56, s66, s56
	s_addc_u32 s57, s67, s57
	s_and_b64 s[64:65], s[10:11], exec
	s_cselect_b32 s49, s57, s63
	s_cselect_b32 s84, s56, s62
	s_add_u32 s60, s60, 0x40080
	s_addc_u32 s61, s61, 0
	s_add_u32 s85, s62, 0x100
	s_addc_u32 s86, s63, 0
	s_mov_b32 s87, -2
	ds_read_b128 v[152:155], v148
	ds_read_b128 v[156:159], v148 offset:1024
	ds_read_b128 v[160:163], v148 offset:2048
	ds_read_b128 v[164:167], v148 offset:3072
	ds_read_b128 v[168:171], v149
	ds_read_b128 v[172:175], v149 offset:1024
	ds_read_b128 v[176:179], v149 offset:2048
	ds_read_b128 v[184:187], v149 offset:3072
	s_add_u32 s62, s60, 0xfffc0080
	s_addc_u32 s63, s61, -1
	s_cmp_eq_u32 s87, 12
	s_cselect_b32 s65, s53, s63
	s_cselect_b32 s64, s83, s62
	s_cselect_b32 s63, s49, s86
	s_cselect_b32 s62, s84, s85
	v_lshl_add_u64 v[220:221], s[60:61], 0, v[138:139]
	s_add_i32 m0, s69, 0xc000
	ds_read_b128 v[188:191], v150
	ds_read_b128 v[192:195], v150 offset:1024
	ds_read_b128 v[196:199], v150 offset:2048
	ds_read_b128 v[200:203], v150 offset:3072
	ds_read_b128 v[204:207], v150 offset:4096
	ds_read_b128 v[208:211], v150 offset:5120
	ds_read_b128 v[212:215], v150 offset:6144
	ds_read_b128 v[216:219], v150 offset:7168
	global_load_lds_dwordx4 v[220:221], off
	v_lshl_add_u64 v[220:221], s[60:61], 0, v[140:141]
	s_add_i32 m0, s69, 0xe000
	s_nop 0
	global_load_lds_dwordx4 v[220:221], off
	s_waitcnt vmcnt(8)
	s_waitcnt lgkmcnt(0)
	s_barrier
	s_setprio 1
	s_waitcnt lgkmcnt(0)
	v_mfma_f32_16x16x32_bf16 v[124:127], v[152:155], v[188:191], 0
	v_mfma_f32_16x16x32_bf16 v[124:127], v[156:159], v[192:195], v[124:127]
	v_mfma_f32_16x16x32_bf16 v[120:123], v[160:163], v[188:191], 0
	v_mfma_f32_16x16x32_bf16 v[120:123], v[164:167], v[192:195], v[120:123]
	v_mfma_f32_16x16x32_bf16 v[116:119], v[152:155], v[196:199], 0
	v_mfma_f32_16x16x32_bf16 v[116:119], v[156:159], v[200:203], v[116:119]
	v_mfma_f32_16x16x32_bf16 v[112:115], v[160:163], v[196:199], 0
	v_mfma_f32_16x16x32_bf16 v[112:115], v[164:167], v[200:203], v[112:115]
	v_mfma_f32_16x16x32_bf16 v[108:111], v[152:155], v[204:207], 0
	v_mfma_f32_16x16x32_bf16 v[108:111], v[156:159], v[208:211], v[108:111]
	v_mfma_f32_16x16x32_bf16 v[104:107], v[160:163], v[204:207], 0
	v_mfma_f32_16x16x32_bf16 v[104:107], v[164:167], v[208:211], v[104:107]
	v_mfma_f32_16x16x32_bf16 v[100:103], v[152:155], v[212:215], 0
	v_mfma_f32_16x16x32_bf16 v[100:103], v[156:159], v[216:219], v[100:103]
	v_mfma_f32_16x16x32_bf16 v[96:99], v[160:163], v[212:215], 0
	v_mfma_f32_16x16x32_bf16 v[96:99], v[164:167], v[216:219], v[96:99]
	v_mfma_f32_16x16x32_bf16 v[68:71], v[168:171], v[188:191], 0
	v_mfma_f32_16x16x32_bf16 v[68:71], v[172:175], v[192:195], v[68:71]
	v_mfma_f32_16x16x32_bf16 v[64:67], v[176:179], v[188:191], 0
	v_mfma_f32_16x16x32_bf16 v[64:67], v[184:187], v[192:195], v[64:67]
	v_mfma_f32_16x16x32_bf16 v[52:55], v[168:171], v[196:199], 0
	v_mfma_f32_16x16x32_bf16 v[52:55], v[172:175], v[200:203], v[52:55]
	v_mfma_f32_16x16x32_bf16 v[48:51], v[176:179], v[196:199], 0
	v_mfma_f32_16x16x32_bf16 v[48:51], v[184:187], v[200:203], v[48:51]
	v_mfma_f32_16x16x32_bf16 v[44:47], v[168:171], v[204:207], 0
	v_mfma_f32_16x16x32_bf16 v[44:47], v[172:175], v[208:211], v[44:47]
	v_mfma_f32_16x16x32_bf16 v[40:43], v[176:179], v[204:207], 0
	v_mfma_f32_16x16x32_bf16 v[40:43], v[184:187], v[208:211], v[40:43]
	s_setprio 2
	s_barrier
	v_mfma_f32_16x16x32_bf16 v[36:39], v[168:171], v[212:215], 0
	v_mfma_f32_16x16x32_bf16 v[36:39], v[172:175], v[216:219], v[36:39]
	v_mfma_f32_16x16x32_bf16 v[32:35], v[176:179], v[212:215], 0
	v_mfma_f32_16x16x32_bf16 v[32:35], v[184:187], v[216:219], v[32:35]
	s_setprio 0
	s_add_i32 s79, s77, s68
	v_lshl_add_u64 v[220:221], s[62:63], 0, v[130:131]
	s_mov_b32 m0, s79
	ds_read_b128 v[188:191], v150 offset:16384
	ds_read_b128 v[192:195], v150 offset:17408
	ds_read_b128 v[196:199], v150 offset:18432
	ds_read_b128 v[200:203], v150 offset:19456
	ds_read_b128 v[204:207], v150 offset:20480
	ds_read_b128 v[208:211], v150 offset:21504
	ds_read_b128 v[212:215], v150 offset:22528
	ds_read_b128 v[216:219], v150 offset:23552
	global_load_lds_dwordx4 v[220:221], off
	s_add_i32 m0, s79, 0x2000
	s_add_u32 s88, s62, 0x40000
	v_lshl_add_u64 v[222:223], s[62:63], 0, v[134:135]
	s_addc_u32 s89, s63, 0
	s_add_i32 s79, s82, s68
	global_load_lds_dwordx4 v[222:223], off
	v_lshl_add_u64 v[224:225], s[88:89], 0, v[130:131]
	s_mov_b32 m0, s79
	v_lshl_add_u64 v[226:227], s[64:65], 0, v[132:133]
	global_load_lds_dwordx4 v[224:225], off
	v_lshl_add_u64 v[224:225], s[88:89], 0, v[134:135]
	s_add_i32 m0, s79, 0x2000
	s_nop 0
	global_load_lds_dwordx4 v[224:225], off
	v_lshl_add_u64 v[224:225], s[64:65], 0, v[128:129]
	s_mov_b32 m0, s69
	s_nop 0
	global_load_lds_dwordx4 v[224:225], off
	s_mov_b32 m0, s70
	s_nop 0
	global_load_lds_dwordx4 v[226:227], off
	s_waitcnt vmcnt(8)
	s_waitcnt lgkmcnt(0)
	s_barrier
	s_setprio 1
	s_waitcnt lgkmcnt(0)
	v_mfma_f32_16x16x32_bf16 v[92:95], v[152:155], v[188:191], 0
	v_mfma_f32_16x16x32_bf16 v[92:95], v[156:159], v[192:195], v[92:95]
	v_mfma_f32_16x16x32_bf16 v[88:91], v[160:163], v[188:191], 0
	v_mfma_f32_16x16x32_bf16 v[88:91], v[164:167], v[192:195], v[88:91]
	v_mfma_f32_16x16x32_bf16 v[84:87], v[152:155], v[196:199], 0
	v_mfma_f32_16x16x32_bf16 v[84:87], v[156:159], v[200:203], v[84:87]
	v_mfma_f32_16x16x32_bf16 v[80:83], v[160:163], v[196:199], 0
	v_mfma_f32_16x16x32_bf16 v[80:83], v[164:167], v[200:203], v[80:83]
	v_mfma_f32_16x16x32_bf16 v[76:79], v[152:155], v[204:207], 0
	v_mfma_f32_16x16x32_bf16 v[76:79], v[156:159], v[208:211], v[76:79]
	v_mfma_f32_16x16x32_bf16 v[72:75], v[160:163], v[204:207], 0
	v_mfma_f32_16x16x32_bf16 v[72:75], v[164:167], v[208:211], v[72:75]
	v_mfma_f32_16x16x32_bf16 v[60:63], v[152:155], v[212:215], 0
	v_mfma_f32_16x16x32_bf16 v[60:63], v[156:159], v[216:219], v[60:63]
	v_mfma_f32_16x16x32_bf16 v[56:59], v[160:163], v[212:215], 0
	v_mfma_f32_16x16x32_bf16 v[56:59], v[164:167], v[216:219], v[56:59]
	v_mfma_f32_16x16x32_bf16 v[28:31], v[168:171], v[188:191], 0
	v_mfma_f32_16x16x32_bf16 v[28:31], v[172:175], v[192:195], v[28:31]
	v_mfma_f32_16x16x32_bf16 v[24:27], v[176:179], v[188:191], 0
	v_mfma_f32_16x16x32_bf16 v[24:27], v[184:187], v[192:195], v[24:27]
	v_mfma_f32_16x16x32_bf16 v[20:23], v[168:171], v[196:199], 0
	v_mfma_f32_16x16x32_bf16 v[20:23], v[172:175], v[200:203], v[20:23]
	v_mfma_f32_16x16x32_bf16 v[16:19], v[176:179], v[196:199], 0
	v_mfma_f32_16x16x32_bf16 v[16:19], v[184:187], v[200:203], v[16:19]
	v_mfma_f32_16x16x32_bf16 v[12:15], v[168:171], v[204:207], 0
	v_mfma_f32_16x16x32_bf16 v[12:15], v[172:175], v[208:211], v[12:15]
	v_mfma_f32_16x16x32_bf16 v[8:11], v[176:179], v[204:207], 0
	v_mfma_f32_16x16x32_bf16 v[8:11], v[184:187], v[208:211], v[8:11]
	s_setprio 2
	s_barrier
	v_mfma_f32_16x16x32_bf16 v[4:7], v[168:171], v[212:215], 0
	v_mfma_f32_16x16x32_bf16 v[4:7], v[172:175], v[216:219], v[4:7]
	v_mfma_f32_16x16x32_bf16 v[0:3], v[176:179], v[212:215], 0
	v_mfma_f32_16x16x32_bf16 v[0:3], v[184:187], v[216:219], v[0:3]
	s_setprio 0
	s_branch .Lmid_gemm9
.LBB0_1162:
	ds_read_b128 v[152:155], v148
	ds_read_b128 v[156:159], v148 offset:1024
	ds_read_b128 v[160:163], v148 offset:2048
	ds_read_b128 v[164:167], v148 offset:3072
	ds_read_b128 v[168:171], v149
	ds_read_b128 v[172:175], v149 offset:1024
	ds_read_b128 v[176:179], v149 offset:2048
	ds_read_b128 v[184:187], v149 offset:3072
	s_add_u32 s62, s60, 0xfffc0080
	s_addc_u32 s63, s61, -1
	s_cmp_eq_u32 s87, 12
	s_cselect_b32 s65, s53, s63
	s_cselect_b32 s64, s83, s62
	s_cselect_b32 s63, s49, s86
	s_cselect_b32 s62, s84, s85
	v_lshl_add_u64 v[220:221], s[60:61], 0, v[138:139]
	s_add_i32 m0, s69, 0xc000
	ds_read_b128 v[188:191], v150
	ds_read_b128 v[192:195], v150 offset:1024
	ds_read_b128 v[196:199], v150 offset:2048
	ds_read_b128 v[200:203], v150 offset:3072
	ds_read_b128 v[204:207], v150 offset:4096
	ds_read_b128 v[208:211], v150 offset:5120
	ds_read_b128 v[212:215], v150 offset:6144
	ds_read_b128 v[216:219], v150 offset:7168
	global_load_lds_dwordx4 v[220:221], off
	v_lshl_add_u64 v[220:221], s[60:61], 0, v[140:141]
	s_add_i32 m0, s69, 0xe000
	s_nop 0
	global_load_lds_dwordx4 v[220:221], off
	s_waitcnt vmcnt(8)
	s_waitcnt lgkmcnt(0)
	s_barrier
	s_setprio 1
	s_waitcnt lgkmcnt(0)
	v_mfma_f32_16x16x32_bf16 v[124:127], v[152:155], v[188:191], v[124:127]
	v_mfma_f32_16x16x32_bf16 v[124:127], v[156:159], v[192:195], v[124:127]
	v_mfma_f32_16x16x32_bf16 v[120:123], v[160:163], v[188:191], v[120:123]
	v_mfma_f32_16x16x32_bf16 v[120:123], v[164:167], v[192:195], v[120:123]
	v_mfma_f32_16x16x32_bf16 v[116:119], v[152:155], v[196:199], v[116:119]
	v_mfma_f32_16x16x32_bf16 v[116:119], v[156:159], v[200:203], v[116:119]
	v_mfma_f32_16x16x32_bf16 v[112:115], v[160:163], v[196:199], v[112:115]
	v_mfma_f32_16x16x32_bf16 v[112:115], v[164:167], v[200:203], v[112:115]
	v_mfma_f32_16x16x32_bf16 v[108:111], v[152:155], v[204:207], v[108:111]
	v_mfma_f32_16x16x32_bf16 v[108:111], v[156:159], v[208:211], v[108:111]
	v_mfma_f32_16x16x32_bf16 v[104:107], v[160:163], v[204:207], v[104:107]
	v_mfma_f32_16x16x32_bf16 v[104:107], v[164:167], v[208:211], v[104:107]
	v_mfma_f32_16x16x32_bf16 v[100:103], v[152:155], v[212:215], v[100:103]
	v_mfma_f32_16x16x32_bf16 v[100:103], v[156:159], v[216:219], v[100:103]
	v_mfma_f32_16x16x32_bf16 v[96:99], v[160:163], v[212:215], v[96:99]
	v_mfma_f32_16x16x32_bf16 v[96:99], v[164:167], v[216:219], v[96:99]
	v_mfma_f32_16x16x32_bf16 v[68:71], v[168:171], v[188:191], v[68:71]
	v_mfma_f32_16x16x32_bf16 v[68:71], v[172:175], v[192:195], v[68:71]
	v_mfma_f32_16x16x32_bf16 v[64:67], v[176:179], v[188:191], v[64:67]
	v_mfma_f32_16x16x32_bf16 v[64:67], v[184:187], v[192:195], v[64:67]
	v_mfma_f32_16x16x32_bf16 v[52:55], v[168:171], v[196:199], v[52:55]
	v_mfma_f32_16x16x32_bf16 v[52:55], v[172:175], v[200:203], v[52:55]
	v_mfma_f32_16x16x32_bf16 v[48:51], v[176:179], v[196:199], v[48:51]
	v_mfma_f32_16x16x32_bf16 v[48:51], v[184:187], v[200:203], v[48:51]
	v_mfma_f32_16x16x32_bf16 v[44:47], v[168:171], v[204:207], v[44:47]
	v_mfma_f32_16x16x32_bf16 v[44:47], v[172:175], v[208:211], v[44:47]
	v_mfma_f32_16x16x32_bf16 v[40:43], v[176:179], v[204:207], v[40:43]
	v_mfma_f32_16x16x32_bf16 v[40:43], v[184:187], v[208:211], v[40:43]
	s_setprio 2
	s_barrier
	v_mfma_f32_16x16x32_bf16 v[36:39], v[168:171], v[212:215], v[36:39]
	v_mfma_f32_16x16x32_bf16 v[36:39], v[172:175], v[216:219], v[36:39]
	v_mfma_f32_16x16x32_bf16 v[32:35], v[176:179], v[212:215], v[32:35]
	v_mfma_f32_16x16x32_bf16 v[32:35], v[184:187], v[216:219], v[32:35]
	s_setprio 0
	s_add_i32 s79, s77, s68
	v_lshl_add_u64 v[220:221], s[62:63], 0, v[130:131]
	s_mov_b32 m0, s79
	ds_read_b128 v[188:191], v150 offset:16384
	ds_read_b128 v[192:195], v150 offset:17408
	ds_read_b128 v[196:199], v150 offset:18432
	ds_read_b128 v[200:203], v150 offset:19456
	ds_read_b128 v[204:207], v150 offset:20480
	ds_read_b128 v[208:211], v150 offset:21504
	ds_read_b128 v[212:215], v150 offset:22528
	ds_read_b128 v[216:219], v150 offset:23552
	global_load_lds_dwordx4 v[220:221], off
	s_add_i32 m0, s79, 0x2000
	s_add_u32 s88, s62, 0x40000
	v_lshl_add_u64 v[222:223], s[62:63], 0, v[134:135]
	s_addc_u32 s89, s63, 0
	s_add_i32 s79, s82, s68
	global_load_lds_dwordx4 v[222:223], off
	v_lshl_add_u64 v[224:225], s[88:89], 0, v[130:131]
	s_mov_b32 m0, s79
	v_lshl_add_u64 v[226:227], s[64:65], 0, v[132:133]
	global_load_lds_dwordx4 v[224:225], off
	v_lshl_add_u64 v[224:225], s[88:89], 0, v[134:135]
	s_add_i32 m0, s79, 0x2000
	s_nop 0
	global_load_lds_dwordx4 v[224:225], off
	v_lshl_add_u64 v[224:225], s[64:65], 0, v[128:129]
	s_mov_b32 m0, s69
	s_nop 0
	global_load_lds_dwordx4 v[224:225], off
	s_mov_b32 m0, s70
	s_nop 0
	global_load_lds_dwordx4 v[226:227], off
	s_waitcnt vmcnt(8)
	s_waitcnt lgkmcnt(0)
	s_barrier
	s_setprio 1
	s_waitcnt lgkmcnt(0)
	v_mfma_f32_16x16x32_bf16 v[92:95], v[152:155], v[188:191], v[92:95]
	v_mfma_f32_16x16x32_bf16 v[92:95], v[156:159], v[192:195], v[92:95]
	v_mfma_f32_16x16x32_bf16 v[88:91], v[160:163], v[188:191], v[88:91]
	v_mfma_f32_16x16x32_bf16 v[88:91], v[164:167], v[192:195], v[88:91]
	v_mfma_f32_16x16x32_bf16 v[84:87], v[152:155], v[196:199], v[84:87]
	v_mfma_f32_16x16x32_bf16 v[84:87], v[156:159], v[200:203], v[84:87]
	v_mfma_f32_16x16x32_bf16 v[80:83], v[160:163], v[196:199], v[80:83]
	v_mfma_f32_16x16x32_bf16 v[80:83], v[164:167], v[200:203], v[80:83]
	v_mfma_f32_16x16x32_bf16 v[76:79], v[152:155], v[204:207], v[76:79]
	v_mfma_f32_16x16x32_bf16 v[76:79], v[156:159], v[208:211], v[76:79]
	v_mfma_f32_16x16x32_bf16 v[72:75], v[160:163], v[204:207], v[72:75]
	v_mfma_f32_16x16x32_bf16 v[72:75], v[164:167], v[208:211], v[72:75]
	v_mfma_f32_16x16x32_bf16 v[60:63], v[152:155], v[212:215], v[60:63]
	v_mfma_f32_16x16x32_bf16 v[60:63], v[156:159], v[216:219], v[60:63]
	v_mfma_f32_16x16x32_bf16 v[56:59], v[160:163], v[212:215], v[56:59]
	v_mfma_f32_16x16x32_bf16 v[56:59], v[164:167], v[216:219], v[56:59]
	v_mfma_f32_16x16x32_bf16 v[28:31], v[168:171], v[188:191], v[28:31]
	v_mfma_f32_16x16x32_bf16 v[28:31], v[172:175], v[192:195], v[28:31]
	v_mfma_f32_16x16x32_bf16 v[24:27], v[176:179], v[188:191], v[24:27]
	v_mfma_f32_16x16x32_bf16 v[24:27], v[184:187], v[192:195], v[24:27]
	v_mfma_f32_16x16x32_bf16 v[20:23], v[168:171], v[196:199], v[20:23]
	v_mfma_f32_16x16x32_bf16 v[20:23], v[172:175], v[200:203], v[20:23]
	v_mfma_f32_16x16x32_bf16 v[16:19], v[176:179], v[196:199], v[16:19]
	v_mfma_f32_16x16x32_bf16 v[16:19], v[184:187], v[200:203], v[16:19]
	v_mfma_f32_16x16x32_bf16 v[12:15], v[168:171], v[204:207], v[12:15]
	v_mfma_f32_16x16x32_bf16 v[12:15], v[172:175], v[208:211], v[12:15]
	v_mfma_f32_16x16x32_bf16 v[8:11], v[176:179], v[204:207], v[8:11]
	v_mfma_f32_16x16x32_bf16 v[8:11], v[184:187], v[208:211], v[8:11]
	s_setprio 2
	s_barrier
	v_mfma_f32_16x16x32_bf16 v[4:7], v[168:171], v[212:215], v[4:7]
	v_mfma_f32_16x16x32_bf16 v[4:7], v[172:175], v[216:219], v[4:7]
	v_mfma_f32_16x16x32_bf16 v[0:3], v[176:179], v[212:215], v[0:3]
	v_mfma_f32_16x16x32_bf16 v[0:3], v[184:187], v[216:219], v[0:3]
	s_setprio 0
.Lmid_gemm9:
	s_add_i32 s79, 0, 0x18000
	s_add_i32 s88, 0, 0x1c000
	v_add_u32_e32 v164, s79, v147
	v_add_u32_e32 v181, s88, v147
	ds_read_b128 v[152:155], v164
	ds_read_b128 v[156:159], v164 offset:1024
	ds_read_b128 v[160:163], v164 offset:2048
	ds_read_b128 v[164:167], v164 offset:3072
	ds_read_b128 v[168:171], v181
	ds_read_b128 v[172:175], v181 offset:1024
	ds_read_b128 v[176:179], v181 offset:2048
	ds_read_b128 v[184:187], v181 offset:3072
	s_add_u32 s64, s64, 0x40000
	s_addc_u32 s65, s65, 0
	s_mov_b32 m0, s71
	v_lshl_add_u64 v[228:229], s[64:65], 0, v[128:129]
	ds_read_b128 v[188:191], v150 offset:32768
	ds_read_b128 v[192:195], v150 offset:33792
	ds_read_b128 v[196:199], v150 offset:34816
	ds_read_b128 v[200:203], v150 offset:35840
	ds_read_b128 v[204:207], v150 offset:36864
	ds_read_b128 v[208:211], v150 offset:37888
	ds_read_b128 v[212:215], v150 offset:38912
	ds_read_b128 v[216:219], v150 offset:39936
	global_load_lds_dwordx4 v[228:229], off
	v_lshl_add_u64 v[228:229], s[64:65], 0, v[132:133]
	s_mov_b32 m0, s72
	s_nop 0
	global_load_lds_dwordx4 v[228:229], off
	s_waitcnt vmcnt(8)
	s_waitcnt lgkmcnt(0)
	s_barrier
	s_setprio 1
	s_waitcnt lgkmcnt(0)
	v_mfma_f32_16x16x32_bf16 v[124:127], v[152:155], v[188:191], v[124:127]
	v_mfma_f32_16x16x32_bf16 v[124:127], v[156:159], v[192:195], v[124:127]
	v_mfma_f32_16x16x32_bf16 v[120:123], v[160:163], v[188:191], v[120:123]
	v_mfma_f32_16x16x32_bf16 v[120:123], v[164:167], v[192:195], v[120:123]
	v_mfma_f32_16x16x32_bf16 v[116:119], v[152:155], v[196:199], v[116:119]
	v_mfma_f32_16x16x32_bf16 v[116:119], v[156:159], v[200:203], v[116:119]
	v_mfma_f32_16x16x32_bf16 v[112:115], v[160:163], v[196:199], v[112:115]
	v_mfma_f32_16x16x32_bf16 v[112:115], v[164:167], v[200:203], v[112:115]
	v_mfma_f32_16x16x32_bf16 v[108:111], v[152:155], v[204:207], v[108:111]
	v_mfma_f32_16x16x32_bf16 v[108:111], v[156:159], v[208:211], v[108:111]
	v_mfma_f32_16x16x32_bf16 v[104:107], v[160:163], v[204:207], v[104:107]
	v_mfma_f32_16x16x32_bf16 v[104:107], v[164:167], v[208:211], v[104:107]
	v_mfma_f32_16x16x32_bf16 v[100:103], v[152:155], v[212:215], v[100:103]
	v_mfma_f32_16x16x32_bf16 v[100:103], v[156:159], v[216:219], v[100:103]
	v_mfma_f32_16x16x32_bf16 v[96:99], v[160:163], v[212:215], v[96:99]
	v_mfma_f32_16x16x32_bf16 v[96:99], v[164:167], v[216:219], v[96:99]
	v_mfma_f32_16x16x32_bf16 v[68:71], v[168:171], v[188:191], v[68:71]
	v_mfma_f32_16x16x32_bf16 v[68:71], v[172:175], v[192:195], v[68:71]
	v_mfma_f32_16x16x32_bf16 v[64:67], v[176:179], v[188:191], v[64:67]
	v_mfma_f32_16x16x32_bf16 v[64:67], v[184:187], v[192:195], v[64:67]
	v_mfma_f32_16x16x32_bf16 v[52:55], v[168:171], v[196:199], v[52:55]
	v_mfma_f32_16x16x32_bf16 v[52:55], v[172:175], v[200:203], v[52:55]
	v_mfma_f32_16x16x32_bf16 v[48:51], v[176:179], v[196:199], v[48:51]
	v_mfma_f32_16x16x32_bf16 v[48:51], v[184:187], v[200:203], v[48:51]
	v_mfma_f32_16x16x32_bf16 v[44:47], v[168:171], v[204:207], v[44:47]
	v_mfma_f32_16x16x32_bf16 v[44:47], v[172:175], v[208:211], v[44:47]
	v_mfma_f32_16x16x32_bf16 v[40:43], v[176:179], v[204:207], v[40:43]
	v_mfma_f32_16x16x32_bf16 v[40:43], v[184:187], v[208:211], v[40:43]
	s_setprio 2
	s_barrier
	v_mfma_f32_16x16x32_bf16 v[36:39], v[168:171], v[212:215], v[36:39]
	v_mfma_f32_16x16x32_bf16 v[36:39], v[172:175], v[216:219], v[36:39]
	v_mfma_f32_16x16x32_bf16 v[32:35], v[176:179], v[212:215], v[32:35]
	v_mfma_f32_16x16x32_bf16 v[32:35], v[184:187], v[216:219], v[32:35]
	s_setprio 0
	s_add_i32 s64, s79, s68
	v_lshl_add_u64 v[220:221], v[220:221], 0, s[12:13]
	s_mov_b32 m0, s64
	ds_read_b128 v[188:191], v150 offset:49152
	ds_read_b128 v[192:195], v150 offset:50176
	ds_read_b128 v[196:199], v150 offset:51200
	ds_read_b128 v[200:203], v150 offset:52224
	ds_read_b128 v[204:207], v150 offset:53248
	ds_read_b128 v[208:211], v150 offset:54272
	ds_read_b128 v[212:215], v150 offset:55296
	ds_read_b128 v[216:219], v150 offset:56320
	global_load_lds_dwordx4 v[220:221], off
	s_add_i32 m0, s64, 0x2000
	s_add_u32 s62, s62, 0x40080
	v_lshl_add_u64 v[220:221], v[222:223], 0, s[12:13]
	s_addc_u32 s63, s63, 0
	s_add_i32 s64, s88, s68
	global_load_lds_dwordx4 v[220:221], off
	v_lshl_add_u64 v[220:221], s[62:63], 0, v[130:131]
	s_mov_b32 m0, s64
	s_nop 0
	global_load_lds_dwordx4 v[220:221], off
	v_lshl_add_u64 v[220:221], s[62:63], 0, v[134:135]
	s_add_i32 m0, s64, 0x2000
	s_nop 0
	global_load_lds_dwordx4 v[220:221], off
	v_lshl_add_u64 v[220:221], v[224:225], 0, s[12:13]
	s_mov_b32 m0, s75
	s_nop 0
	global_load_lds_dwordx4 v[220:221], off
	v_lshl_add_u64 v[220:221], v[226:227], 0, s[12:13]
	s_mov_b32 m0, s76
	s_nop 0
	global_load_lds_dwordx4 v[220:221], off
	s_waitcnt vmcnt(8)
	s_waitcnt lgkmcnt(0)
	s_barrier
	s_setprio 1
	s_waitcnt lgkmcnt(0)
	v_mfma_f32_16x16x32_bf16 v[92:95], v[152:155], v[188:191], v[92:95]
	v_mfma_f32_16x16x32_bf16 v[92:95], v[156:159], v[192:195], v[92:95]
	v_mfma_f32_16x16x32_bf16 v[88:91], v[160:163], v[188:191], v[88:91]
	v_mfma_f32_16x16x32_bf16 v[88:91], v[164:167], v[192:195], v[88:91]
	v_mfma_f32_16x16x32_bf16 v[84:87], v[152:155], v[196:199], v[84:87]
	v_mfma_f32_16x16x32_bf16 v[84:87], v[156:159], v[200:203], v[84:87]
	v_mfma_f32_16x16x32_bf16 v[80:83], v[160:163], v[196:199], v[80:83]
	v_mfma_f32_16x16x32_bf16 v[80:83], v[164:167], v[200:203], v[80:83]
	v_mfma_f32_16x16x32_bf16 v[76:79], v[152:155], v[204:207], v[76:79]
	v_mfma_f32_16x16x32_bf16 v[76:79], v[156:159], v[208:211], v[76:79]
	v_mfma_f32_16x16x32_bf16 v[72:75], v[160:163], v[204:207], v[72:75]
	v_mfma_f32_16x16x32_bf16 v[72:75], v[164:167], v[208:211], v[72:75]
	v_mfma_f32_16x16x32_bf16 v[60:63], v[152:155], v[212:215], v[60:63]
	v_mfma_f32_16x16x32_bf16 v[60:63], v[156:159], v[216:219], v[60:63]
	v_mfma_f32_16x16x32_bf16 v[56:59], v[160:163], v[212:215], v[56:59]
	v_mfma_f32_16x16x32_bf16 v[56:59], v[164:167], v[216:219], v[56:59]
	v_mfma_f32_16x16x32_bf16 v[28:31], v[168:171], v[188:191], v[28:31]
	v_mfma_f32_16x16x32_bf16 v[28:31], v[172:175], v[192:195], v[28:31]
	v_mfma_f32_16x16x32_bf16 v[24:27], v[176:179], v[188:191], v[24:27]
	v_mfma_f32_16x16x32_bf16 v[24:27], v[184:187], v[192:195], v[24:27]
	v_mfma_f32_16x16x32_bf16 v[20:23], v[168:171], v[196:199], v[20:23]
	v_mfma_f32_16x16x32_bf16 v[20:23], v[172:175], v[200:203], v[20:23]
	v_mfma_f32_16x16x32_bf16 v[16:19], v[176:179], v[196:199], v[16:19]
	v_mfma_f32_16x16x32_bf16 v[16:19], v[184:187], v[200:203], v[16:19]
	v_mfma_f32_16x16x32_bf16 v[12:15], v[168:171], v[204:207], v[12:15]
	v_mfma_f32_16x16x32_bf16 v[12:15], v[172:175], v[208:211], v[12:15]
	v_mfma_f32_16x16x32_bf16 v[8:11], v[176:179], v[204:207], v[8:11]
	v_mfma_f32_16x16x32_bf16 v[8:11], v[184:187], v[208:211], v[8:11]
	s_setprio 2
	s_barrier
	v_mfma_f32_16x16x32_bf16 v[4:7], v[168:171], v[212:215], v[4:7]
	v_mfma_f32_16x16x32_bf16 v[4:7], v[172:175], v[216:219], v[4:7]
	v_mfma_f32_16x16x32_bf16 v[0:3], v[176:179], v[212:215], v[0:3]
	v_mfma_f32_16x16x32_bf16 v[0:3], v[184:187], v[216:219], v[0:3]
	s_setprio 0
	s_add_i32 s87, s87, 2
	s_add_u32 s60, s60, 0x100
	s_addc_u32 s61, s61, 0
	s_add_u32 s85, s85, 0x100
	s_addc_u32 s86, s86, 0
	s_cmp_gt_u32 s87, 13
	s_cbranch_scc0 .LBB0_1162
	s_and_b64 vcc, exec, s[16:17]
	s_cbranch_vccz .LBB0_1165
	s_barrier

.LBB0_1310:
	s_ashr_i32 s49, s48, 31
	s_lshl_b64 s[50:51], s[48:49], 19
	s_add_u32 s50, s38, s50
	s_addc_u32 s51, s39, s51
	s_and_b64 s[52:53], s[10:11], exec
	s_cselect_b32 s49, s51, s57
	s_cselect_b32 s82, s50, s56
	s_ashr_i32 s47, s46, 31
	s_lshl_b64 s[52:53], s[46:47], 19
	s_add_u32 s52, s62, s52
	s_addc_u32 s53, s63, s53
	s_and_b64 s[60:61], s[10:11], exec
	s_cselect_b32 s47, s53, s59
	s_cselect_b32 s83, s52, s58
	s_add_u32 s56, s56, 0x40080
	s_addc_u32 s57, s57, 0
	s_add_u32 s84, s58, 0x100
	s_addc_u32 s85, s59, 0
	s_mov_b32 s86, -2
	ds_read_b128 v[152:155], v149
	ds_read_b128 v[156:159], v149 offset:1024
	ds_read_b128 v[160:163], v149 offset:2048
	ds_read_b128 v[164:167], v149 offset:3072
	ds_read_b128 v[168:171], v150
	ds_read_b128 v[172:175], v150 offset:1024
	ds_read_b128 v[176:179], v150 offset:2048
	ds_read_b128 v[184:187], v150 offset:3072
	s_add_u32 s58, s56, 0xfffc0080
	s_addc_u32 s59, s57, -1
	s_cmp_eq_u32 s86, 12
	s_cselect_b32 s61, s49, s59
	s_cselect_b32 s60, s82, s58
	s_cselect_b32 s59, s47, s85
	s_cselect_b32 s58, s83, s84
	v_lshl_add_u64 v[144:145], s[56:57], 0, v[136:137]
	s_add_i32 m0, s55, 0xc000
	ds_read_b128 v[188:191], v151
	ds_read_b128 v[192:195], v151 offset:1024
	ds_read_b128 v[196:199], v151 offset:2048
	ds_read_b128 v[200:203], v151 offset:3072
	ds_read_b128 v[204:207], v151 offset:4096
	ds_read_b128 v[208:211], v151 offset:5120
	ds_read_b128 v[212:215], v151 offset:6144
	ds_read_b128 v[216:219], v151 offset:7168
	global_load_lds_dwordx4 v[144:145], off
	v_lshl_add_u64 v[144:145], s[56:57], 0, v[138:139]
	s_add_i32 m0, s55, 0xe000
	s_nop 0
	global_load_lds_dwordx4 v[144:145], off
	s_waitcnt vmcnt(8)
	s_waitcnt lgkmcnt(0)
	s_barrier
	s_setprio 1
	s_waitcnt lgkmcnt(0)
	v_mfma_f32_16x16x32_bf16 v[124:127], v[152:155], v[188:191], 0
	v_mfma_f32_16x16x32_bf16 v[124:127], v[156:159], v[192:195], v[124:127]
	v_mfma_f32_16x16x32_bf16 v[120:123], v[160:163], v[188:191], 0
	v_mfma_f32_16x16x32_bf16 v[120:123], v[164:167], v[192:195], v[120:123]
	v_mfma_f32_16x16x32_bf16 v[116:119], v[152:155], v[196:199], 0
	v_mfma_f32_16x16x32_bf16 v[116:119], v[156:159], v[200:203], v[116:119]
	v_mfma_f32_16x16x32_bf16 v[108:111], v[160:163], v[196:199], 0
	v_mfma_f32_16x16x32_bf16 v[108:111], v[164:167], v[200:203], v[108:111]
	v_mfma_f32_16x16x32_bf16 v[100:103], v[152:155], v[204:207], 0
	v_mfma_f32_16x16x32_bf16 v[100:103], v[156:159], v[208:211], v[100:103]
	v_mfma_f32_16x16x32_bf16 v[92:95], v[160:163], v[204:207], 0
	v_mfma_f32_16x16x32_bf16 v[92:95], v[164:167], v[208:211], v[92:95]
	v_mfma_f32_16x16x32_bf16 v[84:87], v[152:155], v[212:215], 0
	v_mfma_f32_16x16x32_bf16 v[84:87], v[156:159], v[216:219], v[84:87]
	v_mfma_f32_16x16x32_bf16 v[76:79], v[160:163], v[212:215], 0
	v_mfma_f32_16x16x32_bf16 v[76:79], v[164:167], v[216:219], v[76:79]
	v_mfma_f32_16x16x32_bf16 v[112:115], v[168:171], v[188:191], 0
	v_mfma_f32_16x16x32_bf16 v[112:115], v[172:175], v[192:195], v[112:115]
	v_mfma_f32_16x16x32_bf16 v[104:107], v[176:179], v[188:191], 0
	v_mfma_f32_16x16x32_bf16 v[104:107], v[184:187], v[192:195], v[104:107]
	v_mfma_f32_16x16x32_bf16 v[96:99], v[168:171], v[196:199], 0
	v_mfma_f32_16x16x32_bf16 v[96:99], v[172:175], v[200:203], v[96:99]
	v_mfma_f32_16x16x32_bf16 v[88:91], v[176:179], v[196:199], 0
	v_mfma_f32_16x16x32_bf16 v[88:91], v[184:187], v[200:203], v[88:91]
	v_mfma_f32_16x16x32_bf16 v[80:83], v[168:171], v[204:207], 0
	v_mfma_f32_16x16x32_bf16 v[80:83], v[172:175], v[208:211], v[80:83]
	v_mfma_f32_16x16x32_bf16 v[72:75], v[176:179], v[204:207], 0
	v_mfma_f32_16x16x32_bf16 v[72:75], v[184:187], v[208:211], v[72:75]
	s_setprio 2
	s_barrier
	v_mfma_f32_16x16x32_bf16 v[68:71], v[168:171], v[212:215], 0
	v_mfma_f32_16x16x32_bf16 v[68:71], v[172:175], v[216:219], v[68:71]
	v_mfma_f32_16x16x32_bf16 v[64:67], v[176:179], v[212:215], 0
	v_mfma_f32_16x16x32_bf16 v[64:67], v[184:187], v[216:219], v[64:67]
	s_setprio 0
	s_add_i32 s79, s71, s64
	v_lshl_add_u64 v[144:145], s[58:59], 0, v[130:131]
	s_mov_b32 m0, s79
	ds_read_b128 v[188:191], v151 offset:16384
	ds_read_b128 v[192:195], v151 offset:17408
	ds_read_b128 v[196:199], v151 offset:18432
	ds_read_b128 v[200:203], v151 offset:19456
	ds_read_b128 v[204:207], v151 offset:20480
	ds_read_b128 v[208:211], v151 offset:21504
	ds_read_b128 v[212:215], v151 offset:22528
	ds_read_b128 v[216:219], v151 offset:23552
	global_load_lds_dwordx4 v[144:145], off
	s_add_i32 m0, s79, 0x2000
	s_add_u32 s88, s58, 0x40000
	v_lshl_add_u64 v[220:221], s[58:59], 0, v[134:135]
	s_addc_u32 s89, s59, 0
	s_add_i32 s79, s72, s64
	global_load_lds_dwordx4 v[220:221], off
	v_lshl_add_u64 v[222:223], s[88:89], 0, v[130:131]
	s_mov_b32 m0, s79
	v_lshl_add_u64 v[224:225], s[60:61], 0, v[132:133]
	global_load_lds_dwordx4 v[222:223], off
	v_lshl_add_u64 v[222:223], s[88:89], 0, v[134:135]
	s_add_i32 m0, s79, 0x2000
	s_nop 0
	global_load_lds_dwordx4 v[222:223], off
	v_lshl_add_u64 v[222:223], s[60:61], 0, v[128:129]
	s_mov_b32 m0, s55
	s_nop 0
	global_load_lds_dwordx4 v[222:223], off
	s_mov_b32 m0, s65
	s_nop 0
	global_load_lds_dwordx4 v[224:225], off
	s_waitcnt vmcnt(8)
	s_waitcnt lgkmcnt(0)
	s_barrier
	s_setprio 1
	s_waitcnt lgkmcnt(0)
	v_mfma_f32_16x16x32_bf16 v[60:63], v[152:155], v[188:191], 0
	v_mfma_f32_16x16x32_bf16 v[60:63], v[156:159], v[192:195], v[60:63]
	v_mfma_f32_16x16x32_bf16 v[56:59], v[160:163], v[188:191], 0
	v_mfma_f32_16x16x32_bf16 v[56:59], v[164:167], v[192:195], v[56:59]
	v_mfma_f32_16x16x32_bf16 v[52:55], v[152:155], v[196:199], 0
	v_mfma_f32_16x16x32_bf16 v[52:55], v[156:159], v[200:203], v[52:55]
	v_mfma_f32_16x16x32_bf16 v[44:47], v[160:163], v[196:199], 0
	v_mfma_f32_16x16x32_bf16 v[44:47], v[164:167], v[200:203], v[44:47]
	v_mfma_f32_16x16x32_bf16 v[36:39], v[152:155], v[204:207], 0
	v_mfma_f32_16x16x32_bf16 v[36:39], v[156:159], v[208:211], v[36:39]
	v_mfma_f32_16x16x32_bf16 v[28:31], v[160:163], v[204:207], 0
	v_mfma_f32_16x16x32_bf16 v[28:31], v[164:167], v[208:211], v[28:31]
	v_mfma_f32_16x16x32_bf16 v[20:23], v[152:155], v[212:215], 0
	v_mfma_f32_16x16x32_bf16 v[20:23], v[156:159], v[216:219], v[20:23]
	v_mfma_f32_16x16x32_bf16 v[12:15], v[160:163], v[212:215], 0
	v_mfma_f32_16x16x32_bf16 v[12:15], v[164:167], v[216:219], v[12:15]
	v_mfma_f32_16x16x32_bf16 v[48:51], v[168:171], v[188:191], 0
	v_mfma_f32_16x16x32_bf16 v[48:51], v[172:175], v[192:195], v[48:51]
	v_mfma_f32_16x16x32_bf16 v[40:43], v[176:179], v[188:191], 0
	v_mfma_f32_16x16x32_bf16 v[40:43], v[184:187], v[192:195], v[40:43]
	v_mfma_f32_16x16x32_bf16 v[32:35], v[168:171], v[196:199], 0
	v_mfma_f32_16x16x32_bf16 v[32:35], v[172:175], v[200:203], v[32:35]
	v_mfma_f32_16x16x32_bf16 v[24:27], v[176:179], v[196:199], 0
	v_mfma_f32_16x16x32_bf16 v[24:27], v[184:187], v[200:203], v[24:27]
	v_mfma_f32_16x16x32_bf16 v[16:19], v[168:171], v[204:207], 0
	v_mfma_f32_16x16x32_bf16 v[16:19], v[172:175], v[208:211], v[16:19]
	v_mfma_f32_16x16x32_bf16 v[8:11], v[176:179], v[204:207], 0
	v_mfma_f32_16x16x32_bf16 v[8:11], v[184:187], v[208:211], v[8:11]
	s_setprio 2
	s_barrier
	v_mfma_f32_16x16x32_bf16 v[4:7], v[168:171], v[212:215], 0
	v_mfma_f32_16x16x32_bf16 v[4:7], v[172:175], v[216:219], v[4:7]
	v_mfma_f32_16x16x32_bf16 v[0:3], v[176:179], v[212:215], 0
	v_mfma_f32_16x16x32_bf16 v[0:3], v[184:187], v[216:219], v[0:3]
	s_setprio 0
	s_branch .Lmid_gemm10
.LBB0_1311:
	ds_read_b128 v[152:155], v149
	ds_read_b128 v[156:159], v149 offset:1024
	ds_read_b128 v[160:163], v149 offset:2048
	ds_read_b128 v[164:167], v149 offset:3072
	ds_read_b128 v[168:171], v150
	ds_read_b128 v[172:175], v150 offset:1024
	ds_read_b128 v[176:179], v150 offset:2048
	ds_read_b128 v[184:187], v150 offset:3072
	s_add_u32 s58, s56, 0xfffc0080
	s_addc_u32 s59, s57, -1
	s_cmp_eq_u32 s86, 12
	s_cselect_b32 s61, s49, s59
	s_cselect_b32 s60, s82, s58
	s_cselect_b32 s59, s47, s85
	s_cselect_b32 s58, s83, s84
	v_lshl_add_u64 v[144:145], s[56:57], 0, v[136:137]
	s_add_i32 m0, s55, 0xc000
	ds_read_b128 v[188:191], v151
	ds_read_b128 v[192:195], v151 offset:1024
	ds_read_b128 v[196:199], v151 offset:2048
	ds_read_b128 v[200:203], v151 offset:3072
	ds_read_b128 v[204:207], v151 offset:4096
	ds_read_b128 v[208:211], v151 offset:5120
	ds_read_b128 v[212:215], v151 offset:6144
	ds_read_b128 v[216:219], v151 offset:7168
	global_load_lds_dwordx4 v[144:145], off
	v_lshl_add_u64 v[144:145], s[56:57], 0, v[138:139]
	s_add_i32 m0, s55, 0xe000
	s_nop 0
	global_load_lds_dwordx4 v[144:145], off
	s_waitcnt vmcnt(8)
	s_waitcnt lgkmcnt(0)
	s_barrier
	s_setprio 1
	s_waitcnt lgkmcnt(0)
	v_mfma_f32_16x16x32_bf16 v[124:127], v[152:155], v[188:191], v[124:127]
	v_mfma_f32_16x16x32_bf16 v[124:127], v[156:159], v[192:195], v[124:127]
	v_mfma_f32_16x16x32_bf16 v[120:123], v[160:163], v[188:191], v[120:123]
	v_mfma_f32_16x16x32_bf16 v[120:123], v[164:167], v[192:195], v[120:123]
	v_mfma_f32_16x16x32_bf16 v[116:119], v[152:155], v[196:199], v[116:119]
	v_mfma_f32_16x16x32_bf16 v[116:119], v[156:159], v[200:203], v[116:119]
	v_mfma_f32_16x16x32_bf16 v[108:111], v[160:163], v[196:199], v[108:111]
	v_mfma_f32_16x16x32_bf16 v[108:111], v[164:167], v[200:203], v[108:111]
	v_mfma_f32_16x16x32_bf16 v[100:103], v[152:155], v[204:207], v[100:103]
	v_mfma_f32_16x16x32_bf16 v[100:103], v[156:159], v[208:211], v[100:103]
	v_mfma_f32_16x16x32_bf16 v[92:95], v[160:163], v[204:207], v[92:95]
	v_mfma_f32_16x16x32_bf16 v[92:95], v[164:167], v[208:211], v[92:95]
	v_mfma_f32_16x16x32_bf16 v[84:87], v[152:155], v[212:215], v[84:87]
	v_mfma_f32_16x16x32_bf16 v[84:87], v[156:159], v[216:219], v[84:87]
	v_mfma_f32_16x16x32_bf16 v[76:79], v[160:163], v[212:215], v[76:79]
	v_mfma_f32_16x16x32_bf16 v[76:79], v[164:167], v[216:219], v[76:79]
	v_mfma_f32_16x16x32_bf16 v[112:115], v[168:171], v[188:191], v[112:115]
	v_mfma_f32_16x16x32_bf16 v[112:115], v[172:175], v[192:195], v[112:115]
	v_mfma_f32_16x16x32_bf16 v[104:107], v[176:179], v[188:191], v[104:107]
	v_mfma_f32_16x16x32_bf16 v[104:107], v[184:187], v[192:195], v[104:107]
	v_mfma_f32_16x16x32_bf16 v[96:99], v[168:171], v[196:199], v[96:99]
	v_mfma_f32_16x16x32_bf16 v[96:99], v[172:175], v[200:203], v[96:99]
	v_mfma_f32_16x16x32_bf16 v[88:91], v[176:179], v[196:199], v[88:91]
	v_mfma_f32_16x16x32_bf16 v[88:91], v[184:187], v[200:203], v[88:91]
	v_mfma_f32_16x16x32_bf16 v[80:83], v[168:171], v[204:207], v[80:83]
	v_mfma_f32_16x16x32_bf16 v[80:83], v[172:175], v[208:211], v[80:83]
	v_mfma_f32_16x16x32_bf16 v[72:75], v[176:179], v[204:207], v[72:75]
	v_mfma_f32_16x16x32_bf16 v[72:75], v[184:187], v[208:211], v[72:75]
	s_setprio 2
	s_barrier
	v_mfma_f32_16x16x32_bf16 v[68:71], v[168:171], v[212:215], v[68:71]
	v_mfma_f32_16x16x32_bf16 v[68:71], v[172:175], v[216:219], v[68:71]
	v_mfma_f32_16x16x32_bf16 v[64:67], v[176:179], v[212:215], v[64:67]
	v_mfma_f32_16x16x32_bf16 v[64:67], v[184:187], v[216:219], v[64:67]
	s_setprio 0
	s_add_i32 s79, s71, s64
	v_lshl_add_u64 v[144:145], s[58:59], 0, v[130:131]
	s_mov_b32 m0, s79
	ds_read_b128 v[188:191], v151 offset:16384
	ds_read_b128 v[192:195], v151 offset:17408
	ds_read_b128 v[196:199], v151 offset:18432
	ds_read_b128 v[200:203], v151 offset:19456
	ds_read_b128 v[204:207], v151 offset:20480
	ds_read_b128 v[208:211], v151 offset:21504
	ds_read_b128 v[212:215], v151 offset:22528
	ds_read_b128 v[216:219], v151 offset:23552
	global_load_lds_dwordx4 v[144:145], off
	s_add_i32 m0, s79, 0x2000
	s_add_u32 s88, s58, 0x40000
	v_lshl_add_u64 v[220:221], s[58:59], 0, v[134:135]
	s_addc_u32 s89, s59, 0
	s_add_i32 s79, s72, s64
	global_load_lds_dwordx4 v[220:221], off
	v_lshl_add_u64 v[222:223], s[88:89], 0, v[130:131]
	s_mov_b32 m0, s79
	v_lshl_add_u64 v[224:225], s[60:61], 0, v[132:133]
	global_load_lds_dwordx4 v[222:223], off
	v_lshl_add_u64 v[222:223], s[88:89], 0, v[134:135]
	s_add_i32 m0, s79, 0x2000
	s_nop 0
	global_load_lds_dwordx4 v[222:223], off
	v_lshl_add_u64 v[222:223], s[60:61], 0, v[128:129]
	s_mov_b32 m0, s55
	s_nop 0
	global_load_lds_dwordx4 v[222:223], off
	s_mov_b32 m0, s65
	s_nop 0
	global_load_lds_dwordx4 v[224:225], off
	s_waitcnt vmcnt(8)
	s_waitcnt lgkmcnt(0)
	s_barrier
	s_setprio 1
	s_waitcnt lgkmcnt(0)
	v_mfma_f32_16x16x32_bf16 v[60:63], v[152:155], v[188:191], v[60:63]
	v_mfma_f32_16x16x32_bf16 v[60:63], v[156:159], v[192:195], v[60:63]
	v_mfma_f32_16x16x32_bf16 v[56:59], v[160:163], v[188:191], v[56:59]
	v_mfma_f32_16x16x32_bf16 v[56:59], v[164:167], v[192:195], v[56:59]
	v_mfma_f32_16x16x32_bf16 v[52:55], v[152:155], v[196:199], v[52:55]
	v_mfma_f32_16x16x32_bf16 v[52:55], v[156:159], v[200:203], v[52:55]
	v_mfma_f32_16x16x32_bf16 v[44:47], v[160:163], v[196:199], v[44:47]
	v_mfma_f32_16x16x32_bf16 v[44:47], v[164:167], v[200:203], v[44:47]
	v_mfma_f32_16x16x32_bf16 v[36:39], v[152:155], v[204:207], v[36:39]
	v_mfma_f32_16x16x32_bf16 v[36:39], v[156:159], v[208:211], v[36:39]
	v_mfma_f32_16x16x32_bf16 v[28:31], v[160:163], v[204:207], v[28:31]
	v_mfma_f32_16x16x32_bf16 v[28:31], v[164:167], v[208:211], v[28:31]
	v_mfma_f32_16x16x32_bf16 v[20:23], v[152:155], v[212:215], v[20:23]
	v_mfma_f32_16x16x32_bf16 v[20:23], v[156:159], v[216:219], v[20:23]
	v_mfma_f32_16x16x32_bf16 v[12:15], v[160:163], v[212:215], v[12:15]
	v_mfma_f32_16x16x32_bf16 v[12:15], v[164:167], v[216:219], v[12:15]
	v_mfma_f32_16x16x32_bf16 v[48:51], v[168:171], v[188:191], v[48:51]
	v_mfma_f32_16x16x32_bf16 v[48:51], v[172:175], v[192:195], v[48:51]
	v_mfma_f32_16x16x32_bf16 v[40:43], v[176:179], v[188:191], v[40:43]
	v_mfma_f32_16x16x32_bf16 v[40:43], v[184:187], v[192:195], v[40:43]
	v_mfma_f32_16x16x32_bf16 v[32:35], v[168:171], v[196:199], v[32:35]
	v_mfma_f32_16x16x32_bf16 v[32:35], v[172:175], v[200:203], v[32:35]
	v_mfma_f32_16x16x32_bf16 v[24:27], v[176:179], v[196:199], v[24:27]
	v_mfma_f32_16x16x32_bf16 v[24:27], v[184:187], v[200:203], v[24:27]
	v_mfma_f32_16x16x32_bf16 v[16:19], v[168:171], v[204:207], v[16:19]
	v_mfma_f32_16x16x32_bf16 v[16:19], v[172:175], v[208:211], v[16:19]
	v_mfma_f32_16x16x32_bf16 v[8:11], v[176:179], v[204:207], v[8:11]
	v_mfma_f32_16x16x32_bf16 v[8:11], v[184:187], v[208:211], v[8:11]
	s_setprio 2
	s_barrier
	v_mfma_f32_16x16x32_bf16 v[4:7], v[168:171], v[212:215], v[4:7]
	v_mfma_f32_16x16x32_bf16 v[4:7], v[172:175], v[216:219], v[4:7]
	v_mfma_f32_16x16x32_bf16 v[0:3], v[176:179], v[212:215], v[0:3]
	v_mfma_f32_16x16x32_bf16 v[0:3], v[184:187], v[216:219], v[0:3]
	s_setprio 0
.Lmid_gemm10:
	s_add_i32 s79, 0, 0x18000
	s_add_i32 s87, 0, 0x1c000
	v_add_u32_e32 v164, s79, v147
	v_add_u32_e32 v181, s87, v147
	ds_read_b128 v[152:155], v164
	ds_read_b128 v[156:159], v164 offset:1024
	ds_read_b128 v[160:163], v164 offset:2048
	ds_read_b128 v[164:167], v164 offset:3072
	ds_read_b128 v[168:171], v181
	ds_read_b128 v[172:175], v181 offset:1024
	ds_read_b128 v[176:179], v181 offset:2048
	ds_read_b128 v[184:187], v181 offset:3072
	s_add_u32 s60, s60, 0x40000
	s_addc_u32 s61, s61, 0
	s_mov_b32 m0, s66
	v_lshl_add_u64 v[226:227], s[60:61], 0, v[128:129]
	ds_read_b128 v[188:191], v151 offset:32768
	ds_read_b128 v[192:195], v151 offset:33792
	ds_read_b128 v[196:199], v151 offset:34816
	ds_read_b128 v[200:203], v151 offset:35840
	ds_read_b128 v[204:207], v151 offset:36864
	ds_read_b128 v[208:211], v151 offset:37888
	ds_read_b128 v[212:215], v151 offset:38912
	ds_read_b128 v[216:219], v151 offset:39936
	global_load_lds_dwordx4 v[226:227], off
	v_lshl_add_u64 v[226:227], s[60:61], 0, v[132:133]
	s_mov_b32 m0, s67
	s_nop 0
	global_load_lds_dwordx4 v[226:227], off
	s_waitcnt vmcnt(8)
	s_waitcnt lgkmcnt(0)
	s_barrier
	s_setprio 1
	s_waitcnt lgkmcnt(0)
	v_mfma_f32_16x16x32_bf16 v[124:127], v[152:155], v[188:191], v[124:127]
	v_mfma_f32_16x16x32_bf16 v[124:127], v[156:159], v[192:195], v[124:127]
	v_mfma_f32_16x16x32_bf16 v[120:123], v[160:163], v[188:191], v[120:123]
	v_mfma_f32_16x16x32_bf16 v[120:123], v[164:167], v[192:195], v[120:123]
	v_mfma_f32_16x16x32_bf16 v[116:119], v[152:155], v[196:199], v[116:119]
	v_mfma_f32_16x16x32_bf16 v[116:119], v[156:159], v[200:203], v[116:119]
	v_mfma_f32_16x16x32_bf16 v[108:111], v[160:163], v[196:199], v[108:111]
	v_mfma_f32_16x16x32_bf16 v[108:111], v[164:167], v[200:203], v[108:111]
	v_mfma_f32_16x16x32_bf16 v[100:103], v[152:155], v[204:207], v[100:103]
	v_mfma_f32_16x16x32_bf16 v[100:103], v[156:159], v[208:211], v[100:103]
	v_mfma_f32_16x16x32_bf16 v[92:95], v[160:163], v[204:207], v[92:95]
	v_mfma_f32_16x16x32_bf16 v[92:95], v[164:167], v[208:211], v[92:95]
	v_mfma_f32_16x16x32_bf16 v[84:87], v[152:155], v[212:215], v[84:87]
	v_mfma_f32_16x16x32_bf16 v[84:87], v[156:159], v[216:219], v[84:87]
	v_mfma_f32_16x16x32_bf16 v[76:79], v[160:163], v[212:215], v[76:79]
	v_mfma_f32_16x16x32_bf16 v[76:79], v[164:167], v[216:219], v[76:79]
	v_mfma_f32_16x16x32_bf16 v[112:115], v[168:171], v[188:191], v[112:115]
	v_mfma_f32_16x16x32_bf16 v[112:115], v[172:175], v[192:195], v[112:115]
	v_mfma_f32_16x16x32_bf16 v[104:107], v[176:179], v[188:191], v[104:107]
	v_mfma_f32_16x16x32_bf16 v[104:107], v[184:187], v[192:195], v[104:107]
	v_mfma_f32_16x16x32_bf16 v[96:99], v[168:171], v[196:199], v[96:99]
	v_mfma_f32_16x16x32_bf16 v[96:99], v[172:175], v[200:203], v[96:99]
	v_mfma_f32_16x16x32_bf16 v[88:91], v[176:179], v[196:199], v[88:91]
	v_mfma_f32_16x16x32_bf16 v[88:91], v[184:187], v[200:203], v[88:91]
	v_mfma_f32_16x16x32_bf16 v[80:83], v[168:171], v[204:207], v[80:83]
	v_mfma_f32_16x16x32_bf16 v[80:83], v[172:175], v[208:211], v[80:83]
	v_mfma_f32_16x16x32_bf16 v[72:75], v[176:179], v[204:207], v[72:75]
	v_mfma_f32_16x16x32_bf16 v[72:75], v[184:187], v[208:211], v[72:75]
	s_setprio 2
	s_barrier
	v_mfma_f32_16x16x32_bf16 v[68:71], v[168:171], v[212:215], v[68:71]
	v_mfma_f32_16x16x32_bf16 v[68:71], v[172:175], v[216:219], v[68:71]
	v_mfma_f32_16x16x32_bf16 v[64:67], v[176:179], v[212:215], v[64:67]
	v_mfma_f32_16x16x32_bf16 v[64:67], v[184:187], v[216:219], v[64:67]
	s_setprio 0
	s_add_i32 s60, s79, s64
	v_lshl_add_u64 v[144:145], v[144:145], 0, s[16:17]
	s_mov_b32 m0, s60
	ds_read_b128 v[188:191], v151 offset:49152
	ds_read_b128 v[192:195], v151 offset:50176
	ds_read_b128 v[196:199], v151 offset:51200
	ds_read_b128 v[200:203], v151 offset:52224
	ds_read_b128 v[204:207], v151 offset:53248
	ds_read_b128 v[208:211], v151 offset:54272
	ds_read_b128 v[212:215], v151 offset:55296
	ds_read_b128 v[216:219], v151 offset:56320
	global_load_lds_dwordx4 v[144:145], off
	s_add_i32 m0, s60, 0x2000
	s_add_u32 s58, s58, 0x40080
	v_lshl_add_u64 v[144:145], v[220:221], 0, s[16:17]
	s_addc_u32 s59, s59, 0
	s_add_i32 s60, s87, s64
	global_load_lds_dwordx4 v[144:145], off
	v_lshl_add_u64 v[144:145], s[58:59], 0, v[130:131]
	s_mov_b32 m0, s60
	s_nop 0
	global_load_lds_dwordx4 v[144:145], off
	v_lshl_add_u64 v[144:145], s[58:59], 0, v[134:135]
	s_add_i32 m0, s60, 0x2000
	s_nop 0
	global_load_lds_dwordx4 v[144:145], off
	v_lshl_add_u64 v[144:145], v[222:223], 0, s[16:17]
	s_mov_b32 m0, s69
	s_nop 0
	global_load_lds_dwordx4 v[144:145], off
	v_lshl_add_u64 v[144:145], v[224:225], 0, s[16:17]
	s_mov_b32 m0, s70
	s_nop 0
	global_load_lds_dwordx4 v[144:145], off
	s_waitcnt vmcnt(8)
	s_waitcnt lgkmcnt(0)
	s_barrier
	s_setprio 1
	s_waitcnt lgkmcnt(0)
	v_mfma_f32_16x16x32_bf16 v[60:63], v[152:155], v[188:191], v[60:63]
	v_mfma_f32_16x16x32_bf16 v[60:63], v[156:159], v[192:195], v[60:63]
	v_mfma_f32_16x16x32_bf16 v[56:59], v[160:163], v[188:191], v[56:59]
	v_mfma_f32_16x16x32_bf16 v[56:59], v[164:167], v[192:195], v[56:59]
	v_mfma_f32_16x16x32_bf16 v[52:55], v[152:155], v[196:199], v[52:55]
	v_mfma_f32_16x16x32_bf16 v[52:55], v[156:159], v[200:203], v[52:55]
	v_mfma_f32_16x16x32_bf16 v[44:47], v[160:163], v[196:199], v[44:47]
	v_mfma_f32_16x16x32_bf16 v[44:47], v[164:167], v[200:203], v[44:47]
	v_mfma_f32_16x16x32_bf16 v[36:39], v[152:155], v[204:207], v[36:39]
	v_mfma_f32_16x16x32_bf16 v[36:39], v[156:159], v[208:211], v[36:39]
	v_mfma_f32_16x16x32_bf16 v[28:31], v[160:163], v[204:207], v[28:31]
	v_mfma_f32_16x16x32_bf16 v[28:31], v[164:167], v[208:211], v[28:31]
	v_mfma_f32_16x16x32_bf16 v[20:23], v[152:155], v[212:215], v[20:23]
	v_mfma_f32_16x16x32_bf16 v[20:23], v[156:159], v[216:219], v[20:23]
	v_mfma_f32_16x16x32_bf16 v[12:15], v[160:163], v[212:215], v[12:15]
	v_mfma_f32_16x16x32_bf16 v[12:15], v[164:167], v[216:219], v[12:15]
	v_mfma_f32_16x16x32_bf16 v[48:51], v[168:171], v[188:191], v[48:51]
	v_mfma_f32_16x16x32_bf16 v[48:51], v[172:175], v[192:195], v[48:51]
	v_mfma_f32_16x16x32_bf16 v[40:43], v[176:179], v[188:191], v[40:43]
	v_mfma_f32_16x16x32_bf16 v[40:43], v[184:187], v[192:195], v[40:43]
	v_mfma_f32_16x16x32_bf16 v[32:35], v[168:171], v[196:199], v[32:35]
	v_mfma_f32_16x16x32_bf16 v[32:35], v[172:175], v[200:203], v[32:35]
	v_mfma_f32_16x16x32_bf16 v[24:27], v[176:179], v[196:199], v[24:27]
	v_mfma_f32_16x16x32_bf16 v[24:27], v[184:187], v[200:203], v[24:27]
	v_mfma_f32_16x16x32_bf16 v[16:19], v[168:171], v[204:207], v[16:19]
	v_mfma_f32_16x16x32_bf16 v[16:19], v[172:175], v[208:211], v[16:19]
	v_mfma_f32_16x16x32_bf16 v[8:11], v[176:179], v[204:207], v[8:11]
	v_mfma_f32_16x16x32_bf16 v[8:11], v[184:187], v[208:211], v[8:11]
	s_setprio 2
	s_barrier
	v_mfma_f32_16x16x32_bf16 v[4:7], v[168:171], v[212:215], v[4:7]
	v_mfma_f32_16x16x32_bf16 v[4:7], v[172:175], v[216:219], v[4:7]
	v_mfma_f32_16x16x32_bf16 v[0:3], v[176:179], v[212:215], v[0:3]
	v_mfma_f32_16x16x32_bf16 v[0:3], v[184:187], v[216:219], v[0:3]
	s_setprio 0
	s_add_i32 s86, s86, 2
	s_add_u32 s56, s56, 0x100
	s_addc_u32 s57, s57, 0
	s_add_u32 s84, s84, 0x100
	s_addc_u32 s85, s85, 0
	s_cmp_gt_u32 s86, 13
	s_cbranch_scc0 .LBB0_1311
	s_and_b64 vcc, exec, s[18:19]
	s_cbranch_vccz .LBB0_1314
	s_barrier

.LBB0_1433:
	s_ashr_i32 s19, s18, 31
	s_lshl_b64 s[30:31], s[18:19], 19
	s_add_u32 s30, s80, s30
	s_addc_u32 s31, s81, s31
	s_and_b64 s[36:37], s[8:9], exec
	s_cselect_b32 s19, s31, s47
	s_cselect_b32 s66, s30, s46
	s_ashr_i32 s17, s16, 31
	s_lshl_b64 s[36:37], s[16:17], 19
	s_add_u32 s36, s52, s36
	s_addc_u32 s37, s53, s37
	s_and_b64 s[50:51], s[8:9], exec
	s_cselect_b32 s17, s37, s49
	s_cselect_b32 s67, s36, s48
	s_add_u32 s46, s46, 0x40080
	s_addc_u32 s47, s47, 0
	s_add_u32 s68, s48, 0x100
	s_addc_u32 s69, s49, 0
	s_mov_b32 s70, -2
	ds_read_b128 v[140:143], v147
	ds_read_b128 v[150:153], v147 offset:1024
	ds_read_b128 v[154:157], v147 offset:2048
	ds_read_b128 v[158:161], v147 offset:3072
	ds_read_b128 v[162:165], v148
	ds_read_b128 v[166:169], v148 offset:1024
	ds_read_b128 v[170:173], v148 offset:2048
	ds_read_b128 v[174:177], v148 offset:3072
	s_add_u32 s48, s46, 0xfffc0080
	s_addc_u32 s49, s47, -1
	s_cmp_eq_u32 s70, 12
	s_cselect_b32 s51, s19, s49
	s_cselect_b32 s50, s66, s48
	s_cselect_b32 s49, s17, s69
	s_cselect_b32 s48, s67, s68
	v_lshl_add_u64 v[178:179], s[46:47], 0, v[132:133]
	s_add_i32 m0, s45, 0xc000
	ds_read_b128 v[184:187], v149
	ds_read_b128 v[188:191], v149 offset:1024
	ds_read_b128 v[192:195], v149 offset:2048
	ds_read_b128 v[196:199], v149 offset:3072
	ds_read_b128 v[200:203], v149 offset:4096
	ds_read_b128 v[204:207], v149 offset:5120
	ds_read_b128 v[208:211], v149 offset:6144
	ds_read_b128 v[212:215], v149 offset:7168
	global_load_lds_dwordx4 v[178:179], off
	v_lshl_add_u64 v[178:179], s[46:47], 0, v[134:135]
	s_add_i32 m0, s45, 0xe000
	s_nop 0
	global_load_lds_dwordx4 v[178:179], off
	s_waitcnt vmcnt(8)
	s_waitcnt lgkmcnt(0)
	s_barrier
	s_setprio 1
	s_waitcnt lgkmcnt(0)
	v_mfma_f32_16x16x32_bf16 v[124:127], v[140:143], v[184:187], 0
	v_mfma_f32_16x16x32_bf16 v[124:127], v[150:153], v[188:191], v[124:127]
	v_mfma_f32_16x16x32_bf16 v[120:123], v[154:157], v[184:187], 0
	v_mfma_f32_16x16x32_bf16 v[120:123], v[158:161], v[188:191], v[120:123]
	v_mfma_f32_16x16x32_bf16 v[108:111], v[140:143], v[192:195], 0
	v_mfma_f32_16x16x32_bf16 v[108:111], v[150:153], v[196:199], v[108:111]
	v_mfma_f32_16x16x32_bf16 v[104:107], v[154:157], v[192:195], 0
	v_mfma_f32_16x16x32_bf16 v[104:107], v[158:161], v[196:199], v[104:107]
	v_mfma_f32_16x16x32_bf16 v[92:95], v[140:143], v[200:203], 0
	v_mfma_f32_16x16x32_bf16 v[92:95], v[150:153], v[204:207], v[92:95]
	v_mfma_f32_16x16x32_bf16 v[88:91], v[154:157], v[200:203], 0
	v_mfma_f32_16x16x32_bf16 v[88:91], v[158:161], v[204:207], v[88:91]
	v_mfma_f32_16x16x32_bf16 v[76:79], v[140:143], v[208:211], 0
	v_mfma_f32_16x16x32_bf16 v[76:79], v[150:153], v[212:215], v[76:79]
	v_mfma_f32_16x16x32_bf16 v[72:75], v[154:157], v[208:211], 0
	v_mfma_f32_16x16x32_bf16 v[72:75], v[158:161], v[212:215], v[72:75]
	v_mfma_f32_16x16x32_bf16 v[116:119], v[162:165], v[184:187], 0
	v_mfma_f32_16x16x32_bf16 v[116:119], v[166:169], v[188:191], v[116:119]
	v_mfma_f32_16x16x32_bf16 v[112:115], v[170:173], v[184:187], 0
	v_mfma_f32_16x16x32_bf16 v[112:115], v[174:177], v[188:191], v[112:115]
	v_mfma_f32_16x16x32_bf16 v[100:103], v[162:165], v[192:195], 0
	v_mfma_f32_16x16x32_bf16 v[100:103], v[166:169], v[196:199], v[100:103]
	v_mfma_f32_16x16x32_bf16 v[96:99], v[170:173], v[192:195], 0
	v_mfma_f32_16x16x32_bf16 v[96:99], v[174:177], v[196:199], v[96:99]
	v_mfma_f32_16x16x32_bf16 v[84:87], v[162:165], v[200:203], 0
	v_mfma_f32_16x16x32_bf16 v[84:87], v[166:169], v[204:207], v[84:87]
	v_mfma_f32_16x16x32_bf16 v[80:83], v[170:173], v[200:203], 0
	v_mfma_f32_16x16x32_bf16 v[80:83], v[174:177], v[204:207], v[80:83]
	s_setprio 2
	s_barrier
	v_mfma_f32_16x16x32_bf16 v[68:71], v[162:165], v[208:211], 0
	v_mfma_f32_16x16x32_bf16 v[68:71], v[166:169], v[212:215], v[68:71]
	v_mfma_f32_16x16x32_bf16 v[64:67], v[170:173], v[208:211], 0
	v_mfma_f32_16x16x32_bf16 v[64:67], v[174:177], v[212:215], v[64:67]
	s_setprio 0
	s_add_i32 s71, s62, s54
	v_lshl_add_u64 v[178:179], s[48:49], 0, v[130:131]
	s_mov_b32 m0, s71
	ds_read_b128 v[184:187], v149 offset:16384
	ds_read_b128 v[188:191], v149 offset:17408
	ds_read_b128 v[192:195], v149 offset:18432
	ds_read_b128 v[196:199], v149 offset:19456
	ds_read_b128 v[200:203], v149 offset:20480
	ds_read_b128 v[204:207], v149 offset:21504
	ds_read_b128 v[208:211], v149 offset:22528
	ds_read_b128 v[212:215], v149 offset:23552
	global_load_lds_dwordx4 v[178:179], off
	s_add_i32 m0, s71, 0x2000
	s_add_u32 s72, s48, 0x40000
	v_lshl_add_u64 v[216:217], s[48:49], 0, v[128:129]
	s_addc_u32 s73, s49, 0
	s_add_i32 s71, s63, s54
	global_load_lds_dwordx4 v[216:217], off
	v_lshl_add_u64 v[218:219], s[72:73], 0, v[130:131]
	s_mov_b32 m0, s71
	v_lshl_add_u64 v[220:221], s[50:51], 0, v[128:129]
	global_load_lds_dwordx4 v[218:219], off
	v_lshl_add_u64 v[218:219], s[72:73], 0, v[128:129]
	s_add_i32 m0, s71, 0x2000
	s_nop 0
	global_load_lds_dwordx4 v[218:219], off
	v_lshl_add_u64 v[218:219], s[50:51], 0, v[130:131]
	s_mov_b32 m0, s45
	s_nop 0
	global_load_lds_dwordx4 v[218:219], off
	s_mov_b32 m0, s56
	s_nop 0
	global_load_lds_dwordx4 v[220:221], off
	s_waitcnt vmcnt(8)
	s_waitcnt lgkmcnt(0)
	s_barrier
	s_setprio 1
	s_waitcnt lgkmcnt(0)
	v_mfma_f32_16x16x32_bf16 v[60:63], v[140:143], v[184:187], 0
	v_mfma_f32_16x16x32_bf16 v[60:63], v[150:153], v[188:191], v[60:63]
	v_mfma_f32_16x16x32_bf16 v[56:59], v[154:157], v[184:187], 0
	v_mfma_f32_16x16x32_bf16 v[56:59], v[158:161], v[188:191], v[56:59]
	v_mfma_f32_16x16x32_bf16 v[44:47], v[140:143], v[192:195], 0
	v_mfma_f32_16x16x32_bf16 v[44:47], v[150:153], v[196:199], v[44:47]
	v_mfma_f32_16x16x32_bf16 v[40:43], v[154:157], v[192:195], 0
	v_mfma_f32_16x16x32_bf16 v[40:43], v[158:161], v[196:199], v[40:43]
	v_mfma_f32_16x16x32_bf16 v[28:31], v[140:143], v[200:203], 0
	v_mfma_f32_16x16x32_bf16 v[28:31], v[150:153], v[204:207], v[28:31]
	v_mfma_f32_16x16x32_bf16 v[24:27], v[154:157], v[200:203], 0
	v_mfma_f32_16x16x32_bf16 v[24:27], v[158:161], v[204:207], v[24:27]
	v_mfma_f32_16x16x32_bf16 v[12:15], v[140:143], v[208:211], 0
	v_mfma_f32_16x16x32_bf16 v[12:15], v[150:153], v[212:215], v[12:15]
	v_mfma_f32_16x16x32_bf16 v[8:11], v[154:157], v[208:211], 0
	v_mfma_f32_16x16x32_bf16 v[8:11], v[158:161], v[212:215], v[8:11]
	v_mfma_f32_16x16x32_bf16 v[52:55], v[162:165], v[184:187], 0
	v_mfma_f32_16x16x32_bf16 v[52:55], v[166:169], v[188:191], v[52:55]
	v_mfma_f32_16x16x32_bf16 v[48:51], v[170:173], v[184:187], 0
	v_mfma_f32_16x16x32_bf16 v[48:51], v[174:177], v[188:191], v[48:51]
	v_mfma_f32_16x16x32_bf16 v[36:39], v[162:165], v[192:195], 0
	v_mfma_f32_16x16x32_bf16 v[36:39], v[166:169], v[196:199], v[36:39]
	v_mfma_f32_16x16x32_bf16 v[32:35], v[170:173], v[192:195], 0
	v_mfma_f32_16x16x32_bf16 v[32:35], v[174:177], v[196:199], v[32:35]
	v_mfma_f32_16x16x32_bf16 v[20:23], v[162:165], v[200:203], 0
	v_mfma_f32_16x16x32_bf16 v[20:23], v[166:169], v[204:207], v[20:23]
	v_mfma_f32_16x16x32_bf16 v[16:19], v[170:173], v[200:203], 0
	v_mfma_f32_16x16x32_bf16 v[16:19], v[174:177], v[204:207], v[16:19]
	s_setprio 2
	s_barrier
	v_mfma_f32_16x16x32_bf16 v[4:7], v[162:165], v[208:211], 0
	v_mfma_f32_16x16x32_bf16 v[4:7], v[166:169], v[212:215], v[4:7]
	v_mfma_f32_16x16x32_bf16 v[0:3], v[170:173], v[208:211], 0
	v_mfma_f32_16x16x32_bf16 v[0:3], v[174:177], v[212:215], v[0:3]
	s_setprio 0
	s_branch .Lmid_gemm11
.LBB0_1434:
	ds_read_b128 v[140:143], v147
	ds_read_b128 v[150:153], v147 offset:1024
	ds_read_b128 v[154:157], v147 offset:2048
	ds_read_b128 v[158:161], v147 offset:3072
	ds_read_b128 v[162:165], v148
	ds_read_b128 v[166:169], v148 offset:1024
	ds_read_b128 v[170:173], v148 offset:2048
	ds_read_b128 v[174:177], v148 offset:3072
	s_add_u32 s48, s46, 0xfffc0080
	s_addc_u32 s49, s47, -1
	s_cmp_eq_u32 s70, 12
	s_cselect_b32 s51, s19, s49
	s_cselect_b32 s50, s66, s48
	s_cselect_b32 s49, s17, s69
	s_cselect_b32 s48, s67, s68
	v_lshl_add_u64 v[178:179], s[46:47], 0, v[132:133]
	s_add_i32 m0, s45, 0xc000
	ds_read_b128 v[184:187], v149
	ds_read_b128 v[188:191], v149 offset:1024
	ds_read_b128 v[192:195], v149 offset:2048
	ds_read_b128 v[196:199], v149 offset:3072
	ds_read_b128 v[200:203], v149 offset:4096
	ds_read_b128 v[204:207], v149 offset:5120
	ds_read_b128 v[208:211], v149 offset:6144
	ds_read_b128 v[212:215], v149 offset:7168
	global_load_lds_dwordx4 v[178:179], off
	v_lshl_add_u64 v[178:179], s[46:47], 0, v[134:135]
	s_add_i32 m0, s45, 0xe000
	s_nop 0
	global_load_lds_dwordx4 v[178:179], off
	s_waitcnt vmcnt(8)
	s_waitcnt lgkmcnt(0)
	s_barrier
	s_setprio 1
	s_waitcnt lgkmcnt(0)
	v_mfma_f32_16x16x32_bf16 v[124:127], v[140:143], v[184:187], v[124:127]
	v_mfma_f32_16x16x32_bf16 v[124:127], v[150:153], v[188:191], v[124:127]
	v_mfma_f32_16x16x32_bf16 v[120:123], v[154:157], v[184:187], v[120:123]
	v_mfma_f32_16x16x32_bf16 v[120:123], v[158:161], v[188:191], v[120:123]
	v_mfma_f32_16x16x32_bf16 v[108:111], v[140:143], v[192:195], v[108:111]
	v_mfma_f32_16x16x32_bf16 v[108:111], v[150:153], v[196:199], v[108:111]
	v_mfma_f32_16x16x32_bf16 v[104:107], v[154:157], v[192:195], v[104:107]
	v_mfma_f32_16x16x32_bf16 v[104:107], v[158:161], v[196:199], v[104:107]
	v_mfma_f32_16x16x32_bf16 v[92:95], v[140:143], v[200:203], v[92:95]
	v_mfma_f32_16x16x32_bf16 v[92:95], v[150:153], v[204:207], v[92:95]
	v_mfma_f32_16x16x32_bf16 v[88:91], v[154:157], v[200:203], v[88:91]
	v_mfma_f32_16x16x32_bf16 v[88:91], v[158:161], v[204:207], v[88:91]
	v_mfma_f32_16x16x32_bf16 v[76:79], v[140:143], v[208:211], v[76:79]
	v_mfma_f32_16x16x32_bf16 v[76:79], v[150:153], v[212:215], v[76:79]
	v_mfma_f32_16x16x32_bf16 v[72:75], v[154:157], v[208:211], v[72:75]
	v_mfma_f32_16x16x32_bf16 v[72:75], v[158:161], v[212:215], v[72:75]
	v_mfma_f32_16x16x32_bf16 v[116:119], v[162:165], v[184:187], v[116:119]
	v_mfma_f32_16x16x32_bf16 v[116:119], v[166:169], v[188:191], v[116:119]
	v_mfma_f32_16x16x32_bf16 v[112:115], v[170:173], v[184:187], v[112:115]
	v_mfma_f32_16x16x32_bf16 v[112:115], v[174:177], v[188:191], v[112:115]
	v_mfma_f32_16x16x32_bf16 v[100:103], v[162:165], v[192:195], v[100:103]
	v_mfma_f32_16x16x32_bf16 v[100:103], v[166:169], v[196:199], v[100:103]
	v_mfma_f32_16x16x32_bf16 v[96:99], v[170:173], v[192:195], v[96:99]
	v_mfma_f32_16x16x32_bf16 v[96:99], v[174:177], v[196:199], v[96:99]
	v_mfma_f32_16x16x32_bf16 v[84:87], v[162:165], v[200:203], v[84:87]
	v_mfma_f32_16x16x32_bf16 v[84:87], v[166:169], v[204:207], v[84:87]
	v_mfma_f32_16x16x32_bf16 v[80:83], v[170:173], v[200:203], v[80:83]
	v_mfma_f32_16x16x32_bf16 v[80:83], v[174:177], v[204:207], v[80:83]
	s_setprio 2
	s_barrier
	v_mfma_f32_16x16x32_bf16 v[68:71], v[162:165], v[208:211], v[68:71]
	v_mfma_f32_16x16x32_bf16 v[68:71], v[166:169], v[212:215], v[68:71]
	v_mfma_f32_16x16x32_bf16 v[64:67], v[170:173], v[208:211], v[64:67]
	v_mfma_f32_16x16x32_bf16 v[64:67], v[174:177], v[212:215], v[64:67]
	s_setprio 0
	s_add_i32 s71, s62, s54
	v_lshl_add_u64 v[178:179], s[48:49], 0, v[130:131]
	s_mov_b32 m0, s71
	ds_read_b128 v[184:187], v149 offset:16384
	ds_read_b128 v[188:191], v149 offset:17408
	ds_read_b128 v[192:195], v149 offset:18432
	ds_read_b128 v[196:199], v149 offset:19456
	ds_read_b128 v[200:203], v149 offset:20480
	ds_read_b128 v[204:207], v149 offset:21504
	ds_read_b128 v[208:211], v149 offset:22528
	ds_read_b128 v[212:215], v149 offset:23552
	global_load_lds_dwordx4 v[178:179], off
	s_add_i32 m0, s71, 0x2000
	s_add_u32 s72, s48, 0x40000
	v_lshl_add_u64 v[216:217], s[48:49], 0, v[128:129]
	s_addc_u32 s73, s49, 0
	s_add_i32 s71, s63, s54
	global_load_lds_dwordx4 v[216:217], off
	v_lshl_add_u64 v[218:219], s[72:73], 0, v[130:131]
	s_mov_b32 m0, s71
	v_lshl_add_u64 v[220:221], s[50:51], 0, v[128:129]
	global_load_lds_dwordx4 v[218:219], off
	v_lshl_add_u64 v[218:219], s[72:73], 0, v[128:129]
	s_add_i32 m0, s71, 0x2000
	s_nop 0
	global_load_lds_dwordx4 v[218:219], off
	v_lshl_add_u64 v[218:219], s[50:51], 0, v[130:131]
	s_mov_b32 m0, s45
	s_nop 0
	global_load_lds_dwordx4 v[218:219], off
	s_mov_b32 m0, s56
	s_nop 0
	global_load_lds_dwordx4 v[220:221], off
	s_waitcnt vmcnt(8)
	s_waitcnt lgkmcnt(0)
	s_barrier
	s_setprio 1
	s_waitcnt lgkmcnt(0)
	v_mfma_f32_16x16x32_bf16 v[60:63], v[140:143], v[184:187], v[60:63]
	v_mfma_f32_16x16x32_bf16 v[60:63], v[150:153], v[188:191], v[60:63]
	v_mfma_f32_16x16x32_bf16 v[56:59], v[154:157], v[184:187], v[56:59]
	v_mfma_f32_16x16x32_bf16 v[56:59], v[158:161], v[188:191], v[56:59]
	v_mfma_f32_16x16x32_bf16 v[44:47], v[140:143], v[192:195], v[44:47]
	v_mfma_f32_16x16x32_bf16 v[44:47], v[150:153], v[196:199], v[44:47]
	v_mfma_f32_16x16x32_bf16 v[40:43], v[154:157], v[192:195], v[40:43]
	v_mfma_f32_16x16x32_bf16 v[40:43], v[158:161], v[196:199], v[40:43]
	v_mfma_f32_16x16x32_bf16 v[28:31], v[140:143], v[200:203], v[28:31]
	v_mfma_f32_16x16x32_bf16 v[28:31], v[150:153], v[204:207], v[28:31]
	v_mfma_f32_16x16x32_bf16 v[24:27], v[154:157], v[200:203], v[24:27]
	v_mfma_f32_16x16x32_bf16 v[24:27], v[158:161], v[204:207], v[24:27]
	v_mfma_f32_16x16x32_bf16 v[12:15], v[140:143], v[208:211], v[12:15]
	v_mfma_f32_16x16x32_bf16 v[12:15], v[150:153], v[212:215], v[12:15]
	v_mfma_f32_16x16x32_bf16 v[8:11], v[154:157], v[208:211], v[8:11]
	v_mfma_f32_16x16x32_bf16 v[8:11], v[158:161], v[212:215], v[8:11]
	v_mfma_f32_16x16x32_bf16 v[52:55], v[162:165], v[184:187], v[52:55]
	v_mfma_f32_16x16x32_bf16 v[52:55], v[166:169], v[188:191], v[52:55]
	v_mfma_f32_16x16x32_bf16 v[48:51], v[170:173], v[184:187], v[48:51]
	v_mfma_f32_16x16x32_bf16 v[48:51], v[174:177], v[188:191], v[48:51]
	v_mfma_f32_16x16x32_bf16 v[36:39], v[162:165], v[192:195], v[36:39]
	v_mfma_f32_16x16x32_bf16 v[36:39], v[166:169], v[196:199], v[36:39]
	v_mfma_f32_16x16x32_bf16 v[32:35], v[170:173], v[192:195], v[32:35]
	v_mfma_f32_16x16x32_bf16 v[32:35], v[174:177], v[196:199], v[32:35]
	v_mfma_f32_16x16x32_bf16 v[20:23], v[162:165], v[200:203], v[20:23]
	v_mfma_f32_16x16x32_bf16 v[20:23], v[166:169], v[204:207], v[20:23]
	v_mfma_f32_16x16x32_bf16 v[16:19], v[170:173], v[200:203], v[16:19]
	v_mfma_f32_16x16x32_bf16 v[16:19], v[174:177], v[204:207], v[16:19]
	s_setprio 2
	s_barrier
	v_mfma_f32_16x16x32_bf16 v[4:7], v[162:165], v[208:211], v[4:7]
	v_mfma_f32_16x16x32_bf16 v[4:7], v[166:169], v[212:215], v[4:7]
	v_mfma_f32_16x16x32_bf16 v[0:3], v[170:173], v[208:211], v[0:3]
	v_mfma_f32_16x16x32_bf16 v[0:3], v[174:177], v[212:215], v[0:3]
	s_setprio 0
.Lmid_gemm11:
	s_add_i32 s71, 0, 0x18000
	s_add_i32 s72, 0, 0x1c000
	v_add_u32_e32 v158, s71, v145
	v_add_u32_e32 v174, s72, v145
	ds_read_b128 v[140:143], v158
	ds_read_b128 v[150:153], v158 offset:1024
	ds_read_b128 v[154:157], v158 offset:2048
	ds_read_b128 v[158:161], v158 offset:3072
	ds_read_b128 v[162:165], v174
	ds_read_b128 v[166:169], v174 offset:1024
	ds_read_b128 v[170:173], v174 offset:2048
	ds_read_b128 v[174:177], v174 offset:3072
	s_add_u32 s50, s50, 0x40000
	s_addc_u32 s51, s51, 0
	s_mov_b32 m0, s57
	v_lshl_add_u64 v[222:223], s[50:51], 0, v[130:131]
	ds_read_b128 v[184:187], v149 offset:32768
	ds_read_b128 v[188:191], v149 offset:33792
	ds_read_b128 v[192:195], v149 offset:34816
	ds_read_b128 v[196:199], v149 offset:35840
	ds_read_b128 v[200:203], v149 offset:36864
	ds_read_b128 v[204:207], v149 offset:37888
	ds_read_b128 v[208:211], v149 offset:38912
	ds_read_b128 v[212:215], v149 offset:39936
	global_load_lds_dwordx4 v[222:223], off
	v_lshl_add_u64 v[222:223], s[50:51], 0, v[128:129]
	s_mov_b32 m0, s58
	s_nop 0
	global_load_lds_dwordx4 v[222:223], off
	s_waitcnt vmcnt(8)
	s_waitcnt lgkmcnt(0)
	s_barrier
	s_setprio 1
	s_waitcnt lgkmcnt(0)
	v_mfma_f32_16x16x32_bf16 v[124:127], v[140:143], v[184:187], v[124:127]
	v_mfma_f32_16x16x32_bf16 v[124:127], v[150:153], v[188:191], v[124:127]
	v_mfma_f32_16x16x32_bf16 v[120:123], v[154:157], v[184:187], v[120:123]
	v_mfma_f32_16x16x32_bf16 v[120:123], v[158:161], v[188:191], v[120:123]
	v_mfma_f32_16x16x32_bf16 v[108:111], v[140:143], v[192:195], v[108:111]
	v_mfma_f32_16x16x32_bf16 v[108:111], v[150:153], v[196:199], v[108:111]
	v_mfma_f32_16x16x32_bf16 v[104:107], v[154:157], v[192:195], v[104:107]
	v_mfma_f32_16x16x32_bf16 v[104:107], v[158:161], v[196:199], v[104:107]
	v_mfma_f32_16x16x32_bf16 v[92:95], v[140:143], v[200:203], v[92:95]
	v_mfma_f32_16x16x32_bf16 v[92:95], v[150:153], v[204:207], v[92:95]
	v_mfma_f32_16x16x32_bf16 v[88:91], v[154:157], v[200:203], v[88:91]
	v_mfma_f32_16x16x32_bf16 v[88:91], v[158:161], v[204:207], v[88:91]
	v_mfma_f32_16x16x32_bf16 v[76:79], v[140:143], v[208:211], v[76:79]
	v_mfma_f32_16x16x32_bf16 v[76:79], v[150:153], v[212:215], v[76:79]
	v_mfma_f32_16x16x32_bf16 v[72:75], v[154:157], v[208:211], v[72:75]
	v_mfma_f32_16x16x32_bf16 v[72:75], v[158:161], v[212:215], v[72:75]
	v_mfma_f32_16x16x32_bf16 v[116:119], v[162:165], v[184:187], v[116:119]
	v_mfma_f32_16x16x32_bf16 v[116:119], v[166:169], v[188:191], v[116:119]
	v_mfma_f32_16x16x32_bf16 v[112:115], v[170:173], v[184:187], v[112:115]
	v_mfma_f32_16x16x32_bf16 v[112:115], v[174:177], v[188:191], v[112:115]
	v_mfma_f32_16x16x32_bf16 v[100:103], v[162:165], v[192:195], v[100:103]
	v_mfma_f32_16x16x32_bf16 v[100:103], v[166:169], v[196:199], v[100:103]
	v_mfma_f32_16x16x32_bf16 v[96:99], v[170:173], v[192:195], v[96:99]
	v_mfma_f32_16x16x32_bf16 v[96:99], v[174:177], v[196:199], v[96:99]
	v_mfma_f32_16x16x32_bf16 v[84:87], v[162:165], v[200:203], v[84:87]
	v_mfma_f32_16x16x32_bf16 v[84:87], v[166:169], v[204:207], v[84:87]
	v_mfma_f32_16x16x32_bf16 v[80:83], v[170:173], v[200:203], v[80:83]
	v_mfma_f32_16x16x32_bf16 v[80:83], v[174:177], v[204:207], v[80:83]
	s_setprio 2
	s_barrier
	v_mfma_f32_16x16x32_bf16 v[68:71], v[162:165], v[208:211], v[68:71]
	v_mfma_f32_16x16x32_bf16 v[68:71], v[166:169], v[212:215], v[68:71]
	v_mfma_f32_16x16x32_bf16 v[64:67], v[170:173], v[208:211], v[64:67]
	v_mfma_f32_16x16x32_bf16 v[64:67], v[174:177], v[212:215], v[64:67]
	s_setprio 0
	s_add_i32 s50, s71, s54
	v_lshl_add_u64 v[178:179], v[178:179], 0, s[10:11]
	s_mov_b32 m0, s50
	ds_read_b128 v[184:187], v149 offset:49152
	ds_read_b128 v[188:191], v149 offset:50176
	ds_read_b128 v[192:195], v149 offset:51200
	ds_read_b128 v[196:199], v149 offset:52224
	ds_read_b128 v[200:203], v149 offset:53248
	ds_read_b128 v[204:207], v149 offset:54272
	ds_read_b128 v[208:211], v149 offset:55296
	ds_read_b128 v[212:215], v149 offset:56320
	global_load_lds_dwordx4 v[178:179], off
	s_add_i32 m0, s50, 0x2000
	s_add_u32 s48, s48, 0x40080
	v_lshl_add_u64 v[178:179], v[216:217], 0, s[10:11]
	s_addc_u32 s49, s49, 0
	s_add_i32 s50, s72, s54
	global_load_lds_dwordx4 v[178:179], off
	v_lshl_add_u64 v[178:179], s[48:49], 0, v[130:131]
	s_mov_b32 m0, s50
	s_nop 0
	global_load_lds_dwordx4 v[178:179], off
	v_lshl_add_u64 v[178:179], s[48:49], 0, v[128:129]
	s_add_i32 m0, s50, 0x2000
	s_nop 0
	global_load_lds_dwordx4 v[178:179], off
	v_lshl_add_u64 v[178:179], v[218:219], 0, s[10:11]
	s_mov_b32 m0, s60
	s_nop 0
	global_load_lds_dwordx4 v[178:179], off
	v_lshl_add_u64 v[178:179], v[220:221], 0, s[10:11]
	s_mov_b32 m0, s61
	s_nop 0
	global_load_lds_dwordx4 v[178:179], off
	s_waitcnt vmcnt(8)
	s_waitcnt lgkmcnt(0)
	s_barrier
	s_setprio 1
	s_waitcnt lgkmcnt(0)
	v_mfma_f32_16x16x32_bf16 v[60:63], v[140:143], v[184:187], v[60:63]
	v_mfma_f32_16x16x32_bf16 v[60:63], v[150:153], v[188:191], v[60:63]
	v_mfma_f32_16x16x32_bf16 v[56:59], v[154:157], v[184:187], v[56:59]
	v_mfma_f32_16x16x32_bf16 v[56:59], v[158:161], v[188:191], v[56:59]
	v_mfma_f32_16x16x32_bf16 v[44:47], v[140:143], v[192:195], v[44:47]
	v_mfma_f32_16x16x32_bf16 v[44:47], v[150:153], v[196:199], v[44:47]
	v_mfma_f32_16x16x32_bf16 v[40:43], v[154:157], v[192:195], v[40:43]
	v_mfma_f32_16x16x32_bf16 v[40:43], v[158:161], v[196:199], v[40:43]
	v_mfma_f32_16x16x32_bf16 v[28:31], v[140:143], v[200:203], v[28:31]
	v_mfma_f32_16x16x32_bf16 v[28:31], v[150:153], v[204:207], v[28:31]
	v_mfma_f32_16x16x32_bf16 v[24:27], v[154:157], v[200:203], v[24:27]
	v_mfma_f32_16x16x32_bf16 v[24:27], v[158:161], v[204:207], v[24:27]
	v_mfma_f32_16x16x32_bf16 v[12:15], v[140:143], v[208:211], v[12:15]
	v_mfma_f32_16x16x32_bf16 v[12:15], v[150:153], v[212:215], v[12:15]
	v_mfma_f32_16x16x32_bf16 v[8:11], v[154:157], v[208:211], v[8:11]
	v_mfma_f32_16x16x32_bf16 v[8:11], v[158:161], v[212:215], v[8:11]
	v_mfma_f32_16x16x32_bf16 v[52:55], v[162:165], v[184:187], v[52:55]
	v_mfma_f32_16x16x32_bf16 v[52:55], v[166:169], v[188:191], v[52:55]
	v_mfma_f32_16x16x32_bf16 v[48:51], v[170:173], v[184:187], v[48:51]
	v_mfma_f32_16x16x32_bf16 v[48:51], v[174:177], v[188:191], v[48:51]
	v_mfma_f32_16x16x32_bf16 v[36:39], v[162:165], v[192:195], v[36:39]
	v_mfma_f32_16x16x32_bf16 v[36:39], v[166:169], v[196:199], v[36:39]
	v_mfma_f32_16x16x32_bf16 v[32:35], v[170:173], v[192:195], v[32:35]
	v_mfma_f32_16x16x32_bf16 v[32:35], v[174:177], v[196:199], v[32:35]
	v_mfma_f32_16x16x32_bf16 v[20:23], v[162:165], v[200:203], v[20:23]
	v_mfma_f32_16x16x32_bf16 v[20:23], v[166:169], v[204:207], v[20:23]
	v_mfma_f32_16x16x32_bf16 v[16:19], v[170:173], v[200:203], v[16:19]
	v_mfma_f32_16x16x32_bf16 v[16:19], v[174:177], v[204:207], v[16:19]
	s_setprio 2
	s_barrier
	v_mfma_f32_16x16x32_bf16 v[4:7], v[162:165], v[208:211], v[4:7]
	v_mfma_f32_16x16x32_bf16 v[4:7], v[166:169], v[212:215], v[4:7]
	v_mfma_f32_16x16x32_bf16 v[0:3], v[170:173], v[208:211], v[0:3]
	v_mfma_f32_16x16x32_bf16 v[0:3], v[174:177], v[212:215], v[0:3]
	s_setprio 0
	s_add_i32 s70, s70, 2
	s_add_u32 s46, s46, 0x100
	s_addc_u32 s47, s47, 0
	s_add_u32 s68, s68, 0x100
	s_addc_u32 s69, s69, 0
	s_cmp_gt_u32 s70, 13
	s_cbranch_scc0 .LBB0_1434
	s_and_b64 vcc, exec, s[12:13]
	s_cbranch_vccz .LBB0_1437
	s_barrier

.LBB0_1513:
	s_add_u32 s74, s48, 0x100
	s_addc_u32 s75, s49, 0
	s_mov_b32 s76, -2
	ds_read_b128 v[152:155], v149
	ds_read_b128 v[156:159], v149 offset:1024
	ds_read_b128 v[160:163], v149 offset:2048
	ds_read_b128 v[164:167], v149 offset:3072
	ds_read_b128 v[168:171], v150
	ds_read_b128 v[172:175], v150 offset:1024
	ds_read_b128 v[176:179], v150 offset:2048
	ds_read_b128 v[184:187], v150 offset:3072
	s_add_u32 s48, s46, 0x100
	s_addc_u32 s49, s47, 0
	s_cmp_eq_u32 s76, 40
	s_cselect_b32 s53, s9, s49
	s_cselect_b32 s52, s8, s48
	s_cselect_b32 s51, s45, s75
	s_cselect_b32 s50, s44, s74
	v_lshl_add_u64 v[144:145], s[46:47], 0, v[136:137]
	s_add_i32 m0, s57, 0xc000
	ds_read_b128 v[188:191], v151
	ds_read_b128 v[192:195], v151 offset:1024
	ds_read_b128 v[196:199], v151 offset:2048
	ds_read_b128 v[200:203], v151 offset:3072
	ds_read_b128 v[204:207], v151 offset:4096
	ds_read_b128 v[208:211], v151 offset:5120
	ds_read_b128 v[212:215], v151 offset:6144
	ds_read_b128 v[216:219], v151 offset:7168
	global_load_lds_dwordx4 v[144:145], off
	v_lshl_add_u64 v[144:145], s[46:47], 0, v[138:139]
	s_add_i32 m0, s57, 0xe000
	s_nop 0
	global_load_lds_dwordx4 v[144:145], off
	s_waitcnt vmcnt(8)
	s_waitcnt lgkmcnt(0)
	s_barrier
	s_setprio 1
	s_waitcnt lgkmcnt(0)
	v_mfma_f32_16x16x32_bf16 v[124:127], v[152:155], v[188:191], 0
	v_mfma_f32_16x16x32_bf16 v[124:127], v[156:159], v[192:195], v[124:127]
	v_mfma_f32_16x16x32_bf16 v[120:123], v[160:163], v[188:191], 0
	v_mfma_f32_16x16x32_bf16 v[120:123], v[164:167], v[192:195], v[120:123]
	v_mfma_f32_16x16x32_bf16 v[116:119], v[152:155], v[196:199], 0
	v_mfma_f32_16x16x32_bf16 v[116:119], v[156:159], v[200:203], v[116:119]
	v_mfma_f32_16x16x32_bf16 v[108:111], v[160:163], v[196:199], 0
	v_mfma_f32_16x16x32_bf16 v[108:111], v[164:167], v[200:203], v[108:111]
	v_mfma_f32_16x16x32_bf16 v[100:103], v[152:155], v[204:207], 0
	v_mfma_f32_16x16x32_bf16 v[100:103], v[156:159], v[208:211], v[100:103]
	v_mfma_f32_16x16x32_bf16 v[92:95], v[160:163], v[204:207], 0
	v_mfma_f32_16x16x32_bf16 v[92:95], v[164:167], v[208:211], v[92:95]
	v_mfma_f32_16x16x32_bf16 v[84:87], v[152:155], v[212:215], 0
	v_mfma_f32_16x16x32_bf16 v[84:87], v[156:159], v[216:219], v[84:87]
	v_mfma_f32_16x16x32_bf16 v[76:79], v[160:163], v[212:215], 0
	v_mfma_f32_16x16x32_bf16 v[76:79], v[164:167], v[216:219], v[76:79]
	v_mfma_f32_16x16x32_bf16 v[112:115], v[168:171], v[188:191], 0
	v_mfma_f32_16x16x32_bf16 v[112:115], v[172:175], v[192:195], v[112:115]
	v_mfma_f32_16x16x32_bf16 v[104:107], v[176:179], v[188:191], 0
	v_mfma_f32_16x16x32_bf16 v[104:107], v[184:187], v[192:195], v[104:107]
	v_mfma_f32_16x16x32_bf16 v[96:99], v[168:171], v[196:199], 0
	v_mfma_f32_16x16x32_bf16 v[96:99], v[172:175], v[200:203], v[96:99]
	v_mfma_f32_16x16x32_bf16 v[88:91], v[176:179], v[196:199], 0
	v_mfma_f32_16x16x32_bf16 v[88:91], v[184:187], v[200:203], v[88:91]
	v_mfma_f32_16x16x32_bf16 v[80:83], v[168:171], v[204:207], 0
	v_mfma_f32_16x16x32_bf16 v[80:83], v[172:175], v[208:211], v[80:83]
	v_mfma_f32_16x16x32_bf16 v[72:75], v[176:179], v[204:207], 0
	v_mfma_f32_16x16x32_bf16 v[72:75], v[184:187], v[208:211], v[72:75]
	s_setprio 2
	s_barrier
	v_mfma_f32_16x16x32_bf16 v[68:71], v[168:171], v[212:215], 0
	v_mfma_f32_16x16x32_bf16 v[68:71], v[172:175], v[216:219], v[68:71]
	v_mfma_f32_16x16x32_bf16 v[64:67], v[176:179], v[212:215], 0
	v_mfma_f32_16x16x32_bf16 v[64:67], v[184:187], v[216:219], v[64:67]
	s_setprio 0
	s_add_i32 s46, s64, s56
	v_lshl_add_u64 v[144:145], s[50:51], 0, v[130:131]
	s_mov_b32 m0, s46
	ds_read_b128 v[188:191], v151 offset:16384
	ds_read_b128 v[192:195], v151 offset:17408
	ds_read_b128 v[196:199], v151 offset:18432
	ds_read_b128 v[200:203], v151 offset:19456
	ds_read_b128 v[204:207], v151 offset:20480
	ds_read_b128 v[208:211], v151 offset:21504
	ds_read_b128 v[212:215], v151 offset:22528
	ds_read_b128 v[216:219], v151 offset:23552
	global_load_lds_dwordx4 v[144:145], off
	s_add_i32 m0, s46, 0x2000
	s_add_u32 s46, s50, 0xb0000
	v_lshl_add_u64 v[220:221], s[50:51], 0, v[134:135]
	s_addc_u32 s47, s51, 0
	s_add_i32 s77, s65, s56
	global_load_lds_dwordx4 v[220:221], off
	v_lshl_add_u64 v[222:223], s[46:47], 0, v[130:131]
	s_mov_b32 m0, s77
	v_lshl_add_u64 v[224:225], s[52:53], 0, v[132:133]
	global_load_lds_dwordx4 v[222:223], off
	v_lshl_add_u64 v[222:223], s[46:47], 0, v[134:135]
	s_add_i32 m0, s77, 0x2000
	s_nop 0
	global_load_lds_dwordx4 v[222:223], off
	v_lshl_add_u64 v[222:223], s[52:53], 0, v[128:129]
	s_mov_b32 m0, s57
	s_nop 0
	global_load_lds_dwordx4 v[222:223], off
	s_mov_b32 m0, s58
	s_nop 0
	global_load_lds_dwordx4 v[224:225], off
	s_waitcnt vmcnt(8)
	s_waitcnt lgkmcnt(0)
	s_barrier
	s_setprio 1
	s_waitcnt lgkmcnt(0)
	v_mfma_f32_16x16x32_bf16 v[60:63], v[152:155], v[188:191], 0
	v_mfma_f32_16x16x32_bf16 v[60:63], v[156:159], v[192:195], v[60:63]
	v_mfma_f32_16x16x32_bf16 v[56:59], v[160:163], v[188:191], 0
	v_mfma_f32_16x16x32_bf16 v[56:59], v[164:167], v[192:195], v[56:59]
	v_mfma_f32_16x16x32_bf16 v[52:55], v[152:155], v[196:199], 0
	v_mfma_f32_16x16x32_bf16 v[52:55], v[156:159], v[200:203], v[52:55]
	v_mfma_f32_16x16x32_bf16 v[44:47], v[160:163], v[196:199], 0
	v_mfma_f32_16x16x32_bf16 v[44:47], v[164:167], v[200:203], v[44:47]
	v_mfma_f32_16x16x32_bf16 v[36:39], v[152:155], v[204:207], 0
	v_mfma_f32_16x16x32_bf16 v[36:39], v[156:159], v[208:211], v[36:39]
	v_mfma_f32_16x16x32_bf16 v[28:31], v[160:163], v[204:207], 0
	v_mfma_f32_16x16x32_bf16 v[28:31], v[164:167], v[208:211], v[28:31]
	v_mfma_f32_16x16x32_bf16 v[20:23], v[152:155], v[212:215], 0
	v_mfma_f32_16x16x32_bf16 v[20:23], v[156:159], v[216:219], v[20:23]
	v_mfma_f32_16x16x32_bf16 v[12:15], v[160:163], v[212:215], 0
	v_mfma_f32_16x16x32_bf16 v[12:15], v[164:167], v[216:219], v[12:15]
	v_mfma_f32_16x16x32_bf16 v[48:51], v[168:171], v[188:191], 0
	v_mfma_f32_16x16x32_bf16 v[48:51], v[172:175], v[192:195], v[48:51]
	v_mfma_f32_16x16x32_bf16 v[40:43], v[176:179], v[188:191], 0
	v_mfma_f32_16x16x32_bf16 v[40:43], v[184:187], v[192:195], v[40:43]
	v_mfma_f32_16x16x32_bf16 v[32:35], v[168:171], v[196:199], 0
	v_mfma_f32_16x16x32_bf16 v[32:35], v[172:175], v[200:203], v[32:35]
	v_mfma_f32_16x16x32_bf16 v[24:27], v[176:179], v[196:199], 0
	v_mfma_f32_16x16x32_bf16 v[24:27], v[184:187], v[200:203], v[24:27]
	v_mfma_f32_16x16x32_bf16 v[16:19], v[168:171], v[204:207], 0
	v_mfma_f32_16x16x32_bf16 v[16:19], v[172:175], v[208:211], v[16:19]
	v_mfma_f32_16x16x32_bf16 v[8:11], v[176:179], v[204:207], 0
	v_mfma_f32_16x16x32_bf16 v[8:11], v[184:187], v[208:211], v[8:11]
	s_setprio 2
	s_barrier
	v_mfma_f32_16x16x32_bf16 v[4:7], v[168:171], v[212:215], 0
	v_mfma_f32_16x16x32_bf16 v[4:7], v[172:175], v[216:219], v[4:7]
	v_mfma_f32_16x16x32_bf16 v[0:3], v[176:179], v[212:215], 0
	v_mfma_f32_16x16x32_bf16 v[0:3], v[184:187], v[216:219], v[0:3]
	s_setprio 0
	s_branch .Lmid_gemm12
.LBB0_1514:
	ds_read_b128 v[152:155], v149
	ds_read_b128 v[156:159], v149 offset:1024
	ds_read_b128 v[160:163], v149 offset:2048
	ds_read_b128 v[164:167], v149 offset:3072
	ds_read_b128 v[168:171], v150
	ds_read_b128 v[172:175], v150 offset:1024
	ds_read_b128 v[176:179], v150 offset:2048
	ds_read_b128 v[184:187], v150 offset:3072
	s_add_u32 s48, s46, 0x100
	s_addc_u32 s49, s47, 0
	s_cmp_eq_u32 s76, 40
	s_cselect_b32 s53, s9, s49
	s_cselect_b32 s52, s8, s48
	s_cselect_b32 s51, s45, s75
	s_cselect_b32 s50, s44, s74
	v_lshl_add_u64 v[144:145], s[46:47], 0, v[136:137]
	s_add_i32 m0, s57, 0xc000
	ds_read_b128 v[188:191], v151
	ds_read_b128 v[192:195], v151 offset:1024
	ds_read_b128 v[196:199], v151 offset:2048
	ds_read_b128 v[200:203], v151 offset:3072
	ds_read_b128 v[204:207], v151 offset:4096
	ds_read_b128 v[208:211], v151 offset:5120
	ds_read_b128 v[212:215], v151 offset:6144
	ds_read_b128 v[216:219], v151 offset:7168
	global_load_lds_dwordx4 v[144:145], off
	v_lshl_add_u64 v[144:145], s[46:47], 0, v[138:139]
	s_add_i32 m0, s57, 0xe000
	s_nop 0
	global_load_lds_dwordx4 v[144:145], off
	s_waitcnt vmcnt(8)
	s_waitcnt lgkmcnt(0)
	s_barrier
	s_setprio 1
	s_waitcnt lgkmcnt(0)
	v_mfma_f32_16x16x32_bf16 v[124:127], v[152:155], v[188:191], v[124:127]
	v_mfma_f32_16x16x32_bf16 v[124:127], v[156:159], v[192:195], v[124:127]
	v_mfma_f32_16x16x32_bf16 v[120:123], v[160:163], v[188:191], v[120:123]
	v_mfma_f32_16x16x32_bf16 v[120:123], v[164:167], v[192:195], v[120:123]
	v_mfma_f32_16x16x32_bf16 v[116:119], v[152:155], v[196:199], v[116:119]
	v_mfma_f32_16x16x32_bf16 v[116:119], v[156:159], v[200:203], v[116:119]
	v_mfma_f32_16x16x32_bf16 v[108:111], v[160:163], v[196:199], v[108:111]
	v_mfma_f32_16x16x32_bf16 v[108:111], v[164:167], v[200:203], v[108:111]
	v_mfma_f32_16x16x32_bf16 v[100:103], v[152:155], v[204:207], v[100:103]
	v_mfma_f32_16x16x32_bf16 v[100:103], v[156:159], v[208:211], v[100:103]
	v_mfma_f32_16x16x32_bf16 v[92:95], v[160:163], v[204:207], v[92:95]
	v_mfma_f32_16x16x32_bf16 v[92:95], v[164:167], v[208:211], v[92:95]
	v_mfma_f32_16x16x32_bf16 v[84:87], v[152:155], v[212:215], v[84:87]
	v_mfma_f32_16x16x32_bf16 v[84:87], v[156:159], v[216:219], v[84:87]
	v_mfma_f32_16x16x32_bf16 v[76:79], v[160:163], v[212:215], v[76:79]
	v_mfma_f32_16x16x32_bf16 v[76:79], v[164:167], v[216:219], v[76:79]
	v_mfma_f32_16x16x32_bf16 v[112:115], v[168:171], v[188:191], v[112:115]
	v_mfma_f32_16x16x32_bf16 v[112:115], v[172:175], v[192:195], v[112:115]
	v_mfma_f32_16x16x32_bf16 v[104:107], v[176:179], v[188:191], v[104:107]
	v_mfma_f32_16x16x32_bf16 v[104:107], v[184:187], v[192:195], v[104:107]
	v_mfma_f32_16x16x32_bf16 v[96:99], v[168:171], v[196:199], v[96:99]
	v_mfma_f32_16x16x32_bf16 v[96:99], v[172:175], v[200:203], v[96:99]
	v_mfma_f32_16x16x32_bf16 v[88:91], v[176:179], v[196:199], v[88:91]
	v_mfma_f32_16x16x32_bf16 v[88:91], v[184:187], v[200:203], v[88:91]
	v_mfma_f32_16x16x32_bf16 v[80:83], v[168:171], v[204:207], v[80:83]
	v_mfma_f32_16x16x32_bf16 v[80:83], v[172:175], v[208:211], v[80:83]
	v_mfma_f32_16x16x32_bf16 v[72:75], v[176:179], v[204:207], v[72:75]
	v_mfma_f32_16x16x32_bf16 v[72:75], v[184:187], v[208:211], v[72:75]
	s_setprio 2
	s_barrier
	v_mfma_f32_16x16x32_bf16 v[68:71], v[168:171], v[212:215], v[68:71]
	v_mfma_f32_16x16x32_bf16 v[68:71], v[172:175], v[216:219], v[68:71]
	v_mfma_f32_16x16x32_bf16 v[64:67], v[176:179], v[212:215], v[64:67]
	v_mfma_f32_16x16x32_bf16 v[64:67], v[184:187], v[216:219], v[64:67]
	s_setprio 0
	s_add_i32 s46, s64, s56
	v_lshl_add_u64 v[144:145], s[50:51], 0, v[130:131]
	s_mov_b32 m0, s46
	ds_read_b128 v[188:191], v151 offset:16384
	ds_read_b128 v[192:195], v151 offset:17408
	ds_read_b128 v[196:199], v151 offset:18432
	ds_read_b128 v[200:203], v151 offset:19456
	ds_read_b128 v[204:207], v151 offset:20480
	ds_read_b128 v[208:211], v151 offset:21504
	ds_read_b128 v[212:215], v151 offset:22528
	ds_read_b128 v[216:219], v151 offset:23552
	global_load_lds_dwordx4 v[144:145], off
	s_add_i32 m0, s46, 0x2000
	s_add_u32 s46, s50, 0xb0000
	v_lshl_add_u64 v[220:221], s[50:51], 0, v[134:135]
	s_addc_u32 s47, s51, 0
	s_add_i32 s77, s65, s56
	global_load_lds_dwordx4 v[220:221], off
	v_lshl_add_u64 v[222:223], s[46:47], 0, v[130:131]
	s_mov_b32 m0, s77
	v_lshl_add_u64 v[224:225], s[52:53], 0, v[132:133]
	global_load_lds_dwordx4 v[222:223], off
	v_lshl_add_u64 v[222:223], s[46:47], 0, v[134:135]
	s_add_i32 m0, s77, 0x2000
	s_nop 0
	global_load_lds_dwordx4 v[222:223], off
	v_lshl_add_u64 v[222:223], s[52:53], 0, v[128:129]
	s_mov_b32 m0, s57
	s_nop 0
	global_load_lds_dwordx4 v[222:223], off
	s_mov_b32 m0, s58
	s_nop 0
	global_load_lds_dwordx4 v[224:225], off
	s_waitcnt vmcnt(8)
	s_waitcnt lgkmcnt(0)
	s_barrier
	s_setprio 1
	s_waitcnt lgkmcnt(0)
	v_mfma_f32_16x16x32_bf16 v[60:63], v[152:155], v[188:191], v[60:63]
	v_mfma_f32_16x16x32_bf16 v[60:63], v[156:159], v[192:195], v[60:63]
	v_mfma_f32_16x16x32_bf16 v[56:59], v[160:163], v[188:191], v[56:59]
	v_mfma_f32_16x16x32_bf16 v[56:59], v[164:167], v[192:195], v[56:59]
	v_mfma_f32_16x16x32_bf16 v[52:55], v[152:155], v[196:199], v[52:55]
	v_mfma_f32_16x16x32_bf16 v[52:55], v[156:159], v[200:203], v[52:55]
	v_mfma_f32_16x16x32_bf16 v[44:47], v[160:163], v[196:199], v[44:47]
	v_mfma_f32_16x16x32_bf16 v[44:47], v[164:167], v[200:203], v[44:47]
	v_mfma_f32_16x16x32_bf16 v[36:39], v[152:155], v[204:207], v[36:39]
	v_mfma_f32_16x16x32_bf16 v[36:39], v[156:159], v[208:211], v[36:39]
	v_mfma_f32_16x16x32_bf16 v[28:31], v[160:163], v[204:207], v[28:31]
	v_mfma_f32_16x16x32_bf16 v[28:31], v[164:167], v[208:211], v[28:31]
	v_mfma_f32_16x16x32_bf16 v[20:23], v[152:155], v[212:215], v[20:23]
	v_mfma_f32_16x16x32_bf16 v[20:23], v[156:159], v[216:219], v[20:23]
	v_mfma_f32_16x16x32_bf16 v[12:15], v[160:163], v[212:215], v[12:15]
	v_mfma_f32_16x16x32_bf16 v[12:15], v[164:167], v[216:219], v[12:15]
	v_mfma_f32_16x16x32_bf16 v[48:51], v[168:171], v[188:191], v[48:51]
	v_mfma_f32_16x16x32_bf16 v[48:51], v[172:175], v[192:195], v[48:51]
	v_mfma_f32_16x16x32_bf16 v[40:43], v[176:179], v[188:191], v[40:43]
	v_mfma_f32_16x16x32_bf16 v[40:43], v[184:187], v[192:195], v[40:43]
	v_mfma_f32_16x16x32_bf16 v[32:35], v[168:171], v[196:199], v[32:35]
	v_mfma_f32_16x16x32_bf16 v[32:35], v[172:175], v[200:203], v[32:35]
	v_mfma_f32_16x16x32_bf16 v[24:27], v[176:179], v[196:199], v[24:27]
	v_mfma_f32_16x16x32_bf16 v[24:27], v[184:187], v[200:203], v[24:27]
	v_mfma_f32_16x16x32_bf16 v[16:19], v[168:171], v[204:207], v[16:19]
	v_mfma_f32_16x16x32_bf16 v[16:19], v[172:175], v[208:211], v[16:19]
	v_mfma_f32_16x16x32_bf16 v[8:11], v[176:179], v[204:207], v[8:11]
	v_mfma_f32_16x16x32_bf16 v[8:11], v[184:187], v[208:211], v[8:11]
	s_setprio 2
	s_barrier
	v_mfma_f32_16x16x32_bf16 v[4:7], v[168:171], v[212:215], v[4:7]
	v_mfma_f32_16x16x32_bf16 v[4:7], v[172:175], v[216:219], v[4:7]
	v_mfma_f32_16x16x32_bf16 v[0:3], v[176:179], v[212:215], v[0:3]
	v_mfma_f32_16x16x32_bf16 v[0:3], v[184:187], v[216:219], v[0:3]
	s_setprio 0
.Lmid_gemm12:
	s_add_i32 s77, 0, 0x18000
	s_add_i32 s79, 0, 0x1c000
	v_add_u32_e32 v164, s77, v147
	v_add_u32_e32 v181, s79, v147
	ds_read_b128 v[152:155], v164
	ds_read_b128 v[156:159], v164 offset:1024
	ds_read_b128 v[160:163], v164 offset:2048
	ds_read_b128 v[164:167], v164 offset:3072
	ds_read_b128 v[168:171], v181
	ds_read_b128 v[172:175], v181 offset:1024
	ds_read_b128 v[176:179], v181 offset:2048
	ds_read_b128 v[184:187], v181 offset:3072
	s_add_u32 s46, s52, 0xb0000
	s_addc_u32 s47, s53, 0
	s_mov_b32 m0, s59
	v_lshl_add_u64 v[226:227], s[46:47], 0, v[128:129]
	ds_read_b128 v[188:191], v151 offset:32768
	ds_read_b128 v[192:195], v151 offset:33792
	ds_read_b128 v[196:199], v151 offset:34816
	ds_read_b128 v[200:203], v151 offset:35840
	ds_read_b128 v[204:207], v151 offset:36864
	ds_read_b128 v[208:211], v151 offset:37888
	ds_read_b128 v[212:215], v151 offset:38912
	ds_read_b128 v[216:219], v151 offset:39936
	global_load_lds_dwordx4 v[226:227], off
	v_lshl_add_u64 v[226:227], s[46:47], 0, v[132:133]
	s_mov_b32 m0, s60
	s_nop 0
	global_load_lds_dwordx4 v[226:227], off
	s_waitcnt vmcnt(8)
	s_waitcnt lgkmcnt(0)
	s_barrier
	s_setprio 1
	s_waitcnt lgkmcnt(0)
	v_mfma_f32_16x16x32_bf16 v[124:127], v[152:155], v[188:191], v[124:127]
	v_mfma_f32_16x16x32_bf16 v[124:127], v[156:159], v[192:195], v[124:127]
	v_mfma_f32_16x16x32_bf16 v[120:123], v[160:163], v[188:191], v[120:123]
	v_mfma_f32_16x16x32_bf16 v[120:123], v[164:167], v[192:195], v[120:123]
	v_mfma_f32_16x16x32_bf16 v[116:119], v[152:155], v[196:199], v[116:119]
	v_mfma_f32_16x16x32_bf16 v[116:119], v[156:159], v[200:203], v[116:119]
	v_mfma_f32_16x16x32_bf16 v[108:111], v[160:163], v[196:199], v[108:111]
	v_mfma_f32_16x16x32_bf16 v[108:111], v[164:167], v[200:203], v[108:111]
	v_mfma_f32_16x16x32_bf16 v[100:103], v[152:155], v[204:207], v[100:103]
	v_mfma_f32_16x16x32_bf16 v[100:103], v[156:159], v[208:211], v[100:103]
	v_mfma_f32_16x16x32_bf16 v[92:95], v[160:163], v[204:207], v[92:95]
	v_mfma_f32_16x16x32_bf16 v[92:95], v[164:167], v[208:211], v[92:95]
	v_mfma_f32_16x16x32_bf16 v[84:87], v[152:155], v[212:215], v[84:87]
	v_mfma_f32_16x16x32_bf16 v[84:87], v[156:159], v[216:219], v[84:87]
	v_mfma_f32_16x16x32_bf16 v[76:79], v[160:163], v[212:215], v[76:79]
	v_mfma_f32_16x16x32_bf16 v[76:79], v[164:167], v[216:219], v[76:79]
	v_mfma_f32_16x16x32_bf16 v[112:115], v[168:171], v[188:191], v[112:115]
	v_mfma_f32_16x16x32_bf16 v[112:115], v[172:175], v[192:195], v[112:115]
	v_mfma_f32_16x16x32_bf16 v[104:107], v[176:179], v[188:191], v[104:107]
	v_mfma_f32_16x16x32_bf16 v[104:107], v[184:187], v[192:195], v[104:107]
	v_mfma_f32_16x16x32_bf16 v[96:99], v[168:171], v[196:199], v[96:99]
	v_mfma_f32_16x16x32_bf16 v[96:99], v[172:175], v[200:203], v[96:99]
	v_mfma_f32_16x16x32_bf16 v[88:91], v[176:179], v[196:199], v[88:91]
	v_mfma_f32_16x16x32_bf16 v[88:91], v[184:187], v[200:203], v[88:91]
	v_mfma_f32_16x16x32_bf16 v[80:83], v[168:171], v[204:207], v[80:83]
	v_mfma_f32_16x16x32_bf16 v[80:83], v[172:175], v[208:211], v[80:83]
	v_mfma_f32_16x16x32_bf16 v[72:75], v[176:179], v[204:207], v[72:75]
	v_mfma_f32_16x16x32_bf16 v[72:75], v[184:187], v[208:211], v[72:75]
	s_setprio 2
	s_barrier
	v_mfma_f32_16x16x32_bf16 v[68:71], v[168:171], v[212:215], v[68:71]
	v_mfma_f32_16x16x32_bf16 v[68:71], v[172:175], v[216:219], v[68:71]
	v_mfma_f32_16x16x32_bf16 v[64:67], v[176:179], v[212:215], v[64:67]
	v_mfma_f32_16x16x32_bf16 v[64:67], v[184:187], v[216:219], v[64:67]
	s_setprio 0
	s_add_i32 s46, s77, s56
	v_lshl_add_u64 v[144:145], v[144:145], 0, s[10:11]
	s_mov_b32 m0, s46
	ds_read_b128 v[188:191], v151 offset:49152
	ds_read_b128 v[192:195], v151 offset:50176
	ds_read_b128 v[196:199], v151 offset:51200
	ds_read_b128 v[200:203], v151 offset:52224
	ds_read_b128 v[204:207], v151 offset:53248
	ds_read_b128 v[208:211], v151 offset:54272
	ds_read_b128 v[212:215], v151 offset:55296
	ds_read_b128 v[216:219], v151 offset:56320
	global_load_lds_dwordx4 v[144:145], off
	s_add_i32 m0, s46, 0x2000
	s_add_u32 s46, s50, 0xb0080
	v_lshl_add_u64 v[144:145], v[220:221], 0, s[10:11]
	s_addc_u32 s47, s51, 0
	s_add_i32 s50, s79, s56
	global_load_lds_dwordx4 v[144:145], off
	v_lshl_add_u64 v[144:145], s[46:47], 0, v[130:131]
	s_mov_b32 m0, s50
	s_nop 0
	global_load_lds_dwordx4 v[144:145], off
	v_lshl_add_u64 v[144:145], s[46:47], 0, v[134:135]
	s_add_i32 m0, s50, 0x2000
	s_nop 0
	global_load_lds_dwordx4 v[144:145], off
	v_lshl_add_u64 v[144:145], v[222:223], 0, s[10:11]
	s_mov_b32 m0, s62
	s_nop 0
	global_load_lds_dwordx4 v[144:145], off
	v_lshl_add_u64 v[144:145], v[224:225], 0, s[10:11]
	s_mov_b32 m0, s63
	s_nop 0
	global_load_lds_dwordx4 v[144:145], off
	s_waitcnt vmcnt(8)
	s_waitcnt lgkmcnt(0)
	s_barrier
	s_setprio 1
	s_waitcnt lgkmcnt(0)
	v_mfma_f32_16x16x32_bf16 v[60:63], v[152:155], v[188:191], v[60:63]
	v_mfma_f32_16x16x32_bf16 v[60:63], v[156:159], v[192:195], v[60:63]
	v_mfma_f32_16x16x32_bf16 v[56:59], v[160:163], v[188:191], v[56:59]
	v_mfma_f32_16x16x32_bf16 v[56:59], v[164:167], v[192:195], v[56:59]
	v_mfma_f32_16x16x32_bf16 v[52:55], v[152:155], v[196:199], v[52:55]
	v_mfma_f32_16x16x32_bf16 v[52:55], v[156:159], v[200:203], v[52:55]
	v_mfma_f32_16x16x32_bf16 v[44:47], v[160:163], v[196:199], v[44:47]
	v_mfma_f32_16x16x32_bf16 v[44:47], v[164:167], v[200:203], v[44:47]
	v_mfma_f32_16x16x32_bf16 v[36:39], v[152:155], v[204:207], v[36:39]
	v_mfma_f32_16x16x32_bf16 v[36:39], v[156:159], v[208:211], v[36:39]
	v_mfma_f32_16x16x32_bf16 v[28:31], v[160:163], v[204:207], v[28:31]
	v_mfma_f32_16x16x32_bf16 v[28:31], v[164:167], v[208:211], v[28:31]
	v_mfma_f32_16x16x32_bf16 v[20:23], v[152:155], v[212:215], v[20:23]
	v_mfma_f32_16x16x32_bf16 v[20:23], v[156:159], v[216:219], v[20:23]
	v_mfma_f32_16x16x32_bf16 v[12:15], v[160:163], v[212:215], v[12:15]
	v_mfma_f32_16x16x32_bf16 v[12:15], v[164:167], v[216:219], v[12:15]
	v_mfma_f32_16x16x32_bf16 v[48:51], v[168:171], v[188:191], v[48:51]
	v_mfma_f32_16x16x32_bf16 v[48:51], v[172:175], v[192:195], v[48:51]
	v_mfma_f32_16x16x32_bf16 v[40:43], v[176:179], v[188:191], v[40:43]
	v_mfma_f32_16x16x32_bf16 v[40:43], v[184:187], v[192:195], v[40:43]
	v_mfma_f32_16x16x32_bf16 v[32:35], v[168:171], v[196:199], v[32:35]
	v_mfma_f32_16x16x32_bf16 v[32:35], v[172:175], v[200:203], v[32:35]
	v_mfma_f32_16x16x32_bf16 v[24:27], v[176:179], v[196:199], v[24:27]
	v_mfma_f32_16x16x32_bf16 v[24:27], v[184:187], v[200:203], v[24:27]
	v_mfma_f32_16x16x32_bf16 v[16:19], v[168:171], v[204:207], v[16:19]
	v_mfma_f32_16x16x32_bf16 v[16:19], v[172:175], v[208:211], v[16:19]
	v_mfma_f32_16x16x32_bf16 v[8:11], v[176:179], v[204:207], v[8:11]
	v_mfma_f32_16x16x32_bf16 v[8:11], v[184:187], v[208:211], v[8:11]
	s_setprio 2
	s_barrier
	v_mfma_f32_16x16x32_bf16 v[4:7], v[168:171], v[212:215], v[4:7]
	v_mfma_f32_16x16x32_bf16 v[4:7], v[172:175], v[216:219], v[4:7]
	v_mfma_f32_16x16x32_bf16 v[0:3], v[176:179], v[212:215], v[0:3]
	v_mfma_f32_16x16x32_bf16 v[0:3], v[184:187], v[216:219], v[0:3]
	s_setprio 0
	s_add_i32 s76, s76, 2
	s_add_u32 s74, s74, 0x100
	s_addc_u32 s75, s75, 0
	s_cmp_gt_u32 s76, 41
	s_mov_b64 s[46:47], s[48:49]
	s_cbranch_scc0 .LBB0_1514
	s_and_b64 vcc, exec, s[12:13]
	s_cbranch_vccz .LBB0_1517
	s_barrier
